# v036
# speedup vs baseline: 1.0393x; 1.0046x over previous
; #define STAGE_A(P, half, kt) do { const char* _u = Ab + ((size_t)(half) * 128 * lda + (size_t)(kt) * BK) * 2; \
;     _Pragma("unroll") for (int _i = 0; _i < 2; ++_i) \
;       __builtin_amdgcn_global_load_lds((const unsigned*)(_u + offA[_i]), \
;         (__attribute__((address_space(3))) unsigned*)((__attribute__((address_space(3))) char*)(P) + tidg * 16 + _i * 8192), 16, 0, 0); } while (0)
; #define STAGE_B(P, half, kt) do { const char* _u = Bb + ((size_t)(half) * 128 * ldb + (size_t)(kt) * BK) * 2; \
;     _Pragma("unroll") for (int _i = 0; _i < 2; ++_i) \
;       __builtin_amdgcn_global_load_lds((const unsigned*)(_u + offB[_i]), \
;         (__attribute__((address_space(3))) unsigned*)((__attribute__((address_space(3))) char*)(P) + tidg * 16 + _i * 8192), 16, 0, 0); } while (0)
; #define WAIT_V(n) asm volatile("s_waitcnt vmcnt(" #n ")" ::: "memory")
; #define BAR __builtin_amdgcn_s_barrier()
; #define G_THREAD() do { asm volatile("" : "+v"(tidg)); wid = tidg >> 6; lane = tidg & 63; wr = wid >> 2; wc = wid & 3; fr = lane & 15; fq = lane >> 4; \
;     _Pragma("unroll") for (int _i = 0; _i < 2; ++_i) { int _r, _c; stage_rc(tidg * 16 + _i * 8192, _r, _c); offA[_i] = (unsigned)(_r * lda + _c) * 2u; offB[_i] = (unsigned)(_r * ldb + _c) * 2u; } } while (0)
; template <bool PF = true, class Epi, class KRF = KRFull>
; __device__ __forceinline__ void gemm_phase(const u16* __restrict__ A, int lda, const u16* __restrict__ Bt, int ldb, int K, int nM, int nN,
;                                            lds_u16* shm, Epi epi, KRF krf = KRFull(), bool flip = false) {
;     ...
;     G_THREAD();
;     nt = nt_next;
;     f32x4 acc[2][2][4][2] = {};
;     bf16x8 At[4][2], B0[2][2], B1[2][2];
;     if (wr == 1) BAR;
;     WAIT_V(4); BAR;
;     STAGE_B(SB(1, 0), 0, 1); STAGE_A(SA(1, 0), 0, 1); STAGE_B(SB(1, 1), 1, 1);
;     WAIT_V(6); BAR;
.LBB0_902:
	s_or_b64 exec, exec, s[14:15]
	v_bfe_i32 v2, v138, 27, 1
	v_lshlrev_b32_e32 v144, 4, v138
	v_lshrrev_b32_e32 v2, 22, v2
	v_add_u32_e32 v2, v144, v2
	v_and_b32_e32 v2, 0xfffffc00, v2
	v_sub_u32_e32 v2, v144, v2
	v_lshrrev_b32_e32 v3, 4, v2
	v_bitop3_b32 v2, v3, v2, 32 bitop3:0x6c
	v_ashrrev_i32_e32 v5, 31, v2
	v_ashrrev_i32_e32 v1, 31, v138
	v_lshrrev_b32_e32 v5, 26, v5
	v_lshrrev_b32_e32 v1, 26, v1
	v_add_u32_e32 v5, v2, v5
	v_add_u32_e32 v1, v138, v1
	v_ashrrev_i32_e32 v6, 6, v5
	v_and_b32_e32 v5, 0xc0, v5
	v_ashrrev_i32_e32 v4, 6, v1
	v_sub_u32_e32 v2, v2, v5
	v_lshlrev_b32_e32 v3, 3, v4
	v_lshlrev_b32_e32 v7, 5, v4
	v_ashrrev_i16_sdwa v2, v232, sext(v2) dst_sel:DWORD dst_unused:UNUSED_PAD src0_sel:DWORD src1_sel:BYTE_0
	v_and_b32_e32 v3, 0xffff0, v3
	v_and_b32_e32 v7, 32, v7
	v_bfe_i32 v5, v2, 0, 16
	v_add_u32_e32 v2, v7, v5
	v_add_lshl_u32 v3, v6, v3, 12
	v_add_u32_e32 v146, 0x2000, v144
	v_lshl_add_u32 v178, v2, 1, v3
	v_ashrrev_i32_e32 v2, 31, v146
	v_lshrrev_b32_e32 v2, 22, v2
	v_add_u32_e32 v2, v146, v2
	v_ashrrev_i32_e32 v7, 10, v2
	v_mul_i32_i24_e32 v2, 0x400, v7
	v_sub_u32_e32 v2, v146, v2
	v_lshrrev_b32_e32 v3, 4, v2
	v_bitop3_b32 v2, v3, v2, 32 bitop3:0x6c
	v_ashrrev_i32_e32 v8, 31, v2
	v_lshrrev_b32_e32 v8, 26, v8
	v_add_u32_e32 v8, v2, v8
	v_ashrrev_i32_e32 v9, 6, v8
	v_and_b32_e32 v8, 0xc0, v8
	v_sub_u32_e32 v2, v2, v8
	v_lshlrev_b32_e32 v3, 3, v7
	v_lshlrev_b32_e32 v10, 5, v7
	v_ashrrev_i16_sdwa v2, v232, sext(v2) dst_sel:DWORD dst_unused:UNUSED_PAD src0_sel:DWORD src1_sel:BYTE_0
	v_and_b32_e32 v3, 0xffff0, v3
	v_and_b32_e32 v10, 32, v10
	v_bfe_i32 v8, v2, 0, 16
	v_add_u32_e32 v2, v10, v8
	v_add_lshl_u32 v3, v9, v3, 12
	v_add_u32_e32 v147, 0x18000, v144
	v_lshl_add_u32 v128, v2, 1, v3
	v_lshl_add_u64 v[2:3], s[10:11], 0, v[178:179]
	v_readfirstlane_b32 s2, v147
	v_lshl_add_u64 v[2:3], v[2:3], 0, s[60:61]
	s_mov_b32 m0, s2
	v_mov_b32_e32 v129, v179
	v_add_u32_e32 v148, 0x1a000, v144
	s_waitcnt vmcnt(4)
	s_barrier
	global_load_lds_dwordx4 v[2:3], off
	v_lshl_add_u64 v[2:3], s[10:11], 0, v[128:129]
	v_readfirstlane_b32 s2, v148
	v_lshl_add_u64 v[2:3], v[2:3], 0, s[60:61]
	s_mov_b32 m0, s2
	v_add_u32_e32 v149, 0x8000, v144
	global_load_lds_dwordx4 v[2:3], off
	v_lshl_add_u64 v[2:3], s[12:13], 0, v[178:179]
	v_readfirstlane_b32 s2, v149
	v_lshl_add_u64 v[2:3], v[2:3], 0, s[60:61]
	s_mov_b32 m0, s2
	v_add_u32_e32 v150, 0xa000, v144
	global_load_lds_dwordx4 v[2:3], off
	v_lshl_add_u64 v[2:3], s[12:13], 0, v[128:129]
	v_readfirstlane_b32 s2, v150
	v_add_u32_e32 v151, 0x1c000, v144
	v_lshl_add_u64 v[2:3], v[2:3], 0, s[60:61]
	s_mov_b32 m0, s2
	s_add_u32 s2, s10, 0x80080
	v_readfirstlane_b32 s4, v151
	v_add_u32_e32 v152, 0x1e000, v144
	global_load_lds_dwordx4 v[2:3], off
	s_addc_u32 s3, s11, 0
	s_mov_b32 m0, s4
	v_readfirstlane_b32 s4, v152
	global_load_lds_dwordx4 v178, s[2:3]
	s_mov_b32 m0, s4
	v_and_b32_e32 v10, 15, v138
	global_load_lds_dwordx4 v128, s[2:3]
	v_lshlrev_b32_e32 v2, 6, v10
	v_lshlrev_b32_e32 v10, 2, v138
	v_and_b32_e32 v11, 48, v138
	v_and_b32_e32 v10, 32, v10
	v_or_b32_e32 v3, v2, v11
	v_bitop3_b32 v12, v2, v10, v11 bitop3:0x36
	s_mov_b32 s2, 0x14000
	v_lshlrev_b32_e32 v2, 6, v138
	v_bitop3_b32 v14, v3, s2, v10 bitop3:0xde
	s_mov_b32 s2, 0x18000
	v_lshlrev_b32_e32 v18, 13, v0
	v_and_b32_e32 v0, 0x3c0, v2
	v_bitop3_b32 v13, v3, s94, v10 bitop3:0xde
	v_bitop3_b32 v15, v3, s2, v10 bitop3:0xde
	v_bitop3_b32 v16, v3, s97, v10 bitop3:0xde
	v_bitop3_b32 v10, v0, v10, v11 bitop3:0x36
	v_lshlrev_b32_e32 v0, 15, v4
	v_and_b32_e32 v17, 0x3000, v2
	v_and_b32_e32 v0, 0xffff0000, v0
	v_lshlrev_b32_e32 v2, 15, v7
	v_lshl_add_u32 v0, v6, 12, v0
	v_and_b32_e32 v2, 0xffff0000, v2
	v_and_or_b32 v0, v1, 64, v0
	v_lshl_add_u32 v2, v9, 12, v2
	v_lshlrev_b32_e32 v3, 6, v7
	s_waitcnt vmcnt(6)
	v_lshl_add_u32 v0, v5, 1, v0
	v_mov_b32_e32 v1, v179
	v_and_or_b32 v2, v3, 64, v2
	v_or_b32_e32 v11, 0x800, v18
	v_or_b32_e32 v19, 0x1000, v18
	v_or_b32_e32 v20, 0x1800, v18
	v_lshl_add_u64 v[130:131], s[10:11], 0, v[0:1]
	v_lshl_add_u32 v2, v8, 1, v2
	v_mov_b32_e32 v3, v179
	v_lshl_add_u64 v[134:135], s[12:13], 0, v[0:1]
	v_mov_b32_e32 v0, 0
	v_lshl_add_u64 v[132:133], s[10:11], 0, v[2:3]
	v_lshl_add_u64 v[136:137], s[12:13], 0, v[2:3]
	s_mov_b32 s2, -2
	s_mov_b64 s[14:15], 0
	v_add_u32_e32 v154, v13, v17
	v_add_u32_e32 v142, v12, v18
	v_add_u32_e32 v141, v10, v11
	v_add_u32_e32 v140, v10, v19
	v_add_u32_e32 v139, v10, v20
	v_add_u32_e32 v153, v14, v17
	v_add_u32_e32 v145, v15, v17
	v_add_u32_e32 v143, v16, v17
	v_mov_b32_e32 v1, v0
	v_mov_b32_e32 v2, v0
	v_mov_b32_e32 v3, v0
	v_mov_b32_e32 v4, v0
	v_mov_b32_e32 v5, v0
	v_mov_b32_e32 v6, v0
	v_mov_b32_e32 v7, v0
	v_mov_b32_e32 v8, v0
	v_mov_b32_e32 v9, v0
	v_mov_b32_e32 v10, v0
	v_mov_b32_e32 v11, v0
	v_mov_b32_e32 v12, v0
	v_mov_b32_e32 v13, v0
	v_mov_b32_e32 v14, v0
	v_mov_b32_e32 v15, v0
	v_mov_b32_e32 v16, v0
	v_mov_b32_e32 v17, v0
	v_mov_b32_e32 v18, v0
	v_mov_b32_e32 v19, v0
	v_mov_b32_e32 v20, v0
	v_mov_b32_e32 v21, v0
	v_mov_b32_e32 v22, v0
	v_mov_b32_e32 v23, v0
	v_mov_b32_e32 v24, v0
	v_mov_b32_e32 v25, v0
	v_mov_b32_e32 v26, v0
	v_mov_b32_e32 v27, v0
	v_mov_b32_e32 v28, v0
	v_mov_b32_e32 v29, v0
	v_mov_b32_e32 v30, v0
	v_mov_b32_e32 v31, v0
	v_mov_b32_e32 v32, v0
	v_mov_b32_e32 v33, v0
	v_mov_b32_e32 v34, v0
	v_mov_b32_e32 v35, v0
	v_mov_b32_e32 v36, v0
	v_mov_b32_e32 v37, v0
	v_mov_b32_e32 v38, v0
	v_mov_b32_e32 v39, v0
	v_mov_b32_e32 v40, v0
	v_mov_b32_e32 v41, v0
	v_mov_b32_e32 v42, v0
	v_mov_b32_e32 v43, v0
	v_mov_b32_e32 v44, v0
	v_mov_b32_e32 v45, v0
	v_mov_b32_e32 v46, v0
	v_mov_b32_e32 v47, v0
	v_mov_b32_e32 v48, v0
	v_mov_b32_e32 v49, v0
	v_mov_b32_e32 v50, v0
; #define STAGE_A(P, half, kt) do { const char* _u = Ab + ((size_t)(half) * 128 * lda + (size_t)(kt) * BK) * 2; \
;     _Pragma("unroll") for (int _i = 0; _i < 2; ++_i) \
;       __builtin_amdgcn_global_load_lds((const unsigned*)(_u + offA[_i]), \
;         (__attribute__((address_space(3))) unsigned*)((__attribute__((address_space(3))) char*)(P) + tidg * 16 + _i * 8192), 16, 0, 0); } while (0)
; #define STAGE_B(P, half, kt) do { const char* _u = Bb + ((size_t)(half) * 128 * ldb + (size_t)(kt) * BK) * 2; \
;     _Pragma("unroll") for (int _i = 0; _i < 2; ++_i) \
;       __builtin_amdgcn_global_load_lds((const unsigned*)(_u + offB[_i]), \
;         (__attribute__((address_space(3))) unsigned*)((__attribute__((address_space(3))) char*)(P) + tidg * 16 + _i * 8192), 16, 0, 0); } while (0)
; #define LDA(dst, b, h) _Pragma("unroll") for (int m = 0; m < 4; ++m) _Pragma("unroll") for (int k = 0; k < 2; ++k) \
;     dst[m][k] = *reinterpret_cast<const bf16x8*>((const char*)SA(b, h) + lds_byte(wr * 64 + m * 16 + fr, k * 32 + fq * 8))
; #define LDB(dst, b, h) _Pragma("unroll") for (int n = 0; n < 2; ++n) _Pragma("unroll") for (int k = 0; k < 2; ++k) \
;     dst[n][k] = *reinterpret_cast<const bf16x8*>((const char*)SB(b, h) + lds_byte(wc * 32 + n * 16 + fr, k * 32 + fq * 8))
; #define WAIT_V(n) asm volatile("s_waitcnt vmcnt(" #n ")" ::: "memory")
; #define WAIT_L(n) asm volatile("s_waitcnt lgkmcnt(" #n ")" ::: "memory")
; #define BAR __builtin_amdgcn_s_barrier()
; #define SCHED __builtin_amdgcn_sched_barrier(0)
; template <bool PF = true, class Epi, class KRF = KRFull>
; __device__ __forceinline__ void gemm_phase(const u16* __restrict__ A, int lda, const u16* __restrict__ Bt, int ldb, int K, int nM, int nN,
;                                            lds_u16* shm, Epi epi, KRF krf = KRFull(), bool flip = false) {
;     ...
;     f32x4 acc[2][2][4][2] = {};
;     bf16x8 At[4][2], B0[2][2], B1[2][2];
;     if (wr == 1) BAR;
;     WAIT_V(4); BAR;
;     STAGE_B(SB(1, 0), 0, 1); STAGE_A(SA(1, 0), 0, 1); STAGE_B(SB(1, 1), 1, 1);
;     WAIT_V(6); BAR;
;     for (int t = 0; t < nt - 2; t += 2) {
;       LDB(B0, 0, 0); SCHED; LDA(At, 0, 0); STAGE_A(SA(1, 1), 1, t + 1);
;       WAIT_L(8); BAR; WAIT_L(0); MMA(0, 0, At, B0); BAR; SCHED;
;       LDB(B1, 0, 1); STAGE_B(SB(0, 0), 0, t + 2);
;       BAR; WAIT_L(0); MMA(0, 1, At, B1); BAR;
;       LDA(At, 0, 1); STAGE_A(SA(0, 0), 0, t + 2);
	v_mov_b32_e32 v51, v0
	v_mov_b32_e32 v52, v0
	v_mov_b32_e32 v53, v0
	v_mov_b32_e32 v54, v0
	v_mov_b32_e32 v55, v0
	v_mov_b32_e32 v56, v0
	v_mov_b32_e32 v57, v0
	v_mov_b32_e32 v58, v0
	v_mov_b32_e32 v59, v0
	v_mov_b32_e32 v60, v0
	v_mov_b32_e32 v61, v0
	v_mov_b32_e32 v62, v0
	v_mov_b32_e32 v63, v0
	v_mov_b32_e32 v64, v0
	v_mov_b32_e32 v65, v0
	v_mov_b32_e32 v66, v0
	v_mov_b32_e32 v67, v0
	v_mov_b32_e32 v68, v0
	v_mov_b32_e32 v69, v0
	v_mov_b32_e32 v70, v0
	v_mov_b32_e32 v71, v0
	v_mov_b32_e32 v72, v0
	v_mov_b32_e32 v73, v0
	v_mov_b32_e32 v74, v0
	v_mov_b32_e32 v75, v0
	v_mov_b32_e32 v76, v0
	v_mov_b32_e32 v77, v0
	v_mov_b32_e32 v78, v0
	v_mov_b32_e32 v79, v0
	v_mov_b32_e32 v80, v0
	v_mov_b32_e32 v81, v0
	v_mov_b32_e32 v82, v0
	v_mov_b32_e32 v83, v0
	v_mov_b32_e32 v84, v0
	v_mov_b32_e32 v85, v0
	v_mov_b32_e32 v86, v0
	v_mov_b32_e32 v87, v0
	v_mov_b32_e32 v88, v0
	v_mov_b32_e32 v89, v0
	v_mov_b32_e32 v90, v0
	v_mov_b32_e32 v91, v0
	v_mov_b32_e32 v92, v0
	v_mov_b32_e32 v93, v0
	v_mov_b32_e32 v94, v0
	v_mov_b32_e32 v95, v0
	v_mov_b32_e32 v96, v0
	v_mov_b32_e32 v97, v0
	v_mov_b32_e32 v98, v0
	v_mov_b32_e32 v99, v0
	v_mov_b32_e32 v100, v0
	v_mov_b32_e32 v101, v0
	v_mov_b32_e32 v102, v0
	v_mov_b32_e32 v103, v0
	v_mov_b32_e32 v104, v0
	v_mov_b32_e32 v105, v0
	v_mov_b32_e32 v106, v0
	v_mov_b32_e32 v107, v0
	v_mov_b32_e32 v108, v0
	v_mov_b32_e32 v109, v0
	v_mov_b32_e32 v110, v0
	v_mov_b32_e32 v111, v0
	v_mov_b32_e32 v112, v0
	v_mov_b32_e32 v113, v0
	v_mov_b32_e32 v114, v0
	v_mov_b32_e32 v115, v0
	v_mov_b32_e32 v116, v0
	v_mov_b32_e32 v117, v0
	v_mov_b32_e32 v118, v0
	v_mov_b32_e32 v119, v0
	v_mov_b32_e32 v120, v0
	v_mov_b32_e32 v121, v0
	v_mov_b32_e32 v122, v0
	v_mov_b32_e32 v123, v0
	v_mov_b32_e32 v124, v0
	v_mov_b32_e32 v125, v0
	v_mov_b32_e32 v126, v0
	v_mov_b32_e32 v127, v0
	s_barrier
	v_readfirstlane_b32 s3, v144
.LBB0_903:
	ds_read_b128 v[158:161], v154
	ds_read_b128 v[162:165], v154 offset:1024
	ds_read_b128 v[166:169], v154 offset:2048
	ds_read_b128 v[170:173], v154 offset:3072
	v_lshl_add_u64 v[174:175], v[134:135], 0, s[14:15]
	v_lshl_add_u64 v[156:157], v[174:175], 0, s[62:63]
	s_add_u32 m0, s3, 0xc000
	ds_read_b128 v[180:183], v142
	ds_read_b128 v[184:187], v142 offset:1024
	ds_read_b128 v[188:191], v141
	ds_read_b128 v[192:195], v141 offset:1024
	ds_read_b128 v[196:199], v140
	ds_read_b128 v[200:203], v140 offset:1024
	ds_read_b128 v[204:207], v139
	ds_read_b128 v[208:211], v139 offset:1024
	global_load_lds_dwordx4 v[156:157], off
	v_lshl_add_u64 v[222:223], v[136:137], 0, s[14:15]
	v_lshl_add_u64 v[212:213], v[222:223], 0, s[62:63]
	s_add_u32 m0, s3, 0xe000
	s_nop 0
	global_load_lds_dwordx4 v[212:213], off
	s_waitcnt lgkmcnt(8)
	s_barrier
	s_waitcnt lgkmcnt(0)
	s_setprio 1
	s_waitcnt lgkmcnt(0)
	v_mfma_f32_16x16x32_bf16 v[124:127], v[158:161], v[180:183], v[124:127]
	v_mfma_f32_16x16x32_bf16 v[120:123], v[166:169], v[180:183], v[120:123]
	v_mfma_f32_16x16x32_bf16 v[116:119], v[158:161], v[188:191], v[116:119]
	v_mfma_f32_16x16x32_bf16 v[112:115], v[166:169], v[188:191], v[112:115]
	v_mfma_f32_16x16x32_bf16 v[108:111], v[158:161], v[196:199], v[108:111]
	v_mfma_f32_16x16x32_bf16 v[104:107], v[166:169], v[196:199], v[104:107]
	v_mfma_f32_16x16x32_bf16 v[100:103], v[158:161], v[204:207], v[100:103]
	v_mfma_f32_16x16x32_bf16 v[96:99], v[166:169], v[204:207], v[96:99]
	v_mfma_f32_16x16x32_bf16 v[124:127], v[162:165], v[184:187], v[124:127]
	v_mfma_f32_16x16x32_bf16 v[120:123], v[170:173], v[184:187], v[120:123]
	v_mfma_f32_16x16x32_bf16 v[116:119], v[162:165], v[192:195], v[116:119]
	v_mfma_f32_16x16x32_bf16 v[112:115], v[170:173], v[192:195], v[112:115]
	v_mfma_f32_16x16x32_bf16 v[108:111], v[162:165], v[200:203], v[108:111]
	v_mfma_f32_16x16x32_bf16 v[104:107], v[170:173], v[200:203], v[104:107]
	v_mfma_f32_16x16x32_bf16 v[100:103], v[162:165], v[208:211], v[100:103]
	v_mfma_f32_16x16x32_bf16 v[96:99], v[170:173], v[208:211], v[96:99]
	s_setprio 0
	s_barrier
	v_lshl_add_u64 v[224:225], v[130:131], 0, s[14:15]
	v_lshl_add_u64 v[226:227], v[224:225], 0, s[64:65]
	s_add_u32 m0, s3, 0x10000
	ds_read_b128 v[212:215], v153
	ds_read_b128 v[216:219], v153 offset:1024
	ds_read_b128 v[238:241], v153 offset:2048
	ds_read_b128 v[242:245], v153 offset:3072
	global_load_lds_dwordx4 v[226:227], off
	v_lshl_add_u64 v[226:227], v[132:133], 0, s[14:15]
	v_lshl_add_u64 v[228:229], v[226:227], 0, s[64:65]
	s_add_u32 m0, s3, 0x12000
	s_nop 0
	global_load_lds_dwordx4 v[228:229], off
	s_barrier
	s_waitcnt lgkmcnt(0)
	s_setprio 1
	s_waitcnt lgkmcnt(0)
	v_mfma_f32_16x16x32_bf16 v[92:95], v[212:215], v[180:183], v[92:95]
	v_mfma_f32_16x16x32_bf16 v[88:91], v[238:241], v[180:183], v[88:91]
	v_mfma_f32_16x16x32_bf16 v[84:87], v[212:215], v[188:191], v[84:87]
	v_mfma_f32_16x16x32_bf16 v[80:83], v[238:241], v[188:191], v[80:83]
	v_mfma_f32_16x16x32_bf16 v[76:79], v[212:215], v[196:199], v[76:79]
	v_mfma_f32_16x16x32_bf16 v[72:75], v[238:241], v[196:199], v[72:75]
	v_mfma_f32_16x16x32_bf16 v[68:71], v[212:215], v[204:207], v[68:71]
	v_mfma_f32_16x16x32_bf16 v[64:67], v[238:241], v[204:207], v[64:67]
	v_mfma_f32_16x16x32_bf16 v[92:95], v[216:219], v[184:187], v[92:95]
	v_mfma_f32_16x16x32_bf16 v[88:91], v[242:245], v[184:187], v[88:91]
	v_mfma_f32_16x16x32_bf16 v[84:87], v[216:219], v[192:195], v[84:87]
	v_mfma_f32_16x16x32_bf16 v[80:83], v[242:245], v[192:195], v[80:83]
	v_mfma_f32_16x16x32_bf16 v[76:79], v[216:219], v[200:203], v[76:79]
	v_mfma_f32_16x16x32_bf16 v[72:75], v[242:245], v[200:203], v[72:75]
	v_mfma_f32_16x16x32_bf16 v[68:71], v[216:219], v[208:211], v[68:71]
	v_mfma_f32_16x16x32_bf16 v[64:67], v[242:245], v[208:211], v[64:67]
	s_setprio 0
	v_lshl_add_u64 v[228:229], v[174:175], 0, s[64:65]
	s_mov_b32 m0, s3
	s_barrier
; #define STAGE_A(P, half, kt) do { const char* _u = Ab + ((size_t)(half) * 128 * lda + (size_t)(kt) * BK) * 2; \
;     _Pragma("unroll") for (int _i = 0; _i < 2; ++_i) \
;       __builtin_amdgcn_global_load_lds((const unsigned*)(_u + offA[_i]), \
;         (__attribute__((address_space(3))) unsigned*)((__attribute__((address_space(3))) char*)(P) + tidg * 16 + _i * 8192), 16, 0, 0); } while (0)
; #define STAGE_B(P, half, kt) do { const char* _u = Bb + ((size_t)(half) * 128 * ldb + (size_t)(kt) * BK) * 2; \
;     _Pragma("unroll") for (int _i = 0; _i < 2; ++_i) \
;       __builtin_amdgcn_global_load_lds((const unsigned*)(_u + offB[_i]), \
;         (__attribute__((address_space(3))) unsigned*)((__attribute__((address_space(3))) char*)(P) + tidg * 16 + _i * 8192), 16, 0, 0); } while (0)
; #define LDA(dst, b, h) _Pragma("unroll") for (int m = 0; m < 4; ++m) _Pragma("unroll") for (int k = 0; k < 2; ++k) \
;     dst[m][k] = *reinterpret_cast<const bf16x8*>((const char*)SA(b, h) + lds_byte(wr * 64 + m * 16 + fr, k * 32 + fq * 8))
; #define LDB(dst, b, h) _Pragma("unroll") for (int n = 0; n < 2; ++n) _Pragma("unroll") for (int k = 0; k < 2; ++k) \
;     dst[n][k] = *reinterpret_cast<const bf16x8*>((const char*)SB(b, h) + lds_byte(wc * 32 + n * 16 + fr, k * 32 + fq * 8))
; #define WAIT_V(n) asm volatile("s_waitcnt vmcnt(" #n ")" ::: "memory")
; #define WAIT_L(n) asm volatile("s_waitcnt lgkmcnt(" #n ")" ::: "memory")
; #define BAR __builtin_amdgcn_s_barrier()
; #define SCHED __builtin_amdgcn_sched_barrier(0)
; template <bool PF = true, class Epi, class KRF = KRFull>
; __device__ __forceinline__ void gemm_phase(const u16* __restrict__ A, int lda, const u16* __restrict__ Bt, int ldb, int K, int nM, int nN,
;                                            lds_u16* shm, Epi epi, KRF krf = KRFull(), bool flip = false) {
;     ...
;       LDA(At, 0, 1); STAGE_A(SA(0, 0), 0, t + 2);
;       BAR; WAIT_L(0); MMA(1, 0, At, B0); BAR; SCHED;
;       STAGE_B(SB(0, 1), 1, t + 2);
;       WAIT_V(6); BAR; MMA(1, 1, At, B1); BAR;
;       LDB(B0, 1, 0); SCHED; LDA(At, 1, 0); STAGE_A(SA(0, 1), 1, t + 2);
;       WAIT_L(8); BAR; WAIT_L(0); MMA(0, 0, At, B0); BAR; SCHED;
;       LDB(B1, 1, 1); STAGE_B(SB(1, 0), 0, t + 3);
;       BAR; WAIT_L(0); MMA(0, 1, At, B1); BAR;
	ds_read_b128 v[180:183], v142 offset:16384
	ds_read_b128 v[184:187], v142 offset:17408
	ds_read_b128 v[188:191], v141 offset:16384
	ds_read_b128 v[192:195], v141 offset:17408
	ds_read_b128 v[196:199], v140 offset:16384
	ds_read_b128 v[200:203], v140 offset:17408
	ds_read_b128 v[204:207], v139 offset:16384
	ds_read_b128 v[208:211], v139 offset:17408
	global_load_lds_dwordx4 v[228:229], off
	v_lshl_add_u64 v[228:229], v[222:223], 0, s[64:65]
	s_add_u32 m0, s3, 0x2000
	s_nop 0
	global_load_lds_dwordx4 v[228:229], off
	s_barrier
	s_waitcnt lgkmcnt(0)
	s_setprio 1
	s_waitcnt lgkmcnt(0)
	v_mfma_f32_16x16x32_bf16 v[60:63], v[158:161], v[180:183], v[60:63]
	v_mfma_f32_16x16x32_bf16 v[56:59], v[166:169], v[180:183], v[56:59]
	v_mfma_f32_16x16x32_bf16 v[52:55], v[158:161], v[188:191], v[52:55]
	v_mfma_f32_16x16x32_bf16 v[48:51], v[166:169], v[188:191], v[48:51]
	v_mfma_f32_16x16x32_bf16 v[44:47], v[158:161], v[196:199], v[44:47]
	v_mfma_f32_16x16x32_bf16 v[40:43], v[166:169], v[196:199], v[40:43]
	v_mfma_f32_16x16x32_bf16 v[36:39], v[158:161], v[204:207], v[36:39]
	v_mfma_f32_16x16x32_bf16 v[32:35], v[166:169], v[204:207], v[32:35]
	v_mfma_f32_16x16x32_bf16 v[60:63], v[162:165], v[184:187], v[60:63]
	v_mfma_f32_16x16x32_bf16 v[56:59], v[170:173], v[184:187], v[56:59]
	v_mfma_f32_16x16x32_bf16 v[52:55], v[162:165], v[192:195], v[52:55]
	v_mfma_f32_16x16x32_bf16 v[48:51], v[170:173], v[192:195], v[48:51]
	v_mfma_f32_16x16x32_bf16 v[44:47], v[162:165], v[200:203], v[44:47]
	v_mfma_f32_16x16x32_bf16 v[40:43], v[170:173], v[200:203], v[40:43]
	v_mfma_f32_16x16x32_bf16 v[36:39], v[162:165], v[208:211], v[36:39]
	v_mfma_f32_16x16x32_bf16 v[32:35], v[170:173], v[208:211], v[32:35]
	s_setprio 0
	s_barrier
	v_lshl_add_u64 v[158:159], v[224:225], 0, s[66:67]
	s_add_u32 m0, s3, 0x14000
	s_nop 0
	global_load_lds_dwordx4 v[158:159], off
	v_lshl_add_u64 v[158:159], v[226:227], 0, s[66:67]
	s_add_u32 m0, s3, 0x16000
	s_nop 0
	global_load_lds_dwordx4 v[158:159], off
	s_waitcnt vmcnt(6)
	s_barrier
	s_setprio 1
	v_mfma_f32_16x16x32_bf16 v[28:31], v[212:215], v[180:183], v[28:31]
	v_mfma_f32_16x16x32_bf16 v[24:27], v[238:241], v[180:183], v[24:27]
	v_mfma_f32_16x16x32_bf16 v[20:23], v[212:215], v[188:191], v[20:23]
	v_mfma_f32_16x16x32_bf16 v[16:19], v[238:241], v[188:191], v[16:19]
	v_mfma_f32_16x16x32_bf16 v[12:15], v[212:215], v[196:199], v[12:15]
	v_mfma_f32_16x16x32_bf16 v[8:11], v[238:241], v[196:199], v[8:11]
	v_mfma_f32_16x16x32_bf16 v[4:7], v[212:215], v[204:207], v[4:7]
	v_mfma_f32_16x16x32_bf16 v[0:3], v[238:241], v[204:207], v[0:3]
	v_mfma_f32_16x16x32_bf16 v[28:31], v[216:219], v[184:187], v[28:31]
	v_mfma_f32_16x16x32_bf16 v[24:27], v[242:245], v[184:187], v[24:27]
	v_mfma_f32_16x16x32_bf16 v[20:23], v[216:219], v[192:195], v[20:23]
	v_mfma_f32_16x16x32_bf16 v[16:19], v[242:245], v[192:195], v[16:19]
	v_mfma_f32_16x16x32_bf16 v[12:15], v[216:219], v[200:203], v[12:15]
	v_mfma_f32_16x16x32_bf16 v[8:11], v[242:245], v[200:203], v[8:11]
	v_mfma_f32_16x16x32_bf16 v[4:7], v[216:219], v[208:211], v[4:7]
	v_mfma_f32_16x16x32_bf16 v[0:3], v[242:245], v[208:211], v[0:3]
	s_setprio 0
	s_barrier
	ds_read_b128 v[158:161], v145
	ds_read_b128 v[162:165], v145 offset:1024
	ds_read_b128 v[166:169], v145 offset:2048
	ds_read_b128 v[170:173], v145 offset:3072
	v_lshl_add_u64 v[212:213], v[174:175], 0, s[66:67]
	s_add_u32 m0, s3, 0x4000
	ds_read_b128 v[180:183], v142 offset:32768
	ds_read_b128 v[184:187], v142 offset:33792
	ds_read_b128 v[188:191], v141 offset:32768
	ds_read_b128 v[192:195], v141 offset:33792
	ds_read_b128 v[196:199], v140 offset:32768
	ds_read_b128 v[200:203], v140 offset:33792
	ds_read_b128 v[204:207], v139 offset:32768
	ds_read_b128 v[208:211], v139 offset:33792
	global_load_lds_dwordx4 v[212:213], off
	v_lshl_add_u64 v[212:213], v[222:223], 0, s[66:67]
	s_add_u32 m0, s3, 0x6000
	s_nop 0
	global_load_lds_dwordx4 v[212:213], off
	s_waitcnt lgkmcnt(8)
	s_barrier
	s_waitcnt lgkmcnt(0)
	s_setprio 1
	s_waitcnt lgkmcnt(0)
	v_mfma_f32_16x16x32_bf16 v[124:127], v[158:161], v[180:183], v[124:127]
	v_mfma_f32_16x16x32_bf16 v[120:123], v[166:169], v[180:183], v[120:123]
	v_mfma_f32_16x16x32_bf16 v[116:119], v[158:161], v[188:191], v[116:119]
	v_mfma_f32_16x16x32_bf16 v[112:115], v[166:169], v[188:191], v[112:115]
	v_mfma_f32_16x16x32_bf16 v[108:111], v[158:161], v[196:199], v[108:111]
	v_mfma_f32_16x16x32_bf16 v[104:107], v[166:169], v[196:199], v[104:107]
	v_mfma_f32_16x16x32_bf16 v[100:103], v[158:161], v[204:207], v[100:103]
	v_mfma_f32_16x16x32_bf16 v[96:99], v[166:169], v[204:207], v[96:99]
	v_mfma_f32_16x16x32_bf16 v[124:127], v[162:165], v[184:187], v[124:127]
	v_mfma_f32_16x16x32_bf16 v[120:123], v[170:173], v[184:187], v[120:123]
	v_mfma_f32_16x16x32_bf16 v[116:119], v[162:165], v[192:195], v[116:119]
	v_mfma_f32_16x16x32_bf16 v[112:115], v[170:173], v[192:195], v[112:115]
	v_mfma_f32_16x16x32_bf16 v[108:111], v[162:165], v[200:203], v[108:111]
	v_mfma_f32_16x16x32_bf16 v[104:107], v[170:173], v[200:203], v[104:107]
	v_mfma_f32_16x16x32_bf16 v[100:103], v[162:165], v[208:211], v[100:103]
	v_mfma_f32_16x16x32_bf16 v[96:99], v[170:173], v[208:211], v[96:99]
	s_setprio 0
	s_barrier
	v_lshl_add_u64 v[228:229], v[224:225], 0, s[68:69]
	s_add_u32 m0, s3, 0x18000
	ds_read_b128 v[212:215], v143
	ds_read_b128 v[216:219], v143 offset:1024
	ds_read_b128 v[238:241], v143 offset:2048
	ds_read_b128 v[242:245], v143 offset:3072
	global_load_lds_dwordx4 v[228:229], off
	v_lshl_add_u64 v[228:229], v[226:227], 0, s[68:69]
	s_add_u32 m0, s3, 0x1a000
	s_nop 0
	global_load_lds_dwordx4 v[228:229], off
	s_barrier
; #define STAGE_A(P, half, kt) do { const char* _u = Ab + ((size_t)(half) * 128 * lda + (size_t)(kt) * BK) * 2; \
;     _Pragma("unroll") for (int _i = 0; _i < 2; ++_i) \
;       __builtin_amdgcn_global_load_lds((const unsigned*)(_u + offA[_i]), \
;         (__attribute__((address_space(3))) unsigned*)((__attribute__((address_space(3))) char*)(P) + tidg * 16 + _i * 8192), 16, 0, 0); } while (0)
; #define STAGE_B(P, half, kt) do { const char* _u = Bb + ((size_t)(half) * 128 * ldb + (size_t)(kt) * BK) * 2; \
;     _Pragma("unroll") for (int _i = 0; _i < 2; ++_i) \
;       __builtin_amdgcn_global_load_lds((const unsigned*)(_u + offB[_i]), \
;         (__attribute__((address_space(3))) unsigned*)((__attribute__((address_space(3))) char*)(P) + tidg * 16 + _i * 8192), 16, 0, 0); } while (0)
; #define LDA(dst, b, h) _Pragma("unroll") for (int m = 0; m < 4; ++m) _Pragma("unroll") for (int k = 0; k < 2; ++k) \
;     dst[m][k] = *reinterpret_cast<const bf16x8*>((const char*)SA(b, h) + lds_byte(wr * 64 + m * 16 + fr, k * 32 + fq * 8))
; #define LDB(dst, b, h) _Pragma("unroll") for (int n = 0; n < 2; ++n) _Pragma("unroll") for (int k = 0; k < 2; ++k) \
;     dst[n][k] = *reinterpret_cast<const bf16x8*>((const char*)SB(b, h) + lds_byte(wc * 32 + n * 16 + fr, k * 32 + fq * 8))
; #define MMA(ai, bj, At_, Bt_) do { __builtin_amdgcn_s_setprio(1); \
;     _Pragma("unroll") for (int m = 0; m < 4; ++m) _Pragma("unroll") for (int n = 0; n < 2; ++n) _Pragma("unroll") for (int k = 0; k < 2; ++k) \
;       acc[ai][bj][m][n] = __builtin_amdgcn_mfma_f32_16x16x32_bf16(Bt_[n][k], At_[m][k], acc[ai][bj][m][n], 0, 0, 0); \
;     __builtin_amdgcn_s_setprio(0); } while (0)
; #define WAIT_V(n) asm volatile("s_waitcnt vmcnt(" #n ")" ::: "memory")
; template <bool PF = true, class Epi, class KRF = KRFull>
; __device__ __forceinline__ void gemm_phase(const u16* __restrict__ A, int lda, const u16* __restrict__ Bt, int ldb, int K, int nM, int nN,
;                                            lds_u16* shm, Epi epi, KRF krf = KRFull(), bool flip = false) {
;     ...
;       BAR; WAIT_L(0); MMA(0, 1, At, B1); BAR;
;       LDA(At, 1, 1); STAGE_A(SA(1, 0), 0, t + 3);
;       BAR; WAIT_L(0); MMA(1, 0, At, B0); BAR; SCHED;
;       STAGE_B(SB(1, 1), 1, t + 3);
;       WAIT_V(6); BAR; MMA(1, 1, At, B1); BAR;
;     }
;     { LDB(B0, 0, 0); LDA(At, 0, 0); STAGE_A(SA(1, 1), 1, nt - 1);
	s_waitcnt lgkmcnt(0)
	s_setprio 1
	s_waitcnt lgkmcnt(0)
	v_mfma_f32_16x16x32_bf16 v[92:95], v[212:215], v[180:183], v[92:95]
	v_mfma_f32_16x16x32_bf16 v[88:91], v[238:241], v[180:183], v[88:91]
	v_mfma_f32_16x16x32_bf16 v[84:87], v[212:215], v[188:191], v[84:87]
	v_mfma_f32_16x16x32_bf16 v[80:83], v[238:241], v[188:191], v[80:83]
	v_mfma_f32_16x16x32_bf16 v[76:79], v[212:215], v[196:199], v[76:79]
	v_mfma_f32_16x16x32_bf16 v[72:75], v[238:241], v[196:199], v[72:75]
	v_mfma_f32_16x16x32_bf16 v[68:71], v[212:215], v[204:207], v[68:71]
	v_mfma_f32_16x16x32_bf16 v[64:67], v[238:241], v[204:207], v[64:67]
	v_mfma_f32_16x16x32_bf16 v[92:95], v[216:219], v[184:187], v[92:95]
	v_mfma_f32_16x16x32_bf16 v[88:91], v[242:245], v[184:187], v[88:91]
	v_mfma_f32_16x16x32_bf16 v[84:87], v[216:219], v[192:195], v[84:87]
	v_mfma_f32_16x16x32_bf16 v[80:83], v[242:245], v[192:195], v[80:83]
	v_mfma_f32_16x16x32_bf16 v[76:79], v[216:219], v[200:203], v[76:79]
	v_mfma_f32_16x16x32_bf16 v[72:75], v[242:245], v[200:203], v[72:75]
	v_mfma_f32_16x16x32_bf16 v[68:71], v[216:219], v[208:211], v[68:71]
	v_mfma_f32_16x16x32_bf16 v[64:67], v[242:245], v[208:211], v[64:67]
	s_setprio 0
	v_lshl_add_u64 v[174:175], v[174:175], 0, s[68:69]
	s_add_u32 m0, s3, 0x8000
	s_barrier
	ds_read_b128 v[180:183], v142 offset:49152
	ds_read_b128 v[184:187], v142 offset:50176
	ds_read_b128 v[188:191], v141 offset:49152
	ds_read_b128 v[192:195], v141 offset:50176
	ds_read_b128 v[196:199], v140 offset:49152
	ds_read_b128 v[200:203], v140 offset:50176
	ds_read_b128 v[204:207], v139 offset:49152
	ds_read_b128 v[208:211], v139 offset:50176
	global_load_lds_dwordx4 v[174:175], off
	v_lshl_add_u64 v[174:175], v[222:223], 0, s[68:69]
	s_add_u32 m0, s3, 0xa000
	s_nop 0
	global_load_lds_dwordx4 v[174:175], off
	s_barrier
	s_waitcnt lgkmcnt(0)
	s_setprio 1
	s_waitcnt lgkmcnt(0)
	v_mfma_f32_16x16x32_bf16 v[60:63], v[158:161], v[180:183], v[60:63]
	v_mfma_f32_16x16x32_bf16 v[56:59], v[166:169], v[180:183], v[56:59]
	v_mfma_f32_16x16x32_bf16 v[52:55], v[158:161], v[188:191], v[52:55]
	v_mfma_f32_16x16x32_bf16 v[48:51], v[166:169], v[188:191], v[48:51]
	v_mfma_f32_16x16x32_bf16 v[44:47], v[158:161], v[196:199], v[44:47]
	v_mfma_f32_16x16x32_bf16 v[40:43], v[166:169], v[196:199], v[40:43]
	v_mfma_f32_16x16x32_bf16 v[36:39], v[158:161], v[204:207], v[36:39]
	v_mfma_f32_16x16x32_bf16 v[32:35], v[166:169], v[204:207], v[32:35]
	v_mfma_f32_16x16x32_bf16 v[60:63], v[162:165], v[184:187], v[60:63]
	v_mfma_f32_16x16x32_bf16 v[56:59], v[170:173], v[184:187], v[56:59]
	v_mfma_f32_16x16x32_bf16 v[52:55], v[162:165], v[192:195], v[52:55]
	v_mfma_f32_16x16x32_bf16 v[48:51], v[170:173], v[192:195], v[48:51]
	v_mfma_f32_16x16x32_bf16 v[44:47], v[162:165], v[200:203], v[44:47]
	v_mfma_f32_16x16x32_bf16 v[40:43], v[170:173], v[200:203], v[40:43]
	v_mfma_f32_16x16x32_bf16 v[36:39], v[162:165], v[208:211], v[36:39]
	v_mfma_f32_16x16x32_bf16 v[32:35], v[170:173], v[208:211], v[32:35]
	s_setprio 0
	s_barrier
	v_lshl_add_u64 v[158:159], v[224:225], 0, s[70:71]
	s_add_u32 m0, s3, 0x1c000
	s_nop 0
	global_load_lds_dwordx4 v[158:159], off
	v_lshl_add_u64 v[158:159], v[226:227], 0, s[70:71]
	s_add_u32 m0, s3, 0x1e000
	s_nop 0
	global_load_lds_dwordx4 v[158:159], off
	s_waitcnt vmcnt(6)
	s_barrier
	s_setprio 1
	v_mfma_f32_16x16x32_bf16 v[28:31], v[212:215], v[180:183], v[28:31]
	v_mfma_f32_16x16x32_bf16 v[24:27], v[238:241], v[180:183], v[24:27]
	v_mfma_f32_16x16x32_bf16 v[20:23], v[212:215], v[188:191], v[20:23]
	v_mfma_f32_16x16x32_bf16 v[16:19], v[238:241], v[188:191], v[16:19]
	v_mfma_f32_16x16x32_bf16 v[12:15], v[212:215], v[196:199], v[12:15]
	v_mfma_f32_16x16x32_bf16 v[8:11], v[238:241], v[196:199], v[8:11]
	v_mfma_f32_16x16x32_bf16 v[4:7], v[212:215], v[204:207], v[4:7]
	v_mfma_f32_16x16x32_bf16 v[0:3], v[238:241], v[204:207], v[0:3]
	v_mfma_f32_16x16x32_bf16 v[28:31], v[216:219], v[184:187], v[28:31]
	v_mfma_f32_16x16x32_bf16 v[24:27], v[242:245], v[184:187], v[24:27]
	v_mfma_f32_16x16x32_bf16 v[20:23], v[216:219], v[192:195], v[20:23]
	v_mfma_f32_16x16x32_bf16 v[16:19], v[242:245], v[192:195], v[16:19]
	v_mfma_f32_16x16x32_bf16 v[12:15], v[216:219], v[200:203], v[12:15]
	v_mfma_f32_16x16x32_bf16 v[8:11], v[242:245], v[200:203], v[8:11]
	v_mfma_f32_16x16x32_bf16 v[4:7], v[216:219], v[208:211], v[4:7]
	v_mfma_f32_16x16x32_bf16 v[0:3], v[242:245], v[208:211], v[0:3]
	s_setprio 0
	s_add_i32 s2, s2, 2
	s_add_u32 s14, s14, 0x100
	s_addc_u32 s15, s15, 0
	s_cmp_gt_u32 s2, 27
	s_barrier
	s_cbranch_scc0 .LBB0_903
	v_add_u32_e32 v155, 0xc000, v144
	v_add_u32_e32 v156, 0xe000, v144
	v_add_u32_e32 v157, 0x6000, v144
	s_add_u32 s2, s12, 0x80f80
	s_addc_u32 s3, s13, 0
	v_readfirstlane_b32 s4, v155
	v_lshl_add_u64 v[150:151], s[2:3], 0, v[178:179]
	s_mov_b32 m0, s4
	v_lshl_add_u64 v[128:129], s[2:3], 0, v[128:129]
	v_readfirstlane_b32 s2, v156
	ds_read_b128 v[130:133], v154
	ds_read_b128 v[134:137], v154 offset:1024
	ds_read_b128 v[146:149], v154 offset:2048
	ds_read_b128 v[158:161], v154 offset:3072
	ds_read_b128 v[162:165], v142
	ds_read_b128 v[166:169], v142 offset:1024
	ds_read_b128 v[170:173], v141
	ds_read_b128 v[180:183], v141 offset:1024
	ds_read_b128 v[184:187], v140
	ds_read_b128 v[188:191], v140 offset:1024
	ds_read_b128 v[192:195], v139
	ds_read_b128 v[196:199], v139 offset:1024
	global_load_lds_dwordx4 v[150:151], off
	s_mov_b32 m0, s2
	s_nop 0
	global_load_lds_dwordx4 v[128:129], off
	s_barrier
; #define LDA(dst, b, h) _Pragma("unroll") for (int m = 0; m < 4; ++m) _Pragma("unroll") for (int k = 0; k < 2; ++k) \
;     dst[m][k] = *reinterpret_cast<const bf16x8*>((const char*)SA(b, h) + lds_byte(wr * 64 + m * 16 + fr, k * 32 + fq * 8))
; #define LDB(dst, b, h) _Pragma("unroll") for (int n = 0; n < 2; ++n) _Pragma("unroll") for (int k = 0; k < 2; ++k) \
;     dst[n][k] = *reinterpret_cast<const bf16x8*>((const char*)SB(b, h) + lds_byte(wc * 32 + n * 16 + fr, k * 32 + fq * 8))
; #define MMA(ai, bj, At_, Bt_) do { __builtin_amdgcn_s_setprio(1); \
;     _Pragma("unroll") for (int m = 0; m < 4; ++m) _Pragma("unroll") for (int n = 0; n < 2; ++n) _Pragma("unroll") for (int k = 0; k < 2; ++k) \
;       acc[ai][bj][m][n] = __builtin_amdgcn_mfma_f32_16x16x32_bf16(Bt_[n][k], At_[m][k], acc[ai][bj][m][n], 0, 0, 0); \
;     __builtin_amdgcn_s_setprio(0); } while (0)
; #define WAIT_V(n) asm volatile("s_waitcnt vmcnt(" #n ")" ::: "memory")
; #define WAIT_L(n) asm volatile("s_waitcnt lgkmcnt(" #n ")" ::: "memory")
; #define BAR __builtin_amdgcn_s_barrier()
; template <bool PF = true, class Epi, class KRF = KRFull>
; __device__ __forceinline__ void gemm_phase(const u16* __restrict__ A, int lda, const u16* __restrict__ Bt, int ldb, int K, int nM, int nN,
;                                            lds_u16* shm, Epi epi, KRF krf = KRFull(), bool flip = false) {
;     ...
;       BAR; WAIT_L(0); MMA(0, 0, At, B0); BAR;
;       LDB(B1, 0, 1); BAR; WAIT_L(0); MMA(0, 1, At, B1); BAR;
;       LDA(At, 0, 1); WAIT_V(4); BAR; WAIT_L(0); MMA(1, 0, At, B0); MMA(1, 1, At, B1); BAR; }
;     { LDB(B0, 1, 0); LDA(At, 1, 0); WAIT_V(2); BAR; WAIT_L(0); MMA(0, 0, At, B0); BAR;
	s_waitcnt lgkmcnt(0)
	s_setprio 1
	s_waitcnt lgkmcnt(0)
	v_mfma_f32_16x16x32_bf16 v[124:127], v[130:133], v[162:165], v[124:127]
	v_mfma_f32_16x16x32_bf16 v[120:123], v[146:149], v[162:165], v[120:123]
	v_mfma_f32_16x16x32_bf16 v[116:119], v[130:133], v[170:173], v[116:119]
	v_mfma_f32_16x16x32_bf16 v[112:115], v[146:149], v[170:173], v[112:115]
	v_mfma_f32_16x16x32_bf16 v[108:111], v[130:133], v[184:187], v[108:111]
	v_mfma_f32_16x16x32_bf16 v[104:107], v[146:149], v[184:187], v[104:107]
	v_mfma_f32_16x16x32_bf16 v[100:103], v[130:133], v[192:195], v[100:103]
	v_mfma_f32_16x16x32_bf16 v[96:99], v[146:149], v[192:195], v[96:99]
	v_mfma_f32_16x16x32_bf16 v[124:127], v[134:137], v[166:169], v[124:127]
	v_mfma_f32_16x16x32_bf16 v[120:123], v[158:161], v[166:169], v[120:123]
	v_mfma_f32_16x16x32_bf16 v[116:119], v[134:137], v[180:183], v[116:119]
	v_mfma_f32_16x16x32_bf16 v[112:115], v[158:161], v[180:183], v[112:115]
	v_mfma_f32_16x16x32_bf16 v[108:111], v[134:137], v[188:191], v[108:111]
	v_mfma_f32_16x16x32_bf16 v[104:107], v[158:161], v[188:191], v[104:107]
	v_mfma_f32_16x16x32_bf16 v[100:103], v[134:137], v[196:199], v[100:103]
	v_mfma_f32_16x16x32_bf16 v[96:99], v[158:161], v[196:199], v[96:99]
	s_setprio 0
	s_barrier
	ds_read_b128 v[154:157], v153
	ds_read_b128 v[200:203], v153 offset:1024
	ds_read_b128 v[204:207], v153 offset:2048
	ds_read_b128 v[150:153], v153 offset:3072
	s_barrier
	s_waitcnt lgkmcnt(0)
	s_setprio 1
	s_waitcnt lgkmcnt(0)
	v_mfma_f32_16x16x32_bf16 v[92:95], v[154:157], v[162:165], v[92:95]
	v_mfma_f32_16x16x32_bf16 v[88:91], v[204:207], v[162:165], v[88:91]
	v_mfma_f32_16x16x32_bf16 v[84:87], v[154:157], v[170:173], v[84:87]
	v_mfma_f32_16x16x32_bf16 v[80:83], v[204:207], v[170:173], v[80:83]
	v_mfma_f32_16x16x32_bf16 v[76:79], v[154:157], v[184:187], v[76:79]
	v_mfma_f32_16x16x32_bf16 v[72:75], v[204:207], v[184:187], v[72:75]
	v_mfma_f32_16x16x32_bf16 v[68:71], v[154:157], v[192:195], v[68:71]
	v_mfma_f32_16x16x32_bf16 v[64:67], v[204:207], v[192:195], v[64:67]
	v_mfma_f32_16x16x32_bf16 v[92:95], v[200:203], v[166:169], v[92:95]
	v_mfma_f32_16x16x32_bf16 v[88:91], v[150:153], v[166:169], v[88:91]
	v_mfma_f32_16x16x32_bf16 v[84:87], v[200:203], v[180:183], v[84:87]
	v_mfma_f32_16x16x32_bf16 v[80:83], v[150:153], v[180:183], v[80:83]
	v_mfma_f32_16x16x32_bf16 v[76:79], v[200:203], v[188:191], v[76:79]
	v_mfma_f32_16x16x32_bf16 v[72:75], v[150:153], v[188:191], v[72:75]
	v_mfma_f32_16x16x32_bf16 v[68:71], v[200:203], v[196:199], v[68:71]
	v_mfma_f32_16x16x32_bf16 v[64:67], v[150:153], v[196:199], v[64:67]
	s_setprio 0
	s_barrier
	ds_read_b128 v[162:165], v142 offset:16384
	ds_read_b128 v[166:169], v142 offset:17408
	ds_read_b128 v[170:173], v141 offset:16384
	ds_read_b128 v[180:183], v141 offset:17408
	ds_read_b128 v[184:187], v140 offset:16384
	ds_read_b128 v[188:191], v140 offset:17408
	ds_read_b128 v[192:195], v139 offset:16384
	ds_read_b128 v[196:199], v139 offset:17408
	s_waitcnt vmcnt(4)
	s_barrier
	s_waitcnt lgkmcnt(0)
	s_setprio 1
	s_waitcnt lgkmcnt(0)
	v_mfma_f32_16x16x32_bf16 v[60:63], v[130:133], v[162:165], v[60:63]
	v_mfma_f32_16x16x32_bf16 v[56:59], v[146:149], v[162:165], v[56:59]
	v_mfma_f32_16x16x32_bf16 v[52:55], v[130:133], v[170:173], v[52:55]
	v_mfma_f32_16x16x32_bf16 v[48:51], v[146:149], v[170:173], v[48:51]
	v_mfma_f32_16x16x32_bf16 v[44:47], v[130:133], v[184:187], v[44:47]
	v_mfma_f32_16x16x32_bf16 v[40:43], v[146:149], v[184:187], v[40:43]
	v_mfma_f32_16x16x32_bf16 v[36:39], v[130:133], v[192:195], v[36:39]
	v_mfma_f32_16x16x32_bf16 v[32:35], v[146:149], v[192:195], v[32:35]
	v_mfma_f32_16x16x32_bf16 v[60:63], v[134:137], v[166:169], v[60:63]
	v_mfma_f32_16x16x32_bf16 v[56:59], v[158:161], v[166:169], v[56:59]
	v_mfma_f32_16x16x32_bf16 v[52:55], v[134:137], v[180:183], v[52:55]
	v_mfma_f32_16x16x32_bf16 v[48:51], v[158:161], v[180:183], v[48:51]
	v_mfma_f32_16x16x32_bf16 v[44:47], v[134:137], v[188:191], v[44:47]
	v_mfma_f32_16x16x32_bf16 v[40:43], v[158:161], v[188:191], v[40:43]
	v_mfma_f32_16x16x32_bf16 v[36:39], v[134:137], v[196:199], v[36:39]
	v_mfma_f32_16x16x32_bf16 v[32:35], v[158:161], v[196:199], v[32:35]
	s_setprio 0
	s_setprio 1
	v_mfma_f32_16x16x32_bf16 v[28:31], v[154:157], v[162:165], v[28:31]
	v_mfma_f32_16x16x32_bf16 v[24:27], v[204:207], v[162:165], v[24:27]
	v_mfma_f32_16x16x32_bf16 v[20:23], v[154:157], v[170:173], v[20:23]
	v_mfma_f32_16x16x32_bf16 v[16:19], v[204:207], v[170:173], v[16:19]
	v_mfma_f32_16x16x32_bf16 v[12:15], v[154:157], v[184:187], v[12:15]
	v_mfma_f32_16x16x32_bf16 v[8:11], v[204:207], v[184:187], v[8:11]
	v_mfma_f32_16x16x32_bf16 v[4:7], v[154:157], v[192:195], v[4:7]
	v_mfma_f32_16x16x32_bf16 v[0:3], v[204:207], v[192:195], v[0:3]
	v_mfma_f32_16x16x32_bf16 v[28:31], v[200:203], v[166:169], v[28:31]
	v_mfma_f32_16x16x32_bf16 v[24:27], v[150:153], v[166:169], v[24:27]
	v_mfma_f32_16x16x32_bf16 v[20:23], v[200:203], v[180:183], v[20:23]
	v_mfma_f32_16x16x32_bf16 v[16:19], v[150:153], v[180:183], v[16:19]
	v_mfma_f32_16x16x32_bf16 v[12:15], v[200:203], v[188:191], v[12:15]
	v_mfma_f32_16x16x32_bf16 v[8:11], v[150:153], v[188:191], v[8:11]
	v_mfma_f32_16x16x32_bf16 v[4:7], v[200:203], v[196:199], v[4:7]
	v_mfma_f32_16x16x32_bf16 v[0:3], v[150:153], v[196:199], v[0:3]
	s_setprio 0
	s_barrier
	ds_read_b128 v[128:131], v145
	ds_read_b128 v[132:135], v145 offset:1024
	ds_read_b128 v[146:149], v145 offset:2048
	ds_read_b128 v[150:153], v145 offset:3072
	ds_read_b128 v[154:157], v142 offset:32768
	ds_read_b128 v[158:161], v142 offset:33792
	ds_read_b128 v[162:165], v141 offset:32768
	ds_read_b128 v[166:169], v141 offset:33792
	ds_read_b128 v[170:173], v140 offset:32768
	ds_read_b128 v[180:183], v140 offset:33792
	ds_read_b128 v[184:187], v139 offset:32768
	ds_read_b128 v[188:191], v139 offset:33792
	s_waitcnt vmcnt(2)
	s_barrier
; #define LDA(dst, b, h) _Pragma("unroll") for (int m = 0; m < 4; ++m) _Pragma("unroll") for (int k = 0; k < 2; ++k) \
;     dst[m][k] = *reinterpret_cast<const bf16x8*>((const char*)SA(b, h) + lds_byte(wr * 64 + m * 16 + fr, k * 32 + fq * 8))
; #define LDB(dst, b, h) _Pragma("unroll") for (int n = 0; n < 2; ++n) _Pragma("unroll") for (int k = 0; k < 2; ++k) \
;     dst[n][k] = *reinterpret_cast<const bf16x8*>((const char*)SB(b, h) + lds_byte(wc * 32 + n * 16 + fr, k * 32 + fq * 8))
; #define MMA(ai, bj, At_, Bt_) do { __builtin_amdgcn_s_setprio(1); \
;     _Pragma("unroll") for (int m = 0; m < 4; ++m) _Pragma("unroll") for (int n = 0; n < 2; ++n) _Pragma("unroll") for (int k = 0; k < 2; ++k) \
;       acc[ai][bj][m][n] = __builtin_amdgcn_mfma_f32_16x16x32_bf16(Bt_[n][k], At_[m][k], acc[ai][bj][m][n], 0, 0, 0); \
;     __builtin_amdgcn_s_setprio(0); } while (0)
; #define WAIT_V(n) asm volatile("s_waitcnt vmcnt(" #n ")" ::: "memory")
; #define WAIT_L(n) asm volatile("s_waitcnt lgkmcnt(" #n ")" ::: "memory")
; #define BAR __builtin_amdgcn_s_barrier()
; template <bool PF = true, class Epi, class KRF = KRFull>
; __device__ __forceinline__ void gemm_phase(const u16* __restrict__ A, int lda, const u16* __restrict__ Bt, int ldb, int K, int nM, int nN,
;                                            lds_u16* shm, Epi epi, KRF krf = KRFull(), bool flip = false) {
;     ...
;     { LDB(B0, 1, 0); LDA(At, 1, 0); WAIT_V(2); BAR; WAIT_L(0); MMA(0, 0, At, B0); BAR;
;       LDB(B1, 1, 1); WAIT_V(0); BAR; WAIT_L(0); MMA(0, 1, At, B1); BAR;
;       LDA(At, 1, 1); BAR; WAIT_L(0); MMA(1, 0, At, B0); MMA(1, 1, At, B1); BAR; }
;     if (wr == 0) BAR;
	s_waitcnt lgkmcnt(0)
	s_setprio 1
	s_waitcnt lgkmcnt(0)
	v_mfma_f32_16x16x32_bf16 v[124:127], v[128:131], v[154:157], v[124:127]
	v_mfma_f32_16x16x32_bf16 v[120:123], v[146:149], v[154:157], v[120:123]
	v_mfma_f32_16x16x32_bf16 v[116:119], v[128:131], v[162:165], v[116:119]
	v_mfma_f32_16x16x32_bf16 v[112:115], v[146:149], v[162:165], v[112:115]
	v_mfma_f32_16x16x32_bf16 v[108:111], v[128:131], v[170:173], v[108:111]
	v_mfma_f32_16x16x32_bf16 v[104:107], v[146:149], v[170:173], v[104:107]
	v_mfma_f32_16x16x32_bf16 v[100:103], v[128:131], v[184:187], v[100:103]
	v_mfma_f32_16x16x32_bf16 v[96:99], v[146:149], v[184:187], v[96:99]
	v_mfma_f32_16x16x32_bf16 v[124:127], v[132:135], v[158:161], v[124:127]
	v_mfma_f32_16x16x32_bf16 v[120:123], v[150:153], v[158:161], v[120:123]
	v_mfma_f32_16x16x32_bf16 v[116:119], v[132:135], v[166:169], v[116:119]
	v_mfma_f32_16x16x32_bf16 v[112:115], v[150:153], v[166:169], v[112:115]
	v_mfma_f32_16x16x32_bf16 v[108:111], v[132:135], v[180:183], v[108:111]
	v_mfma_f32_16x16x32_bf16 v[104:107], v[150:153], v[180:183], v[104:107]
	v_mfma_f32_16x16x32_bf16 v[100:103], v[132:135], v[188:191], v[100:103]
	v_mfma_f32_16x16x32_bf16 v[96:99], v[150:153], v[188:191], v[96:99]
	s_setprio 0
	s_barrier
	ds_read_b128 v[192:195], v143
	ds_read_b128 v[196:199], v143 offset:1024
	ds_read_b128 v[200:203], v143 offset:2048
	ds_read_b128 v[204:207], v143 offset:3072
	s_waitcnt vmcnt(0)
	s_barrier
	s_waitcnt lgkmcnt(0)
	s_setprio 1
	s_waitcnt lgkmcnt(0)
	v_mfma_f32_16x16x32_bf16 v[92:95], v[192:195], v[154:157], v[92:95]
	v_mfma_f32_16x16x32_bf16 v[88:91], v[200:203], v[154:157], v[88:91]
	v_mfma_f32_16x16x32_bf16 v[84:87], v[192:195], v[162:165], v[84:87]
	v_mfma_f32_16x16x32_bf16 v[80:83], v[200:203], v[162:165], v[80:83]
	v_mfma_f32_16x16x32_bf16 v[76:79], v[192:195], v[170:173], v[76:79]
	v_mfma_f32_16x16x32_bf16 v[72:75], v[200:203], v[170:173], v[72:75]
	v_mfma_f32_16x16x32_bf16 v[68:71], v[192:195], v[184:187], v[68:71]
	v_mfma_f32_16x16x32_bf16 v[64:67], v[200:203], v[184:187], v[64:67]
	v_mfma_f32_16x16x32_bf16 v[92:95], v[196:199], v[158:161], v[92:95]
	v_mfma_f32_16x16x32_bf16 v[88:91], v[204:207], v[158:161], v[88:91]
	v_mfma_f32_16x16x32_bf16 v[84:87], v[196:199], v[166:169], v[84:87]
	v_mfma_f32_16x16x32_bf16 v[80:83], v[204:207], v[166:169], v[80:83]
	v_mfma_f32_16x16x32_bf16 v[76:79], v[196:199], v[180:183], v[76:79]
	v_mfma_f32_16x16x32_bf16 v[72:75], v[204:207], v[180:183], v[72:75]
	v_mfma_f32_16x16x32_bf16 v[68:71], v[196:199], v[188:191], v[68:71]
	v_mfma_f32_16x16x32_bf16 v[64:67], v[204:207], v[188:191], v[64:67]
	s_setprio 0
	s_barrier
	ds_read_b128 v[154:157], v142 offset:49152
	ds_read_b128 v[142:145], v142 offset:50176
	ds_read_b128 v[158:161], v141 offset:49152
	ds_read_b128 v[162:165], v141 offset:50176
	ds_read_b128 v[166:169], v140 offset:49152
	ds_read_b128 v[170:173], v140 offset:50176
	ds_read_b128 v[180:183], v139 offset:49152
	ds_read_b128 v[184:187], v139 offset:50176
	s_barrier
	s_waitcnt lgkmcnt(0)
	s_setprio 1
	s_waitcnt lgkmcnt(0)
	v_mfma_f32_16x16x32_bf16 v[60:63], v[128:131], v[154:157], v[60:63]
	v_mfma_f32_16x16x32_bf16 v[56:59], v[146:149], v[154:157], v[56:59]
	v_mfma_f32_16x16x32_bf16 v[52:55], v[128:131], v[158:161], v[52:55]
	v_mfma_f32_16x16x32_bf16 v[48:51], v[146:149], v[158:161], v[48:51]
	v_mfma_f32_16x16x32_bf16 v[44:47], v[128:131], v[166:169], v[44:47]
	v_mfma_f32_16x16x32_bf16 v[40:43], v[146:149], v[166:169], v[40:43]
	v_mfma_f32_16x16x32_bf16 v[36:39], v[128:131], v[180:183], v[36:39]
	v_mfma_f32_16x16x32_bf16 v[32:35], v[146:149], v[180:183], v[32:35]
	v_mfma_f32_16x16x32_bf16 v[60:63], v[132:135], v[142:145], v[60:63]
	v_mfma_f32_16x16x32_bf16 v[56:59], v[150:153], v[142:145], v[56:59]
	v_mfma_f32_16x16x32_bf16 v[52:55], v[132:135], v[162:165], v[52:55]
	v_mfma_f32_16x16x32_bf16 v[48:51], v[150:153], v[162:165], v[48:51]
	v_mfma_f32_16x16x32_bf16 v[44:47], v[132:135], v[170:173], v[44:47]
	v_mfma_f32_16x16x32_bf16 v[40:43], v[150:153], v[170:173], v[40:43]
	v_mfma_f32_16x16x32_bf16 v[36:39], v[132:135], v[184:187], v[36:39]
	v_mfma_f32_16x16x32_bf16 v[32:35], v[150:153], v[184:187], v[32:35]
	s_setprio 0
	s_setprio 1
	v_mfma_f32_16x16x32_bf16 v[28:31], v[192:195], v[154:157], v[28:31]
	v_mfma_f32_16x16x32_bf16 v[24:27], v[200:203], v[154:157], v[24:27]
	v_mfma_f32_16x16x32_bf16 v[20:23], v[192:195], v[158:161], v[20:23]
	v_mfma_f32_16x16x32_bf16 v[16:19], v[200:203], v[158:161], v[16:19]
	v_mfma_f32_16x16x32_bf16 v[12:15], v[192:195], v[166:169], v[12:15]
	v_mfma_f32_16x16x32_bf16 v[8:11], v[200:203], v[166:169], v[8:11]
	v_mfma_f32_16x16x32_bf16 v[4:7], v[192:195], v[180:183], v[4:7]
	v_mfma_f32_16x16x32_bf16 v[0:3], v[200:203], v[180:183], v[0:3]
	v_mfma_f32_16x16x32_bf16 v[28:31], v[196:199], v[142:145], v[28:31]
	v_mfma_f32_16x16x32_bf16 v[24:27], v[204:207], v[142:145], v[24:27]
	v_mfma_f32_16x16x32_bf16 v[20:23], v[196:199], v[162:165], v[20:23]
	v_mfma_f32_16x16x32_bf16 v[16:19], v[204:207], v[162:165], v[16:19]
	v_mfma_f32_16x16x32_bf16 v[12:15], v[196:199], v[170:173], v[12:15]
	v_mfma_f32_16x16x32_bf16 v[8:11], v[204:207], v[170:173], v[8:11]
	v_mfma_f32_16x16x32_bf16 v[4:7], v[196:199], v[184:187], v[4:7]
	v_mfma_f32_16x16x32_bf16 v[0:3], v[204:207], v[184:187], v[0:3]
	s_setprio 0
	v_cmp_gt_u32_e32 vcc, s95, v138
	s_barrier
	s_and_saveexec_b64 s[14:15], vcc
	s_cbranch_execz .LBB0_906
	s_barrier

; #define STAGE_A(P, half, kt) do { const char* _u = Ab + ((size_t)(half) * 128 * lda + (size_t)(kt) * BK) * 2; \
;     _Pragma("unroll") for (int _i = 0; _i < 2; ++_i) \
;       __builtin_amdgcn_global_load_lds((const unsigned*)(_u + offA[_i]), \
;         (__attribute__((address_space(3))) unsigned*)((__attribute__((address_space(3))) char*)(P) + tidg * 16 + _i * 8192), 16, 0, 0); } while (0)
; #define STAGE_B(P, half, kt) do { const char* _u = Bb + ((size_t)(half) * 128 * ldb + (size_t)(kt) * BK) * 2; \
;     _Pragma("unroll") for (int _i = 0; _i < 2; ++_i) \
;       __builtin_amdgcn_global_load_lds((const unsigned*)(_u + offB[_i]), \
;         (__attribute__((address_space(3))) unsigned*)((__attribute__((address_space(3))) char*)(P) + tidg * 16 + _i * 8192), 16, 0, 0); } while (0)
; #define WAIT_V(n) asm volatile("s_waitcnt vmcnt(" #n ")" ::: "memory")
; #define BAR __builtin_amdgcn_s_barrier()
; #define G_THREAD() do { asm volatile("" : "+v"(tidg)); wid = tidg >> 6; lane = tidg & 63; wr = wid >> 2; wc = wid & 3; fr = lane & 15; fq = lane >> 4; \
;     _Pragma("unroll") for (int _i = 0; _i < 2; ++_i) { int _r, _c; stage_rc(tidg * 16 + _i * 8192, _r, _c); offA[_i] = (unsigned)(_r * lda + _c) * 2u; offB[_i] = (unsigned)(_r * ldb + _c) * 2u; } } while (0)
; template <bool PF = true, class Epi, class KRF = KRFull>
; __device__ __forceinline__ void gemm_phase(const u16* __restrict__ A, int lda, const u16* __restrict__ Bt, int ldb, int K, int nM, int nN,
;                                            lds_u16* shm, Epi epi, KRF krf = KRFull(), bool flip = false) {
;     ...
;     G_THREAD();
;     nt = nt_next;
;     f32x4 acc[2][2][4][2] = {};
;     bf16x8 At[4][2], B0[2][2], B1[2][2];
;     if (wr == 1) BAR;
;     WAIT_V(4); BAR;
;     STAGE_B(SB(1, 0), 0, 1); STAGE_A(SA(1, 0), 0, 1); STAGE_B(SB(1, 1), 1, 1);
;     WAIT_V(6); BAR;
.LBB0_921:
	s_or_b64 exec, exec, s[14:15]
	v_bfe_i32 v2, v138, 27, 1
	v_lshlrev_b32_e32 v144, 4, v138
	v_lshrrev_b32_e32 v2, 22, v2
	v_add_u32_e32 v2, v144, v2
	v_and_b32_e32 v2, 0xfffffc00, v2
	v_sub_u32_e32 v2, v144, v2
	v_lshrrev_b32_e32 v3, 4, v2
	v_ashrrev_i32_e32 v1, 31, v138
	v_bitop3_b32 v2, v3, v2, 32 bitop3:0x6c
	v_lshrrev_b32_e32 v1, 26, v1
	v_ashrrev_i32_e32 v4, 31, v2
	v_add_u32_e32 v1, v138, v1
	v_lshrrev_b32_e32 v4, 26, v4
	v_ashrrev_i32_e32 v1, 6, v1
	v_add_u32_e32 v4, v2, v4
	v_lshlrev_b32_e32 v3, 3, v1
	v_ashrrev_i32_e32 v5, 6, v4
	v_and_b32_e32 v4, 0xc0, v4
	v_and_b32_e32 v3, 0x7ffff0, v3
	v_sub_u32_e32 v2, v2, v4
	v_add_u32_e32 v3, v5, v3
	v_lshlrev_b32_e32 v6, 5, v1
	v_ashrrev_i16_sdwa v2, v232, sext(v2) dst_sel:DWORD dst_unused:UNUSED_PAD src0_sel:DWORD src1_sel:BYTE_0
	s_movk_i32 s24, 0x1600
	v_and_b32_e32 v6, 32, v6
	v_bfe_i32 v4, v2, 0, 16
	v_mul_lo_u32 v2, v3, s24
	v_or_b32_e32 v2, v2, v6
	v_add_u32_e32 v146, 0x2000, v144
	v_add_lshl_u32 v178, v2, v4, 1
	v_ashrrev_i32_e32 v2, 31, v146
	v_lshrrev_b32_e32 v2, 22, v2
	v_add_u32_e32 v2, v146, v2
	v_ashrrev_i32_e32 v7, 10, v2
	v_mul_i32_i24_e32 v2, 0x400, v7
	v_sub_u32_e32 v2, v146, v2
	v_lshrrev_b32_e32 v3, 4, v2
	v_bitop3_b32 v2, v3, v2, 32 bitop3:0x6c
	v_ashrrev_i32_e32 v8, 31, v2
	v_lshrrev_b32_e32 v8, 26, v8
	v_add_u32_e32 v8, v2, v8
	v_lshlrev_b32_e32 v3, 3, v7
	v_ashrrev_i32_e32 v9, 6, v8
	v_and_b32_e32 v8, 0xc0, v8
	v_and_b32_e32 v3, 0x7ffff0, v3
	v_sub_u32_e32 v2, v2, v8
	v_add_u32_e32 v3, v9, v3
	v_lshlrev_b32_e32 v10, 5, v7
	v_ashrrev_i16_sdwa v2, v232, sext(v2) dst_sel:DWORD dst_unused:UNUSED_PAD src0_sel:DWORD src1_sel:BYTE_0
	v_and_b32_e32 v10, 32, v10
	v_bfe_i32 v8, v2, 0, 16
	v_mul_lo_u32 v2, v3, s24
	v_or_b32_e32 v2, v2, v10
	v_add_u32_e32 v147, 0x18000, v144
	v_add_lshl_u32 v128, v2, v8, 1
	v_lshl_add_u64 v[2:3], s[6:7], 0, v[178:179]
	v_readfirstlane_b32 s14, v147
	v_lshl_add_u64 v[2:3], v[2:3], 0, s[60:61]
	s_mov_b32 m0, s14
	v_mov_b32_e32 v129, v179
	v_add_u32_e32 v148, 0x1a000, v144
	s_waitcnt vmcnt(4)
	s_barrier
	global_load_lds_dwordx4 v[2:3], off
	v_lshl_add_u64 v[2:3], s[6:7], 0, v[128:129]
	v_readfirstlane_b32 s14, v148
	v_lshl_add_u64 v[2:3], v[2:3], 0, s[60:61]
	s_mov_b32 m0, s14
	v_add_u32_e32 v149, 0x8000, v144
	global_load_lds_dwordx4 v[2:3], off
	v_lshl_add_u64 v[2:3], s[12:13], 0, v[178:179]
	v_readfirstlane_b32 s14, v149
	v_lshl_add_u64 v[2:3], v[2:3], 0, s[60:61]
	s_mov_b32 m0, s14
	v_add_u32_e32 v150, 0xa000, v144
	global_load_lds_dwordx4 v[2:3], off
	v_lshl_add_u64 v[2:3], s[12:13], 0, v[128:129]
	v_readfirstlane_b32 s14, v150
	v_add_u32_e32 v151, 0x1c000, v144
	v_lshl_add_u64 v[2:3], v[2:3], 0, s[60:61]
	s_mov_b32 m0, s14
	s_add_u32 s14, s6, 0x160080
	v_readfirstlane_b32 s23, v151
	v_add_u32_e32 v152, 0x1e000, v144
	global_load_lds_dwordx4 v[2:3], off
	s_addc_u32 s15, s7, 0
	s_mov_b32 m0, s23
	v_readfirstlane_b32 s23, v152
	global_load_lds_dwordx4 v178, s[14:15]
	s_mov_b32 m0, s23
	v_and_b32_e32 v11, 15, v138
	global_load_lds_dwordx4 v128, s[14:15]
	v_lshlrev_b32_e32 v2, 6, v11
	v_lshlrev_b32_e32 v11, 2, v138
	v_and_b32_e32 v12, 48, v138
	v_and_b32_e32 v11, 32, v11
	v_or_b32_e32 v3, v2, v12
	v_bitop3_b32 v13, v2, v11, v12 bitop3:0x36
	s_mov_b32 s14, 0x14000
	v_lshlrev_b32_e32 v2, 6, v138
	v_bitop3_b32 v15, v3, s14, v11 bitop3:0xde
	s_mov_b32 s14, 0x18000
	v_lshlrev_b32_e32 v19, 13, v0
	v_and_b32_e32 v0, 0x3c0, v2
	v_bitop3_b32 v14, v3, s94, v11 bitop3:0xde
	v_bitop3_b32 v16, v3, s14, v11 bitop3:0xde
	v_bitop3_b32 v17, v3, s97, v11 bitop3:0xde
	v_bitop3_b32 v11, v0, v11, v12 bitop3:0x36
	v_lshrrev_b32_e32 v1, 1, v1
	v_mul_lo_u32 v0, v5, s24
	v_and_b32_e32 v18, 0x3000, v2
	v_mad_u64_u32 v[0:1], s[14:15], v1, s30, v[0:1]
	v_lshrrev_b32_e32 v3, 1, v7
	v_mul_lo_u32 v2, v9, s24
	v_or_b32_e32 v0, v0, v6
	v_mad_u64_u32 v[2:3], s[14:15], v3, s30, v[2:3]
	s_waitcnt vmcnt(6)
	v_add_lshl_u32 v0, v0, v4, 1
	v_mov_b32_e32 v1, v179
	v_or_b32_e32 v2, v2, v10
	v_or_b32_e32 v12, 0x800, v19
	v_or_b32_e32 v20, 0x1000, v19
	v_or_b32_e32 v21, 0x1800, v19
	v_lshl_add_u64 v[130:131], s[6:7], 0, v[0:1]
	v_add_lshl_u32 v2, v2, v8, 1
	v_mov_b32_e32 v3, v179
	v_lshl_add_u64 v[134:135], s[12:13], 0, v[0:1]
	v_mov_b32_e32 v0, 0
	v_lshl_add_u64 v[132:133], s[6:7], 0, v[2:3]
	v_lshl_add_u64 v[136:137], s[12:13], 0, v[2:3]
	s_mov_b32 s23, -2
	s_mov_b64 s[14:15], 0
	v_add_u32_e32 v154, v14, v18
	v_add_u32_e32 v142, v13, v19
	v_add_u32_e32 v141, v11, v12
	v_add_u32_e32 v140, v11, v20
	v_add_u32_e32 v139, v11, v21
	v_add_u32_e32 v153, v15, v18
	v_add_u32_e32 v145, v16, v18
	v_add_u32_e32 v143, v17, v18
	v_mov_b32_e32 v1, v0
	v_mov_b32_e32 v2, v0
	v_mov_b32_e32 v3, v0
	v_mov_b32_e32 v4, v0
	v_mov_b32_e32 v5, v0
	v_mov_b32_e32 v6, v0
	v_mov_b32_e32 v7, v0
	v_mov_b32_e32 v8, v0
	v_mov_b32_e32 v9, v0
	v_mov_b32_e32 v10, v0
	v_mov_b32_e32 v11, v0
	v_mov_b32_e32 v12, v0
	v_mov_b32_e32 v13, v0
	v_mov_b32_e32 v14, v0
	v_mov_b32_e32 v15, v0
	v_mov_b32_e32 v16, v0
	v_mov_b32_e32 v17, v0
	v_mov_b32_e32 v18, v0
	v_mov_b32_e32 v19, v0
	v_mov_b32_e32 v20, v0
	v_mov_b32_e32 v21, v0
	v_mov_b32_e32 v22, v0
	v_mov_b32_e32 v23, v0
	v_mov_b32_e32 v24, v0
	v_mov_b32_e32 v25, v0
	v_mov_b32_e32 v26, v0
	v_mov_b32_e32 v27, v0
	v_mov_b32_e32 v28, v0
	v_mov_b32_e32 v29, v0
	v_mov_b32_e32 v30, v0
	v_mov_b32_e32 v31, v0
	v_mov_b32_e32 v32, v0
	v_mov_b32_e32 v33, v0
	v_mov_b32_e32 v34, v0
	v_mov_b32_e32 v35, v0
	v_mov_b32_e32 v36, v0
	v_mov_b32_e32 v37, v0
	v_mov_b32_e32 v38, v0
	v_mov_b32_e32 v39, v0
	v_mov_b32_e32 v40, v0
	v_mov_b32_e32 v41, v0
	v_mov_b32_e32 v42, v0
	v_mov_b32_e32 v43, v0
	v_mov_b32_e32 v44, v0
	v_mov_b32_e32 v45, v0
	v_mov_b32_e32 v46, v0
	v_mov_b32_e32 v47, v0
; #define STAGE_A(P, half, kt) do { const char* _u = Ab + ((size_t)(half) * 128 * lda + (size_t)(kt) * BK) * 2; \
;     _Pragma("unroll") for (int _i = 0; _i < 2; ++_i) \
;       __builtin_amdgcn_global_load_lds((const unsigned*)(_u + offA[_i]), \
;         (__attribute__((address_space(3))) unsigned*)((__attribute__((address_space(3))) char*)(P) + tidg * 16 + _i * 8192), 16, 0, 0); } while (0)
; #define STAGE_B(P, half, kt) do { const char* _u = Bb + ((size_t)(half) * 128 * ldb + (size_t)(kt) * BK) * 2; \
;     _Pragma("unroll") for (int _i = 0; _i < 2; ++_i) \
;       __builtin_amdgcn_global_load_lds((const unsigned*)(_u + offB[_i]), \
;         (__attribute__((address_space(3))) unsigned*)((__attribute__((address_space(3))) char*)(P) + tidg * 16 + _i * 8192), 16, 0, 0); } while (0)
; #define LDA(dst, b, h) _Pragma("unroll") for (int m = 0; m < 4; ++m) _Pragma("unroll") for (int k = 0; k < 2; ++k) \
;     dst[m][k] = *reinterpret_cast<const bf16x8*>((const char*)SA(b, h) + lds_byte(wr * 64 + m * 16 + fr, k * 32 + fq * 8))
; #define LDB(dst, b, h) _Pragma("unroll") for (int n = 0; n < 2; ++n) _Pragma("unroll") for (int k = 0; k < 2; ++k) \
;     dst[n][k] = *reinterpret_cast<const bf16x8*>((const char*)SB(b, h) + lds_byte(wc * 32 + n * 16 + fr, k * 32 + fq * 8))
; #define WAIT_V(n) asm volatile("s_waitcnt vmcnt(" #n ")" ::: "memory")
; #define WAIT_L(n) asm volatile("s_waitcnt lgkmcnt(" #n ")" ::: "memory")
; #define BAR __builtin_amdgcn_s_barrier()
; #define SCHED __builtin_amdgcn_sched_barrier(0)
; template <bool PF = true, class Epi, class KRF = KRFull>
; __device__ __forceinline__ void gemm_phase(const u16* __restrict__ A, int lda, const u16* __restrict__ Bt, int ldb, int K, int nM, int nN,
;                                            lds_u16* shm, Epi epi, KRF krf = KRFull(), bool flip = false) {
;     ...
;     f32x4 acc[2][2][4][2] = {};
;     bf16x8 At[4][2], B0[2][2], B1[2][2];
;     if (wr == 1) BAR;
;     WAIT_V(4); BAR;
;     STAGE_B(SB(1, 0), 0, 1); STAGE_A(SA(1, 0), 0, 1); STAGE_B(SB(1, 1), 1, 1);
;     WAIT_V(6); BAR;
;     for (int t = 0; t < nt - 2; t += 2) {
;       LDB(B0, 0, 0); SCHED; LDA(At, 0, 0); STAGE_A(SA(1, 1), 1, t + 1);
;       WAIT_L(8); BAR; WAIT_L(0); MMA(0, 0, At, B0); BAR; SCHED;
;       LDB(B1, 0, 1); STAGE_B(SB(0, 0), 0, t + 2);
;       BAR; WAIT_L(0); MMA(0, 1, At, B1); BAR;
;       LDA(At, 0, 1); STAGE_A(SA(0, 0), 0, t + 2);
	v_mov_b32_e32 v48, v0
	v_mov_b32_e32 v49, v0
	v_mov_b32_e32 v50, v0
	v_mov_b32_e32 v51, v0
	v_mov_b32_e32 v52, v0
	v_mov_b32_e32 v53, v0
	v_mov_b32_e32 v54, v0
	v_mov_b32_e32 v55, v0
	v_mov_b32_e32 v56, v0
	v_mov_b32_e32 v57, v0
	v_mov_b32_e32 v58, v0
	v_mov_b32_e32 v59, v0
	v_mov_b32_e32 v60, v0
	v_mov_b32_e32 v61, v0
	v_mov_b32_e32 v62, v0
	v_mov_b32_e32 v63, v0
	v_mov_b32_e32 v64, v0
	v_mov_b32_e32 v65, v0
	v_mov_b32_e32 v66, v0
	v_mov_b32_e32 v67, v0
	v_mov_b32_e32 v68, v0
	v_mov_b32_e32 v69, v0
	v_mov_b32_e32 v70, v0
	v_mov_b32_e32 v71, v0
	v_mov_b32_e32 v72, v0
	v_mov_b32_e32 v73, v0
	v_mov_b32_e32 v74, v0
	v_mov_b32_e32 v75, v0
	v_mov_b32_e32 v76, v0
	v_mov_b32_e32 v77, v0
	v_mov_b32_e32 v78, v0
	v_mov_b32_e32 v79, v0
	v_mov_b32_e32 v80, v0
	v_mov_b32_e32 v81, v0
	v_mov_b32_e32 v82, v0
	v_mov_b32_e32 v83, v0
	v_mov_b32_e32 v84, v0
	v_mov_b32_e32 v85, v0
	v_mov_b32_e32 v86, v0
	v_mov_b32_e32 v87, v0
	v_mov_b32_e32 v88, v0
	v_mov_b32_e32 v89, v0
	v_mov_b32_e32 v90, v0
	v_mov_b32_e32 v91, v0
	v_mov_b32_e32 v92, v0
	v_mov_b32_e32 v93, v0
	v_mov_b32_e32 v94, v0
	v_mov_b32_e32 v95, v0
	v_mov_b32_e32 v96, v0
	v_mov_b32_e32 v97, v0
	v_mov_b32_e32 v98, v0
	v_mov_b32_e32 v99, v0
	v_mov_b32_e32 v100, v0
	v_mov_b32_e32 v101, v0
	v_mov_b32_e32 v102, v0
	v_mov_b32_e32 v103, v0
	v_mov_b32_e32 v104, v0
	v_mov_b32_e32 v105, v0
	v_mov_b32_e32 v106, v0
	v_mov_b32_e32 v107, v0
	v_mov_b32_e32 v108, v0
	v_mov_b32_e32 v109, v0
	v_mov_b32_e32 v110, v0
	v_mov_b32_e32 v111, v0
	v_mov_b32_e32 v112, v0
	v_mov_b32_e32 v113, v0
	v_mov_b32_e32 v114, v0
	v_mov_b32_e32 v115, v0
	v_mov_b32_e32 v116, v0
	v_mov_b32_e32 v117, v0
	v_mov_b32_e32 v118, v0
	v_mov_b32_e32 v119, v0
	v_mov_b32_e32 v120, v0
	v_mov_b32_e32 v121, v0
	v_mov_b32_e32 v122, v0
	v_mov_b32_e32 v123, v0
	v_mov_b32_e32 v124, v0
	v_mov_b32_e32 v125, v0
	v_mov_b32_e32 v126, v0
	v_mov_b32_e32 v127, v0
	s_barrier
	v_readfirstlane_b32 s24, v144
.LBB0_922:
	ds_read_b128 v[158:161], v154
	ds_read_b128 v[162:165], v154 offset:1024
	ds_read_b128 v[166:169], v154 offset:2048
	ds_read_b128 v[170:173], v154 offset:3072
	v_lshl_add_u64 v[174:175], v[134:135], 0, s[14:15]
	v_lshl_add_u64 v[156:157], v[174:175], 0, s[72:73]
	s_add_u32 m0, s24, 0xc000
	ds_read_b128 v[180:183], v142
	ds_read_b128 v[184:187], v142 offset:1024
	ds_read_b128 v[188:191], v141
	ds_read_b128 v[192:195], v141 offset:1024
	ds_read_b128 v[196:199], v140
	ds_read_b128 v[200:203], v140 offset:1024
	ds_read_b128 v[204:207], v139
	ds_read_b128 v[208:211], v139 offset:1024
	global_load_lds_dwordx4 v[156:157], off
	v_lshl_add_u64 v[222:223], v[136:137], 0, s[14:15]
	v_lshl_add_u64 v[212:213], v[222:223], 0, s[72:73]
	s_add_u32 m0, s24, 0xe000
	s_nop 0
	global_load_lds_dwordx4 v[212:213], off
	s_waitcnt lgkmcnt(8)
	s_barrier
	s_waitcnt lgkmcnt(0)
	s_setprio 1
	s_waitcnt lgkmcnt(0)
	v_mfma_f32_16x16x32_bf16 v[124:127], v[158:161], v[180:183], v[124:127]
	v_mfma_f32_16x16x32_bf16 v[120:123], v[166:169], v[180:183], v[120:123]
	v_mfma_f32_16x16x32_bf16 v[116:119], v[158:161], v[188:191], v[116:119]
	v_mfma_f32_16x16x32_bf16 v[112:115], v[166:169], v[188:191], v[112:115]
	v_mfma_f32_16x16x32_bf16 v[108:111], v[158:161], v[196:199], v[108:111]
	v_mfma_f32_16x16x32_bf16 v[104:107], v[166:169], v[196:199], v[104:107]
	v_mfma_f32_16x16x32_bf16 v[100:103], v[158:161], v[204:207], v[100:103]
	v_mfma_f32_16x16x32_bf16 v[96:99], v[166:169], v[204:207], v[96:99]
	v_mfma_f32_16x16x32_bf16 v[124:127], v[162:165], v[184:187], v[124:127]
	v_mfma_f32_16x16x32_bf16 v[120:123], v[170:173], v[184:187], v[120:123]
	v_mfma_f32_16x16x32_bf16 v[116:119], v[162:165], v[192:195], v[116:119]
	v_mfma_f32_16x16x32_bf16 v[112:115], v[170:173], v[192:195], v[112:115]
	v_mfma_f32_16x16x32_bf16 v[108:111], v[162:165], v[200:203], v[108:111]
	v_mfma_f32_16x16x32_bf16 v[104:107], v[170:173], v[200:203], v[104:107]
	v_mfma_f32_16x16x32_bf16 v[100:103], v[162:165], v[208:211], v[100:103]
	v_mfma_f32_16x16x32_bf16 v[96:99], v[170:173], v[208:211], v[96:99]
	s_setprio 0
	s_barrier
	v_lshl_add_u64 v[224:225], v[130:131], 0, s[14:15]
	v_lshl_add_u64 v[226:227], v[224:225], 0, s[64:65]
	s_add_u32 m0, s24, 0x10000
	ds_read_b128 v[212:215], v153
	ds_read_b128 v[216:219], v153 offset:1024
	ds_read_b128 v[238:241], v153 offset:2048
	ds_read_b128 v[242:245], v153 offset:3072
	global_load_lds_dwordx4 v[226:227], off
	v_lshl_add_u64 v[226:227], v[132:133], 0, s[14:15]
	v_lshl_add_u64 v[228:229], v[226:227], 0, s[64:65]
	s_add_u32 m0, s24, 0x12000
	s_nop 0
	global_load_lds_dwordx4 v[228:229], off
	s_barrier
	s_waitcnt lgkmcnt(0)
	s_setprio 1
	s_waitcnt lgkmcnt(0)
	v_mfma_f32_16x16x32_bf16 v[92:95], v[212:215], v[180:183], v[92:95]
	v_mfma_f32_16x16x32_bf16 v[88:91], v[238:241], v[180:183], v[88:91]
	v_mfma_f32_16x16x32_bf16 v[84:87], v[212:215], v[188:191], v[84:87]
	v_mfma_f32_16x16x32_bf16 v[80:83], v[238:241], v[188:191], v[80:83]
	v_mfma_f32_16x16x32_bf16 v[76:79], v[212:215], v[196:199], v[76:79]
	v_mfma_f32_16x16x32_bf16 v[72:75], v[238:241], v[196:199], v[72:75]
	v_mfma_f32_16x16x32_bf16 v[68:71], v[212:215], v[204:207], v[68:71]
	v_mfma_f32_16x16x32_bf16 v[64:67], v[238:241], v[204:207], v[64:67]
	v_mfma_f32_16x16x32_bf16 v[92:95], v[216:219], v[184:187], v[92:95]
	v_mfma_f32_16x16x32_bf16 v[88:91], v[242:245], v[184:187], v[88:91]
	v_mfma_f32_16x16x32_bf16 v[84:87], v[216:219], v[192:195], v[84:87]
	v_mfma_f32_16x16x32_bf16 v[80:83], v[242:245], v[192:195], v[80:83]
	v_mfma_f32_16x16x32_bf16 v[76:79], v[216:219], v[200:203], v[76:79]
	v_mfma_f32_16x16x32_bf16 v[72:75], v[242:245], v[200:203], v[72:75]
	v_mfma_f32_16x16x32_bf16 v[68:71], v[216:219], v[208:211], v[68:71]
	v_mfma_f32_16x16x32_bf16 v[64:67], v[242:245], v[208:211], v[64:67]
	s_setprio 0
	v_lshl_add_u64 v[228:229], v[174:175], 0, s[64:65]
	s_mov_b32 m0, s24
	s_barrier
; #define STAGE_A(P, half, kt) do { const char* _u = Ab + ((size_t)(half) * 128 * lda + (size_t)(kt) * BK) * 2; \
;     _Pragma("unroll") for (int _i = 0; _i < 2; ++_i) \
;       __builtin_amdgcn_global_load_lds((const unsigned*)(_u + offA[_i]), \
;         (__attribute__((address_space(3))) unsigned*)((__attribute__((address_space(3))) char*)(P) + tidg * 16 + _i * 8192), 16, 0, 0); } while (0)
; #define STAGE_B(P, half, kt) do { const char* _u = Bb + ((size_t)(half) * 128 * ldb + (size_t)(kt) * BK) * 2; \
;     _Pragma("unroll") for (int _i = 0; _i < 2; ++_i) \
;       __builtin_amdgcn_global_load_lds((const unsigned*)(_u + offB[_i]), \
;         (__attribute__((address_space(3))) unsigned*)((__attribute__((address_space(3))) char*)(P) + tidg * 16 + _i * 8192), 16, 0, 0); } while (0)
; #define LDA(dst, b, h) _Pragma("unroll") for (int m = 0; m < 4; ++m) _Pragma("unroll") for (int k = 0; k < 2; ++k) \
;     dst[m][k] = *reinterpret_cast<const bf16x8*>((const char*)SA(b, h) + lds_byte(wr * 64 + m * 16 + fr, k * 32 + fq * 8))
; #define LDB(dst, b, h) _Pragma("unroll") for (int n = 0; n < 2; ++n) _Pragma("unroll") for (int k = 0; k < 2; ++k) \
;     dst[n][k] = *reinterpret_cast<const bf16x8*>((const char*)SB(b, h) + lds_byte(wc * 32 + n * 16 + fr, k * 32 + fq * 8))
; #define WAIT_V(n) asm volatile("s_waitcnt vmcnt(" #n ")" ::: "memory")
; #define WAIT_L(n) asm volatile("s_waitcnt lgkmcnt(" #n ")" ::: "memory")
; #define BAR __builtin_amdgcn_s_barrier()
; #define SCHED __builtin_amdgcn_sched_barrier(0)
; template <bool PF = true, class Epi, class KRF = KRFull>
; __device__ __forceinline__ void gemm_phase(const u16* __restrict__ A, int lda, const u16* __restrict__ Bt, int ldb, int K, int nM, int nN,
;                                            lds_u16* shm, Epi epi, KRF krf = KRFull(), bool flip = false) {
;     ...
;       LDA(At, 0, 1); STAGE_A(SA(0, 0), 0, t + 2);
;       BAR; WAIT_L(0); MMA(1, 0, At, B0); BAR; SCHED;
;       STAGE_B(SB(0, 1), 1, t + 2);
;       WAIT_V(6); BAR; MMA(1, 1, At, B1); BAR;
;       LDB(B0, 1, 0); SCHED; LDA(At, 1, 0); STAGE_A(SA(0, 1), 1, t + 2);
;       WAIT_L(8); BAR; WAIT_L(0); MMA(0, 0, At, B0); BAR; SCHED;
;       LDB(B1, 1, 1); STAGE_B(SB(1, 0), 0, t + 3);
;       BAR; WAIT_L(0); MMA(0, 1, At, B1); BAR;
	ds_read_b128 v[180:183], v142 offset:16384
	ds_read_b128 v[184:187], v142 offset:17408
	ds_read_b128 v[188:191], v141 offset:16384
	ds_read_b128 v[192:195], v141 offset:17408
	ds_read_b128 v[196:199], v140 offset:16384
	ds_read_b128 v[200:203], v140 offset:17408
	ds_read_b128 v[204:207], v139 offset:16384
	ds_read_b128 v[208:211], v139 offset:17408
	global_load_lds_dwordx4 v[228:229], off
	v_lshl_add_u64 v[228:229], v[222:223], 0, s[64:65]
	s_add_u32 m0, s24, 0x2000
	s_nop 0
	global_load_lds_dwordx4 v[228:229], off
	s_barrier
	s_waitcnt lgkmcnt(0)
	s_setprio 1
	s_waitcnt lgkmcnt(0)
	v_mfma_f32_16x16x32_bf16 v[60:63], v[158:161], v[180:183], v[60:63]
	v_mfma_f32_16x16x32_bf16 v[56:59], v[166:169], v[180:183], v[56:59]
	v_mfma_f32_16x16x32_bf16 v[52:55], v[158:161], v[188:191], v[52:55]
	v_mfma_f32_16x16x32_bf16 v[48:51], v[166:169], v[188:191], v[48:51]
	v_mfma_f32_16x16x32_bf16 v[44:47], v[158:161], v[196:199], v[44:47]
	v_mfma_f32_16x16x32_bf16 v[40:43], v[166:169], v[196:199], v[40:43]
	v_mfma_f32_16x16x32_bf16 v[36:39], v[158:161], v[204:207], v[36:39]
	v_mfma_f32_16x16x32_bf16 v[32:35], v[166:169], v[204:207], v[32:35]
	v_mfma_f32_16x16x32_bf16 v[60:63], v[162:165], v[184:187], v[60:63]
	v_mfma_f32_16x16x32_bf16 v[56:59], v[170:173], v[184:187], v[56:59]
	v_mfma_f32_16x16x32_bf16 v[52:55], v[162:165], v[192:195], v[52:55]
	v_mfma_f32_16x16x32_bf16 v[48:51], v[170:173], v[192:195], v[48:51]
	v_mfma_f32_16x16x32_bf16 v[44:47], v[162:165], v[200:203], v[44:47]
	v_mfma_f32_16x16x32_bf16 v[40:43], v[170:173], v[200:203], v[40:43]
	v_mfma_f32_16x16x32_bf16 v[36:39], v[162:165], v[208:211], v[36:39]
	v_mfma_f32_16x16x32_bf16 v[32:35], v[170:173], v[208:211], v[32:35]
	s_setprio 0
	s_barrier
	v_lshl_add_u64 v[158:159], v[224:225], 0, s[74:75]
	s_add_u32 m0, s24, 0x14000
	s_nop 0
	global_load_lds_dwordx4 v[158:159], off
	v_lshl_add_u64 v[158:159], v[226:227], 0, s[74:75]
	s_add_u32 m0, s24, 0x16000
	s_nop 0
	global_load_lds_dwordx4 v[158:159], off
	s_waitcnt vmcnt(6)
	s_barrier
	s_setprio 1
	v_mfma_f32_16x16x32_bf16 v[28:31], v[212:215], v[180:183], v[28:31]
	v_mfma_f32_16x16x32_bf16 v[24:27], v[238:241], v[180:183], v[24:27]
	v_mfma_f32_16x16x32_bf16 v[20:23], v[212:215], v[188:191], v[20:23]
	v_mfma_f32_16x16x32_bf16 v[16:19], v[238:241], v[188:191], v[16:19]
	v_mfma_f32_16x16x32_bf16 v[12:15], v[212:215], v[196:199], v[12:15]
	v_mfma_f32_16x16x32_bf16 v[8:11], v[238:241], v[196:199], v[8:11]
	v_mfma_f32_16x16x32_bf16 v[4:7], v[212:215], v[204:207], v[4:7]
	v_mfma_f32_16x16x32_bf16 v[0:3], v[238:241], v[204:207], v[0:3]
	v_mfma_f32_16x16x32_bf16 v[28:31], v[216:219], v[184:187], v[28:31]
	v_mfma_f32_16x16x32_bf16 v[24:27], v[242:245], v[184:187], v[24:27]
	v_mfma_f32_16x16x32_bf16 v[20:23], v[216:219], v[192:195], v[20:23]
	v_mfma_f32_16x16x32_bf16 v[16:19], v[242:245], v[192:195], v[16:19]
	v_mfma_f32_16x16x32_bf16 v[12:15], v[216:219], v[200:203], v[12:15]
	v_mfma_f32_16x16x32_bf16 v[8:11], v[242:245], v[200:203], v[8:11]
	v_mfma_f32_16x16x32_bf16 v[4:7], v[216:219], v[208:211], v[4:7]
	v_mfma_f32_16x16x32_bf16 v[0:3], v[242:245], v[208:211], v[0:3]
	s_setprio 0
	s_barrier
	ds_read_b128 v[158:161], v145
	ds_read_b128 v[162:165], v145 offset:1024
	ds_read_b128 v[166:169], v145 offset:2048
	ds_read_b128 v[170:173], v145 offset:3072
	v_lshl_add_u64 v[212:213], v[174:175], 0, s[74:75]
	s_add_u32 m0, s24, 0x4000
	ds_read_b128 v[180:183], v142 offset:32768
	ds_read_b128 v[184:187], v142 offset:33792
	ds_read_b128 v[188:191], v141 offset:32768
	ds_read_b128 v[192:195], v141 offset:33792
	ds_read_b128 v[196:199], v140 offset:32768
	ds_read_b128 v[200:203], v140 offset:33792
	ds_read_b128 v[204:207], v139 offset:32768
	ds_read_b128 v[208:211], v139 offset:33792
	global_load_lds_dwordx4 v[212:213], off
	v_lshl_add_u64 v[212:213], v[222:223], 0, s[74:75]
	s_add_u32 m0, s24, 0x6000
	s_nop 0
	global_load_lds_dwordx4 v[212:213], off
	s_waitcnt lgkmcnt(8)
	s_barrier
	s_waitcnt lgkmcnt(0)
	s_setprio 1
	s_waitcnt lgkmcnt(0)
	v_mfma_f32_16x16x32_bf16 v[124:127], v[158:161], v[180:183], v[124:127]
	v_mfma_f32_16x16x32_bf16 v[120:123], v[166:169], v[180:183], v[120:123]
	v_mfma_f32_16x16x32_bf16 v[116:119], v[158:161], v[188:191], v[116:119]
	v_mfma_f32_16x16x32_bf16 v[112:115], v[166:169], v[188:191], v[112:115]
	v_mfma_f32_16x16x32_bf16 v[108:111], v[158:161], v[196:199], v[108:111]
	v_mfma_f32_16x16x32_bf16 v[104:107], v[166:169], v[196:199], v[104:107]
	v_mfma_f32_16x16x32_bf16 v[100:103], v[158:161], v[204:207], v[100:103]
	v_mfma_f32_16x16x32_bf16 v[96:99], v[166:169], v[204:207], v[96:99]
	v_mfma_f32_16x16x32_bf16 v[124:127], v[162:165], v[184:187], v[124:127]
	v_mfma_f32_16x16x32_bf16 v[120:123], v[170:173], v[184:187], v[120:123]
	v_mfma_f32_16x16x32_bf16 v[116:119], v[162:165], v[192:195], v[116:119]
	v_mfma_f32_16x16x32_bf16 v[112:115], v[170:173], v[192:195], v[112:115]
	v_mfma_f32_16x16x32_bf16 v[108:111], v[162:165], v[200:203], v[108:111]
	v_mfma_f32_16x16x32_bf16 v[104:107], v[170:173], v[200:203], v[104:107]
	v_mfma_f32_16x16x32_bf16 v[100:103], v[162:165], v[208:211], v[100:103]
	v_mfma_f32_16x16x32_bf16 v[96:99], v[170:173], v[208:211], v[96:99]
	s_setprio 0
	s_barrier
	v_lshl_add_u64 v[228:229], v[224:225], 0, s[68:69]
	s_add_u32 m0, s24, 0x18000
	ds_read_b128 v[212:215], v143
	ds_read_b128 v[216:219], v143 offset:1024
	ds_read_b128 v[238:241], v143 offset:2048
	ds_read_b128 v[242:245], v143 offset:3072
	global_load_lds_dwordx4 v[228:229], off
	v_lshl_add_u64 v[228:229], v[226:227], 0, s[68:69]
	s_add_u32 m0, s24, 0x1a000
	s_nop 0
	global_load_lds_dwordx4 v[228:229], off
	s_barrier
; #define STAGE_A(P, half, kt) do { const char* _u = Ab + ((size_t)(half) * 128 * lda + (size_t)(kt) * BK) * 2; \
;     _Pragma("unroll") for (int _i = 0; _i < 2; ++_i) \
;       __builtin_amdgcn_global_load_lds((const unsigned*)(_u + offA[_i]), \
;         (__attribute__((address_space(3))) unsigned*)((__attribute__((address_space(3))) char*)(P) + tidg * 16 + _i * 8192), 16, 0, 0); } while (0)
; #define STAGE_B(P, half, kt) do { const char* _u = Bb + ((size_t)(half) * 128 * ldb + (size_t)(kt) * BK) * 2; \
;     _Pragma("unroll") for (int _i = 0; _i < 2; ++_i) \
;       __builtin_amdgcn_global_load_lds((const unsigned*)(_u + offB[_i]), \
;         (__attribute__((address_space(3))) unsigned*)((__attribute__((address_space(3))) char*)(P) + tidg * 16 + _i * 8192), 16, 0, 0); } while (0)
; #define LDA(dst, b, h) _Pragma("unroll") for (int m = 0; m < 4; ++m) _Pragma("unroll") for (int k = 0; k < 2; ++k) \
;     dst[m][k] = *reinterpret_cast<const bf16x8*>((const char*)SA(b, h) + lds_byte(wr * 64 + m * 16 + fr, k * 32 + fq * 8))
; #define LDB(dst, b, h) _Pragma("unroll") for (int n = 0; n < 2; ++n) _Pragma("unroll") for (int k = 0; k < 2; ++k) \
;     dst[n][k] = *reinterpret_cast<const bf16x8*>((const char*)SB(b, h) + lds_byte(wc * 32 + n * 16 + fr, k * 32 + fq * 8))
; #define MMA(ai, bj, At_, Bt_) do { __builtin_amdgcn_s_setprio(1); \
;     _Pragma("unroll") for (int m = 0; m < 4; ++m) _Pragma("unroll") for (int n = 0; n < 2; ++n) _Pragma("unroll") for (int k = 0; k < 2; ++k) \
;       acc[ai][bj][m][n] = __builtin_amdgcn_mfma_f32_16x16x32_bf16(Bt_[n][k], At_[m][k], acc[ai][bj][m][n], 0, 0, 0); \
;     __builtin_amdgcn_s_setprio(0); } while (0)
; #define WAIT_V(n) asm volatile("s_waitcnt vmcnt(" #n ")" ::: "memory")
; template <bool PF = true, class Epi, class KRF = KRFull>
; __device__ __forceinline__ void gemm_phase(const u16* __restrict__ A, int lda, const u16* __restrict__ Bt, int ldb, int K, int nM, int nN,
;                                            lds_u16* shm, Epi epi, KRF krf = KRFull(), bool flip = false) {
;     ...
;       BAR; WAIT_L(0); MMA(0, 1, At, B1); BAR;
;       LDA(At, 1, 1); STAGE_A(SA(1, 0), 0, t + 3);
;       BAR; WAIT_L(0); MMA(1, 0, At, B0); BAR; SCHED;
;       STAGE_B(SB(1, 1), 1, t + 3);
;       WAIT_V(6); BAR; MMA(1, 1, At, B1); BAR;
;     }
;     { LDB(B0, 0, 0); LDA(At, 0, 0); STAGE_A(SA(1, 1), 1, nt - 1);
	s_waitcnt lgkmcnt(0)
	s_setprio 1
	s_waitcnt lgkmcnt(0)
	v_mfma_f32_16x16x32_bf16 v[92:95], v[212:215], v[180:183], v[92:95]
	v_mfma_f32_16x16x32_bf16 v[88:91], v[238:241], v[180:183], v[88:91]
	v_mfma_f32_16x16x32_bf16 v[84:87], v[212:215], v[188:191], v[84:87]
	v_mfma_f32_16x16x32_bf16 v[80:83], v[238:241], v[188:191], v[80:83]
	v_mfma_f32_16x16x32_bf16 v[76:79], v[212:215], v[196:199], v[76:79]
	v_mfma_f32_16x16x32_bf16 v[72:75], v[238:241], v[196:199], v[72:75]
	v_mfma_f32_16x16x32_bf16 v[68:71], v[212:215], v[204:207], v[68:71]
	v_mfma_f32_16x16x32_bf16 v[64:67], v[238:241], v[204:207], v[64:67]
	v_mfma_f32_16x16x32_bf16 v[92:95], v[216:219], v[184:187], v[92:95]
	v_mfma_f32_16x16x32_bf16 v[88:91], v[242:245], v[184:187], v[88:91]
	v_mfma_f32_16x16x32_bf16 v[84:87], v[216:219], v[192:195], v[84:87]
	v_mfma_f32_16x16x32_bf16 v[80:83], v[242:245], v[192:195], v[80:83]
	v_mfma_f32_16x16x32_bf16 v[76:79], v[216:219], v[200:203], v[76:79]
	v_mfma_f32_16x16x32_bf16 v[72:75], v[242:245], v[200:203], v[72:75]
	v_mfma_f32_16x16x32_bf16 v[68:71], v[216:219], v[208:211], v[68:71]
	v_mfma_f32_16x16x32_bf16 v[64:67], v[242:245], v[208:211], v[64:67]
	s_setprio 0
	v_lshl_add_u64 v[174:175], v[174:175], 0, s[68:69]
	s_add_u32 m0, s24, 0x8000
	s_barrier
	ds_read_b128 v[180:183], v142 offset:49152
	ds_read_b128 v[184:187], v142 offset:50176
	ds_read_b128 v[188:191], v141 offset:49152
	ds_read_b128 v[192:195], v141 offset:50176
	ds_read_b128 v[196:199], v140 offset:49152
	ds_read_b128 v[200:203], v140 offset:50176
	ds_read_b128 v[204:207], v139 offset:49152
	ds_read_b128 v[208:211], v139 offset:50176
	global_load_lds_dwordx4 v[174:175], off
	v_lshl_add_u64 v[174:175], v[222:223], 0, s[68:69]
	s_add_u32 m0, s24, 0xa000
	s_nop 0
	global_load_lds_dwordx4 v[174:175], off
	s_barrier
	s_waitcnt lgkmcnt(0)
	s_setprio 1
	s_waitcnt lgkmcnt(0)
	v_mfma_f32_16x16x32_bf16 v[60:63], v[158:161], v[180:183], v[60:63]
	v_mfma_f32_16x16x32_bf16 v[56:59], v[166:169], v[180:183], v[56:59]
	v_mfma_f32_16x16x32_bf16 v[52:55], v[158:161], v[188:191], v[52:55]
	v_mfma_f32_16x16x32_bf16 v[48:51], v[166:169], v[188:191], v[48:51]
	v_mfma_f32_16x16x32_bf16 v[44:47], v[158:161], v[196:199], v[44:47]
	v_mfma_f32_16x16x32_bf16 v[40:43], v[166:169], v[196:199], v[40:43]
	v_mfma_f32_16x16x32_bf16 v[36:39], v[158:161], v[204:207], v[36:39]
	v_mfma_f32_16x16x32_bf16 v[32:35], v[166:169], v[204:207], v[32:35]
	v_mfma_f32_16x16x32_bf16 v[60:63], v[162:165], v[184:187], v[60:63]
	v_mfma_f32_16x16x32_bf16 v[56:59], v[170:173], v[184:187], v[56:59]
	v_mfma_f32_16x16x32_bf16 v[52:55], v[162:165], v[192:195], v[52:55]
	v_mfma_f32_16x16x32_bf16 v[48:51], v[170:173], v[192:195], v[48:51]
	v_mfma_f32_16x16x32_bf16 v[44:47], v[162:165], v[200:203], v[44:47]
	v_mfma_f32_16x16x32_bf16 v[40:43], v[170:173], v[200:203], v[40:43]
	v_mfma_f32_16x16x32_bf16 v[36:39], v[162:165], v[208:211], v[36:39]
	v_mfma_f32_16x16x32_bf16 v[32:35], v[170:173], v[208:211], v[32:35]
	s_setprio 0
	s_barrier
	v_lshl_add_u64 v[158:159], v[224:225], 0, s[76:77]
	s_add_u32 m0, s24, 0x1c000
	s_nop 0
	global_load_lds_dwordx4 v[158:159], off
	v_lshl_add_u64 v[158:159], v[226:227], 0, s[76:77]
	s_add_u32 m0, s24, 0x1e000
	s_nop 0
	global_load_lds_dwordx4 v[158:159], off
	s_waitcnt vmcnt(6)
	s_barrier
	s_setprio 1
	v_mfma_f32_16x16x32_bf16 v[28:31], v[212:215], v[180:183], v[28:31]
	v_mfma_f32_16x16x32_bf16 v[24:27], v[238:241], v[180:183], v[24:27]
	v_mfma_f32_16x16x32_bf16 v[20:23], v[212:215], v[188:191], v[20:23]
	v_mfma_f32_16x16x32_bf16 v[16:19], v[238:241], v[188:191], v[16:19]
	v_mfma_f32_16x16x32_bf16 v[12:15], v[212:215], v[196:199], v[12:15]
	v_mfma_f32_16x16x32_bf16 v[8:11], v[238:241], v[196:199], v[8:11]
	v_mfma_f32_16x16x32_bf16 v[4:7], v[212:215], v[204:207], v[4:7]
	v_mfma_f32_16x16x32_bf16 v[0:3], v[238:241], v[204:207], v[0:3]
	v_mfma_f32_16x16x32_bf16 v[28:31], v[216:219], v[184:187], v[28:31]
	v_mfma_f32_16x16x32_bf16 v[24:27], v[242:245], v[184:187], v[24:27]
	v_mfma_f32_16x16x32_bf16 v[20:23], v[216:219], v[192:195], v[20:23]
	v_mfma_f32_16x16x32_bf16 v[16:19], v[242:245], v[192:195], v[16:19]
	v_mfma_f32_16x16x32_bf16 v[12:15], v[216:219], v[200:203], v[12:15]
	v_mfma_f32_16x16x32_bf16 v[8:11], v[242:245], v[200:203], v[8:11]
	v_mfma_f32_16x16x32_bf16 v[4:7], v[216:219], v[208:211], v[4:7]
	v_mfma_f32_16x16x32_bf16 v[0:3], v[242:245], v[208:211], v[0:3]
	s_setprio 0
	s_add_i32 s23, s23, 2
	s_add_u32 s14, s14, 0x100
	s_addc_u32 s15, s15, 0
	s_cmpk_gt_u32 s23, 0x53
	s_barrier
	s_cbranch_scc0 .LBB0_922
	v_add_u32_e32 v155, 0xc000, v144
	v_add_u32_e32 v156, 0xe000, v144
	v_add_u32_e32 v157, 0x6000, v144
	s_add_u32 s14, s12, 0x162b80
	s_addc_u32 s15, s13, 0
	v_readfirstlane_b32 s23, v155
	v_lshl_add_u64 v[150:151], s[14:15], 0, v[178:179]
	s_mov_b32 m0, s23
	v_lshl_add_u64 v[128:129], s[14:15], 0, v[128:129]
	v_readfirstlane_b32 s14, v156
	ds_read_b128 v[130:133], v154
	ds_read_b128 v[134:137], v154 offset:1024
	ds_read_b128 v[146:149], v154 offset:2048
	ds_read_b128 v[158:161], v154 offset:3072
	ds_read_b128 v[162:165], v142
	ds_read_b128 v[166:169], v142 offset:1024
	ds_read_b128 v[170:173], v141
	ds_read_b128 v[180:183], v141 offset:1024
	ds_read_b128 v[184:187], v140
	ds_read_b128 v[188:191], v140 offset:1024
	ds_read_b128 v[192:195], v139
	ds_read_b128 v[196:199], v139 offset:1024
	global_load_lds_dwordx4 v[150:151], off
	s_mov_b32 m0, s14
	s_nop 0
	global_load_lds_dwordx4 v[128:129], off
	s_barrier
; #define LDA(dst, b, h) _Pragma("unroll") for (int m = 0; m < 4; ++m) _Pragma("unroll") for (int k = 0; k < 2; ++k) \
;     dst[m][k] = *reinterpret_cast<const bf16x8*>((const char*)SA(b, h) + lds_byte(wr * 64 + m * 16 + fr, k * 32 + fq * 8))
; #define LDB(dst, b, h) _Pragma("unroll") for (int n = 0; n < 2; ++n) _Pragma("unroll") for (int k = 0; k < 2; ++k) \
;     dst[n][k] = *reinterpret_cast<const bf16x8*>((const char*)SB(b, h) + lds_byte(wc * 32 + n * 16 + fr, k * 32 + fq * 8))
; #define MMA(ai, bj, At_, Bt_) do { __builtin_amdgcn_s_setprio(1); \
;     _Pragma("unroll") for (int m = 0; m < 4; ++m) _Pragma("unroll") for (int n = 0; n < 2; ++n) _Pragma("unroll") for (int k = 0; k < 2; ++k) \
;       acc[ai][bj][m][n] = __builtin_amdgcn_mfma_f32_16x16x32_bf16(Bt_[n][k], At_[m][k], acc[ai][bj][m][n], 0, 0, 0); \
;     __builtin_amdgcn_s_setprio(0); } while (0)
; #define WAIT_V(n) asm volatile("s_waitcnt vmcnt(" #n ")" ::: "memory")
; #define WAIT_L(n) asm volatile("s_waitcnt lgkmcnt(" #n ")" ::: "memory")
; #define BAR __builtin_amdgcn_s_barrier()
; template <bool PF = true, class Epi, class KRF = KRFull>
; __device__ __forceinline__ void gemm_phase(const u16* __restrict__ A, int lda, const u16* __restrict__ Bt, int ldb, int K, int nM, int nN,
;                                            lds_u16* shm, Epi epi, KRF krf = KRFull(), bool flip = false) {
;     ...
;       BAR; WAIT_L(0); MMA(0, 0, At, B0); BAR;
;       LDB(B1, 0, 1); BAR; WAIT_L(0); MMA(0, 1, At, B1); BAR;
;       LDA(At, 0, 1); WAIT_V(4); BAR; WAIT_L(0); MMA(1, 0, At, B0); MMA(1, 1, At, B1); BAR; }
;     { LDB(B0, 1, 0); LDA(At, 1, 0); WAIT_V(2); BAR; WAIT_L(0); MMA(0, 0, At, B0); BAR;
	s_waitcnt lgkmcnt(0)
	s_setprio 1
	s_waitcnt lgkmcnt(0)
	v_mfma_f32_16x16x32_bf16 v[124:127], v[130:133], v[162:165], v[124:127]
	v_mfma_f32_16x16x32_bf16 v[120:123], v[146:149], v[162:165], v[120:123]
	v_mfma_f32_16x16x32_bf16 v[116:119], v[130:133], v[170:173], v[116:119]
	v_mfma_f32_16x16x32_bf16 v[112:115], v[146:149], v[170:173], v[112:115]
	v_mfma_f32_16x16x32_bf16 v[108:111], v[130:133], v[184:187], v[108:111]
	v_mfma_f32_16x16x32_bf16 v[104:107], v[146:149], v[184:187], v[104:107]
	v_mfma_f32_16x16x32_bf16 v[100:103], v[130:133], v[192:195], v[100:103]
	v_mfma_f32_16x16x32_bf16 v[96:99], v[146:149], v[192:195], v[96:99]
	v_mfma_f32_16x16x32_bf16 v[124:127], v[134:137], v[166:169], v[124:127]
	v_mfma_f32_16x16x32_bf16 v[120:123], v[158:161], v[166:169], v[120:123]
	v_mfma_f32_16x16x32_bf16 v[116:119], v[134:137], v[180:183], v[116:119]
	v_mfma_f32_16x16x32_bf16 v[112:115], v[158:161], v[180:183], v[112:115]
	v_mfma_f32_16x16x32_bf16 v[108:111], v[134:137], v[188:191], v[108:111]
	v_mfma_f32_16x16x32_bf16 v[104:107], v[158:161], v[188:191], v[104:107]
	v_mfma_f32_16x16x32_bf16 v[100:103], v[134:137], v[196:199], v[100:103]
	v_mfma_f32_16x16x32_bf16 v[96:99], v[158:161], v[196:199], v[96:99]
	s_setprio 0
	s_barrier
	ds_read_b128 v[154:157], v153
	ds_read_b128 v[200:203], v153 offset:1024
	ds_read_b128 v[204:207], v153 offset:2048
	ds_read_b128 v[150:153], v153 offset:3072
	s_barrier
	s_waitcnt lgkmcnt(0)
	s_setprio 1
	s_waitcnt lgkmcnt(0)
	v_mfma_f32_16x16x32_bf16 v[92:95], v[154:157], v[162:165], v[92:95]
	v_mfma_f32_16x16x32_bf16 v[88:91], v[204:207], v[162:165], v[88:91]
	v_mfma_f32_16x16x32_bf16 v[84:87], v[154:157], v[170:173], v[84:87]
	v_mfma_f32_16x16x32_bf16 v[80:83], v[204:207], v[170:173], v[80:83]
	v_mfma_f32_16x16x32_bf16 v[76:79], v[154:157], v[184:187], v[76:79]
	v_mfma_f32_16x16x32_bf16 v[72:75], v[204:207], v[184:187], v[72:75]
	v_mfma_f32_16x16x32_bf16 v[68:71], v[154:157], v[192:195], v[68:71]
	v_mfma_f32_16x16x32_bf16 v[64:67], v[204:207], v[192:195], v[64:67]
	v_mfma_f32_16x16x32_bf16 v[92:95], v[200:203], v[166:169], v[92:95]
	v_mfma_f32_16x16x32_bf16 v[88:91], v[150:153], v[166:169], v[88:91]
	v_mfma_f32_16x16x32_bf16 v[84:87], v[200:203], v[180:183], v[84:87]
	v_mfma_f32_16x16x32_bf16 v[80:83], v[150:153], v[180:183], v[80:83]
	v_mfma_f32_16x16x32_bf16 v[76:79], v[200:203], v[188:191], v[76:79]
	v_mfma_f32_16x16x32_bf16 v[72:75], v[150:153], v[188:191], v[72:75]
	v_mfma_f32_16x16x32_bf16 v[68:71], v[200:203], v[196:199], v[68:71]
	v_mfma_f32_16x16x32_bf16 v[64:67], v[150:153], v[196:199], v[64:67]
	s_setprio 0
	s_barrier
	ds_read_b128 v[162:165], v142 offset:16384
	ds_read_b128 v[166:169], v142 offset:17408
	ds_read_b128 v[170:173], v141 offset:16384
	ds_read_b128 v[180:183], v141 offset:17408
	ds_read_b128 v[184:187], v140 offset:16384
	ds_read_b128 v[188:191], v140 offset:17408
	ds_read_b128 v[192:195], v139 offset:16384
	ds_read_b128 v[196:199], v139 offset:17408
	s_waitcnt vmcnt(4)
	s_barrier
	s_waitcnt lgkmcnt(0)
	s_setprio 1
	s_waitcnt lgkmcnt(0)
	v_mfma_f32_16x16x32_bf16 v[60:63], v[130:133], v[162:165], v[60:63]
	v_mfma_f32_16x16x32_bf16 v[56:59], v[146:149], v[162:165], v[56:59]
	v_mfma_f32_16x16x32_bf16 v[52:55], v[130:133], v[170:173], v[52:55]
	v_mfma_f32_16x16x32_bf16 v[48:51], v[146:149], v[170:173], v[48:51]
	v_mfma_f32_16x16x32_bf16 v[44:47], v[130:133], v[184:187], v[44:47]
	v_mfma_f32_16x16x32_bf16 v[40:43], v[146:149], v[184:187], v[40:43]
	v_mfma_f32_16x16x32_bf16 v[36:39], v[130:133], v[192:195], v[36:39]
	v_mfma_f32_16x16x32_bf16 v[32:35], v[146:149], v[192:195], v[32:35]
	v_mfma_f32_16x16x32_bf16 v[60:63], v[134:137], v[166:169], v[60:63]
	v_mfma_f32_16x16x32_bf16 v[56:59], v[158:161], v[166:169], v[56:59]
	v_mfma_f32_16x16x32_bf16 v[52:55], v[134:137], v[180:183], v[52:55]
	v_mfma_f32_16x16x32_bf16 v[48:51], v[158:161], v[180:183], v[48:51]
	v_mfma_f32_16x16x32_bf16 v[44:47], v[134:137], v[188:191], v[44:47]
	v_mfma_f32_16x16x32_bf16 v[40:43], v[158:161], v[188:191], v[40:43]
	v_mfma_f32_16x16x32_bf16 v[36:39], v[134:137], v[196:199], v[36:39]
	v_mfma_f32_16x16x32_bf16 v[32:35], v[158:161], v[196:199], v[32:35]
	s_setprio 0
	s_setprio 1
	v_mfma_f32_16x16x32_bf16 v[28:31], v[154:157], v[162:165], v[28:31]
	v_mfma_f32_16x16x32_bf16 v[24:27], v[204:207], v[162:165], v[24:27]
	v_mfma_f32_16x16x32_bf16 v[20:23], v[154:157], v[170:173], v[20:23]
	v_mfma_f32_16x16x32_bf16 v[16:19], v[204:207], v[170:173], v[16:19]
	v_mfma_f32_16x16x32_bf16 v[12:15], v[154:157], v[184:187], v[12:15]
	v_mfma_f32_16x16x32_bf16 v[8:11], v[204:207], v[184:187], v[8:11]
	v_mfma_f32_16x16x32_bf16 v[4:7], v[154:157], v[192:195], v[4:7]
	v_mfma_f32_16x16x32_bf16 v[0:3], v[204:207], v[192:195], v[0:3]
	v_mfma_f32_16x16x32_bf16 v[28:31], v[200:203], v[166:169], v[28:31]
	v_mfma_f32_16x16x32_bf16 v[24:27], v[150:153], v[166:169], v[24:27]
	v_mfma_f32_16x16x32_bf16 v[20:23], v[200:203], v[180:183], v[20:23]
	v_mfma_f32_16x16x32_bf16 v[16:19], v[150:153], v[180:183], v[16:19]
	v_mfma_f32_16x16x32_bf16 v[12:15], v[200:203], v[188:191], v[12:15]
	v_mfma_f32_16x16x32_bf16 v[8:11], v[150:153], v[188:191], v[8:11]
	v_mfma_f32_16x16x32_bf16 v[4:7], v[200:203], v[196:199], v[4:7]
	v_mfma_f32_16x16x32_bf16 v[0:3], v[150:153], v[196:199], v[0:3]
	s_setprio 0
	s_barrier
	ds_read_b128 v[128:131], v145
	ds_read_b128 v[132:135], v145 offset:1024
	ds_read_b128 v[146:149], v145 offset:2048
	ds_read_b128 v[150:153], v145 offset:3072
	ds_read_b128 v[154:157], v142 offset:32768
	ds_read_b128 v[158:161], v142 offset:33792
	ds_read_b128 v[162:165], v141 offset:32768
	ds_read_b128 v[166:169], v141 offset:33792
	ds_read_b128 v[170:173], v140 offset:32768
	ds_read_b128 v[180:183], v140 offset:33792
	ds_read_b128 v[184:187], v139 offset:32768
	ds_read_b128 v[188:191], v139 offset:33792
	s_waitcnt vmcnt(2)
	s_barrier
; #define LDA(dst, b, h) _Pragma("unroll") for (int m = 0; m < 4; ++m) _Pragma("unroll") for (int k = 0; k < 2; ++k) \
;     dst[m][k] = *reinterpret_cast<const bf16x8*>((const char*)SA(b, h) + lds_byte(wr * 64 + m * 16 + fr, k * 32 + fq * 8))
; #define LDB(dst, b, h) _Pragma("unroll") for (int n = 0; n < 2; ++n) _Pragma("unroll") for (int k = 0; k < 2; ++k) \
;     dst[n][k] = *reinterpret_cast<const bf16x8*>((const char*)SB(b, h) + lds_byte(wc * 32 + n * 16 + fr, k * 32 + fq * 8))
; #define MMA(ai, bj, At_, Bt_) do { __builtin_amdgcn_s_setprio(1); \
;     _Pragma("unroll") for (int m = 0; m < 4; ++m) _Pragma("unroll") for (int n = 0; n < 2; ++n) _Pragma("unroll") for (int k = 0; k < 2; ++k) \
;       acc[ai][bj][m][n] = __builtin_amdgcn_mfma_f32_16x16x32_bf16(Bt_[n][k], At_[m][k], acc[ai][bj][m][n], 0, 0, 0); \
;     __builtin_amdgcn_s_setprio(0); } while (0)
; #define WAIT_V(n) asm volatile("s_waitcnt vmcnt(" #n ")" ::: "memory")
; #define WAIT_L(n) asm volatile("s_waitcnt lgkmcnt(" #n ")" ::: "memory")
; #define BAR __builtin_amdgcn_s_barrier()
; template <bool PF = true, class Epi, class KRF = KRFull>
; __device__ __forceinline__ void gemm_phase(const u16* __restrict__ A, int lda, const u16* __restrict__ Bt, int ldb, int K, int nM, int nN,
;                                            lds_u16* shm, Epi epi, KRF krf = KRFull(), bool flip = false) {
;     ...
;     { LDB(B0, 1, 0); LDA(At, 1, 0); WAIT_V(2); BAR; WAIT_L(0); MMA(0, 0, At, B0); BAR;
;       LDB(B1, 1, 1); WAIT_V(0); BAR; WAIT_L(0); MMA(0, 1, At, B1); BAR;
;       LDA(At, 1, 1); BAR; WAIT_L(0); MMA(1, 0, At, B0); MMA(1, 1, At, B1); BAR; }
;     if (wr == 0) BAR;
	s_waitcnt lgkmcnt(0)
	s_setprio 1
	s_waitcnt lgkmcnt(0)
	v_mfma_f32_16x16x32_bf16 v[124:127], v[128:131], v[154:157], v[124:127]
	v_mfma_f32_16x16x32_bf16 v[120:123], v[146:149], v[154:157], v[120:123]
	v_mfma_f32_16x16x32_bf16 v[116:119], v[128:131], v[162:165], v[116:119]
	v_mfma_f32_16x16x32_bf16 v[112:115], v[146:149], v[162:165], v[112:115]
	v_mfma_f32_16x16x32_bf16 v[108:111], v[128:131], v[170:173], v[108:111]
	v_mfma_f32_16x16x32_bf16 v[104:107], v[146:149], v[170:173], v[104:107]
	v_mfma_f32_16x16x32_bf16 v[100:103], v[128:131], v[184:187], v[100:103]
	v_mfma_f32_16x16x32_bf16 v[96:99], v[146:149], v[184:187], v[96:99]
	v_mfma_f32_16x16x32_bf16 v[124:127], v[132:135], v[158:161], v[124:127]
	v_mfma_f32_16x16x32_bf16 v[120:123], v[150:153], v[158:161], v[120:123]
	v_mfma_f32_16x16x32_bf16 v[116:119], v[132:135], v[166:169], v[116:119]
	v_mfma_f32_16x16x32_bf16 v[112:115], v[150:153], v[166:169], v[112:115]
	v_mfma_f32_16x16x32_bf16 v[108:111], v[132:135], v[180:183], v[108:111]
	v_mfma_f32_16x16x32_bf16 v[104:107], v[150:153], v[180:183], v[104:107]
	v_mfma_f32_16x16x32_bf16 v[100:103], v[132:135], v[188:191], v[100:103]
	v_mfma_f32_16x16x32_bf16 v[96:99], v[150:153], v[188:191], v[96:99]
	s_setprio 0
	s_barrier
	ds_read_b128 v[192:195], v143
	ds_read_b128 v[196:199], v143 offset:1024
	ds_read_b128 v[200:203], v143 offset:2048
	ds_read_b128 v[204:207], v143 offset:3072
	s_waitcnt vmcnt(0)
	s_barrier
	s_waitcnt lgkmcnt(0)
	s_setprio 1
	s_waitcnt lgkmcnt(0)
	v_mfma_f32_16x16x32_bf16 v[92:95], v[192:195], v[154:157], v[92:95]
	v_mfma_f32_16x16x32_bf16 v[88:91], v[200:203], v[154:157], v[88:91]
	v_mfma_f32_16x16x32_bf16 v[84:87], v[192:195], v[162:165], v[84:87]
	v_mfma_f32_16x16x32_bf16 v[80:83], v[200:203], v[162:165], v[80:83]
	v_mfma_f32_16x16x32_bf16 v[76:79], v[192:195], v[170:173], v[76:79]
	v_mfma_f32_16x16x32_bf16 v[72:75], v[200:203], v[170:173], v[72:75]
	v_mfma_f32_16x16x32_bf16 v[68:71], v[192:195], v[184:187], v[68:71]
	v_mfma_f32_16x16x32_bf16 v[64:67], v[200:203], v[184:187], v[64:67]
	v_mfma_f32_16x16x32_bf16 v[92:95], v[196:199], v[158:161], v[92:95]
	v_mfma_f32_16x16x32_bf16 v[88:91], v[204:207], v[158:161], v[88:91]
	v_mfma_f32_16x16x32_bf16 v[84:87], v[196:199], v[166:169], v[84:87]
	v_mfma_f32_16x16x32_bf16 v[80:83], v[204:207], v[166:169], v[80:83]
	v_mfma_f32_16x16x32_bf16 v[76:79], v[196:199], v[180:183], v[76:79]
	v_mfma_f32_16x16x32_bf16 v[72:75], v[204:207], v[180:183], v[72:75]
	v_mfma_f32_16x16x32_bf16 v[68:71], v[196:199], v[188:191], v[68:71]
	v_mfma_f32_16x16x32_bf16 v[64:67], v[204:207], v[188:191], v[64:67]
	s_setprio 0
	s_barrier
	ds_read_b128 v[154:157], v142 offset:49152
	ds_read_b128 v[142:145], v142 offset:50176
	ds_read_b128 v[158:161], v141 offset:49152
	ds_read_b128 v[162:165], v141 offset:50176
	ds_read_b128 v[166:169], v140 offset:49152
	ds_read_b128 v[170:173], v140 offset:50176
	ds_read_b128 v[180:183], v139 offset:49152
	ds_read_b128 v[184:187], v139 offset:50176
	s_barrier
	s_waitcnt lgkmcnt(0)
	s_setprio 1
	s_waitcnt lgkmcnt(0)
	v_mfma_f32_16x16x32_bf16 v[60:63], v[128:131], v[154:157], v[60:63]
	v_mfma_f32_16x16x32_bf16 v[56:59], v[146:149], v[154:157], v[56:59]
	v_mfma_f32_16x16x32_bf16 v[52:55], v[128:131], v[158:161], v[52:55]
	v_mfma_f32_16x16x32_bf16 v[48:51], v[146:149], v[158:161], v[48:51]
	v_mfma_f32_16x16x32_bf16 v[44:47], v[128:131], v[166:169], v[44:47]
	v_mfma_f32_16x16x32_bf16 v[40:43], v[146:149], v[166:169], v[40:43]
	v_mfma_f32_16x16x32_bf16 v[36:39], v[128:131], v[180:183], v[36:39]
	v_mfma_f32_16x16x32_bf16 v[32:35], v[146:149], v[180:183], v[32:35]
	v_mfma_f32_16x16x32_bf16 v[60:63], v[132:135], v[142:145], v[60:63]
	v_mfma_f32_16x16x32_bf16 v[56:59], v[150:153], v[142:145], v[56:59]
	v_mfma_f32_16x16x32_bf16 v[52:55], v[132:135], v[162:165], v[52:55]
	v_mfma_f32_16x16x32_bf16 v[48:51], v[150:153], v[162:165], v[48:51]
	v_mfma_f32_16x16x32_bf16 v[44:47], v[132:135], v[170:173], v[44:47]
	v_mfma_f32_16x16x32_bf16 v[40:43], v[150:153], v[170:173], v[40:43]
	v_mfma_f32_16x16x32_bf16 v[36:39], v[132:135], v[184:187], v[36:39]
	v_mfma_f32_16x16x32_bf16 v[32:35], v[150:153], v[184:187], v[32:35]
	s_setprio 0
	s_setprio 1
	v_mfma_f32_16x16x32_bf16 v[28:31], v[192:195], v[154:157], v[28:31]
	v_mfma_f32_16x16x32_bf16 v[24:27], v[200:203], v[154:157], v[24:27]
	v_mfma_f32_16x16x32_bf16 v[20:23], v[192:195], v[158:161], v[20:23]
	v_mfma_f32_16x16x32_bf16 v[16:19], v[200:203], v[158:161], v[16:19]
	v_mfma_f32_16x16x32_bf16 v[12:15], v[192:195], v[166:169], v[12:15]
	v_mfma_f32_16x16x32_bf16 v[8:11], v[200:203], v[166:169], v[8:11]
	v_mfma_f32_16x16x32_bf16 v[4:7], v[192:195], v[180:183], v[4:7]
	v_mfma_f32_16x16x32_bf16 v[0:3], v[200:203], v[180:183], v[0:3]
	v_mfma_f32_16x16x32_bf16 v[28:31], v[196:199], v[142:145], v[28:31]
	v_mfma_f32_16x16x32_bf16 v[24:27], v[204:207], v[142:145], v[24:27]
	v_mfma_f32_16x16x32_bf16 v[20:23], v[196:199], v[162:165], v[20:23]
	v_mfma_f32_16x16x32_bf16 v[16:19], v[204:207], v[162:165], v[16:19]
	v_mfma_f32_16x16x32_bf16 v[12:15], v[196:199], v[170:173], v[12:15]
	v_mfma_f32_16x16x32_bf16 v[8:11], v[204:207], v[170:173], v[8:11]
	v_mfma_f32_16x16x32_bf16 v[4:7], v[196:199], v[184:187], v[4:7]
	v_mfma_f32_16x16x32_bf16 v[0:3], v[204:207], v[184:187], v[0:3]
	s_setprio 0
	v_cmp_gt_u32_e32 vcc, s95, v138
	s_barrier
	s_and_saveexec_b64 s[14:15], vcc
	s_cbranch_execz .LBB0_925
	s_barrier

; #define STAGE_A(P, half, kt) do { const char* _u = Ab + ((size_t)(half) * 128 * lda + (size_t)(kt) * BK) * 2; \
;     _Pragma("unroll") for (int _i = 0; _i < 2; ++_i) \
;       __builtin_amdgcn_global_load_lds((const unsigned*)(_u + offA[_i]), \
;         (__attribute__((address_space(3))) unsigned*)((__attribute__((address_space(3))) char*)(P) + tidg * 16 + _i * 8192), 16, 0, 0); } while (0)
; #define STAGE_B(P, half, kt) do { const char* _u = Bb + ((size_t)(half) * 128 * ldb + (size_t)(kt) * BK) * 2; \
;     _Pragma("unroll") for (int _i = 0; _i < 2; ++_i) \
;       __builtin_amdgcn_global_load_lds((const unsigned*)(_u + offB[_i]), \
;         (__attribute__((address_space(3))) unsigned*)((__attribute__((address_space(3))) char*)(P) + tidg * 16 + _i * 8192), 16, 0, 0); } while (0)
; #define WAIT_V(n) asm volatile("s_waitcnt vmcnt(" #n ")" ::: "memory")
; #define BAR __builtin_amdgcn_s_barrier()
; #define G_THREAD() do { asm volatile("" : "+v"(tidg)); wid = tidg >> 6; lane = tidg & 63; wr = wid >> 2; wc = wid & 3; fr = lane & 15; fq = lane >> 4; \
;     _Pragma("unroll") for (int _i = 0; _i < 2; ++_i) { int _r, _c; stage_rc(tidg * 16 + _i * 8192, _r, _c); offA[_i] = (unsigned)(_r * lda + _c) * 2u; offB[_i] = (unsigned)(_r * ldb + _c) * 2u; } } while (0)
; template <bool PF = true, class Epi, class KRF = KRFull>
; __device__ __forceinline__ void gemm_phase(const u16* __restrict__ A, int lda, const u16* __restrict__ Bt, int ldb, int K, int nM, int nN,
;                                            lds_u16* shm, Epi epi, KRF krf = KRFull(), bool flip = false) {
;     ...
;     G_THREAD();
;     nt = nt_next;
;     f32x4 acc[2][2][4][2] = {};
;     bf16x8 At[4][2], B0[2][2], B1[2][2];
;     if (wr == 1) BAR;
;     WAIT_V(4); BAR;
;     STAGE_B(SB(1, 0), 0, 1); STAGE_A(SA(1, 0), 0, 1); STAGE_B(SB(1, 1), 1, 1);
;     WAIT_V(6); BAR;
.LBB0_947:
	s_or_b64 exec, exec, s[10:11]
	v_bfe_i32 v2, v138, 27, 1
	v_lshlrev_b32_e32 v146, 4, v138
	v_lshrrev_b32_e32 v2, 22, v2
	v_add_u32_e32 v2, v146, v2
	v_and_b32_e32 v2, 0xfffffc00, v2
	v_sub_u32_e32 v2, v146, v2
	v_lshrrev_b32_e32 v3, 4, v2
	v_bitop3_b32 v2, v3, v2, 32 bitop3:0x6c
	v_ashrrev_i32_e32 v5, 31, v2
	v_ashrrev_i32_e32 v1, 31, v138
	v_lshrrev_b32_e32 v5, 26, v5
	v_lshrrev_b32_e32 v1, 26, v1
	v_add_u32_e32 v5, v2, v5
	v_add_u32_e32 v1, v138, v1
	v_ashrrev_i32_e32 v6, 6, v5
	v_and_b32_e32 v5, 0xc0, v5
	v_ashrrev_i32_e32 v4, 6, v1
	v_sub_u32_e32 v2, v2, v5
	v_lshlrev_b32_e32 v3, 3, v4
	v_lshlrev_b32_e32 v7, 5, v4
	v_ashrrev_i16_sdwa v2, v232, sext(v2) dst_sel:DWORD dst_unused:UNUSED_PAD src0_sel:DWORD src1_sel:BYTE_0
	v_and_b32_e32 v3, 0xffff0, v3
	v_and_b32_e32 v7, 32, v7
	v_bfe_i32 v5, v2, 0, 16
	v_add_u32_e32 v2, v7, v5
	v_add_lshl_u32 v3, v6, v3, 12
	v_add_u32_e32 v148, 0x2000, v146
	v_lshl_add_u32 v178, v2, 1, v3
	v_ashrrev_i32_e32 v2, 31, v148
	v_lshrrev_b32_e32 v2, 22, v2
	v_add_u32_e32 v2, v148, v2
	v_ashrrev_i32_e32 v7, 10, v2
	v_mul_i32_i24_e32 v2, 0x400, v7
	v_sub_u32_e32 v2, v148, v2
	v_lshrrev_b32_e32 v3, 4, v2
	v_bitop3_b32 v2, v3, v2, 32 bitop3:0x6c
	v_ashrrev_i32_e32 v8, 31, v2
	v_lshrrev_b32_e32 v8, 26, v8
	v_add_u32_e32 v8, v2, v8
	v_ashrrev_i32_e32 v9, 6, v8
	v_and_b32_e32 v8, 0xc0, v8
	v_sub_u32_e32 v2, v2, v8
	v_lshlrev_b32_e32 v3, 3, v7
	v_lshlrev_b32_e32 v10, 5, v7
	v_ashrrev_i16_sdwa v2, v232, sext(v2) dst_sel:DWORD dst_unused:UNUSED_PAD src0_sel:DWORD src1_sel:BYTE_0
	v_and_b32_e32 v3, 0xffff0, v3
	v_and_b32_e32 v10, 32, v10
	v_bfe_i32 v8, v2, 0, 16
	v_add_u32_e32 v2, v10, v8
	v_add_lshl_u32 v3, v9, v3, 12
	v_add_u32_e32 v149, 0x18000, v146
	v_lshl_add_u32 v128, v2, 1, v3
	v_lshl_add_u64 v[2:3], s[8:9], 0, v[178:179]
	v_readfirstlane_b32 s2, v149
	v_lshl_add_u64 v[2:3], v[2:3], 0, s[60:61]
	s_mov_b32 m0, s2
	v_mov_b32_e32 v129, v179
	v_add_u32_e32 v150, 0x1a000, v146
	s_waitcnt vmcnt(4)
	s_barrier
	global_load_lds_dwordx4 v[2:3], off
	v_lshl_add_u64 v[2:3], s[8:9], 0, v[128:129]
	v_readfirstlane_b32 s2, v150
	v_lshl_add_u64 v[2:3], v[2:3], 0, s[60:61]
	s_mov_b32 m0, s2
	v_add_u32_e32 v151, 0x8000, v146
	global_load_lds_dwordx4 v[2:3], off
	v_lshl_add_u64 v[2:3], s[6:7], 0, v[178:179]
	v_readfirstlane_b32 s2, v151
	v_lshl_add_u64 v[2:3], v[2:3], 0, s[60:61]
	s_mov_b32 m0, s2
	v_add_u32_e32 v152, 0xa000, v146
	global_load_lds_dwordx4 v[2:3], off
	v_lshl_add_u64 v[2:3], s[6:7], 0, v[128:129]
	v_readfirstlane_b32 s2, v152
	v_add_u32_e32 v153, 0x1c000, v146
	v_lshl_add_u64 v[2:3], v[2:3], 0, s[60:61]
	s_mov_b32 m0, s2
	s_add_u32 s2, s8, 0x80080
	v_readfirstlane_b32 s10, v153
	v_add_u32_e32 v154, 0x1e000, v146
	global_load_lds_dwordx4 v[2:3], off
	s_addc_u32 s3, s9, 0
	s_mov_b32 m0, s10
	v_readfirstlane_b32 s10, v154
	global_load_lds_dwordx4 v178, s[2:3]
	s_mov_b32 m0, s10
	v_and_b32_e32 v10, 15, v138
	global_load_lds_dwordx4 v128, s[2:3]
	v_lshlrev_b32_e32 v2, 6, v10
	v_lshlrev_b32_e32 v10, 2, v138
	v_and_b32_e32 v11, 48, v138
	v_and_b32_e32 v10, 32, v10
	v_or_b32_e32 v3, v2, v11
	v_bitop3_b32 v12, v2, v10, v11 bitop3:0x36
	s_mov_b32 s2, 0x14000
	v_lshlrev_b32_e32 v2, 6, v138
	v_bitop3_b32 v14, v3, s2, v10 bitop3:0xde
	s_mov_b32 s2, 0x18000
	v_lshlrev_b32_e32 v18, 13, v0
	v_and_b32_e32 v0, 0x3c0, v2
	v_bitop3_b32 v13, v3, s94, v10 bitop3:0xde
	v_bitop3_b32 v15, v3, s2, v10 bitop3:0xde
	v_bitop3_b32 v16, v3, s97, v10 bitop3:0xde
	v_bitop3_b32 v10, v0, v10, v11 bitop3:0x36
	v_lshlrev_b32_e32 v0, 15, v4
	v_and_b32_e32 v17, 0x3000, v2
	v_and_b32_e32 v0, 0xffff0000, v0
	v_lshlrev_b32_e32 v2, 15, v7
	v_lshl_add_u32 v0, v6, 12, v0
	v_and_b32_e32 v2, 0xffff0000, v2
	v_and_or_b32 v0, v1, 64, v0
	v_lshl_add_u32 v2, v9, 12, v2
	v_lshlrev_b32_e32 v3, 6, v7
	s_waitcnt vmcnt(6)
	v_lshl_add_u32 v0, v5, 1, v0
	v_mov_b32_e32 v1, v179
	v_and_or_b32 v2, v3, 64, v2
	v_or_b32_e32 v11, 0x800, v18
	v_or_b32_e32 v19, 0x1000, v18
	v_or_b32_e32 v20, 0x1800, v18
	v_lshl_add_u64 v[130:131], s[8:9], 0, v[0:1]
	v_lshl_add_u32 v2, v8, 1, v2
	v_mov_b32_e32 v3, v179
	v_lshl_add_u64 v[134:135], s[6:7], 0, v[0:1]
	v_mov_b32_e32 v0, 0
	v_lshl_add_u64 v[132:133], s[8:9], 0, v[2:3]
	v_lshl_add_u64 v[136:137], s[6:7], 0, v[2:3]
	s_mov_b32 s2, -2
	s_mov_b64 s[8:9], 0
	v_add_u32_e32 v156, v13, v17
	v_add_u32_e32 v144, v12, v18
	v_add_u32_e32 v143, v10, v11
	v_add_u32_e32 v142, v10, v19
	v_add_u32_e32 v141, v10, v20
	v_add_u32_e32 v155, v14, v17
	v_add_u32_e32 v147, v15, v17
	v_add_u32_e32 v145, v16, v17
	v_mov_b32_e32 v1, v0
	v_mov_b32_e32 v2, v0
	v_mov_b32_e32 v3, v0
	v_mov_b32_e32 v4, v0
	v_mov_b32_e32 v5, v0
	v_mov_b32_e32 v6, v0
	v_mov_b32_e32 v7, v0
	v_mov_b32_e32 v8, v0
	v_mov_b32_e32 v9, v0
	v_mov_b32_e32 v10, v0
	v_mov_b32_e32 v11, v0
	v_mov_b32_e32 v12, v0
	v_mov_b32_e32 v13, v0
	v_mov_b32_e32 v14, v0
	v_mov_b32_e32 v15, v0
	v_mov_b32_e32 v16, v0
	v_mov_b32_e32 v17, v0
	v_mov_b32_e32 v18, v0
	v_mov_b32_e32 v19, v0
	v_mov_b32_e32 v20, v0
	v_mov_b32_e32 v21, v0
	v_mov_b32_e32 v22, v0
	v_mov_b32_e32 v23, v0
	v_mov_b32_e32 v24, v0
	v_mov_b32_e32 v25, v0
	v_mov_b32_e32 v26, v0
	v_mov_b32_e32 v27, v0
	v_mov_b32_e32 v28, v0
	v_mov_b32_e32 v29, v0
	v_mov_b32_e32 v30, v0
	v_mov_b32_e32 v31, v0
	v_mov_b32_e32 v32, v0
	v_mov_b32_e32 v33, v0
	v_mov_b32_e32 v34, v0
	v_mov_b32_e32 v35, v0
	v_mov_b32_e32 v36, v0
	v_mov_b32_e32 v37, v0
	v_mov_b32_e32 v38, v0
	v_mov_b32_e32 v39, v0
	v_mov_b32_e32 v40, v0
	v_mov_b32_e32 v41, v0
	v_mov_b32_e32 v42, v0
	v_mov_b32_e32 v43, v0
	v_mov_b32_e32 v44, v0
	v_mov_b32_e32 v45, v0
	v_mov_b32_e32 v46, v0
	v_mov_b32_e32 v47, v0
	v_mov_b32_e32 v48, v0
	v_mov_b32_e32 v49, v0
	v_mov_b32_e32 v50, v0
	v_mov_b32_e32 v51, v0
; #define STAGE_A(P, half, kt) do { const char* _u = Ab + ((size_t)(half) * 128 * lda + (size_t)(kt) * BK) * 2; \
;     _Pragma("unroll") for (int _i = 0; _i < 2; ++_i) \
;       __builtin_amdgcn_global_load_lds((const unsigned*)(_u + offA[_i]), \
;         (__attribute__((address_space(3))) unsigned*)((__attribute__((address_space(3))) char*)(P) + tidg * 16 + _i * 8192), 16, 0, 0); } while (0)
; #define STAGE_B(P, half, kt) do { const char* _u = Bb + ((size_t)(half) * 128 * ldb + (size_t)(kt) * BK) * 2; \
;     _Pragma("unroll") for (int _i = 0; _i < 2; ++_i) \
;       __builtin_amdgcn_global_load_lds((const unsigned*)(_u + offB[_i]), \
;         (__attribute__((address_space(3))) unsigned*)((__attribute__((address_space(3))) char*)(P) + tidg * 16 + _i * 8192), 16, 0, 0); } while (0)
; #define LDA(dst, b, h) _Pragma("unroll") for (int m = 0; m < 4; ++m) _Pragma("unroll") for (int k = 0; k < 2; ++k) \
;     dst[m][k] = *reinterpret_cast<const bf16x8*>((const char*)SA(b, h) + lds_byte(wr * 64 + m * 16 + fr, k * 32 + fq * 8))
; #define LDB(dst, b, h) _Pragma("unroll") for (int n = 0; n < 2; ++n) _Pragma("unroll") for (int k = 0; k < 2; ++k) \
;     dst[n][k] = *reinterpret_cast<const bf16x8*>((const char*)SB(b, h) + lds_byte(wc * 32 + n * 16 + fr, k * 32 + fq * 8))
; #define WAIT_L(n) asm volatile("s_waitcnt lgkmcnt(" #n ")" ::: "memory")
; #define BAR __builtin_amdgcn_s_barrier()
; #define SCHED __builtin_amdgcn_sched_barrier(0)
; template <bool PF = true, class Epi, class KRF = KRFull>
; __device__ __forceinline__ void gemm_phase(const u16* __restrict__ A, int lda, const u16* __restrict__ Bt, int ldb, int K, int nM, int nN,
;                                            lds_u16* shm, Epi epi, KRF krf = KRFull(), bool flip = false) {
;     ...
;     f32x4 acc[2][2][4][2] = {};
;     ...
;     for (int t = 0; t < nt - 2; t += 2) {
;       LDB(B0, 0, 0); SCHED; LDA(At, 0, 0); STAGE_A(SA(1, 1), 1, t + 1);
;       WAIT_L(8); BAR; WAIT_L(0); MMA(0, 0, At, B0); BAR; SCHED;
;       LDB(B1, 0, 1); STAGE_B(SB(0, 0), 0, t + 2);
;       BAR; WAIT_L(0); MMA(0, 1, At, B1); BAR;
;       LDA(At, 0, 1); STAGE_A(SA(0, 0), 0, t + 2);
;       BAR; WAIT_L(0); MMA(1, 0, At, B0); BAR; SCHED;
	v_mov_b32_e32 v52, v0
	v_mov_b32_e32 v53, v0
	v_mov_b32_e32 v54, v0
	v_mov_b32_e32 v55, v0
	v_mov_b32_e32 v56, v0
	v_mov_b32_e32 v57, v0
	v_mov_b32_e32 v58, v0
	v_mov_b32_e32 v59, v0
	v_mov_b32_e32 v60, v0
	v_mov_b32_e32 v61, v0
	v_mov_b32_e32 v62, v0
	v_mov_b32_e32 v63, v0
	v_mov_b32_e32 v64, v0
	v_mov_b32_e32 v65, v0
	v_mov_b32_e32 v66, v0
	v_mov_b32_e32 v67, v0
	v_mov_b32_e32 v68, v0
	v_mov_b32_e32 v69, v0
	v_mov_b32_e32 v70, v0
	v_mov_b32_e32 v71, v0
	v_mov_b32_e32 v72, v0
	v_mov_b32_e32 v73, v0
	v_mov_b32_e32 v74, v0
	v_mov_b32_e32 v75, v0
	v_mov_b32_e32 v76, v0
	v_mov_b32_e32 v77, v0
	v_mov_b32_e32 v78, v0
	v_mov_b32_e32 v79, v0
	v_mov_b32_e32 v80, v0
	v_mov_b32_e32 v81, v0
	v_mov_b32_e32 v82, v0
	v_mov_b32_e32 v83, v0
	v_mov_b32_e32 v84, v0
	v_mov_b32_e32 v85, v0
	v_mov_b32_e32 v86, v0
	v_mov_b32_e32 v87, v0
	v_mov_b32_e32 v88, v0
	v_mov_b32_e32 v89, v0
	v_mov_b32_e32 v90, v0
	v_mov_b32_e32 v91, v0
	v_mov_b32_e32 v92, v0
	v_mov_b32_e32 v93, v0
	v_mov_b32_e32 v94, v0
	v_mov_b32_e32 v95, v0
	v_mov_b32_e32 v96, v0
	v_mov_b32_e32 v97, v0
	v_mov_b32_e32 v98, v0
	v_mov_b32_e32 v99, v0
	v_mov_b32_e32 v100, v0
	v_mov_b32_e32 v101, v0
	v_mov_b32_e32 v102, v0
	v_mov_b32_e32 v103, v0
	v_mov_b32_e32 v104, v0
	v_mov_b32_e32 v105, v0
	v_mov_b32_e32 v106, v0
	v_mov_b32_e32 v107, v0
	v_mov_b32_e32 v108, v0
	v_mov_b32_e32 v109, v0
	v_mov_b32_e32 v110, v0
	v_mov_b32_e32 v111, v0
	v_mov_b32_e32 v112, v0
	v_mov_b32_e32 v113, v0
	v_mov_b32_e32 v114, v0
	v_mov_b32_e32 v115, v0
	v_mov_b32_e32 v116, v0
	v_mov_b32_e32 v117, v0
	v_mov_b32_e32 v118, v0
	v_mov_b32_e32 v119, v0
	v_mov_b32_e32 v120, v0
	v_mov_b32_e32 v121, v0
	v_mov_b32_e32 v122, v0
	v_mov_b32_e32 v123, v0
	v_mov_b32_e32 v124, v0
	v_mov_b32_e32 v125, v0
	v_mov_b32_e32 v126, v0
	v_mov_b32_e32 v127, v0
	s_barrier
	v_readfirstlane_b32 s3, v146
.LBB0_948:
	ds_read_b128 v[160:163], v156
	ds_read_b128 v[164:167], v156 offset:1024
	ds_read_b128 v[168:171], v156 offset:2048
	ds_read_b128 v[172:175], v156 offset:3072
	v_lshl_add_u64 v[222:223], v[134:135], 0, s[8:9]
	v_lshl_add_u64 v[158:159], v[222:223], 0, s[62:63]
	s_add_u32 m0, s3, 0xc000
	ds_read_b128 v[180:183], v144
	ds_read_b128 v[184:187], v144 offset:1024
	ds_read_b128 v[188:191], v143
	ds_read_b128 v[192:195], v143 offset:1024
	ds_read_b128 v[196:199], v142
	ds_read_b128 v[200:203], v142 offset:1024
	ds_read_b128 v[204:207], v141
	ds_read_b128 v[208:211], v141 offset:1024
	global_load_lds_dwordx4 v[158:159], off
	v_lshl_add_u64 v[224:225], v[136:137], 0, s[8:9]
	v_lshl_add_u64 v[212:213], v[224:225], 0, s[62:63]
	s_add_u32 m0, s3, 0xe000
	s_nop 0
	global_load_lds_dwordx4 v[212:213], off
	s_waitcnt lgkmcnt(8)
	s_barrier
	s_waitcnt lgkmcnt(0)
	s_setprio 1
	s_waitcnt lgkmcnt(0)
	v_mfma_f32_16x16x32_bf16 v[124:127], v[160:163], v[180:183], v[124:127]
	v_mfma_f32_16x16x32_bf16 v[120:123], v[168:171], v[180:183], v[120:123]
	v_mfma_f32_16x16x32_bf16 v[116:119], v[160:163], v[188:191], v[116:119]
	v_mfma_f32_16x16x32_bf16 v[112:115], v[168:171], v[188:191], v[112:115]
	v_mfma_f32_16x16x32_bf16 v[108:111], v[160:163], v[196:199], v[108:111]
	v_mfma_f32_16x16x32_bf16 v[104:107], v[168:171], v[196:199], v[104:107]
	v_mfma_f32_16x16x32_bf16 v[100:103], v[160:163], v[204:207], v[100:103]
	v_mfma_f32_16x16x32_bf16 v[96:99], v[168:171], v[204:207], v[96:99]
	v_mfma_f32_16x16x32_bf16 v[124:127], v[164:167], v[184:187], v[124:127]
	v_mfma_f32_16x16x32_bf16 v[120:123], v[172:175], v[184:187], v[120:123]
	v_mfma_f32_16x16x32_bf16 v[116:119], v[164:167], v[192:195], v[116:119]
	v_mfma_f32_16x16x32_bf16 v[112:115], v[172:175], v[192:195], v[112:115]
	v_mfma_f32_16x16x32_bf16 v[108:111], v[164:167], v[200:203], v[108:111]
	v_mfma_f32_16x16x32_bf16 v[104:107], v[172:175], v[200:203], v[104:107]
	v_mfma_f32_16x16x32_bf16 v[100:103], v[164:167], v[208:211], v[100:103]
	v_mfma_f32_16x16x32_bf16 v[96:99], v[172:175], v[208:211], v[96:99]
	s_setprio 0
	s_barrier
	v_lshl_add_u64 v[226:227], v[130:131], 0, s[8:9]
	v_lshl_add_u64 v[228:229], v[226:227], 0, s[64:65]
	s_add_u32 m0, s3, 0x10000
	ds_read_b128 v[212:215], v155
	ds_read_b128 v[216:219], v155 offset:1024
	ds_read_b128 v[234:237], v155 offset:2048
	ds_read_b128 v[238:241], v155 offset:3072
	global_load_lds_dwordx4 v[228:229], off
	v_lshl_add_u64 v[228:229], v[132:133], 0, s[8:9]
	v_lshl_add_u64 v[242:243], v[228:229], 0, s[64:65]
	s_add_u32 m0, s3, 0x12000
	s_nop 0
	global_load_lds_dwordx4 v[242:243], off
	s_barrier
	s_waitcnt lgkmcnt(0)
	s_setprio 1
	s_waitcnt lgkmcnt(0)
	v_mfma_f32_16x16x32_bf16 v[92:95], v[212:215], v[180:183], v[92:95]
	v_mfma_f32_16x16x32_bf16 v[88:91], v[234:237], v[180:183], v[88:91]
	v_mfma_f32_16x16x32_bf16 v[84:87], v[212:215], v[188:191], v[84:87]
	v_mfma_f32_16x16x32_bf16 v[80:83], v[234:237], v[188:191], v[80:83]
	v_mfma_f32_16x16x32_bf16 v[76:79], v[212:215], v[196:199], v[76:79]
	v_mfma_f32_16x16x32_bf16 v[72:75], v[234:237], v[196:199], v[72:75]
	v_mfma_f32_16x16x32_bf16 v[68:71], v[212:215], v[204:207], v[68:71]
	v_mfma_f32_16x16x32_bf16 v[64:67], v[234:237], v[204:207], v[64:67]
	v_mfma_f32_16x16x32_bf16 v[92:95], v[216:219], v[184:187], v[92:95]
	v_mfma_f32_16x16x32_bf16 v[88:91], v[238:241], v[184:187], v[88:91]
	v_mfma_f32_16x16x32_bf16 v[84:87], v[216:219], v[192:195], v[84:87]
	v_mfma_f32_16x16x32_bf16 v[80:83], v[238:241], v[192:195], v[80:83]
	v_mfma_f32_16x16x32_bf16 v[76:79], v[216:219], v[200:203], v[76:79]
	v_mfma_f32_16x16x32_bf16 v[72:75], v[238:241], v[200:203], v[72:75]
	v_mfma_f32_16x16x32_bf16 v[68:71], v[216:219], v[208:211], v[68:71]
	v_mfma_f32_16x16x32_bf16 v[64:67], v[238:241], v[208:211], v[64:67]
	s_setprio 0
	v_lshl_add_u64 v[242:243], v[222:223], 0, s[64:65]
	s_mov_b32 m0, s3
	s_barrier
; #define STAGE_A(P, half, kt) do { const char* _u = Ab + ((size_t)(half) * 128 * lda + (size_t)(kt) * BK) * 2; \
;     _Pragma("unroll") for (int _i = 0; _i < 2; ++_i) \
;       __builtin_amdgcn_global_load_lds((const unsigned*)(_u + offA[_i]), \
;         (__attribute__((address_space(3))) unsigned*)((__attribute__((address_space(3))) char*)(P) + tidg * 16 + _i * 8192), 16, 0, 0); } while (0)
; #define STAGE_B(P, half, kt) do { const char* _u = Bb + ((size_t)(half) * 128 * ldb + (size_t)(kt) * BK) * 2; \
;     _Pragma("unroll") for (int _i = 0; _i < 2; ++_i) \
;       __builtin_amdgcn_global_load_lds((const unsigned*)(_u + offB[_i]), \
;         (__attribute__((address_space(3))) unsigned*)((__attribute__((address_space(3))) char*)(P) + tidg * 16 + _i * 8192), 16, 0, 0); } while (0)
; #define LDA(dst, b, h) _Pragma("unroll") for (int m = 0; m < 4; ++m) _Pragma("unroll") for (int k = 0; k < 2; ++k) \
;     dst[m][k] = *reinterpret_cast<const bf16x8*>((const char*)SA(b, h) + lds_byte(wr * 64 + m * 16 + fr, k * 32 + fq * 8))
; #define LDB(dst, b, h) _Pragma("unroll") for (int n = 0; n < 2; ++n) _Pragma("unroll") for (int k = 0; k < 2; ++k) \
;     dst[n][k] = *reinterpret_cast<const bf16x8*>((const char*)SB(b, h) + lds_byte(wc * 32 + n * 16 + fr, k * 32 + fq * 8))
; #define WAIT_V(n) asm volatile("s_waitcnt vmcnt(" #n ")" ::: "memory")
; #define WAIT_L(n) asm volatile("s_waitcnt lgkmcnt(" #n ")" ::: "memory")
; #define BAR __builtin_amdgcn_s_barrier()
; #define SCHED __builtin_amdgcn_sched_barrier(0)
; template <bool PF = true, class Epi, class KRF = KRFull>
; __device__ __forceinline__ void gemm_phase(const u16* __restrict__ A, int lda, const u16* __restrict__ Bt, int ldb, int K, int nM, int nN,
;                                            lds_u16* shm, Epi epi, KRF krf = KRFull(), bool flip = false) {
;     ...
;       LDA(At, 0, 1); STAGE_A(SA(0, 0), 0, t + 2);
;       BAR; WAIT_L(0); MMA(1, 0, At, B0); BAR; SCHED;
;       STAGE_B(SB(0, 1), 1, t + 2);
;       WAIT_V(6); BAR; MMA(1, 1, At, B1); BAR;
;       LDB(B0, 1, 0); SCHED; LDA(At, 1, 0); STAGE_A(SA(0, 1), 1, t + 2);
;       WAIT_L(8); BAR; WAIT_L(0); MMA(0, 0, At, B0); BAR; SCHED;
;       LDB(B1, 1, 1); STAGE_B(SB(1, 0), 0, t + 3);
;       BAR; WAIT_L(0); MMA(0, 1, At, B1); BAR;
;       LDA(At, 1, 1); STAGE_A(SA(1, 0), 0, t + 3);
	ds_read_b128 v[180:183], v144 offset:16384
	ds_read_b128 v[184:187], v144 offset:17408
	ds_read_b128 v[188:191], v143 offset:16384
	ds_read_b128 v[192:195], v143 offset:17408
	ds_read_b128 v[196:199], v142 offset:16384
	ds_read_b128 v[200:203], v142 offset:17408
	ds_read_b128 v[204:207], v141 offset:16384
	ds_read_b128 v[208:211], v141 offset:17408
	global_load_lds_dwordx4 v[242:243], off
	v_lshl_add_u64 v[242:243], v[224:225], 0, s[64:65]
	s_add_u32 m0, s3, 0x2000
	s_nop 0
	global_load_lds_dwordx4 v[242:243], off
	s_barrier
	s_waitcnt lgkmcnt(0)
	s_setprio 1
	s_waitcnt lgkmcnt(0)
	v_mfma_f32_16x16x32_bf16 v[60:63], v[160:163], v[180:183], v[60:63]
	v_mfma_f32_16x16x32_bf16 v[56:59], v[168:171], v[180:183], v[56:59]
	v_mfma_f32_16x16x32_bf16 v[52:55], v[160:163], v[188:191], v[52:55]
	v_mfma_f32_16x16x32_bf16 v[48:51], v[168:171], v[188:191], v[48:51]
	v_mfma_f32_16x16x32_bf16 v[44:47], v[160:163], v[196:199], v[44:47]
	v_mfma_f32_16x16x32_bf16 v[40:43], v[168:171], v[196:199], v[40:43]
	v_mfma_f32_16x16x32_bf16 v[36:39], v[160:163], v[204:207], v[36:39]
	v_mfma_f32_16x16x32_bf16 v[32:35], v[168:171], v[204:207], v[32:35]
	v_mfma_f32_16x16x32_bf16 v[60:63], v[164:167], v[184:187], v[60:63]
	v_mfma_f32_16x16x32_bf16 v[56:59], v[172:175], v[184:187], v[56:59]
	v_mfma_f32_16x16x32_bf16 v[52:55], v[164:167], v[192:195], v[52:55]
	v_mfma_f32_16x16x32_bf16 v[48:51], v[172:175], v[192:195], v[48:51]
	v_mfma_f32_16x16x32_bf16 v[44:47], v[164:167], v[200:203], v[44:47]
	v_mfma_f32_16x16x32_bf16 v[40:43], v[172:175], v[200:203], v[40:43]
	v_mfma_f32_16x16x32_bf16 v[36:39], v[164:167], v[208:211], v[36:39]
	v_mfma_f32_16x16x32_bf16 v[32:35], v[172:175], v[208:211], v[32:35]
	s_setprio 0
	s_barrier
	v_lshl_add_u64 v[160:161], v[226:227], 0, s[66:67]
	s_add_u32 m0, s3, 0x14000
	s_nop 0
	global_load_lds_dwordx4 v[160:161], off
	v_lshl_add_u64 v[160:161], v[228:229], 0, s[66:67]
	s_add_u32 m0, s3, 0x16000
	s_nop 0
	global_load_lds_dwordx4 v[160:161], off
	s_waitcnt vmcnt(6)
	s_barrier
	s_setprio 1
	v_mfma_f32_16x16x32_bf16 v[28:31], v[212:215], v[180:183], v[28:31]
	v_mfma_f32_16x16x32_bf16 v[24:27], v[234:237], v[180:183], v[24:27]
	v_mfma_f32_16x16x32_bf16 v[20:23], v[212:215], v[188:191], v[20:23]
	v_mfma_f32_16x16x32_bf16 v[16:19], v[234:237], v[188:191], v[16:19]
	v_mfma_f32_16x16x32_bf16 v[12:15], v[212:215], v[196:199], v[12:15]
	v_mfma_f32_16x16x32_bf16 v[8:11], v[234:237], v[196:199], v[8:11]
	v_mfma_f32_16x16x32_bf16 v[4:7], v[212:215], v[204:207], v[4:7]
	v_mfma_f32_16x16x32_bf16 v[0:3], v[234:237], v[204:207], v[0:3]
	v_mfma_f32_16x16x32_bf16 v[28:31], v[216:219], v[184:187], v[28:31]
	v_mfma_f32_16x16x32_bf16 v[24:27], v[238:241], v[184:187], v[24:27]
	v_mfma_f32_16x16x32_bf16 v[20:23], v[216:219], v[192:195], v[20:23]
	v_mfma_f32_16x16x32_bf16 v[16:19], v[238:241], v[192:195], v[16:19]
	v_mfma_f32_16x16x32_bf16 v[12:15], v[216:219], v[200:203], v[12:15]
	v_mfma_f32_16x16x32_bf16 v[8:11], v[238:241], v[200:203], v[8:11]
	v_mfma_f32_16x16x32_bf16 v[4:7], v[216:219], v[208:211], v[4:7]
	v_mfma_f32_16x16x32_bf16 v[0:3], v[238:241], v[208:211], v[0:3]
	s_setprio 0
	s_barrier
	ds_read_b128 v[160:163], v147
	ds_read_b128 v[164:167], v147 offset:1024
	ds_read_b128 v[168:171], v147 offset:2048
	ds_read_b128 v[172:175], v147 offset:3072
	v_lshl_add_u64 v[212:213], v[222:223], 0, s[66:67]
	s_add_u32 m0, s3, 0x4000
	ds_read_b128 v[180:183], v144 offset:32768
	ds_read_b128 v[184:187], v144 offset:33792
	ds_read_b128 v[188:191], v143 offset:32768
	ds_read_b128 v[192:195], v143 offset:33792
	ds_read_b128 v[196:199], v142 offset:32768
	ds_read_b128 v[200:203], v142 offset:33792
	ds_read_b128 v[204:207], v141 offset:32768
	ds_read_b128 v[208:211], v141 offset:33792
	global_load_lds_dwordx4 v[212:213], off
	v_lshl_add_u64 v[212:213], v[224:225], 0, s[66:67]
	s_add_u32 m0, s3, 0x6000
	s_nop 0
	global_load_lds_dwordx4 v[212:213], off
	s_waitcnt lgkmcnt(8)
	s_barrier
	s_waitcnt lgkmcnt(0)
	s_setprio 1
	s_waitcnt lgkmcnt(0)
	v_mfma_f32_16x16x32_bf16 v[124:127], v[160:163], v[180:183], v[124:127]
	v_mfma_f32_16x16x32_bf16 v[120:123], v[168:171], v[180:183], v[120:123]
	v_mfma_f32_16x16x32_bf16 v[116:119], v[160:163], v[188:191], v[116:119]
	v_mfma_f32_16x16x32_bf16 v[112:115], v[168:171], v[188:191], v[112:115]
	v_mfma_f32_16x16x32_bf16 v[108:111], v[160:163], v[196:199], v[108:111]
	v_mfma_f32_16x16x32_bf16 v[104:107], v[168:171], v[196:199], v[104:107]
	v_mfma_f32_16x16x32_bf16 v[100:103], v[160:163], v[204:207], v[100:103]
	v_mfma_f32_16x16x32_bf16 v[96:99], v[168:171], v[204:207], v[96:99]
	v_mfma_f32_16x16x32_bf16 v[124:127], v[164:167], v[184:187], v[124:127]
	v_mfma_f32_16x16x32_bf16 v[120:123], v[172:175], v[184:187], v[120:123]
	v_mfma_f32_16x16x32_bf16 v[116:119], v[164:167], v[192:195], v[116:119]
	v_mfma_f32_16x16x32_bf16 v[112:115], v[172:175], v[192:195], v[112:115]
	v_mfma_f32_16x16x32_bf16 v[108:111], v[164:167], v[200:203], v[108:111]
	v_mfma_f32_16x16x32_bf16 v[104:107], v[172:175], v[200:203], v[104:107]
	v_mfma_f32_16x16x32_bf16 v[100:103], v[164:167], v[208:211], v[100:103]
	v_mfma_f32_16x16x32_bf16 v[96:99], v[172:175], v[208:211], v[96:99]
	s_setprio 0
	s_barrier
	v_lshl_add_u64 v[242:243], v[226:227], 0, s[68:69]
	s_add_u32 m0, s3, 0x18000
	ds_read_b128 v[212:215], v145
	ds_read_b128 v[216:219], v145 offset:1024
	ds_read_b128 v[234:237], v145 offset:2048
	ds_read_b128 v[238:241], v145 offset:3072
	global_load_lds_dwordx4 v[242:243], off
	v_lshl_add_u64 v[242:243], v[228:229], 0, s[68:69]
	s_add_u32 m0, s3, 0x1a000
	s_nop 0
	global_load_lds_dwordx4 v[242:243], off
	s_barrier
; #define STAGE_A(P, half, kt) do { const char* _u = Ab + ((size_t)(half) * 128 * lda + (size_t)(kt) * BK) * 2; \
;     _Pragma("unroll") for (int _i = 0; _i < 2; ++_i) \
;       __builtin_amdgcn_global_load_lds((const unsigned*)(_u + offA[_i]), \
;         (__attribute__((address_space(3))) unsigned*)((__attribute__((address_space(3))) char*)(P) + tidg * 16 + _i * 8192), 16, 0, 0); } while (0)
; #define STAGE_B(P, half, kt) do { const char* _u = Bb + ((size_t)(half) * 128 * ldb + (size_t)(kt) * BK) * 2; \
;     _Pragma("unroll") for (int _i = 0; _i < 2; ++_i) \
;       __builtin_amdgcn_global_load_lds((const unsigned*)(_u + offB[_i]), \
;         (__attribute__((address_space(3))) unsigned*)((__attribute__((address_space(3))) char*)(P) + tidg * 16 + _i * 8192), 16, 0, 0); } while (0)
; #define LDA(dst, b, h) _Pragma("unroll") for (int m = 0; m < 4; ++m) _Pragma("unroll") for (int k = 0; k < 2; ++k) \
;     dst[m][k] = *reinterpret_cast<const bf16x8*>((const char*)SA(b, h) + lds_byte(wr * 64 + m * 16 + fr, k * 32 + fq * 8))
; #define LDB(dst, b, h) _Pragma("unroll") for (int n = 0; n < 2; ++n) _Pragma("unroll") for (int k = 0; k < 2; ++k) \
;     dst[n][k] = *reinterpret_cast<const bf16x8*>((const char*)SB(b, h) + lds_byte(wc * 32 + n * 16 + fr, k * 32 + fq * 8))
; #define MMA(ai, bj, At_, Bt_) do { __builtin_amdgcn_s_setprio(1); \
;     _Pragma("unroll") for (int m = 0; m < 4; ++m) _Pragma("unroll") for (int n = 0; n < 2; ++n) _Pragma("unroll") for (int k = 0; k < 2; ++k) \
;       acc[ai][bj][m][n] = __builtin_amdgcn_mfma_f32_16x16x32_bf16(Bt_[n][k], At_[m][k], acc[ai][bj][m][n], 0, 0, 0); \
;     __builtin_amdgcn_s_setprio(0); } while (0)
; #define WAIT_V(n) asm volatile("s_waitcnt vmcnt(" #n ")" ::: "memory")
; #define WAIT_L(n) asm volatile("s_waitcnt lgkmcnt(" #n ")" ::: "memory")
; template <bool PF = true, class Epi, class KRF = KRFull>
; __device__ __forceinline__ void gemm_phase(const u16* __restrict__ A, int lda, const u16* __restrict__ Bt, int ldb, int K, int nM, int nN,
;                                            lds_u16* shm, Epi epi, KRF krf = KRFull(), bool flip = false) {
;     ...
;       LDA(At, 1, 1); STAGE_A(SA(1, 0), 0, t + 3);
;       BAR; WAIT_L(0); MMA(1, 0, At, B0); BAR; SCHED;
;       STAGE_B(SB(1, 1), 1, t + 3);
;       WAIT_V(6); BAR; MMA(1, 1, At, B1); BAR;
;     }
;     { LDB(B0, 0, 0); LDA(At, 0, 0); STAGE_A(SA(1, 1), 1, nt - 1);
	s_waitcnt lgkmcnt(0)
	s_setprio 1
	s_waitcnt lgkmcnt(0)
	v_mfma_f32_16x16x32_bf16 v[92:95], v[212:215], v[180:183], v[92:95]
	v_mfma_f32_16x16x32_bf16 v[88:91], v[234:237], v[180:183], v[88:91]
	v_mfma_f32_16x16x32_bf16 v[84:87], v[212:215], v[188:191], v[84:87]
	v_mfma_f32_16x16x32_bf16 v[80:83], v[234:237], v[188:191], v[80:83]
	v_mfma_f32_16x16x32_bf16 v[76:79], v[212:215], v[196:199], v[76:79]
	v_mfma_f32_16x16x32_bf16 v[72:75], v[234:237], v[196:199], v[72:75]
	v_mfma_f32_16x16x32_bf16 v[68:71], v[212:215], v[204:207], v[68:71]
	v_mfma_f32_16x16x32_bf16 v[64:67], v[234:237], v[204:207], v[64:67]
	v_mfma_f32_16x16x32_bf16 v[92:95], v[216:219], v[184:187], v[92:95]
	v_mfma_f32_16x16x32_bf16 v[88:91], v[238:241], v[184:187], v[88:91]
	v_mfma_f32_16x16x32_bf16 v[84:87], v[216:219], v[192:195], v[84:87]
	v_mfma_f32_16x16x32_bf16 v[80:83], v[238:241], v[192:195], v[80:83]
	v_mfma_f32_16x16x32_bf16 v[76:79], v[216:219], v[200:203], v[76:79]
	v_mfma_f32_16x16x32_bf16 v[72:75], v[238:241], v[200:203], v[72:75]
	v_mfma_f32_16x16x32_bf16 v[68:71], v[216:219], v[208:211], v[68:71]
	v_mfma_f32_16x16x32_bf16 v[64:67], v[238:241], v[208:211], v[64:67]
	s_setprio 0
	v_lshl_add_u64 v[222:223], v[222:223], 0, s[68:69]
	s_add_u32 m0, s3, 0x8000
	s_barrier
	ds_read_b128 v[180:183], v144 offset:49152
	ds_read_b128 v[184:187], v144 offset:50176
	ds_read_b128 v[188:191], v143 offset:49152
	ds_read_b128 v[192:195], v143 offset:50176
	ds_read_b128 v[196:199], v142 offset:49152
	ds_read_b128 v[200:203], v142 offset:50176
	ds_read_b128 v[204:207], v141 offset:49152
	ds_read_b128 v[208:211], v141 offset:50176
	global_load_lds_dwordx4 v[222:223], off
	v_lshl_add_u64 v[222:223], v[224:225], 0, s[68:69]
	s_add_u32 m0, s3, 0xa000
	s_nop 0
	global_load_lds_dwordx4 v[222:223], off
	s_barrier
	s_waitcnt lgkmcnt(0)
	s_setprio 1
	s_waitcnt lgkmcnt(0)
	v_mfma_f32_16x16x32_bf16 v[60:63], v[160:163], v[180:183], v[60:63]
	v_mfma_f32_16x16x32_bf16 v[56:59], v[168:171], v[180:183], v[56:59]
	v_mfma_f32_16x16x32_bf16 v[52:55], v[160:163], v[188:191], v[52:55]
	v_mfma_f32_16x16x32_bf16 v[48:51], v[168:171], v[188:191], v[48:51]
	v_mfma_f32_16x16x32_bf16 v[44:47], v[160:163], v[196:199], v[44:47]
	v_mfma_f32_16x16x32_bf16 v[40:43], v[168:171], v[196:199], v[40:43]
	v_mfma_f32_16x16x32_bf16 v[36:39], v[160:163], v[204:207], v[36:39]
	v_mfma_f32_16x16x32_bf16 v[32:35], v[168:171], v[204:207], v[32:35]
	v_mfma_f32_16x16x32_bf16 v[60:63], v[164:167], v[184:187], v[60:63]
	v_mfma_f32_16x16x32_bf16 v[56:59], v[172:175], v[184:187], v[56:59]
	v_mfma_f32_16x16x32_bf16 v[52:55], v[164:167], v[192:195], v[52:55]
	v_mfma_f32_16x16x32_bf16 v[48:51], v[172:175], v[192:195], v[48:51]
	v_mfma_f32_16x16x32_bf16 v[44:47], v[164:167], v[200:203], v[44:47]
	v_mfma_f32_16x16x32_bf16 v[40:43], v[172:175], v[200:203], v[40:43]
	v_mfma_f32_16x16x32_bf16 v[36:39], v[164:167], v[208:211], v[36:39]
	v_mfma_f32_16x16x32_bf16 v[32:35], v[172:175], v[208:211], v[32:35]
	s_setprio 0
	s_barrier
	v_lshl_add_u64 v[160:161], v[226:227], 0, s[70:71]
	s_add_u32 m0, s3, 0x1c000
	s_nop 0
	global_load_lds_dwordx4 v[160:161], off
	v_lshl_add_u64 v[160:161], v[228:229], 0, s[70:71]
	s_add_u32 m0, s3, 0x1e000
	s_nop 0
	global_load_lds_dwordx4 v[160:161], off
	s_waitcnt vmcnt(6)
	s_barrier
	s_setprio 1
	v_mfma_f32_16x16x32_bf16 v[28:31], v[212:215], v[180:183], v[28:31]
	v_mfma_f32_16x16x32_bf16 v[24:27], v[234:237], v[180:183], v[24:27]
	v_mfma_f32_16x16x32_bf16 v[20:23], v[212:215], v[188:191], v[20:23]
	v_mfma_f32_16x16x32_bf16 v[16:19], v[234:237], v[188:191], v[16:19]
	v_mfma_f32_16x16x32_bf16 v[12:15], v[212:215], v[196:199], v[12:15]
	v_mfma_f32_16x16x32_bf16 v[8:11], v[234:237], v[196:199], v[8:11]
	v_mfma_f32_16x16x32_bf16 v[4:7], v[212:215], v[204:207], v[4:7]
	v_mfma_f32_16x16x32_bf16 v[0:3], v[234:237], v[204:207], v[0:3]
	v_mfma_f32_16x16x32_bf16 v[28:31], v[216:219], v[184:187], v[28:31]
	v_mfma_f32_16x16x32_bf16 v[24:27], v[238:241], v[184:187], v[24:27]
	v_mfma_f32_16x16x32_bf16 v[20:23], v[216:219], v[192:195], v[20:23]
	v_mfma_f32_16x16x32_bf16 v[16:19], v[238:241], v[192:195], v[16:19]
	v_mfma_f32_16x16x32_bf16 v[12:15], v[216:219], v[200:203], v[12:15]
	v_mfma_f32_16x16x32_bf16 v[8:11], v[238:241], v[200:203], v[8:11]
	v_mfma_f32_16x16x32_bf16 v[4:7], v[216:219], v[208:211], v[4:7]
	v_mfma_f32_16x16x32_bf16 v[0:3], v[238:241], v[208:211], v[0:3]
	s_setprio 0
	s_add_i32 s2, s2, 2
	s_add_u32 s8, s8, 0x100
	s_addc_u32 s9, s9, 0
	s_cmp_gt_u32 s2, 27
	s_barrier
	s_cbranch_scc0 .LBB0_948
	v_add_u32_e32 v157, 0xc000, v146
	v_add_u32_e32 v158, 0xe000, v146
	v_add_u32_e32 v159, 0x6000, v146
	s_add_u32 s2, s6, 0x80f80
	s_addc_u32 s3, s7, 0
	v_readfirstlane_b32 s6, v157
	v_lshl_add_u64 v[152:153], s[2:3], 0, v[178:179]
	s_mov_b32 m0, s6
	v_lshl_add_u64 v[128:129], s[2:3], 0, v[128:129]
	v_readfirstlane_b32 s2, v158
	ds_read_b128 v[130:133], v156
	ds_read_b128 v[134:137], v156 offset:1024
	ds_read_b128 v[148:151], v156 offset:2048
	ds_read_b128 v[160:163], v156 offset:3072
	ds_read_b128 v[164:167], v144
	ds_read_b128 v[168:171], v144 offset:1024
	ds_read_b128 v[172:175], v143
	ds_read_b128 v[180:183], v143 offset:1024
	ds_read_b128 v[184:187], v142
	ds_read_b128 v[188:191], v142 offset:1024
	ds_read_b128 v[192:195], v141
	ds_read_b128 v[196:199], v141 offset:1024
	global_load_lds_dwordx4 v[152:153], off
	s_mov_b32 m0, s2
	s_nop 0
	global_load_lds_dwordx4 v[128:129], off
	s_barrier
; #define LDA(dst, b, h) _Pragma("unroll") for (int m = 0; m < 4; ++m) _Pragma("unroll") for (int k = 0; k < 2; ++k) \
;     dst[m][k] = *reinterpret_cast<const bf16x8*>((const char*)SA(b, h) + lds_byte(wr * 64 + m * 16 + fr, k * 32 + fq * 8))
; #define LDB(dst, b, h) _Pragma("unroll") for (int n = 0; n < 2; ++n) _Pragma("unroll") for (int k = 0; k < 2; ++k) \
;     dst[n][k] = *reinterpret_cast<const bf16x8*>((const char*)SB(b, h) + lds_byte(wc * 32 + n * 16 + fr, k * 32 + fq * 8))
; #define MMA(ai, bj, At_, Bt_) do { __builtin_amdgcn_s_setprio(1); \
;     _Pragma("unroll") for (int m = 0; m < 4; ++m) _Pragma("unroll") for (int n = 0; n < 2; ++n) _Pragma("unroll") for (int k = 0; k < 2; ++k) \
;       acc[ai][bj][m][n] = __builtin_amdgcn_mfma_f32_16x16x32_bf16(Bt_[n][k], At_[m][k], acc[ai][bj][m][n], 0, 0, 0); \
;     __builtin_amdgcn_s_setprio(0); } while (0)
; #define WAIT_V(n) asm volatile("s_waitcnt vmcnt(" #n ")" ::: "memory")
; #define WAIT_L(n) asm volatile("s_waitcnt lgkmcnt(" #n ")" ::: "memory")
; #define BAR __builtin_amdgcn_s_barrier()
; template <bool PF = true, class Epi, class KRF = KRFull>
; __device__ __forceinline__ void gemm_phase(const u16* __restrict__ A, int lda, const u16* __restrict__ Bt, int ldb, int K, int nM, int nN,
;                                            lds_u16* shm, Epi epi, KRF krf = KRFull(), bool flip = false) {
;     ...
;       BAR; WAIT_L(0); MMA(0, 0, At, B0); BAR;
;       LDB(B1, 0, 1); BAR; WAIT_L(0); MMA(0, 1, At, B1); BAR;
;       LDA(At, 0, 1); WAIT_V(4); BAR; WAIT_L(0); MMA(1, 0, At, B0); MMA(1, 1, At, B1); BAR; }
	s_waitcnt lgkmcnt(0)
	s_setprio 1
	s_waitcnt lgkmcnt(0)
	v_mfma_f32_16x16x32_bf16 v[124:127], v[130:133], v[164:167], v[124:127]
	v_mfma_f32_16x16x32_bf16 v[120:123], v[148:151], v[164:167], v[120:123]
	v_mfma_f32_16x16x32_bf16 v[116:119], v[130:133], v[172:175], v[116:119]
	v_mfma_f32_16x16x32_bf16 v[112:115], v[148:151], v[172:175], v[112:115]
	v_mfma_f32_16x16x32_bf16 v[108:111], v[130:133], v[184:187], v[108:111]
	v_mfma_f32_16x16x32_bf16 v[104:107], v[148:151], v[184:187], v[104:107]
	v_mfma_f32_16x16x32_bf16 v[100:103], v[130:133], v[192:195], v[100:103]
	v_mfma_f32_16x16x32_bf16 v[96:99], v[148:151], v[192:195], v[96:99]
	v_mfma_f32_16x16x32_bf16 v[124:127], v[134:137], v[168:171], v[124:127]
	v_mfma_f32_16x16x32_bf16 v[120:123], v[160:163], v[168:171], v[120:123]
	v_mfma_f32_16x16x32_bf16 v[116:119], v[134:137], v[180:183], v[116:119]
	v_mfma_f32_16x16x32_bf16 v[112:115], v[160:163], v[180:183], v[112:115]
	v_mfma_f32_16x16x32_bf16 v[108:111], v[134:137], v[188:191], v[108:111]
	v_mfma_f32_16x16x32_bf16 v[104:107], v[160:163], v[188:191], v[104:107]
	v_mfma_f32_16x16x32_bf16 v[100:103], v[134:137], v[196:199], v[100:103]
	v_mfma_f32_16x16x32_bf16 v[96:99], v[160:163], v[196:199], v[96:99]
	s_setprio 0
	s_barrier
	ds_read_b128 v[156:159], v155
	ds_read_b128 v[200:203], v155 offset:1024
	ds_read_b128 v[204:207], v155 offset:2048
	ds_read_b128 v[152:155], v155 offset:3072
	s_barrier
	s_waitcnt lgkmcnt(0)
	s_setprio 1
	s_waitcnt lgkmcnt(0)
	v_mfma_f32_16x16x32_bf16 v[76:79], v[156:159], v[184:187], v[76:79]
	v_mfma_f32_16x16x32_bf16 v[72:75], v[204:207], v[184:187], v[72:75]
	v_mfma_f32_16x16x32_bf16 v[68:71], v[156:159], v[192:195], v[68:71]
	v_mfma_f32_16x16x32_bf16 v[64:67], v[204:207], v[192:195], v[64:67]
	v_mfma_f32_16x16x32_bf16 v[92:95], v[156:159], v[164:167], v[92:95]
	v_mfma_f32_16x16x32_bf16 v[88:91], v[204:207], v[164:167], v[88:91]
	v_mfma_f32_16x16x32_bf16 v[84:87], v[156:159], v[172:175], v[84:87]
	v_mfma_f32_16x16x32_bf16 v[80:83], v[204:207], v[172:175], v[80:83]
	v_mfma_f32_16x16x32_bf16 v[76:79], v[200:203], v[188:191], v[76:79]
	v_mfma_f32_16x16x32_bf16 v[72:75], v[152:155], v[188:191], v[72:75]
	v_mfma_f32_16x16x32_bf16 v[68:71], v[200:203], v[196:199], v[68:71]
	v_mfma_f32_16x16x32_bf16 v[64:67], v[152:155], v[196:199], v[64:67]
	v_mfma_f32_16x16x32_bf16 v[208:211], v[200:203], v[168:171], v[92:95]
	v_mfma_f32_16x16x32_bf16 v[164:167], v[152:155], v[168:171], v[88:91]
	v_mfma_f32_16x16x32_bf16 v[168:171], v[200:203], v[180:183], v[84:87]
	v_mfma_f32_16x16x32_bf16 v[172:175], v[152:155], v[180:183], v[80:83]
	s_setprio 0
	s_barrier
	s_nop 0
	ds_read_b128 v[80:83], v144 offset:16384
	ds_read_b128 v[84:87], v144 offset:17408
	ds_read_b128 v[88:91], v143 offset:16384
	ds_read_b128 v[92:95], v143 offset:17408
	ds_read_b128 v[180:183], v142 offset:16384
	ds_read_b128 v[184:187], v142 offset:17408
	ds_read_b128 v[188:191], v141 offset:16384
	ds_read_b128 v[192:195], v141 offset:17408
	s_waitcnt vmcnt(4)
	s_barrier
	s_waitcnt lgkmcnt(0)
	s_setprio 1
	s_waitcnt lgkmcnt(0)
	v_mfma_f32_16x16x32_bf16 v[44:47], v[130:133], v[180:183], v[44:47]
	v_mfma_f32_16x16x32_bf16 v[40:43], v[148:151], v[180:183], v[40:43]
	v_mfma_f32_16x16x32_bf16 v[36:39], v[130:133], v[188:191], v[36:39]
	v_mfma_f32_16x16x32_bf16 v[32:35], v[148:151], v[188:191], v[32:35]
	v_mfma_f32_16x16x32_bf16 v[60:63], v[130:133], v[80:83], v[60:63]
	v_mfma_f32_16x16x32_bf16 v[56:59], v[148:151], v[80:83], v[56:59]
	v_mfma_f32_16x16x32_bf16 v[52:55], v[130:133], v[88:91], v[52:55]
	v_mfma_f32_16x16x32_bf16 v[48:51], v[148:151], v[88:91], v[48:51]
	v_mfma_f32_16x16x32_bf16 v[44:47], v[134:137], v[184:187], v[44:47]
	v_mfma_f32_16x16x32_bf16 v[40:43], v[160:163], v[184:187], v[40:43]
	v_mfma_f32_16x16x32_bf16 v[36:39], v[134:137], v[192:195], v[36:39]
	v_mfma_f32_16x16x32_bf16 v[32:35], v[160:163], v[192:195], v[32:35]
	v_mfma_f32_16x16x32_bf16 v[196:199], v[134:137], v[84:87], v[60:63]
	v_mfma_f32_16x16x32_bf16 v[212:215], v[160:163], v[84:87], v[56:59]
	v_mfma_f32_16x16x32_bf16 v[216:219], v[134:137], v[92:95], v[52:55]
	v_mfma_f32_16x16x32_bf16 v[238:241], v[160:163], v[92:95], v[48:51]
	s_setprio 0
	s_setprio 1
	v_mfma_f32_16x16x32_bf16 v[0:3], v[204:207], v[188:191], v[0:3]
	v_mfma_f32_16x16x32_bf16 v[28:31], v[156:159], v[80:83], v[28:31]
	v_mfma_f32_16x16x32_bf16 v[24:27], v[204:207], v[80:83], v[24:27]
	v_mfma_f32_16x16x32_bf16 v[20:23], v[156:159], v[88:91], v[20:23]
	v_mfma_f32_16x16x32_bf16 v[16:19], v[204:207], v[88:91], v[16:19]
	v_mfma_f32_16x16x32_bf16 v[12:15], v[156:159], v[180:183], v[12:15]
	v_mfma_f32_16x16x32_bf16 v[8:11], v[204:207], v[180:183], v[8:11]
	v_mfma_f32_16x16x32_bf16 v[4:7], v[156:159], v[188:191], v[4:7]
	v_mfma_f32_16x16x32_bf16 v[0:3], v[152:155], v[192:195], v[0:3]
	v_mfma_f32_16x16x32_bf16 v[128:131], v[200:203], v[84:87], v[28:31]
	v_mfma_f32_16x16x32_bf16 v[132:135], v[152:155], v[84:87], v[24:27]
	v_mfma_f32_16x16x32_bf16 v[148:151], v[200:203], v[92:95], v[20:23]
	v_mfma_f32_16x16x32_bf16 v[160:163], v[152:155], v[92:95], v[16:19]
	v_mfma_f32_16x16x32_bf16 v[242:245], v[200:203], v[184:187], v[12:15]
	v_mfma_f32_16x16x32_bf16 v[180:183], v[152:155], v[184:187], v[8:11]
	v_mfma_f32_16x16x32_bf16 v[156:159], v[200:203], v[192:195], v[4:7]
	s_setprio 0
	s_barrier
; #define LDA(dst, b, h) _Pragma("unroll") for (int m = 0; m < 4; ++m) _Pragma("unroll") for (int k = 0; k < 2; ++k) \
;     dst[m][k] = *reinterpret_cast<const bf16x8*>((const char*)SA(b, h) + lds_byte(wr * 64 + m * 16 + fr, k * 32 + fq * 8))
; #define LDB(dst, b, h) _Pragma("unroll") for (int n = 0; n < 2; ++n) _Pragma("unroll") for (int k = 0; k < 2; ++k) \
;     dst[n][k] = *reinterpret_cast<const bf16x8*>((const char*)SB(b, h) + lds_byte(wc * 32 + n * 16 + fr, k * 32 + fq * 8))
; #define MMA(ai, bj, At_, Bt_) do { __builtin_amdgcn_s_setprio(1); \
;     _Pragma("unroll") for (int m = 0; m < 4; ++m) _Pragma("unroll") for (int n = 0; n < 2; ++n) _Pragma("unroll") for (int k = 0; k < 2; ++k) \
;       acc[ai][bj][m][n] = __builtin_amdgcn_mfma_f32_16x16x32_bf16(Bt_[n][k], At_[m][k], acc[ai][bj][m][n], 0, 0, 0); \
;     __builtin_amdgcn_s_setprio(0); } while (0)
; #define WAIT_V(n) asm volatile("s_waitcnt vmcnt(" #n ")" ::: "memory")
; #define WAIT_L(n) asm volatile("s_waitcnt lgkmcnt(" #n ")" ::: "memory")
; #define BAR __builtin_amdgcn_s_barrier()
; template <bool PF = true, class Epi, class KRF = KRFull>
; __device__ __forceinline__ void gemm_phase(const u16* __restrict__ A, int lda, const u16* __restrict__ Bt, int ldb, int K, int nM, int nN,
;                                            lds_u16* shm, Epi epi, KRF krf = KRFull(), bool flip = false) {
;     ...
;     { LDB(B0, 1, 0); LDA(At, 1, 0); WAIT_V(2); BAR; WAIT_L(0); MMA(0, 0, At, B0); BAR;
;       LDB(B1, 1, 1); WAIT_V(0); BAR; WAIT_L(0); MMA(0, 1, At, B1); BAR;
;       LDA(At, 1, 1); BAR; WAIT_L(0); MMA(1, 0, At, B0); MMA(1, 1, At, B1); BAR; }
;     if (wr == 0) BAR;
	s_nop 0
	ds_read_b128 v[4:7], v147
	ds_read_b128 v[8:11], v147 offset:1024
	ds_read_b128 v[12:15], v147 offset:2048
	ds_read_b128 v[152:155], v147 offset:3072
	ds_read_b128 v[16:19], v144 offset:32768
	ds_read_b128 v[20:23], v144 offset:33792
	ds_read_b128 v[24:27], v143 offset:32768
	ds_read_b128 v[48:51], v143 offset:33792
	ds_read_b128 v[184:187], v142 offset:32768
	ds_read_b128 v[188:191], v142 offset:33792
	ds_read_b128 v[192:195], v141 offset:32768
	ds_read_b128 v[200:203], v141 offset:33792
	s_waitcnt vmcnt(2)
	s_barrier
	s_waitcnt lgkmcnt(0)
	s_setprio 1
	s_waitcnt lgkmcnt(0)
	v_mfma_f32_16x16x32_bf16 v[28:31], v[4:7], v[16:19], v[124:127]
	v_mfma_f32_16x16x32_bf16 v[124:127], v[8:11], v[20:23], v[28:31]
	v_mfma_f32_16x16x32_bf16 v[28:31], v[12:15], v[16:19], v[120:123]
	v_mfma_f32_16x16x32_bf16 v[92:95], v[152:155], v[20:23], v[28:31]
	v_mfma_f32_16x16x32_bf16 v[28:31], v[4:7], v[24:27], v[116:119]
	v_mfma_f32_16x16x32_bf16 v[120:123], v[8:11], v[48:51], v[28:31]
	v_mfma_f32_16x16x32_bf16 v[28:31], v[12:15], v[24:27], v[112:115]
	v_mfma_f32_16x16x32_bf16 v[88:91], v[152:155], v[48:51], v[28:31]
	v_mfma_f32_16x16x32_bf16 v[28:31], v[4:7], v[184:187], v[108:111]
	v_mfma_f32_16x16x32_bf16 v[116:119], v[8:11], v[188:191], v[28:31]
	v_mfma_f32_16x16x32_bf16 v[28:31], v[12:15], v[184:187], v[104:107]
	v_mfma_f32_16x16x32_bf16 v[84:87], v[152:155], v[188:191], v[28:31]
	v_mfma_f32_16x16x32_bf16 v[28:31], v[4:7], v[192:195], v[100:103]
	v_mfma_f32_16x16x32_bf16 v[112:115], v[8:11], v[200:203], v[28:31]
	v_mfma_f32_16x16x32_bf16 v[28:31], v[12:15], v[192:195], v[96:99]
	v_mfma_f32_16x16x32_bf16 v[80:83], v[152:155], v[200:203], v[28:31]
	s_setprio 0
	s_barrier
	ds_read_b128 v[204:207], v145
	ds_read_b128 v[246:249], v145 offset:1024
	ds_read_b128 v[250:253], v145 offset:2048
	ds_read_b128 v[234:237], v145 offset:3072
	s_waitcnt vmcnt(0)
	s_barrier
	s_waitcnt lgkmcnt(0)
	s_setprio 1
	s_waitcnt lgkmcnt(0)
	v_mfma_f32_16x16x32_bf16 v[28:31], v[204:207], v[16:19], v[208:211]
	v_mfma_f32_16x16x32_bf16 v[16:19], v[250:253], v[16:19], v[164:167]
	v_mfma_f32_16x16x32_bf16 v[60:63], v[246:249], v[20:23], v[28:31]
	v_mfma_f32_16x16x32_bf16 v[28:31], v[234:237], v[20:23], v[16:19]
	v_mfma_f32_16x16x32_bf16 v[16:19], v[204:207], v[24:27], v[168:171]
	v_mfma_f32_16x16x32_bf16 v[56:59], v[246:249], v[48:51], v[16:19]
	v_mfma_f32_16x16x32_bf16 v[16:19], v[250:253], v[24:27], v[172:175]
	v_mfma_f32_16x16x32_bf16 v[24:27], v[234:237], v[48:51], v[16:19]
	v_mfma_f32_16x16x32_bf16 v[16:19], v[204:207], v[184:187], v[76:79]
	v_mfma_f32_16x16x32_bf16 v[52:55], v[246:249], v[188:191], v[16:19]
	v_mfma_f32_16x16x32_bf16 v[16:19], v[250:253], v[184:187], v[72:75]
	v_mfma_f32_16x16x32_bf16 v[20:23], v[234:237], v[188:191], v[16:19]
	v_mfma_f32_16x16x32_bf16 v[16:19], v[204:207], v[192:195], v[68:71]
	v_mfma_f32_16x16x32_bf16 v[48:51], v[246:249], v[200:203], v[16:19]
	v_mfma_f32_16x16x32_bf16 v[16:19], v[250:253], v[192:195], v[64:67]
	v_mfma_f32_16x16x32_bf16 v[16:19], v[234:237], v[200:203], v[16:19]
	s_setprio 0
	s_barrier
	ds_read_b128 v[164:167], v144 offset:49152
	ds_read_b128 v[144:147], v144 offset:50176
	ds_read_b128 v[168:171], v143 offset:49152
	ds_read_b128 v[172:175], v143 offset:50176
	ds_read_b128 v[184:187], v142 offset:49152
	ds_read_b128 v[188:191], v142 offset:50176
	ds_read_b128 v[192:195], v141 offset:49152
	ds_read_b128 v[200:203], v141 offset:50176
	s_barrier
	s_waitcnt lgkmcnt(0)
	s_setprio 1
	s_waitcnt lgkmcnt(0)
	v_mfma_f32_16x16x32_bf16 v[64:67], v[4:7], v[164:167], v[196:199]
	v_mfma_f32_16x16x32_bf16 v[108:111], v[8:11], v[144:147], v[64:67]
	v_mfma_f32_16x16x32_bf16 v[64:67], v[12:15], v[164:167], v[212:215]
	v_mfma_f32_16x16x32_bf16 v[76:79], v[152:155], v[144:147], v[64:67]
	v_mfma_f32_16x16x32_bf16 v[64:67], v[4:7], v[168:171], v[216:219]
	v_mfma_f32_16x16x32_bf16 v[44:47], v[4:7], v[184:187], v[44:47]
	v_mfma_f32_16x16x32_bf16 v[4:7], v[4:7], v[192:195], v[36:39]
	v_mfma_f32_16x16x32_bf16 v[104:107], v[8:11], v[172:175], v[64:67]
	v_mfma_f32_16x16x32_bf16 v[64:67], v[12:15], v[168:171], v[238:241]
	v_mfma_f32_16x16x32_bf16 v[40:43], v[12:15], v[184:187], v[40:43]
	v_mfma_f32_16x16x32_bf16 v[96:99], v[8:11], v[200:203], v[4:7]
	v_mfma_f32_16x16x32_bf16 v[4:7], v[12:15], v[192:195], v[32:35]
	v_mfma_f32_16x16x32_bf16 v[72:75], v[152:155], v[172:175], v[64:67]
	v_mfma_f32_16x16x32_bf16 v[100:103], v[8:11], v[188:191], v[44:47]
	v_mfma_f32_16x16x32_bf16 v[68:71], v[152:155], v[188:191], v[40:43]
	v_mfma_f32_16x16x32_bf16 v[64:67], v[152:155], v[200:203], v[4:7]
	s_setprio 0
	s_setprio 1
	v_mfma_f32_16x16x32_bf16 v[4:7], v[204:207], v[164:167], v[128:131]
	v_mfma_f32_16x16x32_bf16 v[44:47], v[246:249], v[144:147], v[4:7]
	v_mfma_f32_16x16x32_bf16 v[4:7], v[250:253], v[164:167], v[132:135]
	v_mfma_f32_16x16x32_bf16 v[12:15], v[234:237], v[144:147], v[4:7]
	v_mfma_f32_16x16x32_bf16 v[4:7], v[204:207], v[168:171], v[148:151]
	v_mfma_f32_16x16x32_bf16 v[40:43], v[246:249], v[172:175], v[4:7]
	v_mfma_f32_16x16x32_bf16 v[4:7], v[250:253], v[168:171], v[160:163]
	v_mfma_f32_16x16x32_bf16 v[8:11], v[234:237], v[172:175], v[4:7]
	v_mfma_f32_16x16x32_bf16 v[4:7], v[204:207], v[184:187], v[242:245]
	v_mfma_f32_16x16x32_bf16 v[36:39], v[246:249], v[188:191], v[4:7]
	v_mfma_f32_16x16x32_bf16 v[4:7], v[250:253], v[184:187], v[180:183]
	v_mfma_f32_16x16x32_bf16 v[32:35], v[204:207], v[192:195], v[156:159]
	v_mfma_f32_16x16x32_bf16 v[0:3], v[250:253], v[192:195], v[0:3]
	v_mfma_f32_16x16x32_bf16 v[4:7], v[234:237], v[188:191], v[4:7]
	v_mfma_f32_16x16x32_bf16 v[32:35], v[246:249], v[200:203], v[32:35]
	v_mfma_f32_16x16x32_bf16 v[0:3], v[234:237], v[200:203], v[0:3]
	s_setprio 0
	v_cmp_gt_u32_e32 vcc, s95, v138
	s_barrier
	s_and_saveexec_b64 s[6:7], vcc
	s_cbranch_execz .LBB0_951
	s_barrier

; #define STAGE_A(P, half, kt) do { const char* _u = Ab + ((size_t)(half) * 128 * lda + (size_t)(kt) * BK) * 2; \
;     _Pragma("unroll") for (int _i = 0; _i < 2; ++_i) \
;       __builtin_amdgcn_global_load_lds((const unsigned*)(_u + offA[_i]), \
;         (__attribute__((address_space(3))) unsigned*)((__attribute__((address_space(3))) char*)(P) + tidg * 16 + _i * 8192), 16, 0, 0); } while (0)
; #define STAGE_B(P, half, kt) do { const char* _u = Bb + ((size_t)(half) * 128 * ldb + (size_t)(kt) * BK) * 2; \
;     _Pragma("unroll") for (int _i = 0; _i < 2; ++_i) \
;       __builtin_amdgcn_global_load_lds((const unsigned*)(_u + offB[_i]), \
;         (__attribute__((address_space(3))) unsigned*)((__attribute__((address_space(3))) char*)(P) + tidg * 16 + _i * 8192), 16, 0, 0); } while (0)
; #define WAIT_V(n) asm volatile("s_waitcnt vmcnt(" #n ")" ::: "memory")
; #define BAR __builtin_amdgcn_s_barrier()
; #define G_THREAD() do { asm volatile("" : "+v"(tidg)); wid = tidg >> 6; lane = tidg & 63; wr = wid >> 2; wc = wid & 3; fr = lane & 15; fq = lane >> 4; \
;     _Pragma("unroll") for (int _i = 0; _i < 2; ++_i) { int _r, _c; stage_rc(tidg * 16 + _i * 8192, _r, _c); offA[_i] = (unsigned)(_r * lda + _c) * 2u; offB[_i] = (unsigned)(_r * ldb + _c) * 2u; } } while (0)
; template <bool PF = true, class Epi, class KRF = KRFull>
; __device__ __forceinline__ void gemm_phase(const u16* __restrict__ A, int lda, const u16* __restrict__ Bt, int ldb, int K, int nM, int nN,
;                                            lds_u16* shm, Epi epi, KRF krf = KRFull(), bool flip = false) {
;     ...
;     G_THREAD();
;     nt = nt_next;
;     f32x4 acc[2][2][4][2] = {};
;     bf16x8 At[4][2], B0[2][2], B1[2][2];
;     if (wr == 1) BAR;
;     WAIT_V(4); BAR;
;     STAGE_B(SB(1, 0), 0, 1); STAGE_A(SA(1, 0), 0, 1); STAGE_B(SB(1, 1), 1, 1);
;     WAIT_V(6); BAR;
.LBB0_1635:
	s_or_b64 exec, exec, s[10:11]
	v_bfe_i32 v2, v142, 27, 1
	v_lshlrev_b32_e32 v146, 4, v142
	v_lshrrev_b32_e32 v2, 22, v2
	v_add_u32_e32 v2, v146, v2
	v_and_b32_e32 v2, 0xfffffc00, v2
	v_sub_u32_e32 v2, v146, v2
	v_lshrrev_b32_e32 v3, 4, v2
	v_bitop3_b32 v2, v3, v2, 32 bitop3:0x6c
	v_ashrrev_i32_e32 v5, 31, v2
	v_ashrrev_i32_e32 v1, 31, v142
	v_lshrrev_b32_e32 v5, 26, v5
	v_lshrrev_b32_e32 v1, 26, v1
	v_add_u32_e32 v5, v2, v5
	v_add_u32_e32 v1, v142, v1
	v_ashrrev_i32_e32 v6, 6, v5
	v_and_b32_e32 v5, 0xc0, v5
	v_ashrrev_i32_e32 v4, 6, v1
	v_sub_u32_e32 v2, v2, v5
	v_lshlrev_b32_e32 v3, 3, v4
	v_lshlrev_b32_e32 v7, 5, v4
	v_ashrrev_i16_sdwa v2, v232, sext(v2) dst_sel:DWORD dst_unused:UNUSED_PAD src0_sel:DWORD src1_sel:BYTE_0
	v_and_b32_e32 v3, 0xffff0, v3
	v_and_b32_e32 v7, 32, v7
	v_bfe_i32 v5, v2, 0, 16
	v_add_u32_e32 v2, v7, v5
	v_add_lshl_u32 v3, v6, v3, 12
	v_add_u32_e32 v148, 0x2000, v146
	v_lshl_add_u32 v178, v2, 1, v3
	v_ashrrev_i32_e32 v2, 31, v148
	v_lshrrev_b32_e32 v2, 22, v2
	v_add_u32_e32 v2, v148, v2
	v_ashrrev_i32_e32 v7, 10, v2
	v_mul_i32_i24_e32 v2, 0x400, v7
	v_sub_u32_e32 v2, v148, v2
	v_lshrrev_b32_e32 v3, 4, v2
	v_bitop3_b32 v2, v3, v2, 32 bitop3:0x6c
	v_ashrrev_i32_e32 v8, 31, v2
	v_lshrrev_b32_e32 v8, 26, v8
	v_add_u32_e32 v8, v2, v8
	v_ashrrev_i32_e32 v9, 6, v8
	v_and_b32_e32 v8, 0xc0, v8
	v_sub_u32_e32 v2, v2, v8
	v_lshlrev_b32_e32 v3, 3, v7
	v_lshlrev_b32_e32 v10, 5, v7
	v_ashrrev_i16_sdwa v2, v232, sext(v2) dst_sel:DWORD dst_unused:UNUSED_PAD src0_sel:DWORD src1_sel:BYTE_0
	v_and_b32_e32 v3, 0xffff0, v3
	v_and_b32_e32 v10, 32, v10
	v_bfe_i32 v8, v2, 0, 16
	v_add_u32_e32 v2, v10, v8
	v_add_lshl_u32 v3, v9, v3, 12
	v_add_u32_e32 v149, 0x18000, v146
	v_lshl_add_u32 v128, v2, 1, v3
	v_lshl_add_u64 v[2:3], s[8:9], 0, v[178:179]
	v_readfirstlane_b32 s2, v149
	v_lshl_add_u64 v[2:3], v[2:3], 0, s[60:61]
	s_mov_b32 m0, s2
	v_mov_b32_e32 v129, v179
	v_add_u32_e32 v150, 0x1a000, v146
	s_waitcnt vmcnt(4)
	s_barrier
	global_load_lds_dwordx4 v[2:3], off
	v_lshl_add_u64 v[2:3], s[8:9], 0, v[128:129]
	v_readfirstlane_b32 s2, v150
	v_lshl_add_u64 v[2:3], v[2:3], 0, s[60:61]
	s_mov_b32 m0, s2
	v_add_u32_e32 v151, 0x8000, v146
	global_load_lds_dwordx4 v[2:3], off
	v_lshl_add_u64 v[2:3], s[6:7], 0, v[178:179]
	v_readfirstlane_b32 s2, v151
	v_lshl_add_u64 v[2:3], v[2:3], 0, s[60:61]
	s_mov_b32 m0, s2
	v_add_u32_e32 v152, 0xa000, v146
	global_load_lds_dwordx4 v[2:3], off
	v_lshl_add_u64 v[2:3], s[6:7], 0, v[128:129]
	v_readfirstlane_b32 s2, v152
	v_add_u32_e32 v153, 0x1c000, v146
	v_lshl_add_u64 v[2:3], v[2:3], 0, s[60:61]
	s_mov_b32 m0, s2
	s_add_u32 s2, s8, 0x80080
	v_readfirstlane_b32 s10, v153
	v_add_u32_e32 v154, 0x1e000, v146
	global_load_lds_dwordx4 v[2:3], off
	s_addc_u32 s3, s9, 0
	s_mov_b32 m0, s10
	v_readfirstlane_b32 s10, v154
	global_load_lds_dwordx4 v178, s[2:3]
	s_mov_b32 m0, s10
	v_and_b32_e32 v10, 15, v142
	global_load_lds_dwordx4 v128, s[2:3]
	v_lshlrev_b32_e32 v2, 6, v10
	v_lshlrev_b32_e32 v10, 2, v142
	v_and_b32_e32 v11, 48, v142
	v_and_b32_e32 v10, 32, v10
	v_or_b32_e32 v3, v2, v11
	v_bitop3_b32 v12, v2, v10, v11 bitop3:0x36
	s_mov_b32 s2, 0x14000
	v_lshlrev_b32_e32 v2, 6, v142
	v_bitop3_b32 v14, v3, s2, v10 bitop3:0xde
	s_mov_b32 s2, 0x18000
	v_lshlrev_b32_e32 v18, 13, v0
	v_and_b32_e32 v0, 0x3c0, v2
	v_bitop3_b32 v13, v3, s94, v10 bitop3:0xde
	v_bitop3_b32 v15, v3, s2, v10 bitop3:0xde
	v_bitop3_b32 v16, v3, s97, v10 bitop3:0xde
	v_bitop3_b32 v10, v0, v10, v11 bitop3:0x36
	v_lshlrev_b32_e32 v0, 15, v4
	v_and_b32_e32 v17, 0x3000, v2
	v_and_b32_e32 v0, 0xffff0000, v0
	v_lshlrev_b32_e32 v2, 15, v7
	v_lshl_add_u32 v0, v6, 12, v0
	v_and_b32_e32 v2, 0xffff0000, v2
	v_and_or_b32 v0, v1, 64, v0
	v_lshl_add_u32 v2, v9, 12, v2
	v_lshlrev_b32_e32 v3, 6, v7
	s_waitcnt vmcnt(6)
	v_lshl_add_u32 v0, v5, 1, v0
	v_mov_b32_e32 v1, v179
	v_and_or_b32 v2, v3, 64, v2
	v_or_b32_e32 v11, 0x800, v18
	v_or_b32_e32 v19, 0x1000, v18
	v_or_b32_e32 v20, 0x1800, v18
	v_lshl_add_u64 v[130:131], s[8:9], 0, v[0:1]
	v_lshl_add_u32 v2, v8, 1, v2
	v_mov_b32_e32 v3, v179
	v_lshl_add_u64 v[134:135], s[6:7], 0, v[0:1]
	v_mov_b32_e32 v0, 0
	v_lshl_add_u64 v[132:133], s[8:9], 0, v[2:3]
	v_lshl_add_u64 v[136:137], s[6:7], 0, v[2:3]
	s_mov_b32 s2, -2
	s_mov_b64 s[8:9], 0
	v_add_u32_e32 v156, v13, v17
	v_add_u32_e32 v144, v12, v18
	v_add_u32_e32 v143, v10, v11
	v_add_u32_e32 v141, v10, v19
	v_add_u32_e32 v140, v10, v20
	v_add_u32_e32 v155, v14, v17
	v_add_u32_e32 v147, v15, v17
	v_add_u32_e32 v145, v16, v17
	v_mov_b32_e32 v1, v0
	v_mov_b32_e32 v2, v0
	v_mov_b32_e32 v3, v0
	v_mov_b32_e32 v4, v0
	v_mov_b32_e32 v5, v0
	v_mov_b32_e32 v6, v0
	v_mov_b32_e32 v7, v0
	v_mov_b32_e32 v8, v0
	v_mov_b32_e32 v9, v0
	v_mov_b32_e32 v10, v0
	v_mov_b32_e32 v11, v0
	v_mov_b32_e32 v12, v0
	v_mov_b32_e32 v13, v0
	v_mov_b32_e32 v14, v0
	v_mov_b32_e32 v15, v0
	v_mov_b32_e32 v16, v0
	v_mov_b32_e32 v17, v0
	v_mov_b32_e32 v18, v0
	v_mov_b32_e32 v19, v0
	v_mov_b32_e32 v20, v0
	v_mov_b32_e32 v21, v0
	v_mov_b32_e32 v22, v0
	v_mov_b32_e32 v23, v0
	v_mov_b32_e32 v24, v0
	v_mov_b32_e32 v25, v0
	v_mov_b32_e32 v26, v0
	v_mov_b32_e32 v27, v0
	v_mov_b32_e32 v28, v0
	v_mov_b32_e32 v29, v0
	v_mov_b32_e32 v30, v0
	v_mov_b32_e32 v31, v0
	v_mov_b32_e32 v32, v0
	v_mov_b32_e32 v33, v0
	v_mov_b32_e32 v34, v0
	v_mov_b32_e32 v35, v0
	v_mov_b32_e32 v36, v0
	v_mov_b32_e32 v37, v0
	v_mov_b32_e32 v38, v0
	v_mov_b32_e32 v39, v0
	v_mov_b32_e32 v40, v0
	v_mov_b32_e32 v41, v0
	v_mov_b32_e32 v42, v0
	v_mov_b32_e32 v43, v0
	v_mov_b32_e32 v44, v0
	v_mov_b32_e32 v45, v0
	v_mov_b32_e32 v46, v0
	v_mov_b32_e32 v47, v0
	v_mov_b32_e32 v48, v0
	v_mov_b32_e32 v49, v0
	v_mov_b32_e32 v50, v0
	v_mov_b32_e32 v51, v0
; #define STAGE_A(P, half, kt) do { const char* _u = Ab + ((size_t)(half) * 128 * lda + (size_t)(kt) * BK) * 2; \
;     _Pragma("unroll") for (int _i = 0; _i < 2; ++_i) \
;       __builtin_amdgcn_global_load_lds((const unsigned*)(_u + offA[_i]), \
;         (__attribute__((address_space(3))) unsigned*)((__attribute__((address_space(3))) char*)(P) + tidg * 16 + _i * 8192), 16, 0, 0); } while (0)
; #define STAGE_B(P, half, kt) do { const char* _u = Bb + ((size_t)(half) * 128 * ldb + (size_t)(kt) * BK) * 2; \
;     _Pragma("unroll") for (int _i = 0; _i < 2; ++_i) \
;       __builtin_amdgcn_global_load_lds((const unsigned*)(_u + offB[_i]), \
;         (__attribute__((address_space(3))) unsigned*)((__attribute__((address_space(3))) char*)(P) + tidg * 16 + _i * 8192), 16, 0, 0); } while (0)
; #define LDA(dst, b, h) _Pragma("unroll") for (int m = 0; m < 4; ++m) _Pragma("unroll") for (int k = 0; k < 2; ++k) \
;     dst[m][k] = *reinterpret_cast<const bf16x8*>((const char*)SA(b, h) + lds_byte(wr * 64 + m * 16 + fr, k * 32 + fq * 8))
; #define LDB(dst, b, h) _Pragma("unroll") for (int n = 0; n < 2; ++n) _Pragma("unroll") for (int k = 0; k < 2; ++k) \
;     dst[n][k] = *reinterpret_cast<const bf16x8*>((const char*)SB(b, h) + lds_byte(wc * 32 + n * 16 + fr, k * 32 + fq * 8))
; #define WAIT_L(n) asm volatile("s_waitcnt lgkmcnt(" #n ")" ::: "memory")
; #define BAR __builtin_amdgcn_s_barrier()
; #define SCHED __builtin_amdgcn_sched_barrier(0)
; template <bool PF = true, class Epi, class KRF = KRFull>
; __device__ __forceinline__ void gemm_phase(const u16* __restrict__ A, int lda, const u16* __restrict__ Bt, int ldb, int K, int nM, int nN,
;                                            lds_u16* shm, Epi epi, KRF krf = KRFull(), bool flip = false) {
;     ...
;     f32x4 acc[2][2][4][2] = {};
;     ...
;     for (int t = 0; t < nt - 2; t += 2) {
;       LDB(B0, 0, 0); SCHED; LDA(At, 0, 0); STAGE_A(SA(1, 1), 1, t + 1);
;       WAIT_L(8); BAR; WAIT_L(0); MMA(0, 0, At, B0); BAR; SCHED;
;       LDB(B1, 0, 1); STAGE_B(SB(0, 0), 0, t + 2);
;       BAR; WAIT_L(0); MMA(0, 1, At, B1); BAR;
;       LDA(At, 0, 1); STAGE_A(SA(0, 0), 0, t + 2);
;       BAR; WAIT_L(0); MMA(1, 0, At, B0); BAR; SCHED;
	v_mov_b32_e32 v52, v0
	v_mov_b32_e32 v53, v0
	v_mov_b32_e32 v54, v0
	v_mov_b32_e32 v55, v0
	v_mov_b32_e32 v56, v0
	v_mov_b32_e32 v57, v0
	v_mov_b32_e32 v58, v0
	v_mov_b32_e32 v59, v0
	v_mov_b32_e32 v60, v0
	v_mov_b32_e32 v61, v0
	v_mov_b32_e32 v62, v0
	v_mov_b32_e32 v63, v0
	v_mov_b32_e32 v64, v0
	v_mov_b32_e32 v65, v0
	v_mov_b32_e32 v66, v0
	v_mov_b32_e32 v67, v0
	v_mov_b32_e32 v68, v0
	v_mov_b32_e32 v69, v0
	v_mov_b32_e32 v70, v0
	v_mov_b32_e32 v71, v0
	v_mov_b32_e32 v72, v0
	v_mov_b32_e32 v73, v0
	v_mov_b32_e32 v74, v0
	v_mov_b32_e32 v75, v0
	v_mov_b32_e32 v76, v0
	v_mov_b32_e32 v77, v0
	v_mov_b32_e32 v78, v0
	v_mov_b32_e32 v79, v0
	v_mov_b32_e32 v80, v0
	v_mov_b32_e32 v81, v0
	v_mov_b32_e32 v82, v0
	v_mov_b32_e32 v83, v0
	v_mov_b32_e32 v84, v0
	v_mov_b32_e32 v85, v0
	v_mov_b32_e32 v86, v0
	v_mov_b32_e32 v87, v0
	v_mov_b32_e32 v88, v0
	v_mov_b32_e32 v89, v0
	v_mov_b32_e32 v90, v0
	v_mov_b32_e32 v91, v0
	v_mov_b32_e32 v92, v0
	v_mov_b32_e32 v93, v0
	v_mov_b32_e32 v94, v0
	v_mov_b32_e32 v95, v0
	v_mov_b32_e32 v96, v0
	v_mov_b32_e32 v97, v0
	v_mov_b32_e32 v98, v0
	v_mov_b32_e32 v99, v0
	v_mov_b32_e32 v100, v0
	v_mov_b32_e32 v101, v0
	v_mov_b32_e32 v102, v0
	v_mov_b32_e32 v103, v0
	v_mov_b32_e32 v104, v0
	v_mov_b32_e32 v105, v0
	v_mov_b32_e32 v106, v0
	v_mov_b32_e32 v107, v0
	v_mov_b32_e32 v108, v0
	v_mov_b32_e32 v109, v0
	v_mov_b32_e32 v110, v0
	v_mov_b32_e32 v111, v0
	v_mov_b32_e32 v112, v0
	v_mov_b32_e32 v113, v0
	v_mov_b32_e32 v114, v0
	v_mov_b32_e32 v115, v0
	v_mov_b32_e32 v116, v0
	v_mov_b32_e32 v117, v0
	v_mov_b32_e32 v118, v0
	v_mov_b32_e32 v119, v0
	v_mov_b32_e32 v120, v0
	v_mov_b32_e32 v121, v0
	v_mov_b32_e32 v122, v0
	v_mov_b32_e32 v123, v0
	v_mov_b32_e32 v124, v0
	v_mov_b32_e32 v125, v0
	v_mov_b32_e32 v126, v0
	v_mov_b32_e32 v127, v0
	s_barrier
	v_readfirstlane_b32 s3, v146
.LBB0_1636:
	ds_read_b128 v[160:163], v156
	ds_read_b128 v[164:167], v156 offset:1024
	ds_read_b128 v[168:171], v156 offset:2048
	ds_read_b128 v[172:175], v156 offset:3072
	v_lshl_add_u64 v[222:223], v[134:135], 0, s[8:9]
	v_lshl_add_u64 v[158:159], v[222:223], 0, s[62:63]
	s_add_u32 m0, s3, 0xc000
	ds_read_b128 v[180:183], v144
	ds_read_b128 v[184:187], v144 offset:1024
	ds_read_b128 v[188:191], v143
	ds_read_b128 v[192:195], v143 offset:1024
	ds_read_b128 v[196:199], v141
	ds_read_b128 v[200:203], v141 offset:1024
	ds_read_b128 v[204:207], v140
	ds_read_b128 v[208:211], v140 offset:1024
	global_load_lds_dwordx4 v[158:159], off
	v_lshl_add_u64 v[224:225], v[136:137], 0, s[8:9]
	v_lshl_add_u64 v[212:213], v[224:225], 0, s[62:63]
	s_add_u32 m0, s3, 0xe000
	s_nop 0
	global_load_lds_dwordx4 v[212:213], off
	s_waitcnt lgkmcnt(8)
	s_barrier
	s_waitcnt lgkmcnt(0)
	s_setprio 1
	s_waitcnt lgkmcnt(0)
	v_mfma_f32_16x16x32_bf16 v[124:127], v[160:163], v[180:183], v[124:127]
	v_mfma_f32_16x16x32_bf16 v[120:123], v[168:171], v[180:183], v[120:123]
	v_mfma_f32_16x16x32_bf16 v[116:119], v[160:163], v[188:191], v[116:119]
	v_mfma_f32_16x16x32_bf16 v[112:115], v[168:171], v[188:191], v[112:115]
	v_mfma_f32_16x16x32_bf16 v[108:111], v[160:163], v[196:199], v[108:111]
	v_mfma_f32_16x16x32_bf16 v[104:107], v[168:171], v[196:199], v[104:107]
	v_mfma_f32_16x16x32_bf16 v[100:103], v[160:163], v[204:207], v[100:103]
	v_mfma_f32_16x16x32_bf16 v[96:99], v[168:171], v[204:207], v[96:99]
	v_mfma_f32_16x16x32_bf16 v[124:127], v[164:167], v[184:187], v[124:127]
	v_mfma_f32_16x16x32_bf16 v[120:123], v[172:175], v[184:187], v[120:123]
	v_mfma_f32_16x16x32_bf16 v[116:119], v[164:167], v[192:195], v[116:119]
	v_mfma_f32_16x16x32_bf16 v[112:115], v[172:175], v[192:195], v[112:115]
	v_mfma_f32_16x16x32_bf16 v[108:111], v[164:167], v[200:203], v[108:111]
	v_mfma_f32_16x16x32_bf16 v[104:107], v[172:175], v[200:203], v[104:107]
	v_mfma_f32_16x16x32_bf16 v[100:103], v[164:167], v[208:211], v[100:103]
	v_mfma_f32_16x16x32_bf16 v[96:99], v[172:175], v[208:211], v[96:99]
	s_setprio 0
	s_barrier
	v_lshl_add_u64 v[226:227], v[130:131], 0, s[8:9]
	v_lshl_add_u64 v[228:229], v[226:227], 0, s[64:65]
	s_add_u32 m0, s3, 0x10000
	ds_read_b128 v[212:215], v155
	ds_read_b128 v[216:219], v155 offset:1024
	ds_read_b128 v[234:237], v155 offset:2048
	ds_read_b128 v[238:241], v155 offset:3072
	global_load_lds_dwordx4 v[228:229], off
	v_lshl_add_u64 v[228:229], v[132:133], 0, s[8:9]
	v_lshl_add_u64 v[242:243], v[228:229], 0, s[64:65]
	s_add_u32 m0, s3, 0x12000
	s_nop 0
	global_load_lds_dwordx4 v[242:243], off
	s_barrier
	s_waitcnt lgkmcnt(0)
	s_setprio 1
	s_waitcnt lgkmcnt(0)
	v_mfma_f32_16x16x32_bf16 v[92:95], v[212:215], v[180:183], v[92:95]
	v_mfma_f32_16x16x32_bf16 v[88:91], v[234:237], v[180:183], v[88:91]
	v_mfma_f32_16x16x32_bf16 v[84:87], v[212:215], v[188:191], v[84:87]
	v_mfma_f32_16x16x32_bf16 v[80:83], v[234:237], v[188:191], v[80:83]
	v_mfma_f32_16x16x32_bf16 v[76:79], v[212:215], v[196:199], v[76:79]
	v_mfma_f32_16x16x32_bf16 v[72:75], v[234:237], v[196:199], v[72:75]
	v_mfma_f32_16x16x32_bf16 v[68:71], v[212:215], v[204:207], v[68:71]
	v_mfma_f32_16x16x32_bf16 v[64:67], v[234:237], v[204:207], v[64:67]
	v_mfma_f32_16x16x32_bf16 v[92:95], v[216:219], v[184:187], v[92:95]
	v_mfma_f32_16x16x32_bf16 v[88:91], v[238:241], v[184:187], v[88:91]
	v_mfma_f32_16x16x32_bf16 v[84:87], v[216:219], v[192:195], v[84:87]
	v_mfma_f32_16x16x32_bf16 v[80:83], v[238:241], v[192:195], v[80:83]
	v_mfma_f32_16x16x32_bf16 v[76:79], v[216:219], v[200:203], v[76:79]
	v_mfma_f32_16x16x32_bf16 v[72:75], v[238:241], v[200:203], v[72:75]
	v_mfma_f32_16x16x32_bf16 v[68:71], v[216:219], v[208:211], v[68:71]
	v_mfma_f32_16x16x32_bf16 v[64:67], v[238:241], v[208:211], v[64:67]
	s_setprio 0
	v_lshl_add_u64 v[242:243], v[222:223], 0, s[64:65]
	s_mov_b32 m0, s3
	s_barrier
; #define STAGE_A(P, half, kt) do { const char* _u = Ab + ((size_t)(half) * 128 * lda + (size_t)(kt) * BK) * 2; \
;     _Pragma("unroll") for (int _i = 0; _i < 2; ++_i) \
;       __builtin_amdgcn_global_load_lds((const unsigned*)(_u + offA[_i]), \
;         (__attribute__((address_space(3))) unsigned*)((__attribute__((address_space(3))) char*)(P) + tidg * 16 + _i * 8192), 16, 0, 0); } while (0)
; #define STAGE_B(P, half, kt) do { const char* _u = Bb + ((size_t)(half) * 128 * ldb + (size_t)(kt) * BK) * 2; \
;     _Pragma("unroll") for (int _i = 0; _i < 2; ++_i) \
;       __builtin_amdgcn_global_load_lds((const unsigned*)(_u + offB[_i]), \
;         (__attribute__((address_space(3))) unsigned*)((__attribute__((address_space(3))) char*)(P) + tidg * 16 + _i * 8192), 16, 0, 0); } while (0)
; #define LDA(dst, b, h) _Pragma("unroll") for (int m = 0; m < 4; ++m) _Pragma("unroll") for (int k = 0; k < 2; ++k) \
;     dst[m][k] = *reinterpret_cast<const bf16x8*>((const char*)SA(b, h) + lds_byte(wr * 64 + m * 16 + fr, k * 32 + fq * 8))
; #define LDB(dst, b, h) _Pragma("unroll") for (int n = 0; n < 2; ++n) _Pragma("unroll") for (int k = 0; k < 2; ++k) \
;     dst[n][k] = *reinterpret_cast<const bf16x8*>((const char*)SB(b, h) + lds_byte(wc * 32 + n * 16 + fr, k * 32 + fq * 8))
; #define WAIT_V(n) asm volatile("s_waitcnt vmcnt(" #n ")" ::: "memory")
; #define WAIT_L(n) asm volatile("s_waitcnt lgkmcnt(" #n ")" ::: "memory")
; #define BAR __builtin_amdgcn_s_barrier()
; #define SCHED __builtin_amdgcn_sched_barrier(0)
; template <bool PF = true, class Epi, class KRF = KRFull>
; __device__ __forceinline__ void gemm_phase(const u16* __restrict__ A, int lda, const u16* __restrict__ Bt, int ldb, int K, int nM, int nN,
;                                            lds_u16* shm, Epi epi, KRF krf = KRFull(), bool flip = false) {
;     ...
;       LDA(At, 0, 1); STAGE_A(SA(0, 0), 0, t + 2);
;       BAR; WAIT_L(0); MMA(1, 0, At, B0); BAR; SCHED;
;       STAGE_B(SB(0, 1), 1, t + 2);
;       WAIT_V(6); BAR; MMA(1, 1, At, B1); BAR;
;       LDB(B0, 1, 0); SCHED; LDA(At, 1, 0); STAGE_A(SA(0, 1), 1, t + 2);
;       WAIT_L(8); BAR; WAIT_L(0); MMA(0, 0, At, B0); BAR; SCHED;
;       LDB(B1, 1, 1); STAGE_B(SB(1, 0), 0, t + 3);
;       BAR; WAIT_L(0); MMA(0, 1, At, B1); BAR;
;       LDA(At, 1, 1); STAGE_A(SA(1, 0), 0, t + 3);
	ds_read_b128 v[180:183], v144 offset:16384
	ds_read_b128 v[184:187], v144 offset:17408
	ds_read_b128 v[188:191], v143 offset:16384
	ds_read_b128 v[192:195], v143 offset:17408
	ds_read_b128 v[196:199], v141 offset:16384
	ds_read_b128 v[200:203], v141 offset:17408
	ds_read_b128 v[204:207], v140 offset:16384
	ds_read_b128 v[208:211], v140 offset:17408
	global_load_lds_dwordx4 v[242:243], off
	v_lshl_add_u64 v[242:243], v[224:225], 0, s[64:65]
	s_add_u32 m0, s3, 0x2000
	s_nop 0
	global_load_lds_dwordx4 v[242:243], off
	s_barrier
	s_waitcnt lgkmcnt(0)
	s_setprio 1
	s_waitcnt lgkmcnt(0)
	v_mfma_f32_16x16x32_bf16 v[60:63], v[160:163], v[180:183], v[60:63]
	v_mfma_f32_16x16x32_bf16 v[56:59], v[168:171], v[180:183], v[56:59]
	v_mfma_f32_16x16x32_bf16 v[52:55], v[160:163], v[188:191], v[52:55]
	v_mfma_f32_16x16x32_bf16 v[48:51], v[168:171], v[188:191], v[48:51]
	v_mfma_f32_16x16x32_bf16 v[44:47], v[160:163], v[196:199], v[44:47]
	v_mfma_f32_16x16x32_bf16 v[40:43], v[168:171], v[196:199], v[40:43]
	v_mfma_f32_16x16x32_bf16 v[36:39], v[160:163], v[204:207], v[36:39]
	v_mfma_f32_16x16x32_bf16 v[32:35], v[168:171], v[204:207], v[32:35]
	v_mfma_f32_16x16x32_bf16 v[60:63], v[164:167], v[184:187], v[60:63]
	v_mfma_f32_16x16x32_bf16 v[56:59], v[172:175], v[184:187], v[56:59]
	v_mfma_f32_16x16x32_bf16 v[52:55], v[164:167], v[192:195], v[52:55]
	v_mfma_f32_16x16x32_bf16 v[48:51], v[172:175], v[192:195], v[48:51]
	v_mfma_f32_16x16x32_bf16 v[44:47], v[164:167], v[200:203], v[44:47]
	v_mfma_f32_16x16x32_bf16 v[40:43], v[172:175], v[200:203], v[40:43]
	v_mfma_f32_16x16x32_bf16 v[36:39], v[164:167], v[208:211], v[36:39]
	v_mfma_f32_16x16x32_bf16 v[32:35], v[172:175], v[208:211], v[32:35]
	s_setprio 0
	s_barrier
	v_lshl_add_u64 v[160:161], v[226:227], 0, s[66:67]
	s_add_u32 m0, s3, 0x14000
	s_nop 0
	global_load_lds_dwordx4 v[160:161], off
	v_lshl_add_u64 v[160:161], v[228:229], 0, s[66:67]
	s_add_u32 m0, s3, 0x16000
	s_nop 0
	global_load_lds_dwordx4 v[160:161], off
	s_waitcnt vmcnt(6)
	s_barrier
	s_setprio 1
	v_mfma_f32_16x16x32_bf16 v[28:31], v[212:215], v[180:183], v[28:31]
	v_mfma_f32_16x16x32_bf16 v[24:27], v[234:237], v[180:183], v[24:27]
	v_mfma_f32_16x16x32_bf16 v[20:23], v[212:215], v[188:191], v[20:23]
	v_mfma_f32_16x16x32_bf16 v[16:19], v[234:237], v[188:191], v[16:19]
	v_mfma_f32_16x16x32_bf16 v[12:15], v[212:215], v[196:199], v[12:15]
	v_mfma_f32_16x16x32_bf16 v[8:11], v[234:237], v[196:199], v[8:11]
	v_mfma_f32_16x16x32_bf16 v[4:7], v[212:215], v[204:207], v[4:7]
	v_mfma_f32_16x16x32_bf16 v[0:3], v[234:237], v[204:207], v[0:3]
	v_mfma_f32_16x16x32_bf16 v[28:31], v[216:219], v[184:187], v[28:31]
	v_mfma_f32_16x16x32_bf16 v[24:27], v[238:241], v[184:187], v[24:27]
	v_mfma_f32_16x16x32_bf16 v[20:23], v[216:219], v[192:195], v[20:23]
	v_mfma_f32_16x16x32_bf16 v[16:19], v[238:241], v[192:195], v[16:19]
	v_mfma_f32_16x16x32_bf16 v[12:15], v[216:219], v[200:203], v[12:15]
	v_mfma_f32_16x16x32_bf16 v[8:11], v[238:241], v[200:203], v[8:11]
	v_mfma_f32_16x16x32_bf16 v[4:7], v[216:219], v[208:211], v[4:7]
	v_mfma_f32_16x16x32_bf16 v[0:3], v[238:241], v[208:211], v[0:3]
	s_setprio 0
	s_barrier
	ds_read_b128 v[160:163], v147
	ds_read_b128 v[164:167], v147 offset:1024
	ds_read_b128 v[168:171], v147 offset:2048
	ds_read_b128 v[172:175], v147 offset:3072
	v_lshl_add_u64 v[212:213], v[222:223], 0, s[66:67]
	s_add_u32 m0, s3, 0x4000
	ds_read_b128 v[180:183], v144 offset:32768
	ds_read_b128 v[184:187], v144 offset:33792
	ds_read_b128 v[188:191], v143 offset:32768
	ds_read_b128 v[192:195], v143 offset:33792
	ds_read_b128 v[196:199], v141 offset:32768
	ds_read_b128 v[200:203], v141 offset:33792
	ds_read_b128 v[204:207], v140 offset:32768
	ds_read_b128 v[208:211], v140 offset:33792
	global_load_lds_dwordx4 v[212:213], off
	v_lshl_add_u64 v[212:213], v[224:225], 0, s[66:67]
	s_add_u32 m0, s3, 0x6000
	s_nop 0
	global_load_lds_dwordx4 v[212:213], off
	s_waitcnt lgkmcnt(8)
	s_barrier
	s_waitcnt lgkmcnt(0)
	s_setprio 1
	s_waitcnt lgkmcnt(0)
	v_mfma_f32_16x16x32_bf16 v[124:127], v[160:163], v[180:183], v[124:127]
	v_mfma_f32_16x16x32_bf16 v[120:123], v[168:171], v[180:183], v[120:123]
	v_mfma_f32_16x16x32_bf16 v[116:119], v[160:163], v[188:191], v[116:119]
	v_mfma_f32_16x16x32_bf16 v[112:115], v[168:171], v[188:191], v[112:115]
	v_mfma_f32_16x16x32_bf16 v[108:111], v[160:163], v[196:199], v[108:111]
	v_mfma_f32_16x16x32_bf16 v[104:107], v[168:171], v[196:199], v[104:107]
	v_mfma_f32_16x16x32_bf16 v[100:103], v[160:163], v[204:207], v[100:103]
	v_mfma_f32_16x16x32_bf16 v[96:99], v[168:171], v[204:207], v[96:99]
	v_mfma_f32_16x16x32_bf16 v[124:127], v[164:167], v[184:187], v[124:127]
	v_mfma_f32_16x16x32_bf16 v[120:123], v[172:175], v[184:187], v[120:123]
	v_mfma_f32_16x16x32_bf16 v[116:119], v[164:167], v[192:195], v[116:119]
	v_mfma_f32_16x16x32_bf16 v[112:115], v[172:175], v[192:195], v[112:115]
	v_mfma_f32_16x16x32_bf16 v[108:111], v[164:167], v[200:203], v[108:111]
	v_mfma_f32_16x16x32_bf16 v[104:107], v[172:175], v[200:203], v[104:107]
	v_mfma_f32_16x16x32_bf16 v[100:103], v[164:167], v[208:211], v[100:103]
	v_mfma_f32_16x16x32_bf16 v[96:99], v[172:175], v[208:211], v[96:99]
	s_setprio 0
	s_barrier
	v_lshl_add_u64 v[242:243], v[226:227], 0, s[68:69]
	s_add_u32 m0, s3, 0x18000
	ds_read_b128 v[212:215], v145
	ds_read_b128 v[216:219], v145 offset:1024
	ds_read_b128 v[234:237], v145 offset:2048
	ds_read_b128 v[238:241], v145 offset:3072
	global_load_lds_dwordx4 v[242:243], off
	v_lshl_add_u64 v[242:243], v[228:229], 0, s[68:69]
	s_add_u32 m0, s3, 0x1a000
	s_nop 0
	global_load_lds_dwordx4 v[242:243], off
	s_barrier
; #define STAGE_A(P, half, kt) do { const char* _u = Ab + ((size_t)(half) * 128 * lda + (size_t)(kt) * BK) * 2; \
;     _Pragma("unroll") for (int _i = 0; _i < 2; ++_i) \
;       __builtin_amdgcn_global_load_lds((const unsigned*)(_u + offA[_i]), \
;         (__attribute__((address_space(3))) unsigned*)((__attribute__((address_space(3))) char*)(P) + tidg * 16 + _i * 8192), 16, 0, 0); } while (0)
; #define STAGE_B(P, half, kt) do { const char* _u = Bb + ((size_t)(half) * 128 * ldb + (size_t)(kt) * BK) * 2; \
;     _Pragma("unroll") for (int _i = 0; _i < 2; ++_i) \
;       __builtin_amdgcn_global_load_lds((const unsigned*)(_u + offB[_i]), \
;         (__attribute__((address_space(3))) unsigned*)((__attribute__((address_space(3))) char*)(P) + tidg * 16 + _i * 8192), 16, 0, 0); } while (0)
; #define LDA(dst, b, h) _Pragma("unroll") for (int m = 0; m < 4; ++m) _Pragma("unroll") for (int k = 0; k < 2; ++k) \
;     dst[m][k] = *reinterpret_cast<const bf16x8*>((const char*)SA(b, h) + lds_byte(wr * 64 + m * 16 + fr, k * 32 + fq * 8))
; #define LDB(dst, b, h) _Pragma("unroll") for (int n = 0; n < 2; ++n) _Pragma("unroll") for (int k = 0; k < 2; ++k) \
;     dst[n][k] = *reinterpret_cast<const bf16x8*>((const char*)SB(b, h) + lds_byte(wc * 32 + n * 16 + fr, k * 32 + fq * 8))
; #define MMA(ai, bj, At_, Bt_) do { __builtin_amdgcn_s_setprio(1); \
;     _Pragma("unroll") for (int m = 0; m < 4; ++m) _Pragma("unroll") for (int n = 0; n < 2; ++n) _Pragma("unroll") for (int k = 0; k < 2; ++k) \
;       acc[ai][bj][m][n] = __builtin_amdgcn_mfma_f32_16x16x32_bf16(Bt_[n][k], At_[m][k], acc[ai][bj][m][n], 0, 0, 0); \
;     __builtin_amdgcn_s_setprio(0); } while (0)
; #define WAIT_V(n) asm volatile("s_waitcnt vmcnt(" #n ")" ::: "memory")
; #define WAIT_L(n) asm volatile("s_waitcnt lgkmcnt(" #n ")" ::: "memory")
; template <bool PF = true, class Epi, class KRF = KRFull>
; __device__ __forceinline__ void gemm_phase(const u16* __restrict__ A, int lda, const u16* __restrict__ Bt, int ldb, int K, int nM, int nN,
;                                            lds_u16* shm, Epi epi, KRF krf = KRFull(), bool flip = false) {
;     ...
;       LDA(At, 1, 1); STAGE_A(SA(1, 0), 0, t + 3);
;       BAR; WAIT_L(0); MMA(1, 0, At, B0); BAR; SCHED;
;       STAGE_B(SB(1, 1), 1, t + 3);
;       WAIT_V(6); BAR; MMA(1, 1, At, B1); BAR;
;     }
;     { LDB(B0, 0, 0); LDA(At, 0, 0); STAGE_A(SA(1, 1), 1, nt - 1);
	s_waitcnt lgkmcnt(0)
	s_setprio 1
	s_waitcnt lgkmcnt(0)
	v_mfma_f32_16x16x32_bf16 v[92:95], v[212:215], v[180:183], v[92:95]
	v_mfma_f32_16x16x32_bf16 v[88:91], v[234:237], v[180:183], v[88:91]
	v_mfma_f32_16x16x32_bf16 v[84:87], v[212:215], v[188:191], v[84:87]
	v_mfma_f32_16x16x32_bf16 v[80:83], v[234:237], v[188:191], v[80:83]
	v_mfma_f32_16x16x32_bf16 v[76:79], v[212:215], v[196:199], v[76:79]
	v_mfma_f32_16x16x32_bf16 v[72:75], v[234:237], v[196:199], v[72:75]
	v_mfma_f32_16x16x32_bf16 v[68:71], v[212:215], v[204:207], v[68:71]
	v_mfma_f32_16x16x32_bf16 v[64:67], v[234:237], v[204:207], v[64:67]
	v_mfma_f32_16x16x32_bf16 v[92:95], v[216:219], v[184:187], v[92:95]
	v_mfma_f32_16x16x32_bf16 v[88:91], v[238:241], v[184:187], v[88:91]
	v_mfma_f32_16x16x32_bf16 v[84:87], v[216:219], v[192:195], v[84:87]
	v_mfma_f32_16x16x32_bf16 v[80:83], v[238:241], v[192:195], v[80:83]
	v_mfma_f32_16x16x32_bf16 v[76:79], v[216:219], v[200:203], v[76:79]
	v_mfma_f32_16x16x32_bf16 v[72:75], v[238:241], v[200:203], v[72:75]
	v_mfma_f32_16x16x32_bf16 v[68:71], v[216:219], v[208:211], v[68:71]
	v_mfma_f32_16x16x32_bf16 v[64:67], v[238:241], v[208:211], v[64:67]
	s_setprio 0
	v_lshl_add_u64 v[222:223], v[222:223], 0, s[68:69]
	s_add_u32 m0, s3, 0x8000
	s_barrier
	ds_read_b128 v[180:183], v144 offset:49152
	ds_read_b128 v[184:187], v144 offset:50176
	ds_read_b128 v[188:191], v143 offset:49152
	ds_read_b128 v[192:195], v143 offset:50176
	ds_read_b128 v[196:199], v141 offset:49152
	ds_read_b128 v[200:203], v141 offset:50176
	ds_read_b128 v[204:207], v140 offset:49152
	ds_read_b128 v[208:211], v140 offset:50176
	global_load_lds_dwordx4 v[222:223], off
	v_lshl_add_u64 v[222:223], v[224:225], 0, s[68:69]
	s_add_u32 m0, s3, 0xa000
	s_nop 0
	global_load_lds_dwordx4 v[222:223], off
	s_barrier
	s_waitcnt lgkmcnt(0)
	s_setprio 1
	s_waitcnt lgkmcnt(0)
	v_mfma_f32_16x16x32_bf16 v[60:63], v[160:163], v[180:183], v[60:63]
	v_mfma_f32_16x16x32_bf16 v[56:59], v[168:171], v[180:183], v[56:59]
	v_mfma_f32_16x16x32_bf16 v[52:55], v[160:163], v[188:191], v[52:55]
	v_mfma_f32_16x16x32_bf16 v[48:51], v[168:171], v[188:191], v[48:51]
	v_mfma_f32_16x16x32_bf16 v[44:47], v[160:163], v[196:199], v[44:47]
	v_mfma_f32_16x16x32_bf16 v[40:43], v[168:171], v[196:199], v[40:43]
	v_mfma_f32_16x16x32_bf16 v[36:39], v[160:163], v[204:207], v[36:39]
	v_mfma_f32_16x16x32_bf16 v[32:35], v[168:171], v[204:207], v[32:35]
	v_mfma_f32_16x16x32_bf16 v[60:63], v[164:167], v[184:187], v[60:63]
	v_mfma_f32_16x16x32_bf16 v[56:59], v[172:175], v[184:187], v[56:59]
	v_mfma_f32_16x16x32_bf16 v[52:55], v[164:167], v[192:195], v[52:55]
	v_mfma_f32_16x16x32_bf16 v[48:51], v[172:175], v[192:195], v[48:51]
	v_mfma_f32_16x16x32_bf16 v[44:47], v[164:167], v[200:203], v[44:47]
	v_mfma_f32_16x16x32_bf16 v[40:43], v[172:175], v[200:203], v[40:43]
	v_mfma_f32_16x16x32_bf16 v[36:39], v[164:167], v[208:211], v[36:39]
	v_mfma_f32_16x16x32_bf16 v[32:35], v[172:175], v[208:211], v[32:35]
	s_setprio 0
	s_barrier
	v_lshl_add_u64 v[160:161], v[226:227], 0, s[70:71]
	s_add_u32 m0, s3, 0x1c000
	s_nop 0
	global_load_lds_dwordx4 v[160:161], off
	v_lshl_add_u64 v[160:161], v[228:229], 0, s[70:71]
	s_add_u32 m0, s3, 0x1e000
	s_nop 0
	global_load_lds_dwordx4 v[160:161], off
	s_waitcnt vmcnt(6)
	s_barrier
	s_setprio 1
	v_mfma_f32_16x16x32_bf16 v[28:31], v[212:215], v[180:183], v[28:31]
	v_mfma_f32_16x16x32_bf16 v[24:27], v[234:237], v[180:183], v[24:27]
	v_mfma_f32_16x16x32_bf16 v[20:23], v[212:215], v[188:191], v[20:23]
	v_mfma_f32_16x16x32_bf16 v[16:19], v[234:237], v[188:191], v[16:19]
	v_mfma_f32_16x16x32_bf16 v[12:15], v[212:215], v[196:199], v[12:15]
	v_mfma_f32_16x16x32_bf16 v[8:11], v[234:237], v[196:199], v[8:11]
	v_mfma_f32_16x16x32_bf16 v[4:7], v[212:215], v[204:207], v[4:7]
	v_mfma_f32_16x16x32_bf16 v[0:3], v[234:237], v[204:207], v[0:3]
	v_mfma_f32_16x16x32_bf16 v[28:31], v[216:219], v[184:187], v[28:31]
	v_mfma_f32_16x16x32_bf16 v[24:27], v[238:241], v[184:187], v[24:27]
	v_mfma_f32_16x16x32_bf16 v[20:23], v[216:219], v[192:195], v[20:23]
	v_mfma_f32_16x16x32_bf16 v[16:19], v[238:241], v[192:195], v[16:19]
	v_mfma_f32_16x16x32_bf16 v[12:15], v[216:219], v[200:203], v[12:15]
	v_mfma_f32_16x16x32_bf16 v[8:11], v[238:241], v[200:203], v[8:11]
	v_mfma_f32_16x16x32_bf16 v[4:7], v[216:219], v[208:211], v[4:7]
	v_mfma_f32_16x16x32_bf16 v[0:3], v[238:241], v[208:211], v[0:3]
	s_setprio 0
	s_add_i32 s2, s2, 2
	s_add_u32 s8, s8, 0x100
	s_addc_u32 s9, s9, 0
	s_cmp_gt_u32 s2, 27
	s_barrier
	s_cbranch_scc0 .LBB0_1636
	v_add_u32_e32 v157, 0xc000, v146
	v_add_u32_e32 v158, 0xe000, v146
	v_add_u32_e32 v159, 0x6000, v146
	s_add_u32 s2, s6, 0x80f80
	s_addc_u32 s3, s7, 0
	v_readfirstlane_b32 s6, v157
	v_lshl_add_u64 v[152:153], s[2:3], 0, v[178:179]
	s_mov_b32 m0, s6
	v_lshl_add_u64 v[128:129], s[2:3], 0, v[128:129]
	v_readfirstlane_b32 s2, v158
	ds_read_b128 v[130:133], v156
	ds_read_b128 v[134:137], v156 offset:1024
	ds_read_b128 v[148:151], v156 offset:2048
	ds_read_b128 v[160:163], v156 offset:3072
	ds_read_b128 v[164:167], v144
	ds_read_b128 v[168:171], v144 offset:1024
	ds_read_b128 v[172:175], v143
	ds_read_b128 v[180:183], v143 offset:1024
	ds_read_b128 v[184:187], v141
	ds_read_b128 v[188:191], v141 offset:1024
	ds_read_b128 v[192:195], v140
	ds_read_b128 v[196:199], v140 offset:1024
	global_load_lds_dwordx4 v[152:153], off
	s_mov_b32 m0, s2
	s_nop 0
	global_load_lds_dwordx4 v[128:129], off
	s_barrier
; #define LDA(dst, b, h) _Pragma("unroll") for (int m = 0; m < 4; ++m) _Pragma("unroll") for (int k = 0; k < 2; ++k) \
;     dst[m][k] = *reinterpret_cast<const bf16x8*>((const char*)SA(b, h) + lds_byte(wr * 64 + m * 16 + fr, k * 32 + fq * 8))
; #define LDB(dst, b, h) _Pragma("unroll") for (int n = 0; n < 2; ++n) _Pragma("unroll") for (int k = 0; k < 2; ++k) \
;     dst[n][k] = *reinterpret_cast<const bf16x8*>((const char*)SB(b, h) + lds_byte(wc * 32 + n * 16 + fr, k * 32 + fq * 8))
; #define MMA(ai, bj, At_, Bt_) do { __builtin_amdgcn_s_setprio(1); \
;     _Pragma("unroll") for (int m = 0; m < 4; ++m) _Pragma("unroll") for (int n = 0; n < 2; ++n) _Pragma("unroll") for (int k = 0; k < 2; ++k) \
;       acc[ai][bj][m][n] = __builtin_amdgcn_mfma_f32_16x16x32_bf16(Bt_[n][k], At_[m][k], acc[ai][bj][m][n], 0, 0, 0); \
;     __builtin_amdgcn_s_setprio(0); } while (0)
; #define WAIT_V(n) asm volatile("s_waitcnt vmcnt(" #n ")" ::: "memory")
; #define WAIT_L(n) asm volatile("s_waitcnt lgkmcnt(" #n ")" ::: "memory")
; #define BAR __builtin_amdgcn_s_barrier()
; template <bool PF = true, class Epi, class KRF = KRFull>
; __device__ __forceinline__ void gemm_phase(const u16* __restrict__ A, int lda, const u16* __restrict__ Bt, int ldb, int K, int nM, int nN,
;                                            lds_u16* shm, Epi epi, KRF krf = KRFull(), bool flip = false) {
;     ...
;       BAR; WAIT_L(0); MMA(0, 0, At, B0); BAR;
;       LDB(B1, 0, 1); BAR; WAIT_L(0); MMA(0, 1, At, B1); BAR;
;       LDA(At, 0, 1); WAIT_V(4); BAR; WAIT_L(0); MMA(1, 0, At, B0); MMA(1, 1, At, B1); BAR; }
	s_waitcnt lgkmcnt(0)
	s_setprio 1
	s_waitcnt lgkmcnt(0)
	v_mfma_f32_16x16x32_bf16 v[124:127], v[130:133], v[164:167], v[124:127]
	v_mfma_f32_16x16x32_bf16 v[120:123], v[148:151], v[164:167], v[120:123]
	v_mfma_f32_16x16x32_bf16 v[116:119], v[130:133], v[172:175], v[116:119]
	v_mfma_f32_16x16x32_bf16 v[112:115], v[148:151], v[172:175], v[112:115]
	v_mfma_f32_16x16x32_bf16 v[108:111], v[130:133], v[184:187], v[108:111]
	v_mfma_f32_16x16x32_bf16 v[104:107], v[148:151], v[184:187], v[104:107]
	v_mfma_f32_16x16x32_bf16 v[100:103], v[130:133], v[192:195], v[100:103]
	v_mfma_f32_16x16x32_bf16 v[96:99], v[148:151], v[192:195], v[96:99]
	v_mfma_f32_16x16x32_bf16 v[124:127], v[134:137], v[168:171], v[124:127]
	v_mfma_f32_16x16x32_bf16 v[120:123], v[160:163], v[168:171], v[120:123]
	v_mfma_f32_16x16x32_bf16 v[116:119], v[134:137], v[180:183], v[116:119]
	v_mfma_f32_16x16x32_bf16 v[112:115], v[160:163], v[180:183], v[112:115]
	v_mfma_f32_16x16x32_bf16 v[108:111], v[134:137], v[188:191], v[108:111]
	v_mfma_f32_16x16x32_bf16 v[104:107], v[160:163], v[188:191], v[104:107]
	v_mfma_f32_16x16x32_bf16 v[100:103], v[134:137], v[196:199], v[100:103]
	v_mfma_f32_16x16x32_bf16 v[96:99], v[160:163], v[196:199], v[96:99]
	s_setprio 0
	s_barrier
	ds_read_b128 v[156:159], v155
	ds_read_b128 v[200:203], v155 offset:1024
	ds_read_b128 v[204:207], v155 offset:2048
	ds_read_b128 v[152:155], v155 offset:3072
	s_barrier
	s_waitcnt lgkmcnt(0)
	s_setprio 1
	s_waitcnt lgkmcnt(0)
	v_mfma_f32_16x16x32_bf16 v[76:79], v[156:159], v[184:187], v[76:79]
	v_mfma_f32_16x16x32_bf16 v[72:75], v[204:207], v[184:187], v[72:75]
	v_mfma_f32_16x16x32_bf16 v[68:71], v[156:159], v[192:195], v[68:71]
	v_mfma_f32_16x16x32_bf16 v[64:67], v[204:207], v[192:195], v[64:67]
	v_mfma_f32_16x16x32_bf16 v[92:95], v[156:159], v[164:167], v[92:95]
	v_mfma_f32_16x16x32_bf16 v[88:91], v[204:207], v[164:167], v[88:91]
	v_mfma_f32_16x16x32_bf16 v[84:87], v[156:159], v[172:175], v[84:87]
	v_mfma_f32_16x16x32_bf16 v[80:83], v[204:207], v[172:175], v[80:83]
	v_mfma_f32_16x16x32_bf16 v[76:79], v[200:203], v[188:191], v[76:79]
	v_mfma_f32_16x16x32_bf16 v[72:75], v[152:155], v[188:191], v[72:75]
	v_mfma_f32_16x16x32_bf16 v[68:71], v[200:203], v[196:199], v[68:71]
	v_mfma_f32_16x16x32_bf16 v[64:67], v[152:155], v[196:199], v[64:67]
	v_mfma_f32_16x16x32_bf16 v[208:211], v[200:203], v[168:171], v[92:95]
	v_mfma_f32_16x16x32_bf16 v[164:167], v[152:155], v[168:171], v[88:91]
	v_mfma_f32_16x16x32_bf16 v[168:171], v[200:203], v[180:183], v[84:87]
	v_mfma_f32_16x16x32_bf16 v[172:175], v[152:155], v[180:183], v[80:83]
	s_setprio 0
	s_barrier
	s_nop 0
	ds_read_b128 v[80:83], v144 offset:16384
	ds_read_b128 v[84:87], v144 offset:17408
	ds_read_b128 v[88:91], v143 offset:16384
	ds_read_b128 v[92:95], v143 offset:17408
	ds_read_b128 v[180:183], v141 offset:16384
	ds_read_b128 v[184:187], v141 offset:17408
	ds_read_b128 v[188:191], v140 offset:16384
	ds_read_b128 v[192:195], v140 offset:17408
	s_waitcnt vmcnt(4)
	s_barrier
	s_waitcnt lgkmcnt(0)
	s_setprio 1
	s_waitcnt lgkmcnt(0)
	v_mfma_f32_16x16x32_bf16 v[44:47], v[130:133], v[180:183], v[44:47]
	v_mfma_f32_16x16x32_bf16 v[40:43], v[148:151], v[180:183], v[40:43]
	v_mfma_f32_16x16x32_bf16 v[36:39], v[130:133], v[188:191], v[36:39]
	v_mfma_f32_16x16x32_bf16 v[32:35], v[148:151], v[188:191], v[32:35]
	v_mfma_f32_16x16x32_bf16 v[60:63], v[130:133], v[80:83], v[60:63]
	v_mfma_f32_16x16x32_bf16 v[56:59], v[148:151], v[80:83], v[56:59]
	v_mfma_f32_16x16x32_bf16 v[52:55], v[130:133], v[88:91], v[52:55]
	v_mfma_f32_16x16x32_bf16 v[48:51], v[148:151], v[88:91], v[48:51]
	v_mfma_f32_16x16x32_bf16 v[44:47], v[134:137], v[184:187], v[44:47]
	v_mfma_f32_16x16x32_bf16 v[40:43], v[160:163], v[184:187], v[40:43]
	v_mfma_f32_16x16x32_bf16 v[36:39], v[134:137], v[192:195], v[36:39]
	v_mfma_f32_16x16x32_bf16 v[32:35], v[160:163], v[192:195], v[32:35]
	v_mfma_f32_16x16x32_bf16 v[196:199], v[134:137], v[84:87], v[60:63]
	v_mfma_f32_16x16x32_bf16 v[212:215], v[160:163], v[84:87], v[56:59]
	v_mfma_f32_16x16x32_bf16 v[216:219], v[134:137], v[92:95], v[52:55]
	v_mfma_f32_16x16x32_bf16 v[234:237], v[160:163], v[92:95], v[48:51]
	s_setprio 0
	s_setprio 1
	v_mfma_f32_16x16x32_bf16 v[0:3], v[204:207], v[188:191], v[0:3]
	v_mfma_f32_16x16x32_bf16 v[28:31], v[156:159], v[80:83], v[28:31]
	v_mfma_f32_16x16x32_bf16 v[24:27], v[204:207], v[80:83], v[24:27]
	v_mfma_f32_16x16x32_bf16 v[20:23], v[156:159], v[88:91], v[20:23]
	v_mfma_f32_16x16x32_bf16 v[16:19], v[204:207], v[88:91], v[16:19]
	v_mfma_f32_16x16x32_bf16 v[12:15], v[156:159], v[180:183], v[12:15]
	v_mfma_f32_16x16x32_bf16 v[8:11], v[204:207], v[180:183], v[8:11]
	v_mfma_f32_16x16x32_bf16 v[4:7], v[156:159], v[188:191], v[4:7]
	v_mfma_f32_16x16x32_bf16 v[0:3], v[152:155], v[192:195], v[0:3]
	v_mfma_f32_16x16x32_bf16 v[128:131], v[200:203], v[84:87], v[28:31]
	v_mfma_f32_16x16x32_bf16 v[132:135], v[152:155], v[84:87], v[24:27]
	v_mfma_f32_16x16x32_bf16 v[148:151], v[200:203], v[92:95], v[20:23]
	v_mfma_f32_16x16x32_bf16 v[160:163], v[152:155], v[92:95], v[16:19]
	v_mfma_f32_16x16x32_bf16 v[238:241], v[200:203], v[184:187], v[12:15]
	v_mfma_f32_16x16x32_bf16 v[180:183], v[152:155], v[184:187], v[8:11]
	v_mfma_f32_16x16x32_bf16 v[156:159], v[200:203], v[192:195], v[4:7]
	s_setprio 0
	s_barrier
; #define LDA(dst, b, h) _Pragma("unroll") for (int m = 0; m < 4; ++m) _Pragma("unroll") for (int k = 0; k < 2; ++k) \
;     dst[m][k] = *reinterpret_cast<const bf16x8*>((const char*)SA(b, h) + lds_byte(wr * 64 + m * 16 + fr, k * 32 + fq * 8))
; #define LDB(dst, b, h) _Pragma("unroll") for (int n = 0; n < 2; ++n) _Pragma("unroll") for (int k = 0; k < 2; ++k) \
;     dst[n][k] = *reinterpret_cast<const bf16x8*>((const char*)SB(b, h) + lds_byte(wc * 32 + n * 16 + fr, k * 32 + fq * 8))
; #define MMA(ai, bj, At_, Bt_) do { __builtin_amdgcn_s_setprio(1); \
;     _Pragma("unroll") for (int m = 0; m < 4; ++m) _Pragma("unroll") for (int n = 0; n < 2; ++n) _Pragma("unroll") for (int k = 0; k < 2; ++k) \
;       acc[ai][bj][m][n] = __builtin_amdgcn_mfma_f32_16x16x32_bf16(Bt_[n][k], At_[m][k], acc[ai][bj][m][n], 0, 0, 0); \
;     __builtin_amdgcn_s_setprio(0); } while (0)
; #define WAIT_V(n) asm volatile("s_waitcnt vmcnt(" #n ")" ::: "memory")
; #define WAIT_L(n) asm volatile("s_waitcnt lgkmcnt(" #n ")" ::: "memory")
; #define BAR __builtin_amdgcn_s_barrier()
; template <bool PF = true, class Epi, class KRF = KRFull>
; __device__ __forceinline__ void gemm_phase(const u16* __restrict__ A, int lda, const u16* __restrict__ Bt, int ldb, int K, int nM, int nN,
;                                            lds_u16* shm, Epi epi, KRF krf = KRFull(), bool flip = false) {
;     ...
;     { LDB(B0, 1, 0); LDA(At, 1, 0); WAIT_V(2); BAR; WAIT_L(0); MMA(0, 0, At, B0); BAR;
;       LDB(B1, 1, 1); WAIT_V(0); BAR; WAIT_L(0); MMA(0, 1, At, B1); BAR;
;       LDA(At, 1, 1); BAR; WAIT_L(0); MMA(1, 0, At, B0); MMA(1, 1, At, B1); BAR; }
;     if (wr == 0) BAR;
	s_nop 0
	ds_read_b128 v[4:7], v147
	ds_read_b128 v[8:11], v147 offset:1024
	ds_read_b128 v[12:15], v147 offset:2048
	ds_read_b128 v[152:155], v147 offset:3072
	ds_read_b128 v[16:19], v144 offset:32768
	ds_read_b128 v[20:23], v144 offset:33792
	ds_read_b128 v[24:27], v143 offset:32768
	ds_read_b128 v[48:51], v143 offset:33792
	ds_read_b128 v[184:187], v141 offset:32768
	ds_read_b128 v[188:191], v141 offset:33792
	ds_read_b128 v[192:195], v140 offset:32768
	ds_read_b128 v[200:203], v140 offset:33792
	s_waitcnt vmcnt(2)
	s_barrier
	s_waitcnt lgkmcnt(0)
	s_setprio 1
	s_waitcnt lgkmcnt(0)
	v_mfma_f32_16x16x32_bf16 v[28:31], v[4:7], v[16:19], v[124:127]
	v_mfma_f32_16x16x32_bf16 v[124:127], v[8:11], v[20:23], v[28:31]
	v_mfma_f32_16x16x32_bf16 v[28:31], v[12:15], v[16:19], v[120:123]
	v_mfma_f32_16x16x32_bf16 v[92:95], v[152:155], v[20:23], v[28:31]
	v_mfma_f32_16x16x32_bf16 v[28:31], v[4:7], v[24:27], v[116:119]
	v_mfma_f32_16x16x32_bf16 v[120:123], v[8:11], v[48:51], v[28:31]
	v_mfma_f32_16x16x32_bf16 v[28:31], v[12:15], v[24:27], v[112:115]
	v_mfma_f32_16x16x32_bf16 v[88:91], v[152:155], v[48:51], v[28:31]
	v_mfma_f32_16x16x32_bf16 v[28:31], v[4:7], v[184:187], v[108:111]
	v_mfma_f32_16x16x32_bf16 v[116:119], v[8:11], v[188:191], v[28:31]
	v_mfma_f32_16x16x32_bf16 v[28:31], v[12:15], v[184:187], v[104:107]
	v_mfma_f32_16x16x32_bf16 v[84:87], v[152:155], v[188:191], v[28:31]
	v_mfma_f32_16x16x32_bf16 v[28:31], v[4:7], v[192:195], v[100:103]
	v_mfma_f32_16x16x32_bf16 v[112:115], v[8:11], v[200:203], v[28:31]
	v_mfma_f32_16x16x32_bf16 v[28:31], v[12:15], v[192:195], v[96:99]
	v_mfma_f32_16x16x32_bf16 v[80:83], v[152:155], v[200:203], v[28:31]
	s_setprio 0
	s_barrier
	ds_read_b128 v[204:207], v145
	ds_read_b128 v[242:245], v145 offset:1024
	ds_read_b128 v[246:249], v145 offset:2048
	ds_read_b128 v[250:253], v145 offset:3072
	s_waitcnt vmcnt(0)
	s_barrier
	s_waitcnt lgkmcnt(0)
	s_setprio 1
	s_waitcnt lgkmcnt(0)
	v_mfma_f32_16x16x32_bf16 v[28:31], v[204:207], v[16:19], v[208:211]
	v_mfma_f32_16x16x32_bf16 v[16:19], v[246:249], v[16:19], v[164:167]
	v_mfma_f32_16x16x32_bf16 v[60:63], v[242:245], v[20:23], v[28:31]
	v_mfma_f32_16x16x32_bf16 v[28:31], v[250:253], v[20:23], v[16:19]
	v_mfma_f32_16x16x32_bf16 v[16:19], v[204:207], v[24:27], v[168:171]
	v_mfma_f32_16x16x32_bf16 v[56:59], v[242:245], v[48:51], v[16:19]
	v_mfma_f32_16x16x32_bf16 v[16:19], v[246:249], v[24:27], v[172:175]
	v_mfma_f32_16x16x32_bf16 v[24:27], v[250:253], v[48:51], v[16:19]
	v_mfma_f32_16x16x32_bf16 v[16:19], v[204:207], v[184:187], v[76:79]
	v_mfma_f32_16x16x32_bf16 v[52:55], v[242:245], v[188:191], v[16:19]
	v_mfma_f32_16x16x32_bf16 v[16:19], v[246:249], v[184:187], v[72:75]
	v_mfma_f32_16x16x32_bf16 v[20:23], v[250:253], v[188:191], v[16:19]
	v_mfma_f32_16x16x32_bf16 v[16:19], v[204:207], v[192:195], v[68:71]
	v_mfma_f32_16x16x32_bf16 v[48:51], v[242:245], v[200:203], v[16:19]
	v_mfma_f32_16x16x32_bf16 v[16:19], v[246:249], v[192:195], v[64:67]
	v_mfma_f32_16x16x32_bf16 v[16:19], v[250:253], v[200:203], v[16:19]
	s_setprio 0
	s_barrier
	ds_read_b128 v[164:167], v144 offset:49152
	ds_read_b128 v[144:147], v144 offset:50176
	ds_read_b128 v[168:171], v143 offset:49152
	ds_read_b128 v[172:175], v143 offset:50176
	ds_read_b128 v[184:187], v141 offset:49152
	ds_read_b128 v[188:191], v141 offset:50176
	ds_read_b128 v[192:195], v140 offset:49152
	ds_read_b128 v[200:203], v140 offset:50176
	s_barrier
	s_waitcnt lgkmcnt(0)
	s_setprio 1
	s_waitcnt lgkmcnt(0)
	v_mfma_f32_16x16x32_bf16 v[64:67], v[4:7], v[164:167], v[196:199]
	v_mfma_f32_16x16x32_bf16 v[108:111], v[8:11], v[144:147], v[64:67]
	v_mfma_f32_16x16x32_bf16 v[64:67], v[12:15], v[164:167], v[212:215]
	v_mfma_f32_16x16x32_bf16 v[76:79], v[152:155], v[144:147], v[64:67]
	v_mfma_f32_16x16x32_bf16 v[64:67], v[4:7], v[168:171], v[216:219]
	v_mfma_f32_16x16x32_bf16 v[44:47], v[4:7], v[184:187], v[44:47]
	v_mfma_f32_16x16x32_bf16 v[4:7], v[4:7], v[192:195], v[36:39]
	v_mfma_f32_16x16x32_bf16 v[104:107], v[8:11], v[172:175], v[64:67]
	v_mfma_f32_16x16x32_bf16 v[64:67], v[12:15], v[168:171], v[234:237]
	v_mfma_f32_16x16x32_bf16 v[40:43], v[12:15], v[184:187], v[40:43]
	v_mfma_f32_16x16x32_bf16 v[96:99], v[8:11], v[200:203], v[4:7]
	v_mfma_f32_16x16x32_bf16 v[4:7], v[12:15], v[192:195], v[32:35]
	v_mfma_f32_16x16x32_bf16 v[72:75], v[152:155], v[172:175], v[64:67]
	v_mfma_f32_16x16x32_bf16 v[100:103], v[8:11], v[188:191], v[44:47]
	v_mfma_f32_16x16x32_bf16 v[68:71], v[152:155], v[188:191], v[40:43]
	v_mfma_f32_16x16x32_bf16 v[64:67], v[152:155], v[200:203], v[4:7]
	s_setprio 0
	s_setprio 1
	v_mfma_f32_16x16x32_bf16 v[4:7], v[204:207], v[164:167], v[128:131]
	v_mfma_f32_16x16x32_bf16 v[44:47], v[242:245], v[144:147], v[4:7]
	v_mfma_f32_16x16x32_bf16 v[4:7], v[246:249], v[164:167], v[132:135]
	v_mfma_f32_16x16x32_bf16 v[12:15], v[250:253], v[144:147], v[4:7]
	v_mfma_f32_16x16x32_bf16 v[4:7], v[204:207], v[168:171], v[148:151]
	v_mfma_f32_16x16x32_bf16 v[40:43], v[242:245], v[172:175], v[4:7]
	v_mfma_f32_16x16x32_bf16 v[4:7], v[246:249], v[168:171], v[160:163]
	v_mfma_f32_16x16x32_bf16 v[8:11], v[250:253], v[172:175], v[4:7]
	v_mfma_f32_16x16x32_bf16 v[4:7], v[204:207], v[184:187], v[238:241]
	v_mfma_f32_16x16x32_bf16 v[36:39], v[242:245], v[188:191], v[4:7]
	v_mfma_f32_16x16x32_bf16 v[4:7], v[246:249], v[184:187], v[180:183]
	v_mfma_f32_16x16x32_bf16 v[32:35], v[204:207], v[192:195], v[156:159]
	v_mfma_f32_16x16x32_bf16 v[0:3], v[246:249], v[192:195], v[0:3]
	v_mfma_f32_16x16x32_bf16 v[4:7], v[250:253], v[188:191], v[4:7]
	v_mfma_f32_16x16x32_bf16 v[32:35], v[242:245], v[200:203], v[32:35]
	v_mfma_f32_16x16x32_bf16 v[0:3], v[250:253], v[200:203], v[0:3]
	s_setprio 0
	v_cmp_gt_u32_e32 vcc, s95, v142
	s_barrier
	s_and_saveexec_b64 s[6:7], vcc
	s_cbranch_execz .LBB0_1639
	s_barrier

; #define STAGE_A(P, half, kt) do { const char* _u = Ab + ((size_t)(half) * 128 * lda + (size_t)(kt) * BK) * 2; \
;     _Pragma("unroll") for (int _i = 0; _i < 2; ++_i) \
;       __builtin_amdgcn_global_load_lds((const unsigned*)(_u + offA[_i]), \
;         (__attribute__((address_space(3))) unsigned*)((__attribute__((address_space(3))) char*)(P) + tidg * 16 + _i * 8192), 16, 0, 0); } while (0)
; #define STAGE_B(P, half, kt) do { const char* _u = Bb + ((size_t)(half) * 128 * ldb + (size_t)(kt) * BK) * 2; \
;     _Pragma("unroll") for (int _i = 0; _i < 2; ++_i) \
;       __builtin_amdgcn_global_load_lds((const unsigned*)(_u + offB[_i]), \
;         (__attribute__((address_space(3))) unsigned*)((__attribute__((address_space(3))) char*)(P) + tidg * 16 + _i * 8192), 16, 0, 0); } while (0)
; #define WAIT_V(n) asm volatile("s_waitcnt vmcnt(" #n ")" ::: "memory")
; #define BAR __builtin_amdgcn_s_barrier()
; #define G_THREAD() do { asm volatile("" : "+v"(tidg)); wid = tidg >> 6; lane = tidg & 63; wr = wid >> 2; wc = wid & 3; fr = lane & 15; fq = lane >> 4; \
;     _Pragma("unroll") for (int _i = 0; _i < 2; ++_i) { int _r, _c; stage_rc(tidg * 16 + _i * 8192, _r, _c); offA[_i] = (unsigned)(_r * lda + _c) * 2u; offB[_i] = (unsigned)(_r * ldb + _c) * 2u; } } while (0)
; template <bool PF = true, class Epi, class KRF = KRFull>
; __device__ __forceinline__ void gemm_phase(const u16* __restrict__ A, int lda, const u16* __restrict__ Bt, int ldb, int K, int nM, int nN,
;                                            lds_u16* shm, Epi epi, KRF krf = KRFull(), bool flip = false) {
;     ...
;   int2 kr = krf(bcol, K);
;   int nt_next = kr.y;
;   const char* Ab = (const char*)A + (size_t)brow * lda * 2 + kr.x * (BK * 2);
;   const char* Bb = (const char*)Bt + (size_t)bcol * ldb * 2 + kr.x * (BK * 2);
;   __syncthreads();
;   STAGE_B(SB(0, 0), 0, 0); STAGE_A(SA(0, 0), 0, 0);
;   STAGE_B(SB(0, 1), 1, 0); STAGE_A(SA(0, 1), 1, 0);
;   for (;;) {
;     G_THREAD();
;     nt = nt_next;
;     f32x4 acc[2][2][4][2] = {};
;     bf16x8 At[4][2], B0[2][2], B1[2][2];
;     if (wr == 1) BAR;
;     WAIT_V(4); BAR;
;     STAGE_B(SB(1, 0), 0, 1); STAGE_A(SA(1, 0), 0, 1); STAGE_B(SB(1, 1), 1, 1);
;     WAIT_V(6); BAR;
.LBB0_2221:
	s_or_b64 exec, exec, s[16:17]
	v_bfe_i32 v2, v138, 27, 1
	v_lshlrev_b32_e32 v145, 4, v138
	v_lshrrev_b32_e32 v2, 22, v2
	v_add_u32_e32 v2, v145, v2
	v_and_b32_e32 v2, 0xfffffc00, v2
	v_sub_u32_e32 v2, v145, v2
	v_lshrrev_b32_e32 v3, 4, v2
	v_bitop3_b32 v2, v3, v2, 32 bitop3:0x6c
	v_ashrrev_i32_e32 v5, 31, v2
	v_ashrrev_i32_e32 v1, 31, v138
	v_lshrrev_b32_e32 v5, 26, v5
	v_lshrrev_b32_e32 v1, 26, v1
	v_add_u32_e32 v5, v2, v5
	v_add_u32_e32 v1, v138, v1
	v_ashrrev_i32_e32 v6, 6, v5
	v_and_b32_e32 v5, 0xc0, v5
	v_ashrrev_i32_e32 v4, 6, v1
	v_sub_u32_e32 v2, v2, v5
	v_lshlrev_b32_e32 v3, 3, v4
	v_lshlrev_b32_e32 v7, 5, v4
	v_ashrrev_i16_sdwa v2, v232, sext(v2) dst_sel:DWORD dst_unused:UNUSED_PAD src0_sel:DWORD src1_sel:BYTE_0
	v_and_b32_e32 v3, 0x3ffff0, v3
	v_and_b32_e32 v7, 32, v7
	v_bfe_i32 v5, v2, 0, 16
	v_add_u32_e32 v2, v7, v5
	v_add_lshl_u32 v3, v6, v3, 10
	v_add_u32_e32 v147, 0x2000, v145
	v_lshl_add_u32 v178, v2, 1, v3
	v_ashrrev_i32_e32 v2, 31, v147
	v_lshrrev_b32_e32 v2, 22, v2
	v_add_u32_e32 v2, v147, v2
	v_ashrrev_i32_e32 v7, 10, v2
	v_mul_i32_i24_e32 v2, 0x400, v7
	v_sub_u32_e32 v2, v147, v2
	v_lshrrev_b32_e32 v3, 4, v2
	v_bitop3_b32 v2, v3, v2, 32 bitop3:0x6c
	v_ashrrev_i32_e32 v8, 31, v2
	v_lshrrev_b32_e32 v8, 26, v8
	v_add_u32_e32 v8, v2, v8
	v_ashrrev_i32_e32 v9, 6, v8
	v_and_b32_e32 v8, 0xc0, v8
	v_sub_u32_e32 v2, v2, v8
	v_lshlrev_b32_e32 v3, 3, v7
	v_lshlrev_b32_e32 v10, 5, v7
	v_ashrrev_i16_sdwa v2, v232, sext(v2) dst_sel:DWORD dst_unused:UNUSED_PAD src0_sel:DWORD src1_sel:BYTE_0
	v_and_b32_e32 v3, 0x3ffff0, v3
	v_and_b32_e32 v10, 32, v10
	v_bfe_i32 v8, v2, 0, 16
	s_and_b64 s[2:3], s[26:27], exec
	v_add_u32_e32 v2, v10, v8
	v_add_lshl_u32 v3, v9, v3, 10
	v_add_u32_e32 v148, 0x18000, v145
	v_lshl_add_u32 v128, v2, 1, v3
	v_lshl_add_u64 v[2:3], s[12:13], 0, v[178:179]
	v_readfirstlane_b32 s3, v148
	v_lshl_add_u64 v[2:3], v[2:3], 0, s[60:61]
	s_mov_b32 m0, s3
	v_mov_b32_e32 v129, v179
	v_add_u32_e32 v149, 0x1a000, v145
	s_waitcnt vmcnt(4)
	s_barrier
	global_load_lds_dwordx4 v[2:3], off
	v_lshl_add_u64 v[2:3], s[12:13], 0, v[128:129]
	v_readfirstlane_b32 s3, v149
	v_lshl_add_u64 v[2:3], v[2:3], 0, s[60:61]
	s_mov_b32 m0, s3
	v_add_u32_e32 v150, 0x8000, v145
	global_load_lds_dwordx4 v[2:3], off
	v_lshl_add_u64 v[2:3], s[8:9], 0, v[178:179]
	v_readfirstlane_b32 s3, v150
	v_lshl_add_u64 v[2:3], v[2:3], 0, s[60:61]
	s_mov_b32 m0, s3
	v_add_u32_e32 v151, 0xa000, v145
	global_load_lds_dwordx4 v[2:3], off
	v_lshl_add_u64 v[2:3], s[8:9], 0, v[128:129]
	v_readfirstlane_b32 s3, v151
	v_add_u32_e32 v152, 0x1c000, v145
	s_cselect_b32 s2, 6, 4
	v_lshl_add_u64 v[2:3], v[2:3], 0, s[60:61]
	s_mov_b32 m0, s3
	s_add_u32 s16, s12, 0x20080
	v_readfirstlane_b32 s3, v152
	v_add_u32_e32 v153, 0x1e000, v145
	global_load_lds_dwordx4 v[2:3], off
	s_addc_u32 s17, s13, 0
	s_mov_b32 m0, s3
	v_readfirstlane_b32 s3, v153
	global_load_lds_dwordx4 v178, s[16:17]
	s_mov_b32 m0, s3
	v_and_b32_e32 v10, 15, v138
	global_load_lds_dwordx4 v128, s[16:17]
	v_lshlrev_b32_e32 v2, 6, v10
	v_lshlrev_b32_e32 v10, 2, v138
	v_and_b32_e32 v11, 48, v138
	v_and_b32_e32 v10, 32, v10
	v_or_b32_e32 v3, v2, v11
	v_bitop3_b32 v12, v2, v10, v11 bitop3:0x36
	s_mov_b32 s7, 0x14000
	v_lshlrev_b32_e32 v2, 6, v138
	v_bitop3_b32 v14, v3, s7, v10 bitop3:0xde
	s_mov_b32 s7, 0x18000
	v_lshlrev_b32_e32 v18, 13, v0
	v_and_b32_e32 v0, 0x3c0, v2
	v_bitop3_b32 v13, v3, s94, v10 bitop3:0xde
	v_bitop3_b32 v15, v3, s7, v10 bitop3:0xde
	v_bitop3_b32 v16, v3, s97, v10 bitop3:0xde
	v_and_b32_e32 v17, 0x3000, v2
	v_bitop3_b32 v10, v0, v10, v11 bitop3:0x36
	v_lshlrev_b32_e32 v0, 13, v4
	v_lshlrev_b32_e32 v2, 13, v7
	v_and_b32_e32 v0, 0xffffc000, v0
	v_and_b32_e32 v2, 0xffffc000, v2
	v_lshl_add_u32 v0, v6, 10, v0
	v_lshl_add_u32 v2, v9, 10, v2
	v_lshlrev_b32_e32 v3, 6, v7
	s_add_i32 s3, s2, -2
	v_and_or_b32 v0, v1, 64, v0
	v_and_or_b32 v2, v3, 64, v2
	v_lshl_add_u32 v0, v5, 1, v0
	v_mov_b32_e32 v1, v179
	v_lshl_add_u32 v2, v8, 1, v2
	v_mov_b32_e32 v3, v179
	s_add_u32 s7, s33, s18
	v_lshl_add_u64 v[130:131], s[12:13], 0, v[0:1]
	v_lshl_add_u64 v[132:133], s[12:13], 0, v[2:3]
	s_addc_u32 s13, s35, s19
	s_add_u32 s12, s4, s7
	s_waitcnt vmcnt(6)
	s_addc_u32 s13, s5, s13
	v_or_b32_e32 v11, 0x800, v18
	v_or_b32_e32 v19, 0x1000, v18
	v_or_b32_e32 v20, 0x1800, v18
	v_lshl_add_u64 v[134:135], s[12:13], 0, v[0:1]
	v_mov_b32_e32 v0, 0
	v_lshl_add_u64 v[136:137], s[12:13], 0, v[2:3]
	s_mov_b32 s7, 0
	s_mov_b64 s[12:13], 0
	v_add_u32_e32 v155, v13, v17
	v_add_u32_e32 v143, v12, v18
	v_add_u32_e32 v142, v10, v11
	v_add_u32_e32 v141, v10, v19
	v_add_u32_e32 v139, v10, v20
	v_add_u32_e32 v154, v14, v17
	v_add_u32_e32 v146, v15, v17
	v_add_u32_e32 v144, v16, v17
	v_mov_b32_e32 v1, v0
	v_mov_b32_e32 v2, v0
	v_mov_b32_e32 v3, v0
	v_mov_b32_e32 v4, v0
	v_mov_b32_e32 v5, v0
	v_mov_b32_e32 v6, v0
	v_mov_b32_e32 v7, v0
	v_mov_b32_e32 v8, v0
	v_mov_b32_e32 v9, v0
	v_mov_b32_e32 v10, v0
	v_mov_b32_e32 v11, v0
	v_mov_b32_e32 v12, v0
	v_mov_b32_e32 v13, v0
	v_mov_b32_e32 v14, v0
	v_mov_b32_e32 v15, v0
	v_mov_b32_e32 v16, v0
	v_mov_b32_e32 v17, v0
	v_mov_b32_e32 v18, v0
	v_mov_b32_e32 v19, v0
	v_mov_b32_e32 v20, v0
	v_mov_b32_e32 v21, v0
	v_mov_b32_e32 v22, v0
	v_mov_b32_e32 v23, v0
	v_mov_b32_e32 v24, v0
	v_mov_b32_e32 v25, v0
	v_mov_b32_e32 v26, v0
	v_mov_b32_e32 v27, v0
	v_mov_b32_e32 v28, v0
	v_mov_b32_e32 v29, v0
	v_mov_b32_e32 v30, v0
	v_mov_b32_e32 v31, v0
	v_mov_b32_e32 v32, v0
	v_mov_b32_e32 v33, v0
	v_mov_b32_e32 v34, v0
	v_mov_b32_e32 v35, v0
	v_mov_b32_e32 v36, v0
	v_mov_b32_e32 v37, v0
	v_mov_b32_e32 v38, v0
	v_mov_b32_e32 v39, v0
	v_mov_b32_e32 v40, v0
	v_mov_b32_e32 v41, v0
	v_mov_b32_e32 v42, v0
; #define STAGE_A(P, half, kt) do { const char* _u = Ab + ((size_t)(half) * 128 * lda + (size_t)(kt) * BK) * 2; \
;     _Pragma("unroll") for (int _i = 0; _i < 2; ++_i) \
;       __builtin_amdgcn_global_load_lds((const unsigned*)(_u + offA[_i]), \
;         (__attribute__((address_space(3))) unsigned*)((__attribute__((address_space(3))) char*)(P) + tidg * 16 + _i * 8192), 16, 0, 0); } while (0)
; #define STAGE_B(P, half, kt) do { const char* _u = Bb + ((size_t)(half) * 128 * ldb + (size_t)(kt) * BK) * 2; \
;     _Pragma("unroll") for (int _i = 0; _i < 2; ++_i) \
;       __builtin_amdgcn_global_load_lds((const unsigned*)(_u + offB[_i]), \
;         (__attribute__((address_space(3))) unsigned*)((__attribute__((address_space(3))) char*)(P) + tidg * 16 + _i * 8192), 16, 0, 0); } while (0)
; #define LDA(dst, b, h) _Pragma("unroll") for (int m = 0; m < 4; ++m) _Pragma("unroll") for (int k = 0; k < 2; ++k) \
;     dst[m][k] = *reinterpret_cast<const bf16x8*>((const char*)SA(b, h) + lds_byte(wr * 64 + m * 16 + fr, k * 32 + fq * 8))
; #define LDB(dst, b, h) _Pragma("unroll") for (int n = 0; n < 2; ++n) _Pragma("unroll") for (int k = 0; k < 2; ++k) \
;     dst[n][k] = *reinterpret_cast<const bf16x8*>((const char*)SB(b, h) + lds_byte(wc * 32 + n * 16 + fr, k * 32 + fq * 8))
; #define WAIT_L(n) asm volatile("s_waitcnt lgkmcnt(" #n ")" ::: "memory")
; #define BAR __builtin_amdgcn_s_barrier()
; #define SCHED __builtin_amdgcn_sched_barrier(0)
; template <bool PF = true, class Epi, class KRF = KRFull>
; __device__ __forceinline__ void gemm_phase(const u16* __restrict__ A, int lda, const u16* __restrict__ Bt, int ldb, int K, int nM, int nN,
;                                            lds_u16* shm, Epi epi, KRF krf = KRFull(), bool flip = false) {
;     ...
;     f32x4 acc[2][2][4][2] = {};
;     ...
;     for (int t = 0; t < nt - 2; t += 2) {
;       LDB(B0, 0, 0); SCHED; LDA(At, 0, 0); STAGE_A(SA(1, 1), 1, t + 1);
;       WAIT_L(8); BAR; WAIT_L(0); MMA(0, 0, At, B0); BAR; SCHED;
;       LDB(B1, 0, 1); STAGE_B(SB(0, 0), 0, t + 2);
;       BAR; WAIT_L(0); MMA(0, 1, At, B1); BAR;
;       LDA(At, 0, 1); STAGE_A(SA(0, 0), 0, t + 2);
;       BAR; WAIT_L(0); MMA(1, 0, At, B0); BAR; SCHED;
	v_mov_b32_e32 v43, v0
	v_mov_b32_e32 v44, v0
	v_mov_b32_e32 v45, v0
	v_mov_b32_e32 v46, v0
	v_mov_b32_e32 v47, v0
	v_mov_b32_e32 v48, v0
	v_mov_b32_e32 v49, v0
	v_mov_b32_e32 v50, v0
	v_mov_b32_e32 v51, v0
	v_mov_b32_e32 v52, v0
	v_mov_b32_e32 v53, v0
	v_mov_b32_e32 v54, v0
	v_mov_b32_e32 v55, v0
	v_mov_b32_e32 v56, v0
	v_mov_b32_e32 v57, v0
	v_mov_b32_e32 v58, v0
	v_mov_b32_e32 v59, v0
	v_mov_b32_e32 v60, v0
	v_mov_b32_e32 v61, v0
	v_mov_b32_e32 v62, v0
	v_mov_b32_e32 v63, v0
	v_mov_b32_e32 v64, v0
	v_mov_b32_e32 v65, v0
	v_mov_b32_e32 v66, v0
	v_mov_b32_e32 v67, v0
	v_mov_b32_e32 v68, v0
	v_mov_b32_e32 v69, v0
	v_mov_b32_e32 v70, v0
	v_mov_b32_e32 v71, v0
	v_mov_b32_e32 v72, v0
	v_mov_b32_e32 v73, v0
	v_mov_b32_e32 v74, v0
	v_mov_b32_e32 v75, v0
	v_mov_b32_e32 v76, v0
	v_mov_b32_e32 v77, v0
	v_mov_b32_e32 v78, v0
	v_mov_b32_e32 v79, v0
	v_mov_b32_e32 v80, v0
	v_mov_b32_e32 v81, v0
	v_mov_b32_e32 v82, v0
	v_mov_b32_e32 v83, v0
	v_mov_b32_e32 v84, v0
	v_mov_b32_e32 v85, v0
	v_mov_b32_e32 v86, v0
	v_mov_b32_e32 v87, v0
	v_mov_b32_e32 v88, v0
	v_mov_b32_e32 v89, v0
	v_mov_b32_e32 v90, v0
	v_mov_b32_e32 v91, v0
	v_mov_b32_e32 v92, v0
	v_mov_b32_e32 v93, v0
	v_mov_b32_e32 v94, v0
	v_mov_b32_e32 v95, v0
	v_mov_b32_e32 v96, v0
	v_mov_b32_e32 v97, v0
	v_mov_b32_e32 v98, v0
	v_mov_b32_e32 v99, v0
	v_mov_b32_e32 v100, v0
	v_mov_b32_e32 v101, v0
	v_mov_b32_e32 v102, v0
	v_mov_b32_e32 v103, v0
	v_mov_b32_e32 v104, v0
	v_mov_b32_e32 v105, v0
	v_mov_b32_e32 v106, v0
	v_mov_b32_e32 v107, v0
	v_mov_b32_e32 v108, v0
	v_mov_b32_e32 v109, v0
	v_mov_b32_e32 v110, v0
	v_mov_b32_e32 v111, v0
	v_mov_b32_e32 v112, v0
	v_mov_b32_e32 v113, v0
	v_mov_b32_e32 v114, v0
	v_mov_b32_e32 v115, v0
	v_mov_b32_e32 v116, v0
	v_mov_b32_e32 v117, v0
	v_mov_b32_e32 v118, v0
	v_mov_b32_e32 v119, v0
	v_mov_b32_e32 v120, v0
	v_mov_b32_e32 v121, v0
	v_mov_b32_e32 v122, v0
	v_mov_b32_e32 v123, v0
	v_mov_b32_e32 v124, v0
	v_mov_b32_e32 v125, v0
	v_mov_b32_e32 v126, v0
	v_mov_b32_e32 v127, v0
	s_barrier
	v_readfirstlane_b32 s16, v145
.LBB0_2222:
	ds_read_b128 v[158:161], v155
	ds_read_b128 v[162:165], v155 offset:1024
	ds_read_b128 v[166:169], v155 offset:2048
	ds_read_b128 v[170:173], v155 offset:3072
	v_lshl_add_u64 v[174:175], v[134:135], 0, s[12:13]
	v_lshl_add_u64 v[212:213], v[174:175], 0, s[82:83]
	s_add_u32 m0, s16, 0xc000
	v_lshl_add_u64 v[234:235], v[136:137], 0, s[12:13]
	ds_read_b128 v[180:183], v143
	ds_read_b128 v[184:187], v143 offset:1024
	ds_read_b128 v[188:191], v142
	ds_read_b128 v[192:195], v142 offset:1024
	ds_read_b128 v[196:199], v141
	ds_read_b128 v[200:203], v141 offset:1024
	ds_read_b128 v[204:207], v139
	ds_read_b128 v[208:211], v139 offset:1024
	global_load_lds_dwordx4 v[212:213], off
	v_lshl_add_u64 v[212:213], v[234:235], 0, s[82:83]
	s_add_u32 m0, s16, 0xe000
	s_nop 0
	global_load_lds_dwordx4 v[212:213], off
	s_waitcnt lgkmcnt(8)
	s_barrier
	s_waitcnt lgkmcnt(0)
	s_setprio 1
	s_waitcnt lgkmcnt(0)
	v_mfma_f32_16x16x32_bf16 v[124:127], v[158:161], v[180:183], v[124:127]
	v_mfma_f32_16x16x32_bf16 v[120:123], v[166:169], v[180:183], v[120:123]
	v_mfma_f32_16x16x32_bf16 v[116:119], v[158:161], v[188:191], v[116:119]
	v_mfma_f32_16x16x32_bf16 v[112:115], v[166:169], v[188:191], v[112:115]
	v_mfma_f32_16x16x32_bf16 v[108:111], v[158:161], v[196:199], v[108:111]
	v_mfma_f32_16x16x32_bf16 v[104:107], v[166:169], v[196:199], v[104:107]
	v_mfma_f32_16x16x32_bf16 v[100:103], v[158:161], v[204:207], v[100:103]
	v_mfma_f32_16x16x32_bf16 v[96:99], v[166:169], v[204:207], v[96:99]
	v_mfma_f32_16x16x32_bf16 v[124:127], v[162:165], v[184:187], v[124:127]
	v_mfma_f32_16x16x32_bf16 v[120:123], v[170:173], v[184:187], v[120:123]
	v_mfma_f32_16x16x32_bf16 v[116:119], v[162:165], v[192:195], v[116:119]
	v_mfma_f32_16x16x32_bf16 v[112:115], v[170:173], v[192:195], v[112:115]
	v_mfma_f32_16x16x32_bf16 v[108:111], v[162:165], v[200:203], v[108:111]
	v_mfma_f32_16x16x32_bf16 v[104:107], v[170:173], v[200:203], v[104:107]
	v_mfma_f32_16x16x32_bf16 v[100:103], v[162:165], v[208:211], v[100:103]
	v_mfma_f32_16x16x32_bf16 v[96:99], v[170:173], v[208:211], v[96:99]
	s_setprio 0
	s_barrier
	v_lshl_add_u64 v[236:237], v[130:131], 0, s[12:13]
	v_lshl_add_u64 v[238:239], v[236:237], 0, s[64:65]
	s_add_u32 m0, s16, 0x10000
	ds_read_b128 v[212:215], v154
	ds_read_b128 v[216:219], v154 offset:1024
	ds_read_b128 v[222:225], v154 offset:2048
	ds_read_b128 v[226:229], v154 offset:3072
	global_load_lds_dwordx4 v[238:239], off
	v_lshl_add_u64 v[238:239], v[132:133], 0, s[12:13]
	v_lshl_add_u64 v[240:241], v[238:239], 0, s[64:65]
	s_add_u32 m0, s16, 0x12000
	s_add_i32 s7, s7, 2
	global_load_lds_dwordx4 v[240:241], off
	s_barrier
	s_waitcnt lgkmcnt(0)
	s_setprio 1
	s_waitcnt lgkmcnt(0)
	v_mfma_f32_16x16x32_bf16 v[92:95], v[212:215], v[180:183], v[92:95]
	v_mfma_f32_16x16x32_bf16 v[88:91], v[222:225], v[180:183], v[88:91]
	v_mfma_f32_16x16x32_bf16 v[84:87], v[212:215], v[188:191], v[84:87]
	v_mfma_f32_16x16x32_bf16 v[80:83], v[222:225], v[188:191], v[80:83]
	v_mfma_f32_16x16x32_bf16 v[76:79], v[212:215], v[196:199], v[76:79]
	v_mfma_f32_16x16x32_bf16 v[72:75], v[222:225], v[196:199], v[72:75]
	v_mfma_f32_16x16x32_bf16 v[68:71], v[212:215], v[204:207], v[68:71]
	v_mfma_f32_16x16x32_bf16 v[64:67], v[222:225], v[204:207], v[64:67]
	v_mfma_f32_16x16x32_bf16 v[92:95], v[216:219], v[184:187], v[92:95]
	v_mfma_f32_16x16x32_bf16 v[88:91], v[226:229], v[184:187], v[88:91]
	v_mfma_f32_16x16x32_bf16 v[84:87], v[216:219], v[192:195], v[84:87]
	v_mfma_f32_16x16x32_bf16 v[80:83], v[226:229], v[192:195], v[80:83]
	v_mfma_f32_16x16x32_bf16 v[76:79], v[216:219], v[200:203], v[76:79]
	v_mfma_f32_16x16x32_bf16 v[72:75], v[226:229], v[200:203], v[72:75]
	v_mfma_f32_16x16x32_bf16 v[68:71], v[216:219], v[208:211], v[68:71]
	v_mfma_f32_16x16x32_bf16 v[64:67], v[226:229], v[208:211], v[64:67]
	s_setprio 0
	v_lshl_add_u64 v[240:241], v[174:175], 0, s[84:85]
	s_mov_b32 m0, s16
	s_barrier
; #define STAGE_A(P, half, kt) do { const char* _u = Ab + ((size_t)(half) * 128 * lda + (size_t)(kt) * BK) * 2; \
;     _Pragma("unroll") for (int _i = 0; _i < 2; ++_i) \
;       __builtin_amdgcn_global_load_lds((const unsigned*)(_u + offA[_i]), \
;         (__attribute__((address_space(3))) unsigned*)((__attribute__((address_space(3))) char*)(P) + tidg * 16 + _i * 8192), 16, 0, 0); } while (0)
; #define STAGE_B(P, half, kt) do { const char* _u = Bb + ((size_t)(half) * 128 * ldb + (size_t)(kt) * BK) * 2; \
;     _Pragma("unroll") for (int _i = 0; _i < 2; ++_i) \
;       __builtin_amdgcn_global_load_lds((const unsigned*)(_u + offB[_i]), \
;         (__attribute__((address_space(3))) unsigned*)((__attribute__((address_space(3))) char*)(P) + tidg * 16 + _i * 8192), 16, 0, 0); } while (0)
; #define LDA(dst, b, h) _Pragma("unroll") for (int m = 0; m < 4; ++m) _Pragma("unroll") for (int k = 0; k < 2; ++k) \
;     dst[m][k] = *reinterpret_cast<const bf16x8*>((const char*)SA(b, h) + lds_byte(wr * 64 + m * 16 + fr, k * 32 + fq * 8))
; #define LDB(dst, b, h) _Pragma("unroll") for (int n = 0; n < 2; ++n) _Pragma("unroll") for (int k = 0; k < 2; ++k) \
;     dst[n][k] = *reinterpret_cast<const bf16x8*>((const char*)SB(b, h) + lds_byte(wc * 32 + n * 16 + fr, k * 32 + fq * 8))
; #define WAIT_V(n) asm volatile("s_waitcnt vmcnt(" #n ")" ::: "memory")
; #define WAIT_L(n) asm volatile("s_waitcnt lgkmcnt(" #n ")" ::: "memory")
; #define BAR __builtin_amdgcn_s_barrier()
; #define SCHED __builtin_amdgcn_sched_barrier(0)
; template <bool PF = true, class Epi, class KRF = KRFull>
; __device__ __forceinline__ void gemm_phase(const u16* __restrict__ A, int lda, const u16* __restrict__ Bt, int ldb, int K, int nM, int nN,
;                                            lds_u16* shm, Epi epi, KRF krf = KRFull(), bool flip = false) {
;     ...
;       LDA(At, 0, 1); STAGE_A(SA(0, 0), 0, t + 2);
;       BAR; WAIT_L(0); MMA(1, 0, At, B0); BAR; SCHED;
;       STAGE_B(SB(0, 1), 1, t + 2);
;       WAIT_V(6); BAR; MMA(1, 1, At, B1); BAR;
;       LDB(B0, 1, 0); SCHED; LDA(At, 1, 0); STAGE_A(SA(0, 1), 1, t + 2);
;       WAIT_L(8); BAR; WAIT_L(0); MMA(0, 0, At, B0); BAR; SCHED;
;       LDB(B1, 1, 1); STAGE_B(SB(1, 0), 0, t + 3);
;       BAR; WAIT_L(0); MMA(0, 1, At, B1); BAR;
;       LDA(At, 1, 1); STAGE_A(SA(1, 0), 0, t + 3);
	ds_read_b128 v[180:183], v143 offset:16384
	ds_read_b128 v[184:187], v143 offset:17408
	ds_read_b128 v[188:191], v142 offset:16384
	ds_read_b128 v[192:195], v142 offset:17408
	ds_read_b128 v[196:199], v141 offset:16384
	ds_read_b128 v[200:203], v141 offset:17408
	ds_read_b128 v[204:207], v139 offset:16384
	ds_read_b128 v[208:211], v139 offset:17408
	global_load_lds_dwordx4 v[240:241], off
	v_lshl_add_u64 v[240:241], v[234:235], 0, s[84:85]
	s_add_u32 m0, s16, 0x2000
	s_nop 0
	global_load_lds_dwordx4 v[240:241], off
	s_barrier
	s_waitcnt lgkmcnt(0)
	s_setprio 1
	s_waitcnt lgkmcnt(0)
	v_mfma_f32_16x16x32_bf16 v[60:63], v[158:161], v[180:183], v[60:63]
	v_mfma_f32_16x16x32_bf16 v[56:59], v[166:169], v[180:183], v[56:59]
	v_mfma_f32_16x16x32_bf16 v[52:55], v[158:161], v[188:191], v[52:55]
	v_mfma_f32_16x16x32_bf16 v[48:51], v[166:169], v[188:191], v[48:51]
	v_mfma_f32_16x16x32_bf16 v[44:47], v[158:161], v[196:199], v[44:47]
	v_mfma_f32_16x16x32_bf16 v[40:43], v[166:169], v[196:199], v[40:43]
	v_mfma_f32_16x16x32_bf16 v[36:39], v[158:161], v[204:207], v[36:39]
	v_mfma_f32_16x16x32_bf16 v[32:35], v[166:169], v[204:207], v[32:35]
	v_mfma_f32_16x16x32_bf16 v[60:63], v[162:165], v[184:187], v[60:63]
	v_mfma_f32_16x16x32_bf16 v[56:59], v[170:173], v[184:187], v[56:59]
	v_mfma_f32_16x16x32_bf16 v[52:55], v[162:165], v[192:195], v[52:55]
	v_mfma_f32_16x16x32_bf16 v[48:51], v[170:173], v[192:195], v[48:51]
	v_mfma_f32_16x16x32_bf16 v[44:47], v[162:165], v[200:203], v[44:47]
	v_mfma_f32_16x16x32_bf16 v[40:43], v[170:173], v[200:203], v[40:43]
	v_mfma_f32_16x16x32_bf16 v[36:39], v[162:165], v[208:211], v[36:39]
	v_mfma_f32_16x16x32_bf16 v[32:35], v[170:173], v[208:211], v[32:35]
	s_setprio 0
	s_barrier
	v_lshl_add_u64 v[158:159], v[236:237], 0, s[86:87]
	s_add_u32 m0, s16, 0x14000
	s_nop 0
	global_load_lds_dwordx4 v[158:159], off
	v_lshl_add_u64 v[158:159], v[238:239], 0, s[86:87]
	s_add_u32 m0, s16, 0x16000
	s_nop 0
	global_load_lds_dwordx4 v[158:159], off
	s_waitcnt vmcnt(6)
	s_barrier
	s_setprio 1
	v_mfma_f32_16x16x32_bf16 v[28:31], v[212:215], v[180:183], v[28:31]
	v_mfma_f32_16x16x32_bf16 v[24:27], v[222:225], v[180:183], v[24:27]
	v_mfma_f32_16x16x32_bf16 v[20:23], v[212:215], v[188:191], v[20:23]
	v_mfma_f32_16x16x32_bf16 v[16:19], v[222:225], v[188:191], v[16:19]
	v_mfma_f32_16x16x32_bf16 v[12:15], v[212:215], v[196:199], v[12:15]
	v_mfma_f32_16x16x32_bf16 v[8:11], v[222:225], v[196:199], v[8:11]
	v_mfma_f32_16x16x32_bf16 v[4:7], v[212:215], v[204:207], v[4:7]
	v_mfma_f32_16x16x32_bf16 v[0:3], v[222:225], v[204:207], v[0:3]
	v_mfma_f32_16x16x32_bf16 v[28:31], v[216:219], v[184:187], v[28:31]
	v_mfma_f32_16x16x32_bf16 v[24:27], v[226:229], v[184:187], v[24:27]
	v_mfma_f32_16x16x32_bf16 v[20:23], v[216:219], v[192:195], v[20:23]
	v_mfma_f32_16x16x32_bf16 v[16:19], v[226:229], v[192:195], v[16:19]
	v_mfma_f32_16x16x32_bf16 v[12:15], v[216:219], v[200:203], v[12:15]
	v_mfma_f32_16x16x32_bf16 v[8:11], v[226:229], v[200:203], v[8:11]
	v_mfma_f32_16x16x32_bf16 v[4:7], v[216:219], v[208:211], v[4:7]
	v_mfma_f32_16x16x32_bf16 v[0:3], v[226:229], v[208:211], v[0:3]
	s_setprio 0
	s_barrier
	ds_read_b128 v[158:161], v146
	ds_read_b128 v[162:165], v146 offset:1024
	ds_read_b128 v[166:169], v146 offset:2048
	ds_read_b128 v[170:173], v146 offset:3072
	v_lshl_add_u64 v[212:213], v[174:175], 0, s[88:89]
	s_add_u32 m0, s16, 0x4000
	ds_read_b128 v[180:183], v143 offset:32768
	ds_read_b128 v[184:187], v143 offset:33792
	ds_read_b128 v[188:191], v142 offset:32768
	ds_read_b128 v[192:195], v142 offset:33792
	ds_read_b128 v[196:199], v141 offset:32768
	ds_read_b128 v[200:203], v141 offset:33792
	ds_read_b128 v[204:207], v139 offset:32768
	ds_read_b128 v[208:211], v139 offset:33792
	global_load_lds_dwordx4 v[212:213], off
	v_lshl_add_u64 v[212:213], v[234:235], 0, s[88:89]
	s_add_u32 m0, s16, 0x6000
	s_nop 0
	global_load_lds_dwordx4 v[212:213], off
	s_waitcnt lgkmcnt(8)
	s_barrier
	s_waitcnt lgkmcnt(0)
	s_setprio 1
	s_waitcnt lgkmcnt(0)
	v_mfma_f32_16x16x32_bf16 v[124:127], v[158:161], v[180:183], v[124:127]
	v_mfma_f32_16x16x32_bf16 v[120:123], v[166:169], v[180:183], v[120:123]
	v_mfma_f32_16x16x32_bf16 v[116:119], v[158:161], v[188:191], v[116:119]
	v_mfma_f32_16x16x32_bf16 v[112:115], v[166:169], v[188:191], v[112:115]
	v_mfma_f32_16x16x32_bf16 v[108:111], v[158:161], v[196:199], v[108:111]
	v_mfma_f32_16x16x32_bf16 v[104:107], v[166:169], v[196:199], v[104:107]
	v_mfma_f32_16x16x32_bf16 v[100:103], v[158:161], v[204:207], v[100:103]
	v_mfma_f32_16x16x32_bf16 v[96:99], v[166:169], v[204:207], v[96:99]
	v_mfma_f32_16x16x32_bf16 v[124:127], v[162:165], v[184:187], v[124:127]
	v_mfma_f32_16x16x32_bf16 v[120:123], v[170:173], v[184:187], v[120:123]
	v_mfma_f32_16x16x32_bf16 v[116:119], v[162:165], v[192:195], v[116:119]
	v_mfma_f32_16x16x32_bf16 v[112:115], v[170:173], v[192:195], v[112:115]
	v_mfma_f32_16x16x32_bf16 v[108:111], v[162:165], v[200:203], v[108:111]
	v_mfma_f32_16x16x32_bf16 v[104:107], v[170:173], v[200:203], v[104:107]
	v_mfma_f32_16x16x32_bf16 v[100:103], v[162:165], v[208:211], v[100:103]
	v_mfma_f32_16x16x32_bf16 v[96:99], v[170:173], v[208:211], v[96:99]
	s_setprio 0
	s_barrier
	v_lshl_add_u64 v[240:241], v[236:237], 0, s[68:69]
	s_add_u32 m0, s16, 0x18000
	ds_read_b128 v[212:215], v144
	ds_read_b128 v[216:219], v144 offset:1024
	ds_read_b128 v[222:225], v144 offset:2048
	ds_read_b128 v[226:229], v144 offset:3072
	global_load_lds_dwordx4 v[240:241], off
	v_lshl_add_u64 v[240:241], v[238:239], 0, s[68:69]
	s_add_u32 m0, s16, 0x1a000
	s_nop 0
	global_load_lds_dwordx4 v[240:241], off
	s_barrier
; #define STAGE_A(P, half, kt) do { const char* _u = Ab + ((size_t)(half) * 128 * lda + (size_t)(kt) * BK) * 2; \
;     _Pragma("unroll") for (int _i = 0; _i < 2; ++_i) \
;       __builtin_amdgcn_global_load_lds((const unsigned*)(_u + offA[_i]), \
;         (__attribute__((address_space(3))) unsigned*)((__attribute__((address_space(3))) char*)(P) + tidg * 16 + _i * 8192), 16, 0, 0); } while (0)
; #define STAGE_B(P, half, kt) do { const char* _u = Bb + ((size_t)(half) * 128 * ldb + (size_t)(kt) * BK) * 2; \
;     _Pragma("unroll") for (int _i = 0; _i < 2; ++_i) \
;       __builtin_amdgcn_global_load_lds((const unsigned*)(_u + offB[_i]), \
;         (__attribute__((address_space(3))) unsigned*)((__attribute__((address_space(3))) char*)(P) + tidg * 16 + _i * 8192), 16, 0, 0); } while (0)
; #define LDA(dst, b, h) _Pragma("unroll") for (int m = 0; m < 4; ++m) _Pragma("unroll") for (int k = 0; k < 2; ++k) \
;     dst[m][k] = *reinterpret_cast<const bf16x8*>((const char*)SA(b, h) + lds_byte(wr * 64 + m * 16 + fr, k * 32 + fq * 8))
; #define LDB(dst, b, h) _Pragma("unroll") for (int n = 0; n < 2; ++n) _Pragma("unroll") for (int k = 0; k < 2; ++k) \
;     dst[n][k] = *reinterpret_cast<const bf16x8*>((const char*)SB(b, h) + lds_byte(wc * 32 + n * 16 + fr, k * 32 + fq * 8))
; #define MMA(ai, bj, At_, Bt_) do { __builtin_amdgcn_s_setprio(1); \
;     _Pragma("unroll") for (int m = 0; m < 4; ++m) _Pragma("unroll") for (int n = 0; n < 2; ++n) _Pragma("unroll") for (int k = 0; k < 2; ++k) \
;       acc[ai][bj][m][n] = __builtin_amdgcn_mfma_f32_16x16x32_bf16(Bt_[n][k], At_[m][k], acc[ai][bj][m][n], 0, 0, 0); \
;     __builtin_amdgcn_s_setprio(0); } while (0)
; #define WAIT_V(n) asm volatile("s_waitcnt vmcnt(" #n ")" ::: "memory")
; #define WAIT_L(n) asm volatile("s_waitcnt lgkmcnt(" #n ")" ::: "memory")
; template <bool PF = true, class Epi, class KRF = KRFull>
; __device__ __forceinline__ void gemm_phase(const u16* __restrict__ A, int lda, const u16* __restrict__ Bt, int ldb, int K, int nM, int nN,
;                                            lds_u16* shm, Epi epi, KRF krf = KRFull(), bool flip = false) {
;     ...
;       LDA(At, 1, 1); STAGE_A(SA(1, 0), 0, t + 3);
;       BAR; WAIT_L(0); MMA(1, 0, At, B0); BAR; SCHED;
;       STAGE_B(SB(1, 1), 1, t + 3);
;       WAIT_V(6); BAR; MMA(1, 1, At, B1); BAR;
;     }
;     { LDB(B0, 0, 0); LDA(At, 0, 0); STAGE_A(SA(1, 1), 1, nt - 1);
	s_waitcnt lgkmcnt(0)
	s_setprio 1
	s_waitcnt lgkmcnt(0)
	v_mfma_f32_16x16x32_bf16 v[92:95], v[212:215], v[180:183], v[92:95]
	v_mfma_f32_16x16x32_bf16 v[88:91], v[222:225], v[180:183], v[88:91]
	v_mfma_f32_16x16x32_bf16 v[84:87], v[212:215], v[188:191], v[84:87]
	v_mfma_f32_16x16x32_bf16 v[80:83], v[222:225], v[188:191], v[80:83]
	v_mfma_f32_16x16x32_bf16 v[76:79], v[212:215], v[196:199], v[76:79]
	v_mfma_f32_16x16x32_bf16 v[72:75], v[222:225], v[196:199], v[72:75]
	v_mfma_f32_16x16x32_bf16 v[68:71], v[212:215], v[204:207], v[68:71]
	v_mfma_f32_16x16x32_bf16 v[64:67], v[222:225], v[204:207], v[64:67]
	v_mfma_f32_16x16x32_bf16 v[92:95], v[216:219], v[184:187], v[92:95]
	v_mfma_f32_16x16x32_bf16 v[88:91], v[226:229], v[184:187], v[88:91]
	v_mfma_f32_16x16x32_bf16 v[84:87], v[216:219], v[192:195], v[84:87]
	v_mfma_f32_16x16x32_bf16 v[80:83], v[226:229], v[192:195], v[80:83]
	v_mfma_f32_16x16x32_bf16 v[76:79], v[216:219], v[200:203], v[76:79]
	v_mfma_f32_16x16x32_bf16 v[72:75], v[226:229], v[200:203], v[72:75]
	v_mfma_f32_16x16x32_bf16 v[68:71], v[216:219], v[208:211], v[68:71]
	v_mfma_f32_16x16x32_bf16 v[64:67], v[226:229], v[208:211], v[64:67]
	s_setprio 0
	v_lshl_add_u64 v[174:175], v[174:175], 0, s[90:91]
	s_add_u32 m0, s16, 0x8000
	s_barrier
	ds_read_b128 v[180:183], v143 offset:49152
	ds_read_b128 v[184:187], v143 offset:50176
	ds_read_b128 v[188:191], v142 offset:49152
	ds_read_b128 v[192:195], v142 offset:50176
	ds_read_b128 v[196:199], v141 offset:49152
	ds_read_b128 v[200:203], v141 offset:50176
	ds_read_b128 v[204:207], v139 offset:49152
	ds_read_b128 v[208:211], v139 offset:50176
	global_load_lds_dwordx4 v[174:175], off
	v_lshl_add_u64 v[174:175], v[234:235], 0, s[90:91]
	s_add_u32 m0, s16, 0xa000
	s_nop 0
	global_load_lds_dwordx4 v[174:175], off
	s_barrier
	s_waitcnt lgkmcnt(0)
	s_setprio 1
	s_waitcnt lgkmcnt(0)
	v_mfma_f32_16x16x32_bf16 v[60:63], v[158:161], v[180:183], v[60:63]
	v_mfma_f32_16x16x32_bf16 v[56:59], v[166:169], v[180:183], v[56:59]
	v_mfma_f32_16x16x32_bf16 v[52:55], v[158:161], v[188:191], v[52:55]
	v_mfma_f32_16x16x32_bf16 v[48:51], v[166:169], v[188:191], v[48:51]
	v_mfma_f32_16x16x32_bf16 v[44:47], v[158:161], v[196:199], v[44:47]
	v_mfma_f32_16x16x32_bf16 v[40:43], v[166:169], v[196:199], v[40:43]
	v_mfma_f32_16x16x32_bf16 v[36:39], v[158:161], v[204:207], v[36:39]
	v_mfma_f32_16x16x32_bf16 v[32:35], v[166:169], v[204:207], v[32:35]
	v_mfma_f32_16x16x32_bf16 v[60:63], v[162:165], v[184:187], v[60:63]
	v_mfma_f32_16x16x32_bf16 v[56:59], v[170:173], v[184:187], v[56:59]
	v_mfma_f32_16x16x32_bf16 v[52:55], v[162:165], v[192:195], v[52:55]
	v_mfma_f32_16x16x32_bf16 v[48:51], v[170:173], v[192:195], v[48:51]
	v_mfma_f32_16x16x32_bf16 v[44:47], v[162:165], v[200:203], v[44:47]
	v_mfma_f32_16x16x32_bf16 v[40:43], v[170:173], v[200:203], v[40:43]
	v_mfma_f32_16x16x32_bf16 v[36:39], v[162:165], v[208:211], v[36:39]
	v_mfma_f32_16x16x32_bf16 v[32:35], v[170:173], v[208:211], v[32:35]
	s_setprio 0
	s_barrier
	v_lshl_add_u64 v[158:159], v[236:237], 0, s[92:93]
	s_add_u32 m0, s16, 0x1c000
	s_nop 0
	global_load_lds_dwordx4 v[158:159], off
	v_lshl_add_u64 v[158:159], v[238:239], 0, s[92:93]
	s_add_u32 m0, s16, 0x1e000
	s_nop 0
	global_load_lds_dwordx4 v[158:159], off
	s_waitcnt vmcnt(6)
	s_barrier
	s_setprio 1
	v_mfma_f32_16x16x32_bf16 v[28:31], v[212:215], v[180:183], v[28:31]
	v_mfma_f32_16x16x32_bf16 v[24:27], v[222:225], v[180:183], v[24:27]
	v_mfma_f32_16x16x32_bf16 v[20:23], v[212:215], v[188:191], v[20:23]
	v_mfma_f32_16x16x32_bf16 v[16:19], v[222:225], v[188:191], v[16:19]
	v_mfma_f32_16x16x32_bf16 v[12:15], v[212:215], v[196:199], v[12:15]
	v_mfma_f32_16x16x32_bf16 v[8:11], v[222:225], v[196:199], v[8:11]
	v_mfma_f32_16x16x32_bf16 v[4:7], v[212:215], v[204:207], v[4:7]
	v_mfma_f32_16x16x32_bf16 v[0:3], v[222:225], v[204:207], v[0:3]
	v_mfma_f32_16x16x32_bf16 v[28:31], v[216:219], v[184:187], v[28:31]
	v_mfma_f32_16x16x32_bf16 v[24:27], v[226:229], v[184:187], v[24:27]
	v_mfma_f32_16x16x32_bf16 v[20:23], v[216:219], v[192:195], v[20:23]
	v_mfma_f32_16x16x32_bf16 v[16:19], v[226:229], v[192:195], v[16:19]
	v_mfma_f32_16x16x32_bf16 v[12:15], v[216:219], v[200:203], v[12:15]
	v_mfma_f32_16x16x32_bf16 v[8:11], v[226:229], v[200:203], v[8:11]
	v_mfma_f32_16x16x32_bf16 v[4:7], v[216:219], v[208:211], v[4:7]
	v_mfma_f32_16x16x32_bf16 v[0:3], v[226:229], v[208:211], v[0:3]
	s_setprio 0
	s_add_u32 s12, s12, 0x100
	s_addc_u32 s13, s13, 0
	s_cmp_ge_u32 s7, s3
	s_barrier
	s_cbranch_scc0 .LBB0_2222
	v_add_u32_e32 v156, 0xc000, v145
	v_add_u32_e32 v157, 0xe000, v145
	v_add_u32_e32 v242, 0x12000, v145
	s_lshl_b32 s2, s2, 7
	s_add_u32 s2, s8, s2
	s_addc_u32 s3, s9, 0
	s_add_u32 s2, s2, 0x1ff80
	s_addc_u32 s3, s3, 0
	v_readfirstlane_b32 s7, v156
	v_lshl_add_u64 v[152:153], s[2:3], 0, v[178:179]
	s_mov_b32 m0, s7
	v_lshl_add_u64 v[128:129], s[2:3], 0, v[128:129]
	v_readfirstlane_b32 s2, v157
	ds_read_b128 v[130:133], v155
	ds_read_b128 v[134:137], v155 offset:1024
	ds_read_b128 v[148:151], v155 offset:2048
	ds_read_b128 v[158:161], v155 offset:3072
	ds_read_b128 v[162:165], v143
	ds_read_b128 v[166:169], v143 offset:1024
	ds_read_b128 v[170:173], v142
	ds_read_b128 v[180:183], v142 offset:1024
	ds_read_b128 v[184:187], v141
	ds_read_b128 v[188:191], v141 offset:1024
	ds_read_b128 v[192:195], v139
	ds_read_b128 v[196:199], v139 offset:1024
	global_load_lds_dwordx4 v[152:153], off
	s_mov_b32 m0, s2
	s_nop 0
	global_load_lds_dwordx4 v[128:129], off
	s_barrier
; #define STAGE_A(P, half, kt) do { const char* _u = Ab + ((size_t)(half) * 128 * lda + (size_t)(kt) * BK) * 2; \
;     _Pragma("unroll") for (int _i = 0; _i < 2; ++_i) \
;       __builtin_amdgcn_global_load_lds((const unsigned*)(_u + offA[_i]), \
;         (__attribute__((address_space(3))) unsigned*)((__attribute__((address_space(3))) char*)(P) + tidg * 16 + _i * 8192), 16, 0, 0); } while (0)
; #define LDA(dst, b, h) _Pragma("unroll") for (int m = 0; m < 4; ++m) _Pragma("unroll") for (int k = 0; k < 2; ++k) \
;     dst[m][k] = *reinterpret_cast<const bf16x8*>((const char*)SA(b, h) + lds_byte(wr * 64 + m * 16 + fr, k * 32 + fq * 8))
; #define LDB(dst, b, h) _Pragma("unroll") for (int n = 0; n < 2; ++n) _Pragma("unroll") for (int k = 0; k < 2; ++k) \
;     dst[n][k] = *reinterpret_cast<const bf16x8*>((const char*)SB(b, h) + lds_byte(wc * 32 + n * 16 + fr, k * 32 + fq * 8))
; #define MMA(ai, bj, At_, Bt_) do { __builtin_amdgcn_s_setprio(1); \
;     _Pragma("unroll") for (int m = 0; m < 4; ++m) _Pragma("unroll") for (int n = 0; n < 2; ++n) _Pragma("unroll") for (int k = 0; k < 2; ++k) \
;       acc[ai][bj][m][n] = __builtin_amdgcn_mfma_f32_16x16x32_bf16(Bt_[n][k], At_[m][k], acc[ai][bj][m][n], 0, 0, 0); \
;     __builtin_amdgcn_s_setprio(0); } while (0)
; #define WAIT_V(n) asm volatile("s_waitcnt vmcnt(" #n ")" ::: "memory")
; #define WAIT_L(n) asm volatile("s_waitcnt lgkmcnt(" #n ")" ::: "memory")
; #define BAR __builtin_amdgcn_s_barrier()
; template <bool PF = true, class Epi, class KRF = KRFull>
; __device__ __forceinline__ void gemm_phase(const u16* __restrict__ A, int lda, const u16* __restrict__ Bt, int ldb, int K, int nM, int nN,
;                                            lds_u16* shm, Epi epi, KRF krf = KRFull(), bool flip = false) {
;     ...
;     { LDB(B0, 0, 0); LDA(At, 0, 0); STAGE_A(SA(1, 1), 1, nt - 1);
;       BAR; WAIT_L(0); MMA(0, 0, At, B0); BAR;
;       LDB(B1, 0, 1); BAR; WAIT_L(0); MMA(0, 1, At, B1); BAR;
;       LDA(At, 0, 1); WAIT_V(4); BAR; WAIT_L(0); MMA(1, 0, At, B0); MMA(1, 1, At, B1); BAR; }
;     { LDB(B0, 1, 0); LDA(At, 1, 0); WAIT_V(2); BAR; WAIT_L(0); MMA(0, 0, At, B0); BAR;
	s_waitcnt lgkmcnt(0)
	s_setprio 1
	s_waitcnt lgkmcnt(0)
	v_mfma_f32_16x16x32_bf16 v[124:127], v[130:133], v[162:165], v[124:127]
	v_mfma_f32_16x16x32_bf16 v[120:123], v[148:151], v[162:165], v[120:123]
	v_mfma_f32_16x16x32_bf16 v[116:119], v[130:133], v[170:173], v[116:119]
	v_mfma_f32_16x16x32_bf16 v[112:115], v[148:151], v[170:173], v[112:115]
	v_mfma_f32_16x16x32_bf16 v[108:111], v[130:133], v[184:187], v[108:111]
	v_mfma_f32_16x16x32_bf16 v[104:107], v[148:151], v[184:187], v[104:107]
	v_mfma_f32_16x16x32_bf16 v[100:103], v[130:133], v[192:195], v[100:103]
	v_mfma_f32_16x16x32_bf16 v[96:99], v[148:151], v[192:195], v[96:99]
	v_mfma_f32_16x16x32_bf16 v[124:127], v[134:137], v[166:169], v[124:127]
	v_mfma_f32_16x16x32_bf16 v[120:123], v[158:161], v[166:169], v[120:123]
	v_mfma_f32_16x16x32_bf16 v[116:119], v[134:137], v[180:183], v[116:119]
	v_mfma_f32_16x16x32_bf16 v[112:115], v[158:161], v[180:183], v[112:115]
	v_mfma_f32_16x16x32_bf16 v[108:111], v[134:137], v[188:191], v[108:111]
	v_mfma_f32_16x16x32_bf16 v[104:107], v[158:161], v[188:191], v[104:107]
	v_mfma_f32_16x16x32_bf16 v[100:103], v[134:137], v[196:199], v[100:103]
	v_mfma_f32_16x16x32_bf16 v[96:99], v[158:161], v[196:199], v[96:99]
	s_setprio 0
	s_barrier
	ds_read_b128 v[200:203], v154
	ds_read_b128 v[204:207], v154 offset:1024
	ds_read_b128 v[208:211], v154 offset:2048
	ds_read_b128 v[152:155], v154 offset:3072
	s_barrier
	s_waitcnt lgkmcnt(0)
	s_setprio 1
	s_waitcnt lgkmcnt(0)
	v_mfma_f32_16x16x32_bf16 v[92:95], v[200:203], v[162:165], v[92:95]
	v_mfma_f32_16x16x32_bf16 v[88:91], v[208:211], v[162:165], v[88:91]
	v_mfma_f32_16x16x32_bf16 v[84:87], v[200:203], v[170:173], v[84:87]
	v_mfma_f32_16x16x32_bf16 v[80:83], v[208:211], v[170:173], v[80:83]
	v_mfma_f32_16x16x32_bf16 v[76:79], v[200:203], v[184:187], v[76:79]
	v_mfma_f32_16x16x32_bf16 v[72:75], v[208:211], v[184:187], v[72:75]
	v_mfma_f32_16x16x32_bf16 v[68:71], v[200:203], v[192:195], v[68:71]
	v_mfma_f32_16x16x32_bf16 v[64:67], v[208:211], v[192:195], v[64:67]
	v_mfma_f32_16x16x32_bf16 v[92:95], v[204:207], v[166:169], v[92:95]
	v_mfma_f32_16x16x32_bf16 v[88:91], v[152:155], v[166:169], v[88:91]
	v_mfma_f32_16x16x32_bf16 v[84:87], v[204:207], v[180:183], v[84:87]
	v_mfma_f32_16x16x32_bf16 v[80:83], v[152:155], v[180:183], v[80:83]
	v_mfma_f32_16x16x32_bf16 v[76:79], v[204:207], v[188:191], v[76:79]
	v_mfma_f32_16x16x32_bf16 v[72:75], v[152:155], v[188:191], v[72:75]
	v_mfma_f32_16x16x32_bf16 v[68:71], v[204:207], v[196:199], v[68:71]
	v_mfma_f32_16x16x32_bf16 v[64:67], v[152:155], v[196:199], v[64:67]
	s_setprio 0
	s_barrier
	ds_read_b128 v[162:165], v143 offset:16384
	ds_read_b128 v[166:169], v143 offset:17408
	ds_read_b128 v[170:173], v142 offset:16384
	ds_read_b128 v[180:183], v142 offset:17408
	ds_read_b128 v[184:187], v141 offset:16384
	ds_read_b128 v[188:191], v141 offset:17408
	ds_read_b128 v[192:195], v139 offset:16384
	ds_read_b128 v[196:199], v139 offset:17408
	s_waitcnt vmcnt(4)
	s_barrier
	s_waitcnt lgkmcnt(0)
	s_setprio 1
	s_waitcnt lgkmcnt(0)
	v_mfma_f32_16x16x32_bf16 v[60:63], v[130:133], v[162:165], v[60:63]
	v_mfma_f32_16x16x32_bf16 v[56:59], v[148:151], v[162:165], v[56:59]
	v_mfma_f32_16x16x32_bf16 v[52:55], v[130:133], v[170:173], v[52:55]
	v_mfma_f32_16x16x32_bf16 v[48:51], v[148:151], v[170:173], v[48:51]
	v_mfma_f32_16x16x32_bf16 v[44:47], v[130:133], v[184:187], v[44:47]
	v_mfma_f32_16x16x32_bf16 v[40:43], v[148:151], v[184:187], v[40:43]
	v_mfma_f32_16x16x32_bf16 v[36:39], v[130:133], v[192:195], v[36:39]
	v_mfma_f32_16x16x32_bf16 v[32:35], v[148:151], v[192:195], v[32:35]
	v_mfma_f32_16x16x32_bf16 v[212:215], v[134:137], v[166:169], v[60:63]
	v_mfma_f32_16x16x32_bf16 v[216:219], v[158:161], v[166:169], v[56:59]
	v_mfma_f32_16x16x32_bf16 v[222:225], v[134:137], v[180:183], v[52:55]
	v_mfma_f32_16x16x32_bf16 v[226:229], v[158:161], v[180:183], v[48:51]
	v_mfma_f32_16x16x32_bf16 v[234:237], v[134:137], v[188:191], v[44:47]
	v_mfma_f32_16x16x32_bf16 v[238:241], v[158:161], v[188:191], v[40:43]
	v_mfma_f32_16x16x32_bf16 v[128:131], v[134:137], v[196:199], v[36:39]
	v_mfma_f32_16x16x32_bf16 v[132:135], v[158:161], v[196:199], v[32:35]
	s_setprio 0
	s_setprio 1
	v_mfma_f32_16x16x32_bf16 v[28:31], v[200:203], v[162:165], v[28:31]
	v_mfma_f32_16x16x32_bf16 v[24:27], v[208:211], v[162:165], v[24:27]
	v_mfma_f32_16x16x32_bf16 v[20:23], v[200:203], v[170:173], v[20:23]
	v_mfma_f32_16x16x32_bf16 v[16:19], v[208:211], v[170:173], v[16:19]
	v_mfma_f32_16x16x32_bf16 v[12:15], v[200:203], v[184:187], v[12:15]
	v_mfma_f32_16x16x32_bf16 v[8:11], v[208:211], v[184:187], v[8:11]
	v_mfma_f32_16x16x32_bf16 v[4:7], v[200:203], v[192:195], v[4:7]
	v_mfma_f32_16x16x32_bf16 v[0:3], v[208:211], v[192:195], v[0:3]
	v_mfma_f32_16x16x32_bf16 v[28:31], v[204:207], v[166:169], v[28:31]
	v_mfma_f32_16x16x32_bf16 v[24:27], v[152:155], v[166:169], v[24:27]
	v_mfma_f32_16x16x32_bf16 v[20:23], v[204:207], v[180:183], v[20:23]
	v_mfma_f32_16x16x32_bf16 v[16:19], v[152:155], v[180:183], v[16:19]
	v_mfma_f32_16x16x32_bf16 v[12:15], v[204:207], v[188:191], v[12:15]
	v_mfma_f32_16x16x32_bf16 v[8:11], v[152:155], v[188:191], v[8:11]
	v_mfma_f32_16x16x32_bf16 v[4:7], v[204:207], v[196:199], v[4:7]
	v_mfma_f32_16x16x32_bf16 v[0:3], v[152:155], v[196:199], v[0:3]
	s_setprio 0
	s_barrier
	ds_read_b128 v[148:151], v146
	ds_read_b128 v[152:155], v146 offset:1024
	ds_read_b128 v[156:159], v146 offset:2048
	ds_read_b128 v[160:163], v146 offset:3072
	ds_read_b128 v[32:35], v143 offset:32768
	ds_read_b128 v[36:39], v143 offset:33792
	ds_read_b128 v[40:43], v142 offset:32768
	ds_read_b128 v[44:47], v142 offset:33792
	ds_read_b128 v[164:167], v141 offset:32768
	ds_read_b128 v[168:171], v141 offset:33792
	ds_read_b128 v[172:175], v139 offset:32768
	ds_read_b128 v[180:183], v139 offset:33792
	s_waitcnt vmcnt(2)
	s_barrier
; #define LDA(dst, b, h) _Pragma("unroll") for (int m = 0; m < 4; ++m) _Pragma("unroll") for (int k = 0; k < 2; ++k) \
;     dst[m][k] = *reinterpret_cast<const bf16x8*>((const char*)SA(b, h) + lds_byte(wr * 64 + m * 16 + fr, k * 32 + fq * 8))
; #define LDB(dst, b, h) _Pragma("unroll") for (int n = 0; n < 2; ++n) _Pragma("unroll") for (int k = 0; k < 2; ++k) \
;     dst[n][k] = *reinterpret_cast<const bf16x8*>((const char*)SB(b, h) + lds_byte(wc * 32 + n * 16 + fr, k * 32 + fq * 8))
; #define MMA(ai, bj, At_, Bt_) do { __builtin_amdgcn_s_setprio(1); \
;     _Pragma("unroll") for (int m = 0; m < 4; ++m) _Pragma("unroll") for (int n = 0; n < 2; ++n) _Pragma("unroll") for (int k = 0; k < 2; ++k) \
;       acc[ai][bj][m][n] = __builtin_amdgcn_mfma_f32_16x16x32_bf16(Bt_[n][k], At_[m][k], acc[ai][bj][m][n], 0, 0, 0); \
;     __builtin_amdgcn_s_setprio(0); } while (0)
; #define WAIT_V(n) asm volatile("s_waitcnt vmcnt(" #n ")" ::: "memory")
; #define WAIT_L(n) asm volatile("s_waitcnt lgkmcnt(" #n ")" ::: "memory")
; #define BAR __builtin_amdgcn_s_barrier()
; template <bool PF = true, class Epi, class KRF = KRFull>
; __device__ __forceinline__ void gemm_phase(const u16* __restrict__ A, int lda, const u16* __restrict__ Bt, int ldb, int K, int nM, int nN,
;                                            lds_u16* shm, Epi epi, KRF krf = KRFull(), bool flip = false) {
;     ...
;     { LDB(B0, 1, 0); LDA(At, 1, 0); WAIT_V(2); BAR; WAIT_L(0); MMA(0, 0, At, B0); BAR;
;       LDB(B1, 1, 1); WAIT_V(0); BAR; WAIT_L(0); MMA(0, 1, At, B1); BAR;
;       LDA(At, 1, 1); BAR; WAIT_L(0); MMA(1, 0, At, B0); MMA(1, 1, At, B1); BAR; }
;     if (wr == 0) BAR;
	s_waitcnt lgkmcnt(0)
	s_setprio 1
	s_waitcnt lgkmcnt(0)
	v_mfma_f32_16x16x32_bf16 v[48:51], v[148:151], v[32:35], v[124:127]
	v_mfma_f32_16x16x32_bf16 v[124:127], v[152:155], v[36:39], v[48:51]
	v_mfma_f32_16x16x32_bf16 v[48:51], v[156:159], v[32:35], v[120:123]
	v_mfma_f32_16x16x32_bf16 v[120:123], v[160:163], v[36:39], v[48:51]
	v_mfma_f32_16x16x32_bf16 v[48:51], v[148:151], v[40:43], v[116:119]
	v_mfma_f32_16x16x32_bf16 v[116:119], v[152:155], v[44:47], v[48:51]
	v_mfma_f32_16x16x32_bf16 v[48:51], v[156:159], v[40:43], v[112:115]
	v_mfma_f32_16x16x32_bf16 v[112:115], v[160:163], v[44:47], v[48:51]
	v_mfma_f32_16x16x32_bf16 v[48:51], v[148:151], v[164:167], v[108:111]
	v_mfma_f32_16x16x32_bf16 v[108:111], v[152:155], v[168:171], v[48:51]
	v_mfma_f32_16x16x32_bf16 v[48:51], v[156:159], v[164:167], v[104:107]
	v_mfma_f32_16x16x32_bf16 v[104:107], v[160:163], v[168:171], v[48:51]
	v_mfma_f32_16x16x32_bf16 v[48:51], v[148:151], v[172:175], v[100:103]
	v_mfma_f32_16x16x32_bf16 v[100:103], v[152:155], v[180:183], v[48:51]
	v_mfma_f32_16x16x32_bf16 v[48:51], v[156:159], v[172:175], v[96:99]
	v_mfma_f32_16x16x32_bf16 v[96:99], v[160:163], v[180:183], v[48:51]
	s_setprio 0
	s_barrier
	ds_read_b128 v[184:187], v144
	ds_read_b128 v[188:191], v144 offset:1024
	ds_read_b128 v[192:195], v144 offset:2048
	ds_read_b128 v[144:147], v144 offset:3072
	s_waitcnt vmcnt(0)
	s_barrier
	s_waitcnt lgkmcnt(0)
	s_setprio 1
	s_waitcnt lgkmcnt(0)
	v_mfma_f32_16x16x32_bf16 v[48:51], v[184:187], v[32:35], v[92:95]
	v_mfma_f32_16x16x32_bf16 v[32:35], v[192:195], v[32:35], v[88:91]
	v_mfma_f32_16x16x32_bf16 v[56:59], v[144:147], v[36:39], v[32:35]
	v_mfma_f32_16x16x32_bf16 v[32:35], v[184:187], v[40:43], v[84:87]
	v_mfma_f32_16x16x32_bf16 v[52:55], v[188:191], v[44:47], v[32:35]
	v_mfma_f32_16x16x32_bf16 v[32:35], v[192:195], v[40:43], v[80:83]
	v_mfma_f32_16x16x32_bf16 v[60:63], v[188:191], v[36:39], v[48:51]
	v_mfma_f32_16x16x32_bf16 v[48:51], v[144:147], v[44:47], v[32:35]
	v_mfma_f32_16x16x32_bf16 v[32:35], v[184:187], v[164:167], v[76:79]
	v_mfma_f32_16x16x32_bf16 v[44:47], v[188:191], v[168:171], v[32:35]
	v_mfma_f32_16x16x32_bf16 v[32:35], v[192:195], v[164:167], v[72:75]
	v_mfma_f32_16x16x32_bf16 v[40:43], v[144:147], v[168:171], v[32:35]
	v_mfma_f32_16x16x32_bf16 v[32:35], v[184:187], v[172:175], v[68:71]
	v_mfma_f32_16x16x32_bf16 v[36:39], v[188:191], v[180:183], v[32:35]
	v_mfma_f32_16x16x32_bf16 v[32:35], v[192:195], v[172:175], v[64:67]
	v_mfma_f32_16x16x32_bf16 v[32:35], v[144:147], v[180:183], v[32:35]
	s_setprio 0
	s_barrier
	ds_read_b128 v[164:167], v143 offset:49152
	ds_read_b128 v[168:171], v143 offset:50176
	ds_read_b128 v[172:175], v142 offset:49152
	ds_read_b128 v[180:183], v142 offset:50176
	ds_read_b128 v[196:199], v141 offset:49152
	ds_read_b128 v[200:203], v141 offset:50176
	ds_read_b128 v[204:207], v139 offset:49152
	ds_read_b128 v[208:211], v139 offset:50176
	s_barrier
	s_waitcnt lgkmcnt(0)
	s_setprio 1
	s_waitcnt lgkmcnt(0)
	v_mfma_f32_16x16x32_bf16 v[64:67], v[148:151], v[164:167], v[212:215]
	v_mfma_f32_16x16x32_bf16 v[92:95], v[152:155], v[168:171], v[64:67]
	v_mfma_f32_16x16x32_bf16 v[64:67], v[156:159], v[164:167], v[216:219]
	v_mfma_f32_16x16x32_bf16 v[88:91], v[160:163], v[168:171], v[64:67]
	v_mfma_f32_16x16x32_bf16 v[64:67], v[148:151], v[172:175], v[222:225]
	v_mfma_f32_16x16x32_bf16 v[84:87], v[152:155], v[180:183], v[64:67]
	v_mfma_f32_16x16x32_bf16 v[64:67], v[156:159], v[172:175], v[226:229]
	v_mfma_f32_16x16x32_bf16 v[80:83], v[160:163], v[180:183], v[64:67]
	v_mfma_f32_16x16x32_bf16 v[64:67], v[148:151], v[196:199], v[234:237]
	v_mfma_f32_16x16x32_bf16 v[76:79], v[152:155], v[200:203], v[64:67]
	v_mfma_f32_16x16x32_bf16 v[64:67], v[156:159], v[196:199], v[238:241]
	v_mfma_f32_16x16x32_bf16 v[72:75], v[160:163], v[200:203], v[64:67]
	v_mfma_f32_16x16x32_bf16 v[64:67], v[148:151], v[204:207], v[128:131]
	v_mfma_f32_16x16x32_bf16 v[68:71], v[152:155], v[208:211], v[64:67]
	v_mfma_f32_16x16x32_bf16 v[64:67], v[156:159], v[204:207], v[132:135]
	v_mfma_f32_16x16x32_bf16 v[64:67], v[160:163], v[208:211], v[64:67]
	s_setprio 0
	s_setprio 1
	v_mfma_f32_16x16x32_bf16 v[28:31], v[184:187], v[164:167], v[28:31]
	v_mfma_f32_16x16x32_bf16 v[24:27], v[192:195], v[164:167], v[24:27]
	v_mfma_f32_16x16x32_bf16 v[20:23], v[184:187], v[172:175], v[20:23]
	v_mfma_f32_16x16x32_bf16 v[16:19], v[192:195], v[172:175], v[16:19]
	v_mfma_f32_16x16x32_bf16 v[12:15], v[184:187], v[196:199], v[12:15]
	v_mfma_f32_16x16x32_bf16 v[8:11], v[192:195], v[196:199], v[8:11]
	v_mfma_f32_16x16x32_bf16 v[4:7], v[184:187], v[204:207], v[4:7]
	v_mfma_f32_16x16x32_bf16 v[0:3], v[192:195], v[204:207], v[0:3]
	v_mfma_f32_16x16x32_bf16 v[28:31], v[188:191], v[168:171], v[28:31]
	v_mfma_f32_16x16x32_bf16 v[24:27], v[144:147], v[168:171], v[24:27]
	v_mfma_f32_16x16x32_bf16 v[20:23], v[188:191], v[180:183], v[20:23]
	v_mfma_f32_16x16x32_bf16 v[16:19], v[144:147], v[180:183], v[16:19]
	v_mfma_f32_16x16x32_bf16 v[12:15], v[188:191], v[200:203], v[12:15]
	v_mfma_f32_16x16x32_bf16 v[8:11], v[144:147], v[200:203], v[8:11]
	v_mfma_f32_16x16x32_bf16 v[4:7], v[188:191], v[208:211], v[4:7]
	v_mfma_f32_16x16x32_bf16 v[0:3], v[144:147], v[208:211], v[0:3]
	s_setprio 0
	v_cmp_gt_u32_e32 vcc, s95, v138
	s_barrier
	s_and_saveexec_b64 s[8:9], vcc
	s_cbranch_execz .LBB0_2225
	s_barrier

; #define STAGE_A(P, half, kt) do { const char* _u = Ab + ((size_t)(half) * 128 * lda + (size_t)(kt) * BK) * 2; \
;     _Pragma("unroll") for (int _i = 0; _i < 2; ++_i) \
;       __builtin_amdgcn_global_load_lds((const unsigned*)(_u + offA[_i]), \
;         (__attribute__((address_space(3))) unsigned*)((__attribute__((address_space(3))) char*)(P) + tidg * 16 + _i * 8192), 16, 0, 0); } while (0)
; #define STAGE_B(P, half, kt) do { const char* _u = Bb + ((size_t)(half) * 128 * ldb + (size_t)(kt) * BK) * 2; \
;     _Pragma("unroll") for (int _i = 0; _i < 2; ++_i) \
;       __builtin_amdgcn_global_load_lds((const unsigned*)(_u + offB[_i]), \
;         (__attribute__((address_space(3))) unsigned*)((__attribute__((address_space(3))) char*)(P) + tidg * 16 + _i * 8192), 16, 0, 0); } while (0)
; #define WAIT_V(n) asm volatile("s_waitcnt vmcnt(" #n ")" ::: "memory")
; #define BAR __builtin_amdgcn_s_barrier()
; #define G_THREAD() do { asm volatile("" : "+v"(tidg)); wid = tidg >> 6; lane = tidg & 63; wr = wid >> 2; wc = wid & 3; fr = lane & 15; fq = lane >> 4; \
;     _Pragma("unroll") for (int _i = 0; _i < 2; ++_i) { int _r, _c; stage_rc(tidg * 16 + _i * 8192, _r, _c); offA[_i] = (unsigned)(_r * lda + _c) * 2u; offB[_i] = (unsigned)(_r * ldb + _c) * 2u; } } while (0)
; template <bool PF = true, class Epi, class KRF = KRFull>
; __device__ __forceinline__ void gemm_phase(const u16* __restrict__ A, int lda, const u16* __restrict__ Bt, int ldb, int K, int nM, int nN,
;                                            lds_u16* shm, Epi epi, KRF krf = KRFull(), bool flip = false) {
;     ...
;     G_THREAD();
;     nt = nt_next;
;     f32x4 acc[2][2][4][2] = {};
;     bf16x8 At[4][2], B0[2][2], B1[2][2];
;     if (wr == 1) BAR;
;     WAIT_V(4); BAR;
;     STAGE_B(SB(1, 0), 0, 1); STAGE_A(SA(1, 0), 0, 1); STAGE_B(SB(1, 1), 1, 1);
;     WAIT_V(6); BAR;
.LBB0_2499:
	s_or_b64 exec, exec, s[16:17]
	v_bfe_i32 v2, v138, 27, 1
	v_lshlrev_b32_e32 v144, 4, v138
	v_lshrrev_b32_e32 v2, 22, v2
	v_add_u32_e32 v2, v144, v2
	v_and_b32_e32 v2, 0xfffffc00, v2
	v_sub_u32_e32 v2, v144, v2
	v_lshrrev_b32_e32 v3, 4, v2
	v_bitop3_b32 v2, v3, v2, 32 bitop3:0x6c
	v_ashrrev_i32_e32 v5, 31, v2
	v_ashrrev_i32_e32 v1, 31, v138
	v_lshrrev_b32_e32 v5, 26, v5
	v_lshrrev_b32_e32 v1, 26, v1
	v_add_u32_e32 v5, v2, v5
	v_add_u32_e32 v1, v138, v1
	v_ashrrev_i32_e32 v6, 6, v5
	v_and_b32_e32 v5, 0xc0, v5
	v_ashrrev_i32_e32 v4, 6, v1
	v_sub_u32_e32 v2, v2, v5
	v_lshlrev_b32_e32 v3, 3, v4
	v_lshlrev_b32_e32 v7, 5, v4
	v_ashrrev_i16_sdwa v2, v232, sext(v2) dst_sel:DWORD dst_unused:UNUSED_PAD src0_sel:DWORD src1_sel:BYTE_0
	v_and_b32_e32 v3, 0x3ffff0, v3
	v_and_b32_e32 v7, 32, v7
	v_bfe_i32 v5, v2, 0, 16
	v_add_u32_e32 v2, v7, v5
	v_add_lshl_u32 v3, v6, v3, 10
	v_add_u32_e32 v146, 0x2000, v144
	v_lshl_add_u32 v178, v2, 1, v3
	v_ashrrev_i32_e32 v2, 31, v146
	v_lshrrev_b32_e32 v2, 22, v2
	v_add_u32_e32 v2, v146, v2
	v_ashrrev_i32_e32 v7, 10, v2
	v_mul_i32_i24_e32 v2, 0x400, v7
	v_sub_u32_e32 v2, v146, v2
	v_lshrrev_b32_e32 v3, 4, v2
	v_bitop3_b32 v2, v3, v2, 32 bitop3:0x6c
	v_ashrrev_i32_e32 v8, 31, v2
	v_lshrrev_b32_e32 v8, 26, v8
	v_add_u32_e32 v8, v2, v8
	v_ashrrev_i32_e32 v9, 6, v8
	v_and_b32_e32 v8, 0xc0, v8
	v_sub_u32_e32 v2, v2, v8
	v_lshlrev_b32_e32 v3, 3, v7
	v_lshlrev_b32_e32 v10, 5, v7
	v_ashrrev_i16_sdwa v2, v232, sext(v2) dst_sel:DWORD dst_unused:UNUSED_PAD src0_sel:DWORD src1_sel:BYTE_0
	v_and_b32_e32 v3, 0x3ffff0, v3
	v_and_b32_e32 v10, 32, v10
	v_bfe_i32 v8, v2, 0, 16
	v_add_u32_e32 v2, v10, v8
	v_add_lshl_u32 v3, v9, v3, 10
	v_add_u32_e32 v147, 0x18000, v144
	v_lshl_add_u32 v128, v2, 1, v3
	v_lshl_add_u64 v[2:3], s[8:9], 0, v[178:179]
	v_readfirstlane_b32 s13, v147
	v_lshl_add_u64 v[2:3], v[2:3], 0, s[60:61]
	s_mov_b32 m0, s13
	v_mov_b32_e32 v129, v179
	v_add_u32_e32 v148, 0x1a000, v144
	s_waitcnt vmcnt(4)
	s_barrier
	global_load_lds_dwordx4 v[2:3], off
	v_lshl_add_u64 v[2:3], s[8:9], 0, v[128:129]
	v_readfirstlane_b32 s13, v148
	v_lshl_add_u64 v[2:3], v[2:3], 0, s[60:61]
	s_mov_b32 m0, s13
	v_add_u32_e32 v149, 0x8000, v144
	global_load_lds_dwordx4 v[2:3], off
	v_lshl_add_u64 v[2:3], s[10:11], 0, v[178:179]
	v_readfirstlane_b32 s13, v149
	v_lshl_add_u64 v[2:3], v[2:3], 0, s[60:61]
	s_mov_b32 m0, s13
	v_add_u32_e32 v150, 0xa000, v144
	global_load_lds_dwordx4 v[2:3], off
	v_lshl_add_u64 v[2:3], s[10:11], 0, v[128:129]
	v_readfirstlane_b32 s13, v150
	v_add_u32_e32 v151, 0x1c000, v144
	v_lshl_add_u64 v[2:3], v[2:3], 0, s[60:61]
	s_mov_b32 m0, s13
	s_add_u32 s16, s8, 0x20080
	v_readfirstlane_b32 s13, v151
	v_add_u32_e32 v152, 0x1e000, v144
	global_load_lds_dwordx4 v[2:3], off
	s_addc_u32 s17, s9, 0
	s_mov_b32 m0, s13
	v_readfirstlane_b32 s13, v152
	global_load_lds_dwordx4 v178, s[16:17]
	s_mov_b32 m0, s13
	v_and_b32_e32 v10, 15, v138
	global_load_lds_dwordx4 v128, s[16:17]
	v_lshlrev_b32_e32 v2, 6, v10
	v_lshlrev_b32_e32 v10, 2, v138
	v_and_b32_e32 v11, 48, v138
	v_and_b32_e32 v10, 32, v10
	v_or_b32_e32 v3, v2, v11
	v_bitop3_b32 v12, v2, v10, v11 bitop3:0x36
	s_mov_b32 s13, 0x14000
	v_lshlrev_b32_e32 v2, 6, v138
	v_bitop3_b32 v14, v3, s13, v10 bitop3:0xde
	s_mov_b32 s13, 0x18000
	v_lshlrev_b32_e32 v18, 13, v0
	v_and_b32_e32 v0, 0x3c0, v2
	v_bitop3_b32 v13, v3, s94, v10 bitop3:0xde
	v_bitop3_b32 v15, v3, s13, v10 bitop3:0xde
	v_bitop3_b32 v16, v3, s97, v10 bitop3:0xde
	v_bitop3_b32 v10, v0, v10, v11 bitop3:0x36
	v_lshlrev_b32_e32 v0, 13, v4
	v_and_b32_e32 v17, 0x3000, v2
	v_and_b32_e32 v0, 0xffffc000, v0
	v_lshlrev_b32_e32 v2, 13, v7
	v_lshl_add_u32 v0, v6, 10, v0
	v_and_b32_e32 v2, 0xffffc000, v2
	v_and_or_b32 v0, v1, 64, v0
	v_lshl_add_u32 v2, v9, 10, v2
	v_lshlrev_b32_e32 v3, 6, v7
	s_waitcnt vmcnt(6)
	v_lshl_add_u32 v0, v5, 1, v0
	v_mov_b32_e32 v1, v179
	v_and_or_b32 v2, v3, 64, v2
	v_or_b32_e32 v11, 0x800, v18
	v_or_b32_e32 v19, 0x1000, v18
	v_or_b32_e32 v20, 0x1800, v18
	v_lshl_add_u64 v[130:131], s[8:9], 0, v[0:1]
	v_lshl_add_u32 v2, v8, 1, v2
	v_mov_b32_e32 v3, v179
	v_lshl_add_u64 v[134:135], s[10:11], 0, v[0:1]
	v_mov_b32_e32 v0, 0
	v_lshl_add_u64 v[132:133], s[8:9], 0, v[2:3]
	v_lshl_add_u64 v[136:137], s[10:11], 0, v[2:3]
	s_mov_b32 s13, -2
	s_mov_b64 s[18:19], 0
	v_add_u32_e32 v154, v13, v17
	v_add_u32_e32 v142, v12, v18
	v_add_u32_e32 v141, v10, v11
	v_add_u32_e32 v140, v10, v19
	v_add_u32_e32 v139, v10, v20
	v_add_u32_e32 v153, v14, v17
	v_add_u32_e32 v145, v15, v17
	v_add_u32_e32 v143, v16, v17
	v_mov_b32_e32 v1, v0
	v_mov_b32_e32 v2, v0
	v_mov_b32_e32 v3, v0
	v_mov_b32_e32 v4, v0
	v_mov_b32_e32 v5, v0
	v_mov_b32_e32 v6, v0
	v_mov_b32_e32 v7, v0
	v_mov_b32_e32 v8, v0
	v_mov_b32_e32 v9, v0
	v_mov_b32_e32 v10, v0
	v_mov_b32_e32 v11, v0
	v_mov_b32_e32 v12, v0
	v_mov_b32_e32 v13, v0
	v_mov_b32_e32 v14, v0
	v_mov_b32_e32 v15, v0
	v_mov_b32_e32 v16, v0
	v_mov_b32_e32 v17, v0
	v_mov_b32_e32 v18, v0
	v_mov_b32_e32 v19, v0
	v_mov_b32_e32 v20, v0
	v_mov_b32_e32 v21, v0
	v_mov_b32_e32 v22, v0
	v_mov_b32_e32 v23, v0
	v_mov_b32_e32 v24, v0
	v_mov_b32_e32 v25, v0
	v_mov_b32_e32 v26, v0
	v_mov_b32_e32 v27, v0
	v_mov_b32_e32 v28, v0
	v_mov_b32_e32 v29, v0
	v_mov_b32_e32 v30, v0
	v_mov_b32_e32 v31, v0
	v_mov_b32_e32 v32, v0
	v_mov_b32_e32 v33, v0
	v_mov_b32_e32 v34, v0
	v_mov_b32_e32 v35, v0
	v_mov_b32_e32 v36, v0
	v_mov_b32_e32 v37, v0
	v_mov_b32_e32 v38, v0
	v_mov_b32_e32 v39, v0
	v_mov_b32_e32 v40, v0
	v_mov_b32_e32 v41, v0
	v_mov_b32_e32 v42, v0
	v_mov_b32_e32 v43, v0
	v_mov_b32_e32 v44, v0
	v_mov_b32_e32 v45, v0
	v_mov_b32_e32 v46, v0
	v_mov_b32_e32 v47, v0
	v_mov_b32_e32 v48, v0
	v_mov_b32_e32 v49, v0
; #define STAGE_A(P, half, kt) do { const char* _u = Ab + ((size_t)(half) * 128 * lda + (size_t)(kt) * BK) * 2; \
;     _Pragma("unroll") for (int _i = 0; _i < 2; ++_i) \
;       __builtin_amdgcn_global_load_lds((const unsigned*)(_u + offA[_i]), \
;         (__attribute__((address_space(3))) unsigned*)((__attribute__((address_space(3))) char*)(P) + tidg * 16 + _i * 8192), 16, 0, 0); } while (0)
; #define STAGE_B(P, half, kt) do { const char* _u = Bb + ((size_t)(half) * 128 * ldb + (size_t)(kt) * BK) * 2; \
;     _Pragma("unroll") for (int _i = 0; _i < 2; ++_i) \
;       __builtin_amdgcn_global_load_lds((const unsigned*)(_u + offB[_i]), \
;         (__attribute__((address_space(3))) unsigned*)((__attribute__((address_space(3))) char*)(P) + tidg * 16 + _i * 8192), 16, 0, 0); } while (0)
; #define LDA(dst, b, h) _Pragma("unroll") for (int m = 0; m < 4; ++m) _Pragma("unroll") for (int k = 0; k < 2; ++k) \
;     dst[m][k] = *reinterpret_cast<const bf16x8*>((const char*)SA(b, h) + lds_byte(wr * 64 + m * 16 + fr, k * 32 + fq * 8))
; #define LDB(dst, b, h) _Pragma("unroll") for (int n = 0; n < 2; ++n) _Pragma("unroll") for (int k = 0; k < 2; ++k) \
;     dst[n][k] = *reinterpret_cast<const bf16x8*>((const char*)SB(b, h) + lds_byte(wc * 32 + n * 16 + fr, k * 32 + fq * 8))
; #define WAIT_L(n) asm volatile("s_waitcnt lgkmcnt(" #n ")" ::: "memory")
; #define BAR __builtin_amdgcn_s_barrier()
; #define SCHED __builtin_amdgcn_sched_barrier(0)
; template <bool PF = true, class Epi, class KRF = KRFull>
; __device__ __forceinline__ void gemm_phase(const u16* __restrict__ A, int lda, const u16* __restrict__ Bt, int ldb, int K, int nM, int nN,
;                                            lds_u16* shm, Epi epi, KRF krf = KRFull(), bool flip = false) {
;     ...
;     f32x4 acc[2][2][4][2] = {};
;     ...
;     for (int t = 0; t < nt - 2; t += 2) {
;       LDB(B0, 0, 0); SCHED; LDA(At, 0, 0); STAGE_A(SA(1, 1), 1, t + 1);
;       WAIT_L(8); BAR; WAIT_L(0); MMA(0, 0, At, B0); BAR; SCHED;
;       LDB(B1, 0, 1); STAGE_B(SB(0, 0), 0, t + 2);
;       BAR; WAIT_L(0); MMA(0, 1, At, B1); BAR;
;       LDA(At, 0, 1); STAGE_A(SA(0, 0), 0, t + 2);
;       BAR; WAIT_L(0); MMA(1, 0, At, B0); BAR; SCHED;
	v_mov_b32_e32 v50, v0
	v_mov_b32_e32 v51, v0
	v_mov_b32_e32 v52, v0
	v_mov_b32_e32 v53, v0
	v_mov_b32_e32 v54, v0
	v_mov_b32_e32 v55, v0
	v_mov_b32_e32 v56, v0
	v_mov_b32_e32 v57, v0
	v_mov_b32_e32 v58, v0
	v_mov_b32_e32 v59, v0
	v_mov_b32_e32 v60, v0
	v_mov_b32_e32 v61, v0
	v_mov_b32_e32 v62, v0
	v_mov_b32_e32 v63, v0
	v_mov_b32_e32 v64, v0
	v_mov_b32_e32 v65, v0
	v_mov_b32_e32 v66, v0
	v_mov_b32_e32 v67, v0
	v_mov_b32_e32 v68, v0
	v_mov_b32_e32 v69, v0
	v_mov_b32_e32 v70, v0
	v_mov_b32_e32 v71, v0
	v_mov_b32_e32 v72, v0
	v_mov_b32_e32 v73, v0
	v_mov_b32_e32 v74, v0
	v_mov_b32_e32 v75, v0
	v_mov_b32_e32 v76, v0
	v_mov_b32_e32 v77, v0
	v_mov_b32_e32 v78, v0
	v_mov_b32_e32 v79, v0
	v_mov_b32_e32 v80, v0
	v_mov_b32_e32 v81, v0
	v_mov_b32_e32 v82, v0
	v_mov_b32_e32 v83, v0
	v_mov_b32_e32 v84, v0
	v_mov_b32_e32 v85, v0
	v_mov_b32_e32 v86, v0
	v_mov_b32_e32 v87, v0
	v_mov_b32_e32 v88, v0
	v_mov_b32_e32 v89, v0
	v_mov_b32_e32 v90, v0
	v_mov_b32_e32 v91, v0
	v_mov_b32_e32 v92, v0
	v_mov_b32_e32 v93, v0
	v_mov_b32_e32 v94, v0
	v_mov_b32_e32 v95, v0
	v_mov_b32_e32 v96, v0
	v_mov_b32_e32 v97, v0
	v_mov_b32_e32 v98, v0
	v_mov_b32_e32 v99, v0
	v_mov_b32_e32 v100, v0
	v_mov_b32_e32 v101, v0
	v_mov_b32_e32 v102, v0
	v_mov_b32_e32 v103, v0
	v_mov_b32_e32 v104, v0
	v_mov_b32_e32 v105, v0
	v_mov_b32_e32 v106, v0
	v_mov_b32_e32 v107, v0
	v_mov_b32_e32 v108, v0
	v_mov_b32_e32 v109, v0
	v_mov_b32_e32 v110, v0
	v_mov_b32_e32 v111, v0
	v_mov_b32_e32 v112, v0
	v_mov_b32_e32 v113, v0
	v_mov_b32_e32 v114, v0
	v_mov_b32_e32 v115, v0
	v_mov_b32_e32 v116, v0
	v_mov_b32_e32 v117, v0
	v_mov_b32_e32 v118, v0
	v_mov_b32_e32 v119, v0
	v_mov_b32_e32 v120, v0
	v_mov_b32_e32 v121, v0
	v_mov_b32_e32 v122, v0
	v_mov_b32_e32 v123, v0
	v_mov_b32_e32 v124, v0
	v_mov_b32_e32 v125, v0
	v_mov_b32_e32 v126, v0
	v_mov_b32_e32 v127, v0
	s_barrier
	v_readfirstlane_b32 s15, v144
.LBB0_2500:
	ds_read_b128 v[158:161], v154
	ds_read_b128 v[162:165], v154 offset:1024
	ds_read_b128 v[166:169], v154 offset:2048
	ds_read_b128 v[170:173], v154 offset:3072
	v_lshl_add_u64 v[174:175], v[134:135], 0, s[18:19]
	v_lshl_add_u64 v[156:157], v[174:175], 0, s[80:81]
	s_add_u32 m0, s15, 0xc000
	ds_read_b128 v[180:183], v142
	ds_read_b128 v[184:187], v142 offset:1024
	ds_read_b128 v[188:191], v141
	ds_read_b128 v[192:195], v141 offset:1024
	ds_read_b128 v[196:199], v140
	ds_read_b128 v[200:203], v140 offset:1024
	ds_read_b128 v[204:207], v139
	ds_read_b128 v[208:211], v139 offset:1024
	global_load_lds_dwordx4 v[156:157], off
	v_lshl_add_u64 v[234:235], v[136:137], 0, s[18:19]
	v_lshl_add_u64 v[212:213], v[234:235], 0, s[80:81]
	s_add_u32 m0, s15, 0xe000
	s_nop 0
	global_load_lds_dwordx4 v[212:213], off
	s_waitcnt lgkmcnt(8)
	s_barrier
	s_waitcnt lgkmcnt(0)
	s_setprio 1
	s_waitcnt lgkmcnt(0)
	v_mfma_f32_16x16x32_bf16 v[124:127], v[158:161], v[180:183], v[124:127]
	v_mfma_f32_16x16x32_bf16 v[120:123], v[166:169], v[180:183], v[120:123]
	v_mfma_f32_16x16x32_bf16 v[116:119], v[158:161], v[188:191], v[116:119]
	v_mfma_f32_16x16x32_bf16 v[112:115], v[166:169], v[188:191], v[112:115]
	v_mfma_f32_16x16x32_bf16 v[108:111], v[158:161], v[196:199], v[108:111]
	v_mfma_f32_16x16x32_bf16 v[104:107], v[166:169], v[196:199], v[104:107]
	v_mfma_f32_16x16x32_bf16 v[100:103], v[158:161], v[204:207], v[100:103]
	v_mfma_f32_16x16x32_bf16 v[96:99], v[166:169], v[204:207], v[96:99]
	v_mfma_f32_16x16x32_bf16 v[124:127], v[162:165], v[184:187], v[124:127]
	v_mfma_f32_16x16x32_bf16 v[120:123], v[170:173], v[184:187], v[120:123]
	v_mfma_f32_16x16x32_bf16 v[116:119], v[162:165], v[192:195], v[116:119]
	v_mfma_f32_16x16x32_bf16 v[112:115], v[170:173], v[192:195], v[112:115]
	v_mfma_f32_16x16x32_bf16 v[108:111], v[162:165], v[200:203], v[108:111]
	v_mfma_f32_16x16x32_bf16 v[104:107], v[170:173], v[200:203], v[104:107]
	v_mfma_f32_16x16x32_bf16 v[100:103], v[162:165], v[208:211], v[100:103]
	v_mfma_f32_16x16x32_bf16 v[96:99], v[170:173], v[208:211], v[96:99]
	s_setprio 0
	s_barrier
	v_lshl_add_u64 v[236:237], v[130:131], 0, s[18:19]
	v_lshl_add_u64 v[238:239], v[236:237], 0, s[64:65]
	s_add_u32 m0, s15, 0x10000
	ds_read_b128 v[212:215], v153
	ds_read_b128 v[216:219], v153 offset:1024
	ds_read_b128 v[222:225], v153 offset:2048
	ds_read_b128 v[226:229], v153 offset:3072
	global_load_lds_dwordx4 v[238:239], off
	v_lshl_add_u64 v[238:239], v[132:133], 0, s[18:19]
	v_lshl_add_u64 v[240:241], v[238:239], 0, s[64:65]
	s_add_u32 m0, s15, 0x12000
	s_nop 0
	global_load_lds_dwordx4 v[240:241], off
	s_barrier
	s_waitcnt lgkmcnt(0)
	s_setprio 1
	s_waitcnt lgkmcnt(0)
	v_mfma_f32_16x16x32_bf16 v[92:95], v[212:215], v[180:183], v[92:95]
	v_mfma_f32_16x16x32_bf16 v[88:91], v[222:225], v[180:183], v[88:91]
	v_mfma_f32_16x16x32_bf16 v[84:87], v[212:215], v[188:191], v[84:87]
	v_mfma_f32_16x16x32_bf16 v[80:83], v[222:225], v[188:191], v[80:83]
	v_mfma_f32_16x16x32_bf16 v[76:79], v[212:215], v[196:199], v[76:79]
	v_mfma_f32_16x16x32_bf16 v[72:75], v[222:225], v[196:199], v[72:75]
	v_mfma_f32_16x16x32_bf16 v[68:71], v[212:215], v[204:207], v[68:71]
	v_mfma_f32_16x16x32_bf16 v[64:67], v[222:225], v[204:207], v[64:67]
	v_mfma_f32_16x16x32_bf16 v[92:95], v[216:219], v[184:187], v[92:95]
	v_mfma_f32_16x16x32_bf16 v[88:91], v[226:229], v[184:187], v[88:91]
	v_mfma_f32_16x16x32_bf16 v[84:87], v[216:219], v[192:195], v[84:87]
	v_mfma_f32_16x16x32_bf16 v[80:83], v[226:229], v[192:195], v[80:83]
	v_mfma_f32_16x16x32_bf16 v[76:79], v[216:219], v[200:203], v[76:79]
	v_mfma_f32_16x16x32_bf16 v[72:75], v[226:229], v[200:203], v[72:75]
	v_mfma_f32_16x16x32_bf16 v[68:71], v[216:219], v[208:211], v[68:71]
	v_mfma_f32_16x16x32_bf16 v[64:67], v[226:229], v[208:211], v[64:67]
	s_setprio 0
	v_lshl_add_u64 v[240:241], v[174:175], 0, s[64:65]
	s_mov_b32 m0, s15
	s_barrier
; #define STAGE_A(P, half, kt) do { const char* _u = Ab + ((size_t)(half) * 128 * lda + (size_t)(kt) * BK) * 2; \
;     _Pragma("unroll") for (int _i = 0; _i < 2; ++_i) \
;       __builtin_amdgcn_global_load_lds((const unsigned*)(_u + offA[_i]), \
;         (__attribute__((address_space(3))) unsigned*)((__attribute__((address_space(3))) char*)(P) + tidg * 16 + _i * 8192), 16, 0, 0); } while (0)
; #define STAGE_B(P, half, kt) do { const char* _u = Bb + ((size_t)(half) * 128 * ldb + (size_t)(kt) * BK) * 2; \
;     _Pragma("unroll") for (int _i = 0; _i < 2; ++_i) \
;       __builtin_amdgcn_global_load_lds((const unsigned*)(_u + offB[_i]), \
;         (__attribute__((address_space(3))) unsigned*)((__attribute__((address_space(3))) char*)(P) + tidg * 16 + _i * 8192), 16, 0, 0); } while (0)
; #define LDA(dst, b, h) _Pragma("unroll") for (int m = 0; m < 4; ++m) _Pragma("unroll") for (int k = 0; k < 2; ++k) \
;     dst[m][k] = *reinterpret_cast<const bf16x8*>((const char*)SA(b, h) + lds_byte(wr * 64 + m * 16 + fr, k * 32 + fq * 8))
; #define LDB(dst, b, h) _Pragma("unroll") for (int n = 0; n < 2; ++n) _Pragma("unroll") for (int k = 0; k < 2; ++k) \
;     dst[n][k] = *reinterpret_cast<const bf16x8*>((const char*)SB(b, h) + lds_byte(wc * 32 + n * 16 + fr, k * 32 + fq * 8))
; #define WAIT_V(n) asm volatile("s_waitcnt vmcnt(" #n ")" ::: "memory")
; #define WAIT_L(n) asm volatile("s_waitcnt lgkmcnt(" #n ")" ::: "memory")
; #define BAR __builtin_amdgcn_s_barrier()
; #define SCHED __builtin_amdgcn_sched_barrier(0)
; template <bool PF = true, class Epi, class KRF = KRFull>
; __device__ __forceinline__ void gemm_phase(const u16* __restrict__ A, int lda, const u16* __restrict__ Bt, int ldb, int K, int nM, int nN,
;                                            lds_u16* shm, Epi epi, KRF krf = KRFull(), bool flip = false) {
;     ...
;       LDA(At, 0, 1); STAGE_A(SA(0, 0), 0, t + 2);
;       BAR; WAIT_L(0); MMA(1, 0, At, B0); BAR; SCHED;
;       STAGE_B(SB(0, 1), 1, t + 2);
;       WAIT_V(6); BAR; MMA(1, 1, At, B1); BAR;
;       LDB(B0, 1, 0); SCHED; LDA(At, 1, 0); STAGE_A(SA(0, 1), 1, t + 2);
;       WAIT_L(8); BAR; WAIT_L(0); MMA(0, 0, At, B0); BAR; SCHED;
;       LDB(B1, 1, 1); STAGE_B(SB(1, 0), 0, t + 3);
;       BAR; WAIT_L(0); MMA(0, 1, At, B1); BAR;
;       LDA(At, 1, 1); STAGE_A(SA(1, 0), 0, t + 3);
	ds_read_b128 v[180:183], v142 offset:16384
	ds_read_b128 v[184:187], v142 offset:17408
	ds_read_b128 v[188:191], v141 offset:16384
	ds_read_b128 v[192:195], v141 offset:17408
	ds_read_b128 v[196:199], v140 offset:16384
	ds_read_b128 v[200:203], v140 offset:17408
	ds_read_b128 v[204:207], v139 offset:16384
	ds_read_b128 v[208:211], v139 offset:17408
	global_load_lds_dwordx4 v[240:241], off
	v_lshl_add_u64 v[240:241], v[234:235], 0, s[64:65]
	s_add_u32 m0, s15, 0x2000
	s_nop 0
	global_load_lds_dwordx4 v[240:241], off
	s_barrier
	s_waitcnt lgkmcnt(0)
	s_setprio 1
	s_waitcnt lgkmcnt(0)
	v_mfma_f32_16x16x32_bf16 v[60:63], v[158:161], v[180:183], v[60:63]
	v_mfma_f32_16x16x32_bf16 v[56:59], v[166:169], v[180:183], v[56:59]
	v_mfma_f32_16x16x32_bf16 v[52:55], v[158:161], v[188:191], v[52:55]
	v_mfma_f32_16x16x32_bf16 v[48:51], v[166:169], v[188:191], v[48:51]
	v_mfma_f32_16x16x32_bf16 v[44:47], v[158:161], v[196:199], v[44:47]
	v_mfma_f32_16x16x32_bf16 v[40:43], v[166:169], v[196:199], v[40:43]
	v_mfma_f32_16x16x32_bf16 v[36:39], v[158:161], v[204:207], v[36:39]
	v_mfma_f32_16x16x32_bf16 v[32:35], v[166:169], v[204:207], v[32:35]
	v_mfma_f32_16x16x32_bf16 v[60:63], v[162:165], v[184:187], v[60:63]
	v_mfma_f32_16x16x32_bf16 v[56:59], v[170:173], v[184:187], v[56:59]
	v_mfma_f32_16x16x32_bf16 v[52:55], v[162:165], v[192:195], v[52:55]
	v_mfma_f32_16x16x32_bf16 v[48:51], v[170:173], v[192:195], v[48:51]
	v_mfma_f32_16x16x32_bf16 v[44:47], v[162:165], v[200:203], v[44:47]
	v_mfma_f32_16x16x32_bf16 v[40:43], v[170:173], v[200:203], v[40:43]
	v_mfma_f32_16x16x32_bf16 v[36:39], v[162:165], v[208:211], v[36:39]
	v_mfma_f32_16x16x32_bf16 v[32:35], v[170:173], v[208:211], v[32:35]
	s_setprio 0
	s_barrier
	v_lshl_add_u64 v[158:159], v[236:237], 0, s[86:87]
	s_add_u32 m0, s15, 0x14000
	s_nop 0
	global_load_lds_dwordx4 v[158:159], off
	v_lshl_add_u64 v[158:159], v[238:239], 0, s[86:87]
	s_add_u32 m0, s15, 0x16000
	s_nop 0
	global_load_lds_dwordx4 v[158:159], off
	s_waitcnt vmcnt(6)
	s_barrier
	s_setprio 1
	v_mfma_f32_16x16x32_bf16 v[28:31], v[212:215], v[180:183], v[28:31]
	v_mfma_f32_16x16x32_bf16 v[24:27], v[222:225], v[180:183], v[24:27]
	v_mfma_f32_16x16x32_bf16 v[20:23], v[212:215], v[188:191], v[20:23]
	v_mfma_f32_16x16x32_bf16 v[16:19], v[222:225], v[188:191], v[16:19]
	v_mfma_f32_16x16x32_bf16 v[12:15], v[212:215], v[196:199], v[12:15]
	v_mfma_f32_16x16x32_bf16 v[8:11], v[222:225], v[196:199], v[8:11]
	v_mfma_f32_16x16x32_bf16 v[4:7], v[212:215], v[204:207], v[4:7]
	v_mfma_f32_16x16x32_bf16 v[0:3], v[222:225], v[204:207], v[0:3]
	v_mfma_f32_16x16x32_bf16 v[28:31], v[216:219], v[184:187], v[28:31]
	v_mfma_f32_16x16x32_bf16 v[24:27], v[226:229], v[184:187], v[24:27]
	v_mfma_f32_16x16x32_bf16 v[20:23], v[216:219], v[192:195], v[20:23]
	v_mfma_f32_16x16x32_bf16 v[16:19], v[226:229], v[192:195], v[16:19]
	v_mfma_f32_16x16x32_bf16 v[12:15], v[216:219], v[200:203], v[12:15]
	v_mfma_f32_16x16x32_bf16 v[8:11], v[226:229], v[200:203], v[8:11]
	v_mfma_f32_16x16x32_bf16 v[4:7], v[216:219], v[208:211], v[4:7]
	v_mfma_f32_16x16x32_bf16 v[0:3], v[226:229], v[208:211], v[0:3]
	s_setprio 0
	s_barrier
	ds_read_b128 v[158:161], v145
	ds_read_b128 v[162:165], v145 offset:1024
	ds_read_b128 v[166:169], v145 offset:2048
	ds_read_b128 v[170:173], v145 offset:3072
	v_lshl_add_u64 v[212:213], v[174:175], 0, s[86:87]
	s_add_u32 m0, s15, 0x4000
	ds_read_b128 v[180:183], v142 offset:32768
	ds_read_b128 v[184:187], v142 offset:33792
	ds_read_b128 v[188:191], v141 offset:32768
	ds_read_b128 v[192:195], v141 offset:33792
	ds_read_b128 v[196:199], v140 offset:32768
	ds_read_b128 v[200:203], v140 offset:33792
	ds_read_b128 v[204:207], v139 offset:32768
	ds_read_b128 v[208:211], v139 offset:33792
	global_load_lds_dwordx4 v[212:213], off
	v_lshl_add_u64 v[212:213], v[234:235], 0, s[86:87]
	s_add_u32 m0, s15, 0x6000
	s_nop 0
	global_load_lds_dwordx4 v[212:213], off
	s_waitcnt lgkmcnt(8)
	s_barrier
	s_waitcnt lgkmcnt(0)
	s_setprio 1
	s_waitcnt lgkmcnt(0)
	v_mfma_f32_16x16x32_bf16 v[124:127], v[158:161], v[180:183], v[124:127]
	v_mfma_f32_16x16x32_bf16 v[120:123], v[166:169], v[180:183], v[120:123]
	v_mfma_f32_16x16x32_bf16 v[116:119], v[158:161], v[188:191], v[116:119]
	v_mfma_f32_16x16x32_bf16 v[112:115], v[166:169], v[188:191], v[112:115]
	v_mfma_f32_16x16x32_bf16 v[108:111], v[158:161], v[196:199], v[108:111]
	v_mfma_f32_16x16x32_bf16 v[104:107], v[166:169], v[196:199], v[104:107]
	v_mfma_f32_16x16x32_bf16 v[100:103], v[158:161], v[204:207], v[100:103]
	v_mfma_f32_16x16x32_bf16 v[96:99], v[166:169], v[204:207], v[96:99]
	v_mfma_f32_16x16x32_bf16 v[124:127], v[162:165], v[184:187], v[124:127]
	v_mfma_f32_16x16x32_bf16 v[120:123], v[170:173], v[184:187], v[120:123]
	v_mfma_f32_16x16x32_bf16 v[116:119], v[162:165], v[192:195], v[116:119]
	v_mfma_f32_16x16x32_bf16 v[112:115], v[170:173], v[192:195], v[112:115]
	v_mfma_f32_16x16x32_bf16 v[108:111], v[162:165], v[200:203], v[108:111]
	v_mfma_f32_16x16x32_bf16 v[104:107], v[170:173], v[200:203], v[104:107]
	v_mfma_f32_16x16x32_bf16 v[100:103], v[162:165], v[208:211], v[100:103]
	v_mfma_f32_16x16x32_bf16 v[96:99], v[170:173], v[208:211], v[96:99]
	s_setprio 0
	s_barrier
	v_lshl_add_u64 v[240:241], v[236:237], 0, s[68:69]
	s_add_u32 m0, s15, 0x18000
	ds_read_b128 v[212:215], v143
	ds_read_b128 v[216:219], v143 offset:1024
	ds_read_b128 v[222:225], v143 offset:2048
	ds_read_b128 v[226:229], v143 offset:3072
	global_load_lds_dwordx4 v[240:241], off
	v_lshl_add_u64 v[240:241], v[238:239], 0, s[68:69]
	s_add_u32 m0, s15, 0x1a000
	s_nop 0
	global_load_lds_dwordx4 v[240:241], off
	s_barrier
; #define STAGE_A(P, half, kt) do { const char* _u = Ab + ((size_t)(half) * 128 * lda + (size_t)(kt) * BK) * 2; \
;     _Pragma("unroll") for (int _i = 0; _i < 2; ++_i) \
;       __builtin_amdgcn_global_load_lds((const unsigned*)(_u + offA[_i]), \
;         (__attribute__((address_space(3))) unsigned*)((__attribute__((address_space(3))) char*)(P) + tidg * 16 + _i * 8192), 16, 0, 0); } while (0)
; #define STAGE_B(P, half, kt) do { const char* _u = Bb + ((size_t)(half) * 128 * ldb + (size_t)(kt) * BK) * 2; \
;     _Pragma("unroll") for (int _i = 0; _i < 2; ++_i) \
;       __builtin_amdgcn_global_load_lds((const unsigned*)(_u + offB[_i]), \
;         (__attribute__((address_space(3))) unsigned*)((__attribute__((address_space(3))) char*)(P) + tidg * 16 + _i * 8192), 16, 0, 0); } while (0)
; #define LDA(dst, b, h) _Pragma("unroll") for (int m = 0; m < 4; ++m) _Pragma("unroll") for (int k = 0; k < 2; ++k) \
;     dst[m][k] = *reinterpret_cast<const bf16x8*>((const char*)SA(b, h) + lds_byte(wr * 64 + m * 16 + fr, k * 32 + fq * 8))
; #define LDB(dst, b, h) _Pragma("unroll") for (int n = 0; n < 2; ++n) _Pragma("unroll") for (int k = 0; k < 2; ++k) \
;     dst[n][k] = *reinterpret_cast<const bf16x8*>((const char*)SB(b, h) + lds_byte(wc * 32 + n * 16 + fr, k * 32 + fq * 8))
; #define MMA(ai, bj, At_, Bt_) do { __builtin_amdgcn_s_setprio(1); \
;     _Pragma("unroll") for (int m = 0; m < 4; ++m) _Pragma("unroll") for (int n = 0; n < 2; ++n) _Pragma("unroll") for (int k = 0; k < 2; ++k) \
;       acc[ai][bj][m][n] = __builtin_amdgcn_mfma_f32_16x16x32_bf16(Bt_[n][k], At_[m][k], acc[ai][bj][m][n], 0, 0, 0); \
;     __builtin_amdgcn_s_setprio(0); } while (0)
; #define WAIT_V(n) asm volatile("s_waitcnt vmcnt(" #n ")" ::: "memory")
; #define WAIT_L(n) asm volatile("s_waitcnt lgkmcnt(" #n ")" ::: "memory")
; template <bool PF = true, class Epi, class KRF = KRFull>
; __device__ __forceinline__ void gemm_phase(const u16* __restrict__ A, int lda, const u16* __restrict__ Bt, int ldb, int K, int nM, int nN,
;                                            lds_u16* shm, Epi epi, KRF krf = KRFull(), bool flip = false) {
;     ...
;       LDA(At, 1, 1); STAGE_A(SA(1, 0), 0, t + 3);
;       BAR; WAIT_L(0); MMA(1, 0, At, B0); BAR; SCHED;
;       STAGE_B(SB(1, 1), 1, t + 3);
;       WAIT_V(6); BAR; MMA(1, 1, At, B1); BAR;
;     }
;     { LDB(B0, 0, 0); LDA(At, 0, 0); STAGE_A(SA(1, 1), 1, nt - 1);
	s_waitcnt lgkmcnt(0)
	s_setprio 1
	s_waitcnt lgkmcnt(0)
	v_mfma_f32_16x16x32_bf16 v[92:95], v[212:215], v[180:183], v[92:95]
	v_mfma_f32_16x16x32_bf16 v[88:91], v[222:225], v[180:183], v[88:91]
	v_mfma_f32_16x16x32_bf16 v[84:87], v[212:215], v[188:191], v[84:87]
	v_mfma_f32_16x16x32_bf16 v[80:83], v[222:225], v[188:191], v[80:83]
	v_mfma_f32_16x16x32_bf16 v[76:79], v[212:215], v[196:199], v[76:79]
	v_mfma_f32_16x16x32_bf16 v[72:75], v[222:225], v[196:199], v[72:75]
	v_mfma_f32_16x16x32_bf16 v[68:71], v[212:215], v[204:207], v[68:71]
	v_mfma_f32_16x16x32_bf16 v[64:67], v[222:225], v[204:207], v[64:67]
	v_mfma_f32_16x16x32_bf16 v[92:95], v[216:219], v[184:187], v[92:95]
	v_mfma_f32_16x16x32_bf16 v[88:91], v[226:229], v[184:187], v[88:91]
	v_mfma_f32_16x16x32_bf16 v[84:87], v[216:219], v[192:195], v[84:87]
	v_mfma_f32_16x16x32_bf16 v[80:83], v[226:229], v[192:195], v[80:83]
	v_mfma_f32_16x16x32_bf16 v[76:79], v[216:219], v[200:203], v[76:79]
	v_mfma_f32_16x16x32_bf16 v[72:75], v[226:229], v[200:203], v[72:75]
	v_mfma_f32_16x16x32_bf16 v[68:71], v[216:219], v[208:211], v[68:71]
	v_mfma_f32_16x16x32_bf16 v[64:67], v[226:229], v[208:211], v[64:67]
	s_setprio 0
	v_lshl_add_u64 v[174:175], v[174:175], 0, s[68:69]
	s_add_u32 m0, s15, 0x8000
	s_barrier
	ds_read_b128 v[180:183], v142 offset:49152
	ds_read_b128 v[184:187], v142 offset:50176
	ds_read_b128 v[188:191], v141 offset:49152
	ds_read_b128 v[192:195], v141 offset:50176
	ds_read_b128 v[196:199], v140 offset:49152
	ds_read_b128 v[200:203], v140 offset:50176
	ds_read_b128 v[204:207], v139 offset:49152
	ds_read_b128 v[208:211], v139 offset:50176
	global_load_lds_dwordx4 v[174:175], off
	v_lshl_add_u64 v[174:175], v[234:235], 0, s[68:69]
	s_add_u32 m0, s15, 0xa000
	s_nop 0
	global_load_lds_dwordx4 v[174:175], off
	s_barrier
	s_waitcnt lgkmcnt(0)
	s_setprio 1
	s_waitcnt lgkmcnt(0)
	v_mfma_f32_16x16x32_bf16 v[60:63], v[158:161], v[180:183], v[60:63]
	v_mfma_f32_16x16x32_bf16 v[56:59], v[166:169], v[180:183], v[56:59]
	v_mfma_f32_16x16x32_bf16 v[52:55], v[158:161], v[188:191], v[52:55]
	v_mfma_f32_16x16x32_bf16 v[48:51], v[166:169], v[188:191], v[48:51]
	v_mfma_f32_16x16x32_bf16 v[44:47], v[158:161], v[196:199], v[44:47]
	v_mfma_f32_16x16x32_bf16 v[40:43], v[166:169], v[196:199], v[40:43]
	v_mfma_f32_16x16x32_bf16 v[36:39], v[158:161], v[204:207], v[36:39]
	v_mfma_f32_16x16x32_bf16 v[32:35], v[166:169], v[204:207], v[32:35]
	v_mfma_f32_16x16x32_bf16 v[60:63], v[162:165], v[184:187], v[60:63]
	v_mfma_f32_16x16x32_bf16 v[56:59], v[170:173], v[184:187], v[56:59]
	v_mfma_f32_16x16x32_bf16 v[52:55], v[162:165], v[192:195], v[52:55]
	v_mfma_f32_16x16x32_bf16 v[48:51], v[170:173], v[192:195], v[48:51]
	v_mfma_f32_16x16x32_bf16 v[44:47], v[162:165], v[200:203], v[44:47]
	v_mfma_f32_16x16x32_bf16 v[40:43], v[170:173], v[200:203], v[40:43]
	v_mfma_f32_16x16x32_bf16 v[36:39], v[162:165], v[208:211], v[36:39]
	v_mfma_f32_16x16x32_bf16 v[32:35], v[170:173], v[208:211], v[32:35]
	s_setprio 0
	s_barrier
	v_lshl_add_u64 v[158:159], v[236:237], 0, s[92:93]
	s_add_u32 m0, s15, 0x1c000
	s_nop 0
	global_load_lds_dwordx4 v[158:159], off
	v_lshl_add_u64 v[158:159], v[238:239], 0, s[92:93]
	s_add_u32 m0, s15, 0x1e000
	s_nop 0
	global_load_lds_dwordx4 v[158:159], off
	s_waitcnt vmcnt(6)
	s_barrier
	s_setprio 1
	v_mfma_f32_16x16x32_bf16 v[28:31], v[212:215], v[180:183], v[28:31]
	v_mfma_f32_16x16x32_bf16 v[24:27], v[222:225], v[180:183], v[24:27]
	v_mfma_f32_16x16x32_bf16 v[20:23], v[212:215], v[188:191], v[20:23]
	v_mfma_f32_16x16x32_bf16 v[16:19], v[222:225], v[188:191], v[16:19]
	v_mfma_f32_16x16x32_bf16 v[12:15], v[212:215], v[196:199], v[12:15]
	v_mfma_f32_16x16x32_bf16 v[8:11], v[222:225], v[196:199], v[8:11]
	v_mfma_f32_16x16x32_bf16 v[4:7], v[212:215], v[204:207], v[4:7]
	v_mfma_f32_16x16x32_bf16 v[0:3], v[222:225], v[204:207], v[0:3]
	v_mfma_f32_16x16x32_bf16 v[28:31], v[216:219], v[184:187], v[28:31]
	v_mfma_f32_16x16x32_bf16 v[24:27], v[226:229], v[184:187], v[24:27]
	v_mfma_f32_16x16x32_bf16 v[20:23], v[216:219], v[192:195], v[20:23]
	v_mfma_f32_16x16x32_bf16 v[16:19], v[226:229], v[192:195], v[16:19]
	v_mfma_f32_16x16x32_bf16 v[12:15], v[216:219], v[200:203], v[12:15]
	v_mfma_f32_16x16x32_bf16 v[8:11], v[226:229], v[200:203], v[8:11]
	v_mfma_f32_16x16x32_bf16 v[4:7], v[216:219], v[208:211], v[4:7]
	v_mfma_f32_16x16x32_bf16 v[0:3], v[226:229], v[208:211], v[0:3]
	s_setprio 0
	s_add_i32 s13, s13, 2
	s_add_u32 s18, s18, 0x100
	s_addc_u32 s19, s19, 0
	s_cmp_gt_u32 s13, 3
	s_barrier
	s_cbranch_scc0 .LBB0_2500
	v_add_u32_e32 v155, 0xc000, v144
	v_add_u32_e32 v156, 0xe000, v144
	v_add_u32_e32 v157, 0x6000, v144
	s_add_u32 s16, s10, 0x20380
	s_addc_u32 s17, s11, 0
	v_readfirstlane_b32 s13, v155
	v_lshl_add_u64 v[150:151], s[16:17], 0, v[178:179]
	s_mov_b32 m0, s13
	v_readfirstlane_b32 s13, v156
	ds_read_b128 v[130:133], v154
	ds_read_b128 v[134:137], v154 offset:1024
	ds_read_b128 v[146:149], v154 offset:2048
	ds_read_b128 v[158:161], v154 offset:3072
	ds_read_b128 v[162:165], v142
	ds_read_b128 v[166:169], v142 offset:1024
	ds_read_b128 v[170:173], v141
	ds_read_b128 v[180:183], v141 offset:1024
	ds_read_b128 v[184:187], v140
	ds_read_b128 v[188:191], v140 offset:1024
	ds_read_b128 v[192:195], v139
	ds_read_b128 v[196:199], v139 offset:1024
	global_load_lds_dwordx4 v[150:151], off
	v_lshl_add_u64 v[128:129], s[16:17], 0, v[128:129]
	s_mov_b32 m0, s13
	s_nop 0
	global_load_lds_dwordx4 v[128:129], off
	s_barrier
; #define STAGE_A(P, half, kt) do { const char* _u = Ab + ((size_t)(half) * 128 * lda + (size_t)(kt) * BK) * 2; \
;     _Pragma("unroll") for (int _i = 0; _i < 2; ++_i) \
;       __builtin_amdgcn_global_load_lds((const unsigned*)(_u + offA[_i]), \
;         (__attribute__((address_space(3))) unsigned*)((__attribute__((address_space(3))) char*)(P) + tidg * 16 + _i * 8192), 16, 0, 0); } while (0)
; #define LDA(dst, b, h) _Pragma("unroll") for (int m = 0; m < 4; ++m) _Pragma("unroll") for (int k = 0; k < 2; ++k) \
;     dst[m][k] = *reinterpret_cast<const bf16x8*>((const char*)SA(b, h) + lds_byte(wr * 64 + m * 16 + fr, k * 32 + fq * 8))
; #define LDB(dst, b, h) _Pragma("unroll") for (int n = 0; n < 2; ++n) _Pragma("unroll") for (int k = 0; k < 2; ++k) \
;     dst[n][k] = *reinterpret_cast<const bf16x8*>((const char*)SB(b, h) + lds_byte(wc * 32 + n * 16 + fr, k * 32 + fq * 8))
; #define MMA(ai, bj, At_, Bt_) do { __builtin_amdgcn_s_setprio(1); \
;     _Pragma("unroll") for (int m = 0; m < 4; ++m) _Pragma("unroll") for (int n = 0; n < 2; ++n) _Pragma("unroll") for (int k = 0; k < 2; ++k) \
;       acc[ai][bj][m][n] = __builtin_amdgcn_mfma_f32_16x16x32_bf16(Bt_[n][k], At_[m][k], acc[ai][bj][m][n], 0, 0, 0); \
;     __builtin_amdgcn_s_setprio(0); } while (0)
; #define WAIT_V(n) asm volatile("s_waitcnt vmcnt(" #n ")" ::: "memory")
; #define WAIT_L(n) asm volatile("s_waitcnt lgkmcnt(" #n ")" ::: "memory")
; #define BAR __builtin_amdgcn_s_barrier()
; template <bool PF = true, class Epi, class KRF = KRFull>
; __device__ __forceinline__ void gemm_phase(const u16* __restrict__ A, int lda, const u16* __restrict__ Bt, int ldb, int K, int nM, int nN,
;                                            lds_u16* shm, Epi epi, KRF krf = KRFull(), bool flip = false) {
;     ...
;     { LDB(B0, 0, 0); LDA(At, 0, 0); STAGE_A(SA(1, 1), 1, nt - 1);
;       BAR; WAIT_L(0); MMA(0, 0, At, B0); BAR;
;       LDB(B1, 0, 1); BAR; WAIT_L(0); MMA(0, 1, At, B1); BAR;
;       LDA(At, 0, 1); WAIT_V(4); BAR; WAIT_L(0); MMA(1, 0, At, B0); MMA(1, 1, At, B1); BAR; }
;     { LDB(B0, 1, 0); LDA(At, 1, 0); WAIT_V(2); BAR; WAIT_L(0); MMA(0, 0, At, B0); BAR;
	s_waitcnt lgkmcnt(0)
	s_setprio 1
	s_waitcnt lgkmcnt(0)
	v_mfma_f32_16x16x32_bf16 v[124:127], v[130:133], v[162:165], v[124:127]
	v_mfma_f32_16x16x32_bf16 v[120:123], v[146:149], v[162:165], v[120:123]
	v_mfma_f32_16x16x32_bf16 v[116:119], v[130:133], v[170:173], v[116:119]
	v_mfma_f32_16x16x32_bf16 v[112:115], v[146:149], v[170:173], v[112:115]
	v_mfma_f32_16x16x32_bf16 v[108:111], v[130:133], v[184:187], v[108:111]
	v_mfma_f32_16x16x32_bf16 v[104:107], v[146:149], v[184:187], v[104:107]
	v_mfma_f32_16x16x32_bf16 v[100:103], v[130:133], v[192:195], v[100:103]
	v_mfma_f32_16x16x32_bf16 v[96:99], v[146:149], v[192:195], v[96:99]
	v_mfma_f32_16x16x32_bf16 v[124:127], v[134:137], v[166:169], v[124:127]
	v_mfma_f32_16x16x32_bf16 v[120:123], v[158:161], v[166:169], v[120:123]
	v_mfma_f32_16x16x32_bf16 v[116:119], v[134:137], v[180:183], v[116:119]
	v_mfma_f32_16x16x32_bf16 v[112:115], v[158:161], v[180:183], v[112:115]
	v_mfma_f32_16x16x32_bf16 v[108:111], v[134:137], v[188:191], v[108:111]
	v_mfma_f32_16x16x32_bf16 v[104:107], v[158:161], v[188:191], v[104:107]
	v_mfma_f32_16x16x32_bf16 v[100:103], v[134:137], v[196:199], v[100:103]
	v_mfma_f32_16x16x32_bf16 v[96:99], v[158:161], v[196:199], v[96:99]
	s_setprio 0
	s_barrier
	ds_read_b128 v[154:157], v153
	ds_read_b128 v[200:203], v153 offset:1024
	ds_read_b128 v[204:207], v153 offset:2048
	ds_read_b128 v[150:153], v153 offset:3072
	s_barrier
	s_waitcnt lgkmcnt(0)
	s_setprio 1
	s_waitcnt lgkmcnt(0)
	v_mfma_f32_16x16x32_bf16 v[88:91], v[204:207], v[162:165], v[88:91]
	v_mfma_f32_16x16x32_bf16 v[80:83], v[204:207], v[170:173], v[80:83]
	v_mfma_f32_16x16x32_bf16 v[76:79], v[154:157], v[184:187], v[76:79]
	v_mfma_f32_16x16x32_bf16 v[72:75], v[204:207], v[184:187], v[72:75]
	v_mfma_f32_16x16x32_bf16 v[68:71], v[154:157], v[192:195], v[68:71]
	v_mfma_f32_16x16x32_bf16 v[92:95], v[154:157], v[162:165], v[92:95]
	v_mfma_f32_16x16x32_bf16 v[88:91], v[150:153], v[166:169], v[88:91]
	v_mfma_f32_16x16x32_bf16 v[84:87], v[154:157], v[170:173], v[84:87]
	v_mfma_f32_16x16x32_bf16 v[80:83], v[150:153], v[180:183], v[80:83]
	v_mfma_f32_16x16x32_bf16 v[76:79], v[200:203], v[188:191], v[76:79]
	v_mfma_f32_16x16x32_bf16 v[72:75], v[150:153], v[188:191], v[72:75]
	v_mfma_f32_16x16x32_bf16 v[68:71], v[200:203], v[196:199], v[68:71]
	v_mfma_f32_16x16x32_bf16 v[64:67], v[204:207], v[192:195], v[64:67]
	v_mfma_f32_16x16x32_bf16 v[208:211], v[200:203], v[166:169], v[92:95]
	v_mfma_f32_16x16x32_bf16 v[162:165], v[200:203], v[180:183], v[84:87]
	v_mfma_f32_16x16x32_bf16 v[166:169], v[150:153], v[196:199], v[64:67]
	s_setprio 0
	s_barrier
	s_nop 2
	ds_read_b128 v[64:67], v142 offset:16384
	ds_read_b128 v[84:87], v142 offset:17408
	ds_read_b128 v[92:95], v141 offset:16384
	ds_read_b128 v[170:173], v141 offset:17408
	ds_read_b128 v[180:183], v140 offset:16384
	ds_read_b128 v[184:187], v140 offset:17408
	ds_read_b128 v[188:191], v139 offset:16384
	ds_read_b128 v[192:195], v139 offset:17408
	s_waitcnt vmcnt(4)
	s_barrier
	s_waitcnt lgkmcnt(0)
	s_setprio 1
	s_waitcnt lgkmcnt(0)
	v_mfma_f32_16x16x32_bf16 v[60:63], v[130:133], v[64:67], v[60:63]
	v_mfma_f32_16x16x32_bf16 v[52:55], v[130:133], v[92:95], v[52:55]
	v_mfma_f32_16x16x32_bf16 v[48:51], v[146:149], v[92:95], v[48:51]
	v_mfma_f32_16x16x32_bf16 v[44:47], v[130:133], v[180:183], v[44:47]
	v_mfma_f32_16x16x32_bf16 v[40:43], v[146:149], v[180:183], v[40:43]
	v_mfma_f32_16x16x32_bf16 v[36:39], v[130:133], v[188:191], v[36:39]
	v_mfma_f32_16x16x32_bf16 v[32:35], v[146:149], v[188:191], v[32:35]
	v_mfma_f32_16x16x32_bf16 v[60:63], v[134:137], v[84:87], v[60:63]
	v_mfma_f32_16x16x32_bf16 v[56:59], v[146:149], v[64:67], v[56:59]
	v_mfma_f32_16x16x32_bf16 v[52:55], v[134:137], v[170:173], v[52:55]
	v_mfma_f32_16x16x32_bf16 v[48:51], v[158:161], v[170:173], v[48:51]
	v_mfma_f32_16x16x32_bf16 v[44:47], v[134:137], v[184:187], v[44:47]
	v_mfma_f32_16x16x32_bf16 v[40:43], v[158:161], v[184:187], v[40:43]
	v_mfma_f32_16x16x32_bf16 v[36:39], v[134:137], v[192:195], v[36:39]
	v_mfma_f32_16x16x32_bf16 v[32:35], v[158:161], v[192:195], v[32:35]
	v_mfma_f32_16x16x32_bf16 v[196:199], v[158:161], v[84:87], v[56:59]
	s_setprio 0
	s_setprio 1
	v_mfma_f32_16x16x32_bf16 v[28:31], v[154:157], v[64:67], v[28:31]
	v_mfma_f32_16x16x32_bf16 v[24:27], v[204:207], v[64:67], v[24:27]
	v_mfma_f32_16x16x32_bf16 v[20:23], v[154:157], v[92:95], v[20:23]
	v_mfma_f32_16x16x32_bf16 v[16:19], v[204:207], v[92:95], v[16:19]
	v_mfma_f32_16x16x32_bf16 v[12:15], v[154:157], v[180:183], v[12:15]
	v_mfma_f32_16x16x32_bf16 v[8:11], v[204:207], v[180:183], v[8:11]
	v_mfma_f32_16x16x32_bf16 v[4:7], v[154:157], v[188:191], v[4:7]
	v_mfma_f32_16x16x32_bf16 v[0:3], v[204:207], v[188:191], v[0:3]
	v_mfma_f32_16x16x32_bf16 v[28:31], v[200:203], v[84:87], v[28:31]
	v_mfma_f32_16x16x32_bf16 v[24:27], v[150:153], v[84:87], v[24:27]
	v_mfma_f32_16x16x32_bf16 v[20:23], v[200:203], v[170:173], v[20:23]
	v_mfma_f32_16x16x32_bf16 v[16:19], v[150:153], v[170:173], v[16:19]
	v_mfma_f32_16x16x32_bf16 v[12:15], v[200:203], v[184:187], v[12:15]
	v_mfma_f32_16x16x32_bf16 v[8:11], v[150:153], v[184:187], v[8:11]
	v_mfma_f32_16x16x32_bf16 v[4:7], v[200:203], v[192:195], v[4:7]
	v_mfma_f32_16x16x32_bf16 v[0:3], v[150:153], v[192:195], v[0:3]
	s_setprio 0
	s_barrier
	ds_read_b128 v[128:131], v145
	ds_read_b128 v[132:135], v145 offset:1024
	ds_read_b128 v[146:149], v145 offset:2048
	ds_read_b128 v[150:153], v145 offset:3072
	ds_read_b128 v[56:59], v142 offset:32768
	ds_read_b128 v[64:67], v142 offset:33792
	ds_read_b128 v[154:157], v141 offset:32768
	ds_read_b128 v[158:161], v141 offset:33792
	ds_read_b128 v[170:173], v140 offset:32768
	ds_read_b128 v[180:183], v140 offset:33792
	ds_read_b128 v[184:187], v139 offset:32768
	ds_read_b128 v[188:191], v139 offset:33792
	s_waitcnt vmcnt(2)
	s_barrier
; #define LDA(dst, b, h) _Pragma("unroll") for (int m = 0; m < 4; ++m) _Pragma("unroll") for (int k = 0; k < 2; ++k) \
;     dst[m][k] = *reinterpret_cast<const bf16x8*>((const char*)SA(b, h) + lds_byte(wr * 64 + m * 16 + fr, k * 32 + fq * 8))
; #define LDB(dst, b, h) _Pragma("unroll") for (int n = 0; n < 2; ++n) _Pragma("unroll") for (int k = 0; k < 2; ++k) \
;     dst[n][k] = *reinterpret_cast<const bf16x8*>((const char*)SB(b, h) + lds_byte(wc * 32 + n * 16 + fr, k * 32 + fq * 8))
; #define MMA(ai, bj, At_, Bt_) do { __builtin_amdgcn_s_setprio(1); \
;     _Pragma("unroll") for (int m = 0; m < 4; ++m) _Pragma("unroll") for (int n = 0; n < 2; ++n) _Pragma("unroll") for (int k = 0; k < 2; ++k) \
;       acc[ai][bj][m][n] = __builtin_amdgcn_mfma_f32_16x16x32_bf16(Bt_[n][k], At_[m][k], acc[ai][bj][m][n], 0, 0, 0); \
;     __builtin_amdgcn_s_setprio(0); } while (0)
; #define WAIT_V(n) asm volatile("s_waitcnt vmcnt(" #n ")" ::: "memory")
; #define WAIT_L(n) asm volatile("s_waitcnt lgkmcnt(" #n ")" ::: "memory")
; #define BAR __builtin_amdgcn_s_barrier()
; template <bool PF = true, class Epi, class KRF = KRFull>
; __device__ __forceinline__ void gemm_phase(const u16* __restrict__ A, int lda, const u16* __restrict__ Bt, int ldb, int K, int nM, int nN,
;                                            lds_u16* shm, Epi epi, KRF krf = KRFull(), bool flip = false) {
;     ...
;     { LDB(B0, 1, 0); LDA(At, 1, 0); WAIT_V(2); BAR; WAIT_L(0); MMA(0, 0, At, B0); BAR;
;       LDB(B1, 1, 1); WAIT_V(0); BAR; WAIT_L(0); MMA(0, 1, At, B1); BAR;
;       LDA(At, 1, 1); BAR; WAIT_L(0); MMA(1, 0, At, B0); MMA(1, 1, At, B1); BAR; }
;     if (wr == 0) BAR;
	s_waitcnt lgkmcnt(0)
	s_setprio 1
	s_waitcnt lgkmcnt(0)
	v_mfma_f32_16x16x32_bf16 v[84:87], v[128:131], v[56:59], v[124:127]
	v_mfma_f32_16x16x32_bf16 v[124:127], v[132:135], v[64:67], v[84:87]
	v_mfma_f32_16x16x32_bf16 v[84:87], v[146:149], v[56:59], v[120:123]
	v_mfma_f32_16x16x32_bf16 v[120:123], v[150:153], v[64:67], v[84:87]
	v_mfma_f32_16x16x32_bf16 v[84:87], v[128:131], v[154:157], v[116:119]
	v_mfma_f32_16x16x32_bf16 v[116:119], v[132:135], v[158:161], v[84:87]
	v_mfma_f32_16x16x32_bf16 v[84:87], v[146:149], v[154:157], v[112:115]
	v_mfma_f32_16x16x32_bf16 v[112:115], v[150:153], v[158:161], v[84:87]
	v_mfma_f32_16x16x32_bf16 v[84:87], v[128:131], v[170:173], v[108:111]
	v_mfma_f32_16x16x32_bf16 v[108:111], v[132:135], v[180:183], v[84:87]
	v_mfma_f32_16x16x32_bf16 v[84:87], v[146:149], v[170:173], v[104:107]
	v_mfma_f32_16x16x32_bf16 v[104:107], v[150:153], v[180:183], v[84:87]
	v_mfma_f32_16x16x32_bf16 v[84:87], v[128:131], v[184:187], v[100:103]
	v_mfma_f32_16x16x32_bf16 v[92:95], v[132:135], v[188:191], v[84:87]
	v_mfma_f32_16x16x32_bf16 v[84:87], v[146:149], v[184:187], v[96:99]
	v_mfma_f32_16x16x32_bf16 v[84:87], v[150:153], v[188:191], v[84:87]
	s_setprio 0
	s_barrier
	ds_read_b128 v[192:195], v143
	ds_read_b128 v[200:203], v143 offset:1024
	ds_read_b128 v[204:207], v143 offset:2048
	ds_read_b128 v[212:215], v143 offset:3072
	s_waitcnt vmcnt(0)
	s_barrier
	s_waitcnt lgkmcnt(0)
	s_setprio 1
	s_waitcnt lgkmcnt(0)
	v_mfma_f32_16x16x32_bf16 v[96:99], v[192:195], v[56:59], v[208:211]
	v_mfma_f32_16x16x32_bf16 v[56:59], v[204:207], v[56:59], v[88:91]
	v_mfma_f32_16x16x32_bf16 v[100:103], v[200:203], v[64:67], v[96:99]
	v_mfma_f32_16x16x32_bf16 v[96:99], v[212:215], v[64:67], v[56:59]
	v_mfma_f32_16x16x32_bf16 v[56:59], v[192:195], v[154:157], v[162:165]
	v_mfma_f32_16x16x32_bf16 v[88:91], v[200:203], v[158:161], v[56:59]
	v_mfma_f32_16x16x32_bf16 v[56:59], v[204:207], v[154:157], v[80:83]
	v_mfma_f32_16x16x32_bf16 v[80:83], v[212:215], v[158:161], v[56:59]
	v_mfma_f32_16x16x32_bf16 v[56:59], v[192:195], v[170:173], v[76:79]
	v_mfma_f32_16x16x32_bf16 v[76:79], v[200:203], v[180:183], v[56:59]
	v_mfma_f32_16x16x32_bf16 v[56:59], v[204:207], v[170:173], v[72:75]
	v_mfma_f32_16x16x32_bf16 v[72:75], v[212:215], v[180:183], v[56:59]
	v_mfma_f32_16x16x32_bf16 v[56:59], v[192:195], v[184:187], v[68:71]
	v_mfma_f32_16x16x32_bf16 v[64:67], v[200:203], v[188:191], v[56:59]
	v_mfma_f32_16x16x32_bf16 v[56:59], v[204:207], v[184:187], v[166:169]
	v_mfma_f32_16x16x32_bf16 v[56:59], v[212:215], v[188:191], v[56:59]
	s_setprio 0
	s_barrier
	ds_read_b128 v[154:157], v142 offset:49152
	ds_read_b128 v[142:145], v142 offset:50176
	ds_read_b128 v[158:161], v141 offset:49152
	ds_read_b128 v[162:165], v141 offset:50176
	ds_read_b128 v[166:169], v140 offset:49152
	ds_read_b128 v[170:173], v140 offset:50176
	ds_read_b128 v[180:183], v139 offset:49152
	ds_read_b128 v[184:187], v139 offset:50176
	s_barrier
	s_waitcnt lgkmcnt(0)
	s_setprio 1
	s_waitcnt lgkmcnt(0)
	v_mfma_f32_16x16x32_bf16 v[60:63], v[128:131], v[154:157], v[60:63]
	v_mfma_f32_16x16x32_bf16 v[68:71], v[132:135], v[142:145], v[60:63]
	v_mfma_f32_16x16x32_bf16 v[60:63], v[146:149], v[154:157], v[196:199]
	v_mfma_f32_16x16x32_bf16 v[52:55], v[128:131], v[158:161], v[52:55]
	v_mfma_f32_16x16x32_bf16 v[48:51], v[146:149], v[158:161], v[48:51]
	v_mfma_f32_16x16x32_bf16 v[44:47], v[128:131], v[166:169], v[44:47]
	v_mfma_f32_16x16x32_bf16 v[40:43], v[146:149], v[166:169], v[40:43]
	v_mfma_f32_16x16x32_bf16 v[36:39], v[128:131], v[180:183], v[36:39]
	v_mfma_f32_16x16x32_bf16 v[32:35], v[146:149], v[180:183], v[32:35]
	v_mfma_f32_16x16x32_bf16 v[60:63], v[150:153], v[142:145], v[60:63]
	v_mfma_f32_16x16x32_bf16 v[52:55], v[132:135], v[162:165], v[52:55]
	v_mfma_f32_16x16x32_bf16 v[48:51], v[150:153], v[162:165], v[48:51]
	v_mfma_f32_16x16x32_bf16 v[44:47], v[132:135], v[170:173], v[44:47]
	v_mfma_f32_16x16x32_bf16 v[40:43], v[150:153], v[170:173], v[40:43]
	v_mfma_f32_16x16x32_bf16 v[36:39], v[132:135], v[184:187], v[36:39]
	v_mfma_f32_16x16x32_bf16 v[32:35], v[150:153], v[184:187], v[32:35]
	s_setprio 0
	s_setprio 1
	v_mfma_f32_16x16x32_bf16 v[28:31], v[192:195], v[154:157], v[28:31]
	v_mfma_f32_16x16x32_bf16 v[24:27], v[204:207], v[154:157], v[24:27]
	v_mfma_f32_16x16x32_bf16 v[20:23], v[192:195], v[158:161], v[20:23]
	v_mfma_f32_16x16x32_bf16 v[16:19], v[204:207], v[158:161], v[16:19]
	v_mfma_f32_16x16x32_bf16 v[12:15], v[192:195], v[166:169], v[12:15]
	v_mfma_f32_16x16x32_bf16 v[8:11], v[204:207], v[166:169], v[8:11]
	v_mfma_f32_16x16x32_bf16 v[4:7], v[192:195], v[180:183], v[4:7]
	v_mfma_f32_16x16x32_bf16 v[0:3], v[204:207], v[180:183], v[0:3]
	v_mfma_f32_16x16x32_bf16 v[28:31], v[200:203], v[142:145], v[28:31]
	v_mfma_f32_16x16x32_bf16 v[24:27], v[212:215], v[142:145], v[24:27]
	v_mfma_f32_16x16x32_bf16 v[20:23], v[200:203], v[162:165], v[20:23]
	v_mfma_f32_16x16x32_bf16 v[16:19], v[212:215], v[162:165], v[16:19]
	v_mfma_f32_16x16x32_bf16 v[12:15], v[200:203], v[170:173], v[12:15]
	v_mfma_f32_16x16x32_bf16 v[8:11], v[212:215], v[170:173], v[8:11]
	v_mfma_f32_16x16x32_bf16 v[4:7], v[200:203], v[184:187], v[4:7]
	v_mfma_f32_16x16x32_bf16 v[0:3], v[212:215], v[184:187], v[0:3]
	s_setprio 0
	v_cmp_gt_u32_e32 vcc, s95, v138
	s_barrier
	s_and_saveexec_b64 s[16:17], vcc
	s_cbranch_execz .LBB0_2503
	s_barrier

; __device__ __forceinline__ int tid_l() { int t = threadIdx.x; asm volatile("" : "+v"(t)); return t; }
; __device__ __forceinline__ int bid_l() { int t = blockIdx.x; asm volatile("" : "+s"(t)); return t; }
; __device__ __forceinline__ int gdim_l() { int t = gridDim.x; asm volatile("" : "+s"(t)); return t; }
; #define STAGE_A(P, half, kt) do { const char* _u = Ab + ((size_t)(half) * 128 * lda + (size_t)(kt) * BK) * 2; \
;     _Pragma("unroll") for (int _i = 0; _i < 2; ++_i) \
;       __builtin_amdgcn_global_load_lds((const unsigned*)(_u + offA[_i]), \
;         (__attribute__((address_space(3))) unsigned*)((__attribute__((address_space(3))) char*)(P) + tidg * 16 + _i * 8192), 16, 0, 0); } while (0)
; #define WAIT_V(n) asm volatile("s_waitcnt vmcnt(" #n ")" ::: "memory")
; #define BAR __builtin_amdgcn_s_barrier()
; template <bool PF = true, class Epi, class KRF = KRFull>
; __device__ __forceinline__ void gemm_phase(const u16* __restrict__ A, int lda, const u16* __restrict__ Bt, int ldb, int K, int nM, int nN,
;                                            lds_u16* shm, Epi epi, KRF krf = KRFull(), bool flip = false) {
;   int tidg = tid_l();
;   int wid, lane, wr, wc, fr, fq;
;   int nt;
;   unsigned offA[2], offB[2];
;     ...
;   G_THREAD();
;   int ntile = nM * nN;
;   const int gdg = gdim_l();
;   const int bidg = flip ? (gdg - 1 - bid_l()) : bid_l();
;   int tix = bidg;
;   if (tix >= ntile) return;
;   int pm, pn; tile_map(tix, nM, nN, pm, pn);
;   int brow = pm * 256, bcol = pn * 256;
;   int2 kr = krf(bcol, K);
;   int nt_next = kr.y;
;   const char* Ab = (const char*)A + (size_t)brow * lda * 2 + kr.x * (BK * 2);
;   const char* Bb = (const char*)Bt + (size_t)bcol * ldb * 2 + kr.x * (BK * 2);
;   __syncthreads();
;   STAGE_B(SB(0, 0), 0, 0); STAGE_A(SA(0, 0), 0, 0);
;   STAGE_B(SB(0, 1), 1, 0); STAGE_A(SA(0, 1), 1, 0);
;   for (;;) {
;     G_THREAD();
;     nt = nt_next;
;     f32x4 acc[2][2][4][2] = {};
;     bf16x8 At[4][2], B0[2][2], B1[2][2];
;     if (wr == 1) BAR;
;     WAIT_V(4); BAR;
;     STAGE_B(SB(1, 0), 0, 1); STAGE_A(SA(1, 0), 0, 1); STAGE_B(SB(1, 1), 1, 1);
;     WAIT_V(6); BAR;
.LBB0_2516:
	s_or_b64 exec, exec, s[16:17]
	v_bfe_i32 v2, v162, 27, 1
	v_lshlrev_b32_e32 v143, 4, v162
	v_lshrrev_b32_e32 v2, 22, v2
	v_add_u32_e32 v2, v143, v2
	v_and_b32_e32 v2, 0xfffffc00, v2
	v_sub_u32_e32 v2, v143, v2
	v_lshrrev_b32_e32 v3, 4, v2
	v_bitop3_b32 v2, v3, v2, 32 bitop3:0x6c
	v_ashrrev_i32_e32 v5, 31, v2
	v_ashrrev_i32_e32 v1, 31, v162
	v_lshrrev_b32_e32 v5, 26, v5
	v_lshrrev_b32_e32 v1, 26, v1
	v_add_u32_e32 v5, v2, v5
	v_add_u32_e32 v1, v162, v1
	v_ashrrev_i32_e32 v6, 6, v5
	v_and_b32_e32 v5, 0xc0, v5
	v_ashrrev_i32_e32 v4, 6, v1
	v_sub_u32_e32 v2, v2, v5
	v_lshlrev_b32_e32 v3, 3, v4
	v_lshlrev_b32_e32 v7, 5, v4
	v_ashrrev_i16_sdwa v2, v232, sext(v2) dst_sel:DWORD dst_unused:UNUSED_PAD src0_sel:DWORD src1_sel:BYTE_0
	v_and_b32_e32 v3, 0xffff0, v3
	v_and_b32_e32 v7, 32, v7
	v_bfe_i32 v5, v2, 0, 16
	v_add_u32_e32 v2, v7, v5
	v_add_lshl_u32 v3, v6, v3, 12
	v_add_u32_e32 v145, 0x2000, v143
	v_lshl_add_u32 v178, v2, 1, v3
	v_ashrrev_i32_e32 v2, 31, v145
	v_lshrrev_b32_e32 v2, 22, v2
	v_add_u32_e32 v2, v145, v2
	v_ashrrev_i32_e32 v7, 10, v2
	v_mul_i32_i24_e32 v2, 0x400, v7
	v_sub_u32_e32 v2, v145, v2
	v_lshrrev_b32_e32 v3, 4, v2
	v_bitop3_b32 v2, v3, v2, 32 bitop3:0x6c
	v_ashrrev_i32_e32 v8, 31, v2
	v_lshrrev_b32_e32 v8, 26, v8
	v_add_u32_e32 v8, v2, v8
	v_ashrrev_i32_e32 v9, 6, v8
	v_and_b32_e32 v8, 0xc0, v8
	v_sub_u32_e32 v2, v2, v8
	v_lshlrev_b32_e32 v3, 3, v7
	v_lshlrev_b32_e32 v10, 5, v7
	v_ashrrev_i16_sdwa v2, v232, sext(v2) dst_sel:DWORD dst_unused:UNUSED_PAD src0_sel:DWORD src1_sel:BYTE_0
	v_and_b32_e32 v3, 0xffff0, v3
	v_and_b32_e32 v10, 32, v10
	v_bfe_i32 v8, v2, 0, 16
	v_add_u32_e32 v2, v10, v8
	v_add_lshl_u32 v3, v9, v3, 12
	v_add_u32_e32 v146, 0x18000, v143
	v_lshl_add_u32 v128, v2, 1, v3
	v_lshl_add_u64 v[2:3], s[10:11], 0, v[178:179]
	v_readfirstlane_b32 s2, v146
	v_lshl_add_u64 v[2:3], v[2:3], 0, s[60:61]
	s_mov_b32 m0, s2
	v_mov_b32_e32 v129, v179
	v_add_u32_e32 v147, 0x1a000, v143
	s_waitcnt vmcnt(4)
	s_barrier
	global_load_lds_dwordx4 v[2:3], off
	v_lshl_add_u64 v[2:3], s[10:11], 0, v[128:129]
	v_readfirstlane_b32 s2, v147
	v_lshl_add_u64 v[2:3], v[2:3], 0, s[60:61]
	s_mov_b32 m0, s2
	v_add_u32_e32 v148, 0x8000, v143
	global_load_lds_dwordx4 v[2:3], off
	v_lshl_add_u64 v[2:3], s[12:13], 0, v[178:179]
	v_readfirstlane_b32 s2, v148
	v_lshl_add_u64 v[2:3], v[2:3], 0, s[60:61]
	s_mov_b32 m0, s2
	v_add_u32_e32 v149, 0xa000, v143
	global_load_lds_dwordx4 v[2:3], off
	v_lshl_add_u64 v[2:3], s[12:13], 0, v[128:129]
	v_readfirstlane_b32 s2, v149
	v_add_u32_e32 v150, 0x1c000, v143
	v_lshl_add_u64 v[2:3], v[2:3], 0, s[60:61]
	s_mov_b32 m0, s2
	s_add_u32 s2, s10, 0x80080
	v_readfirstlane_b32 s15, v150
	v_add_u32_e32 v151, 0x1e000, v143
	global_load_lds_dwordx4 v[2:3], off
	s_addc_u32 s3, s11, 0
	s_mov_b32 m0, s15
	v_readfirstlane_b32 s15, v151
	global_load_lds_dwordx4 v178, s[2:3]
	s_mov_b32 m0, s15
	v_and_b32_e32 v10, 15, v162
	global_load_lds_dwordx4 v128, s[2:3]
	v_lshlrev_b32_e32 v2, 6, v10
	v_lshlrev_b32_e32 v10, 2, v162
	v_and_b32_e32 v11, 48, v162
	v_and_b32_e32 v10, 32, v10
	v_or_b32_e32 v3, v2, v11
	v_bitop3_b32 v12, v2, v10, v11 bitop3:0x36
	s_mov_b32 s2, 0x14000
	v_lshlrev_b32_e32 v2, 6, v162
	v_bitop3_b32 v14, v3, s2, v10 bitop3:0xde
	s_mov_b32 s2, 0x18000
	v_lshlrev_b32_e32 v18, 13, v0
	v_and_b32_e32 v0, 0x3c0, v2
	v_bitop3_b32 v13, v3, s94, v10 bitop3:0xde
	v_bitop3_b32 v15, v3, s2, v10 bitop3:0xde
	v_bitop3_b32 v16, v3, s97, v10 bitop3:0xde
	v_bitop3_b32 v10, v0, v10, v11 bitop3:0x36
	v_lshlrev_b32_e32 v0, 15, v4
	v_and_b32_e32 v17, 0x3000, v2
	v_and_b32_e32 v0, 0xffff0000, v0
	v_lshlrev_b32_e32 v2, 15, v7
	v_lshl_add_u32 v0, v6, 12, v0
	v_and_b32_e32 v2, 0xffff0000, v2
	v_and_or_b32 v0, v1, 64, v0
	v_lshl_add_u32 v2, v9, 12, v2
	v_lshlrev_b32_e32 v3, 6, v7
	s_waitcnt vmcnt(6)
	v_lshl_add_u32 v0, v5, 1, v0
	v_mov_b32_e32 v1, v179
	v_and_or_b32 v2, v3, 64, v2
	v_or_b32_e32 v11, 0x800, v18
	v_or_b32_e32 v19, 0x1000, v18
	v_or_b32_e32 v20, 0x1800, v18
	v_lshl_add_u64 v[130:131], s[10:11], 0, v[0:1]
	v_lshl_add_u32 v2, v8, 1, v2
	v_mov_b32_e32 v3, v179
	v_lshl_add_u64 v[134:135], s[12:13], 0, v[0:1]
	v_mov_b32_e32 v0, 0
	v_lshl_add_u64 v[132:133], s[10:11], 0, v[2:3]
	v_lshl_add_u64 v[136:137], s[12:13], 0, v[2:3]
	s_mov_b32 s2, -2
	s_mov_b64 s[20:21], 0
	v_add_u32_e32 v153, v13, v17
	v_add_u32_e32 v141, v12, v18
	v_add_u32_e32 v140, v10, v11
	v_add_u32_e32 v139, v10, v19
	v_add_u32_e32 v138, v10, v20
	v_add_u32_e32 v152, v14, v17
	v_add_u32_e32 v144, v15, v17
	v_add_u32_e32 v142, v16, v17
	v_mov_b32_e32 v1, v0
	v_mov_b32_e32 v2, v0
	v_mov_b32_e32 v3, v0
	v_mov_b32_e32 v4, v0
	v_mov_b32_e32 v5, v0
	v_mov_b32_e32 v6, v0
	v_mov_b32_e32 v7, v0
	v_mov_b32_e32 v8, v0
	v_mov_b32_e32 v9, v0
	v_mov_b32_e32 v10, v0
	v_mov_b32_e32 v11, v0
	v_mov_b32_e32 v12, v0
	v_mov_b32_e32 v13, v0
	v_mov_b32_e32 v14, v0
	v_mov_b32_e32 v15, v0
	v_mov_b32_e32 v16, v0
	v_mov_b32_e32 v17, v0
	v_mov_b32_e32 v18, v0
	v_mov_b32_e32 v19, v0
	v_mov_b32_e32 v20, v0
	v_mov_b32_e32 v21, v0
	v_mov_b32_e32 v22, v0
	v_mov_b32_e32 v23, v0
	v_mov_b32_e32 v24, v0
	v_mov_b32_e32 v25, v0
	v_mov_b32_e32 v26, v0
	v_mov_b32_e32 v27, v0
	v_mov_b32_e32 v28, v0
	v_mov_b32_e32 v29, v0
	v_mov_b32_e32 v30, v0
	v_mov_b32_e32 v31, v0
	v_mov_b32_e32 v32, v0
	v_mov_b32_e32 v33, v0
	v_mov_b32_e32 v34, v0
	v_mov_b32_e32 v35, v0
	v_mov_b32_e32 v36, v0
	v_mov_b32_e32 v37, v0
	v_mov_b32_e32 v38, v0
	v_mov_b32_e32 v39, v0
	v_mov_b32_e32 v40, v0
	v_mov_b32_e32 v41, v0
	v_mov_b32_e32 v42, v0
	v_mov_b32_e32 v43, v0
	v_mov_b32_e32 v44, v0
	v_mov_b32_e32 v45, v0
	v_mov_b32_e32 v46, v0
	v_mov_b32_e32 v47, v0
	v_mov_b32_e32 v48, v0
	v_mov_b32_e32 v49, v0
	v_mov_b32_e32 v50, v0
; #define STAGE_A(P, half, kt) do { const char* _u = Ab + ((size_t)(half) * 128 * lda + (size_t)(kt) * BK) * 2; \
;     _Pragma("unroll") for (int _i = 0; _i < 2; ++_i) \
;       __builtin_amdgcn_global_load_lds((const unsigned*)(_u + offA[_i]), \
;         (__attribute__((address_space(3))) unsigned*)((__attribute__((address_space(3))) char*)(P) + tidg * 16 + _i * 8192), 16, 0, 0); } while (0)
; #define STAGE_B(P, half, kt) do { const char* _u = Bb + ((size_t)(half) * 128 * ldb + (size_t)(kt) * BK) * 2; \
;     _Pragma("unroll") for (int _i = 0; _i < 2; ++_i) \
;       __builtin_amdgcn_global_load_lds((const unsigned*)(_u + offB[_i]), \
;         (__attribute__((address_space(3))) unsigned*)((__attribute__((address_space(3))) char*)(P) + tidg * 16 + _i * 8192), 16, 0, 0); } while (0)
; #define LDA(dst, b, h) _Pragma("unroll") for (int m = 0; m < 4; ++m) _Pragma("unroll") for (int k = 0; k < 2; ++k) \
;     dst[m][k] = *reinterpret_cast<const bf16x8*>((const char*)SA(b, h) + lds_byte(wr * 64 + m * 16 + fr, k * 32 + fq * 8))
; #define LDB(dst, b, h) _Pragma("unroll") for (int n = 0; n < 2; ++n) _Pragma("unroll") for (int k = 0; k < 2; ++k) \
;     dst[n][k] = *reinterpret_cast<const bf16x8*>((const char*)SB(b, h) + lds_byte(wc * 32 + n * 16 + fr, k * 32 + fq * 8))
; #define WAIT_V(n) asm volatile("s_waitcnt vmcnt(" #n ")" ::: "memory")
; #define WAIT_L(n) asm volatile("s_waitcnt lgkmcnt(" #n ")" ::: "memory")
; template <bool PF = true, class Epi, class KRF = KRFull>
; __device__ __forceinline__ void gemm_phase(const u16* __restrict__ A, int lda, const u16* __restrict__ Bt, int ldb, int K, int nM, int nN,
;                                            lds_u16* shm, Epi epi, KRF krf = KRFull(), bool flip = false) {
;     ...
;     f32x4 acc[2][2][4][2] = {};
;     bf16x8 At[4][2], B0[2][2], B1[2][2];
;     if (wr == 1) BAR;
;     WAIT_V(4); BAR;
;     STAGE_B(SB(1, 0), 0, 1); STAGE_A(SA(1, 0), 0, 1); STAGE_B(SB(1, 1), 1, 1);
;     WAIT_V(6); BAR;
;     for (int t = 0; t < nt - 2; t += 2) {
;       LDB(B0, 0, 0); SCHED; LDA(At, 0, 0); STAGE_A(SA(1, 1), 1, t + 1);
;       WAIT_L(8); BAR; WAIT_L(0); MMA(0, 0, At, B0); BAR; SCHED;
;       LDB(B1, 0, 1); STAGE_B(SB(0, 0), 0, t + 2);
;       BAR; WAIT_L(0); MMA(0, 1, At, B1); BAR;
;       LDA(At, 0, 1); STAGE_A(SA(0, 0), 0, t + 2);
;       BAR; WAIT_L(0); MMA(1, 0, At, B0); BAR; SCHED;
;       STAGE_B(SB(0, 1), 1, t + 2);
	v_mov_b32_e32 v51, v0
	v_mov_b32_e32 v52, v0
	v_mov_b32_e32 v53, v0
	v_mov_b32_e32 v54, v0
	v_mov_b32_e32 v55, v0
	v_mov_b32_e32 v56, v0
	v_mov_b32_e32 v57, v0
	v_mov_b32_e32 v58, v0
	v_mov_b32_e32 v59, v0
	v_mov_b32_e32 v60, v0
	v_mov_b32_e32 v61, v0
	v_mov_b32_e32 v62, v0
	v_mov_b32_e32 v63, v0
	v_mov_b32_e32 v64, v0
	v_mov_b32_e32 v65, v0
	v_mov_b32_e32 v66, v0
	v_mov_b32_e32 v67, v0
	v_mov_b32_e32 v68, v0
	v_mov_b32_e32 v69, v0
	v_mov_b32_e32 v70, v0
	v_mov_b32_e32 v71, v0
	v_mov_b32_e32 v72, v0
	v_mov_b32_e32 v73, v0
	v_mov_b32_e32 v74, v0
	v_mov_b32_e32 v75, v0
	v_mov_b32_e32 v76, v0
	v_mov_b32_e32 v77, v0
	v_mov_b32_e32 v78, v0
	v_mov_b32_e32 v79, v0
	v_mov_b32_e32 v80, v0
	v_mov_b32_e32 v81, v0
	v_mov_b32_e32 v82, v0
	v_mov_b32_e32 v83, v0
	v_mov_b32_e32 v84, v0
	v_mov_b32_e32 v85, v0
	v_mov_b32_e32 v86, v0
	v_mov_b32_e32 v87, v0
	v_mov_b32_e32 v88, v0
	v_mov_b32_e32 v89, v0
	v_mov_b32_e32 v90, v0
	v_mov_b32_e32 v91, v0
	v_mov_b32_e32 v92, v0
	v_mov_b32_e32 v93, v0
	v_mov_b32_e32 v94, v0
	v_mov_b32_e32 v95, v0
	v_mov_b32_e32 v96, v0
	v_mov_b32_e32 v97, v0
	v_mov_b32_e32 v98, v0
	v_mov_b32_e32 v99, v0
	v_mov_b32_e32 v100, v0
	v_mov_b32_e32 v101, v0
	v_mov_b32_e32 v102, v0
	v_mov_b32_e32 v103, v0
	v_mov_b32_e32 v104, v0
	v_mov_b32_e32 v105, v0
	v_mov_b32_e32 v106, v0
	v_mov_b32_e32 v107, v0
	v_mov_b32_e32 v108, v0
	v_mov_b32_e32 v109, v0
	v_mov_b32_e32 v110, v0
	v_mov_b32_e32 v111, v0
	v_mov_b32_e32 v112, v0
	v_mov_b32_e32 v113, v0
	v_mov_b32_e32 v114, v0
	v_mov_b32_e32 v115, v0
	v_mov_b32_e32 v116, v0
	v_mov_b32_e32 v117, v0
	v_mov_b32_e32 v118, v0
	v_mov_b32_e32 v119, v0
	v_mov_b32_e32 v120, v0
	v_mov_b32_e32 v121, v0
	v_mov_b32_e32 v122, v0
	v_mov_b32_e32 v123, v0
	v_mov_b32_e32 v124, v0
	v_mov_b32_e32 v125, v0
	v_mov_b32_e32 v126, v0
	v_mov_b32_e32 v127, v0
	s_barrier
	v_readfirstlane_b32 s3, v143
.LBB0_2517:
	ds_read_b128 v[156:159], v153
	ds_read_b128 v[164:167], v153 offset:1024
	ds_read_b128 v[168:171], v153 offset:2048
	ds_read_b128 v[172:175], v153 offset:3072
	v_lshl_add_u64 v[160:161], v[134:135], 0, s[20:21]
	v_lshl_add_u64 v[212:213], v[160:161], 0, s[62:63]
	s_add_u32 m0, s3, 0xc000
	v_lshl_add_u64 v[234:235], v[136:137], 0, s[20:21]
	ds_read_b128 v[180:183], v141
	ds_read_b128 v[184:187], v141 offset:1024
	ds_read_b128 v[188:191], v140
	ds_read_b128 v[192:195], v140 offset:1024
	ds_read_b128 v[196:199], v139
	ds_read_b128 v[200:203], v139 offset:1024
	ds_read_b128 v[204:207], v138
	ds_read_b128 v[208:211], v138 offset:1024
	global_load_lds_dwordx4 v[212:213], off
	v_lshl_add_u64 v[212:213], v[234:235], 0, s[62:63]
	s_add_u32 m0, s3, 0xe000
	s_nop 0
	global_load_lds_dwordx4 v[212:213], off
	s_waitcnt lgkmcnt(8)
	s_barrier
	s_waitcnt lgkmcnt(0)
	s_setprio 1
	s_waitcnt lgkmcnt(0)
	v_mfma_f32_16x16x32_bf16 v[124:127], v[156:159], v[180:183], v[124:127]
	v_mfma_f32_16x16x32_bf16 v[120:123], v[168:171], v[180:183], v[120:123]
	v_mfma_f32_16x16x32_bf16 v[116:119], v[156:159], v[188:191], v[116:119]
	v_mfma_f32_16x16x32_bf16 v[112:115], v[168:171], v[188:191], v[112:115]
	v_mfma_f32_16x16x32_bf16 v[108:111], v[156:159], v[196:199], v[108:111]
	v_mfma_f32_16x16x32_bf16 v[104:107], v[168:171], v[196:199], v[104:107]
	v_mfma_f32_16x16x32_bf16 v[100:103], v[156:159], v[204:207], v[100:103]
	v_mfma_f32_16x16x32_bf16 v[96:99], v[168:171], v[204:207], v[96:99]
	v_mfma_f32_16x16x32_bf16 v[124:127], v[164:167], v[184:187], v[124:127]
	v_mfma_f32_16x16x32_bf16 v[120:123], v[172:175], v[184:187], v[120:123]
	v_mfma_f32_16x16x32_bf16 v[116:119], v[164:167], v[192:195], v[116:119]
	v_mfma_f32_16x16x32_bf16 v[112:115], v[172:175], v[192:195], v[112:115]
	v_mfma_f32_16x16x32_bf16 v[108:111], v[164:167], v[200:203], v[108:111]
	v_mfma_f32_16x16x32_bf16 v[104:107], v[172:175], v[200:203], v[104:107]
	v_mfma_f32_16x16x32_bf16 v[100:103], v[164:167], v[208:211], v[100:103]
	v_mfma_f32_16x16x32_bf16 v[96:99], v[172:175], v[208:211], v[96:99]
	s_setprio 0
	s_barrier
	v_lshl_add_u64 v[236:237], v[130:131], 0, s[20:21]
	v_lshl_add_u64 v[238:239], v[236:237], 0, s[64:65]
	s_add_u32 m0, s3, 0x10000
	ds_read_b128 v[212:215], v152
	ds_read_b128 v[216:219], v152 offset:1024
	ds_read_b128 v[222:225], v152 offset:2048
	ds_read_b128 v[226:229], v152 offset:3072
	global_load_lds_dwordx4 v[238:239], off
	v_lshl_add_u64 v[238:239], v[132:133], 0, s[20:21]
	v_lshl_add_u64 v[240:241], v[238:239], 0, s[64:65]
	s_add_u32 m0, s3, 0x12000
	s_nop 0
	global_load_lds_dwordx4 v[240:241], off
	s_barrier
	s_waitcnt lgkmcnt(0)
	s_setprio 1
	s_waitcnt lgkmcnt(0)
	v_mfma_f32_16x16x32_bf16 v[92:95], v[212:215], v[180:183], v[92:95]
	v_mfma_f32_16x16x32_bf16 v[88:91], v[222:225], v[180:183], v[88:91]
	v_mfma_f32_16x16x32_bf16 v[84:87], v[212:215], v[188:191], v[84:87]
	v_mfma_f32_16x16x32_bf16 v[80:83], v[222:225], v[188:191], v[80:83]
	v_mfma_f32_16x16x32_bf16 v[76:79], v[212:215], v[196:199], v[76:79]
	v_mfma_f32_16x16x32_bf16 v[72:75], v[222:225], v[196:199], v[72:75]
	v_mfma_f32_16x16x32_bf16 v[68:71], v[212:215], v[204:207], v[68:71]
	v_mfma_f32_16x16x32_bf16 v[64:67], v[222:225], v[204:207], v[64:67]
	v_mfma_f32_16x16x32_bf16 v[92:95], v[216:219], v[184:187], v[92:95]
	v_mfma_f32_16x16x32_bf16 v[88:91], v[226:229], v[184:187], v[88:91]
	v_mfma_f32_16x16x32_bf16 v[84:87], v[216:219], v[192:195], v[84:87]
	v_mfma_f32_16x16x32_bf16 v[80:83], v[226:229], v[192:195], v[80:83]
	v_mfma_f32_16x16x32_bf16 v[76:79], v[216:219], v[200:203], v[76:79]
	v_mfma_f32_16x16x32_bf16 v[72:75], v[226:229], v[200:203], v[72:75]
	v_mfma_f32_16x16x32_bf16 v[68:71], v[216:219], v[208:211], v[68:71]
	v_mfma_f32_16x16x32_bf16 v[64:67], v[226:229], v[208:211], v[64:67]
	s_setprio 0
	v_lshl_add_u64 v[240:241], v[160:161], 0, s[64:65]
	s_mov_b32 m0, s3
	s_barrier
; #define STAGE_A(P, half, kt) do { const char* _u = Ab + ((size_t)(half) * 128 * lda + (size_t)(kt) * BK) * 2; \
;     _Pragma("unroll") for (int _i = 0; _i < 2; ++_i) \
;       __builtin_amdgcn_global_load_lds((const unsigned*)(_u + offA[_i]), \
;         (__attribute__((address_space(3))) unsigned*)((__attribute__((address_space(3))) char*)(P) + tidg * 16 + _i * 8192), 16, 0, 0); } while (0)
; #define STAGE_B(P, half, kt) do { const char* _u = Bb + ((size_t)(half) * 128 * ldb + (size_t)(kt) * BK) * 2; \
;     _Pragma("unroll") for (int _i = 0; _i < 2; ++_i) \
;       __builtin_amdgcn_global_load_lds((const unsigned*)(_u + offB[_i]), \
;         (__attribute__((address_space(3))) unsigned*)((__attribute__((address_space(3))) char*)(P) + tidg * 16 + _i * 8192), 16, 0, 0); } while (0)
; #define LDA(dst, b, h) _Pragma("unroll") for (int m = 0; m < 4; ++m) _Pragma("unroll") for (int k = 0; k < 2; ++k) \
;     dst[m][k] = *reinterpret_cast<const bf16x8*>((const char*)SA(b, h) + lds_byte(wr * 64 + m * 16 + fr, k * 32 + fq * 8))
; #define LDB(dst, b, h) _Pragma("unroll") for (int n = 0; n < 2; ++n) _Pragma("unroll") for (int k = 0; k < 2; ++k) \
;     dst[n][k] = *reinterpret_cast<const bf16x8*>((const char*)SB(b, h) + lds_byte(wc * 32 + n * 16 + fr, k * 32 + fq * 8))
; #define MMA(ai, bj, At_, Bt_) do { __builtin_amdgcn_s_setprio(1); \
;     _Pragma("unroll") for (int m = 0; m < 4; ++m) _Pragma("unroll") for (int n = 0; n < 2; ++n) _Pragma("unroll") for (int k = 0; k < 2; ++k) \
;       acc[ai][bj][m][n] = __builtin_amdgcn_mfma_f32_16x16x32_bf16(Bt_[n][k], At_[m][k], acc[ai][bj][m][n], 0, 0, 0); \
;     __builtin_amdgcn_s_setprio(0); } while (0)
; template <bool PF = true, class Epi, class KRF = KRFull>
; __device__ __forceinline__ void gemm_phase(const u16* __restrict__ A, int lda, const u16* __restrict__ Bt, int ldb, int K, int nM, int nN,
;                                            lds_u16* shm, Epi epi, KRF krf = KRFull(), bool flip = false) {
;     ...
;       LDA(At, 0, 1); STAGE_A(SA(0, 0), 0, t + 2);
;       BAR; WAIT_L(0); MMA(1, 0, At, B0); BAR; SCHED;
;       STAGE_B(SB(0, 1), 1, t + 2);
;       WAIT_V(6); BAR; MMA(1, 1, At, B1); BAR;
;       LDB(B0, 1, 0); SCHED; LDA(At, 1, 0); STAGE_A(SA(0, 1), 1, t + 2);
;       WAIT_L(8); BAR; WAIT_L(0); MMA(0, 0, At, B0); BAR; SCHED;
;       LDB(B1, 1, 1); STAGE_B(SB(1, 0), 0, t + 3);
	ds_read_b128 v[180:183], v141 offset:16384
	ds_read_b128 v[184:187], v141 offset:17408
	ds_read_b128 v[188:191], v140 offset:16384
	ds_read_b128 v[192:195], v140 offset:17408
	ds_read_b128 v[196:199], v139 offset:16384
	ds_read_b128 v[200:203], v139 offset:17408
	ds_read_b128 v[204:207], v138 offset:16384
	ds_read_b128 v[208:211], v138 offset:17408
	global_load_lds_dwordx4 v[240:241], off
	v_lshl_add_u64 v[240:241], v[234:235], 0, s[64:65]
	s_add_u32 m0, s3, 0x2000
	s_nop 0
	global_load_lds_dwordx4 v[240:241], off
	s_barrier
	s_waitcnt lgkmcnt(0)
	s_setprio 1
	s_waitcnt lgkmcnt(0)
	v_mfma_f32_16x16x32_bf16 v[60:63], v[156:159], v[180:183], v[60:63]
	v_mfma_f32_16x16x32_bf16 v[56:59], v[168:171], v[180:183], v[56:59]
	v_mfma_f32_16x16x32_bf16 v[52:55], v[156:159], v[188:191], v[52:55]
	v_mfma_f32_16x16x32_bf16 v[48:51], v[168:171], v[188:191], v[48:51]
	v_mfma_f32_16x16x32_bf16 v[44:47], v[156:159], v[196:199], v[44:47]
	v_mfma_f32_16x16x32_bf16 v[40:43], v[168:171], v[196:199], v[40:43]
	v_mfma_f32_16x16x32_bf16 v[36:39], v[156:159], v[204:207], v[36:39]
	v_mfma_f32_16x16x32_bf16 v[32:35], v[168:171], v[204:207], v[32:35]
	v_mfma_f32_16x16x32_bf16 v[60:63], v[164:167], v[184:187], v[60:63]
	v_mfma_f32_16x16x32_bf16 v[56:59], v[172:175], v[184:187], v[56:59]
	v_mfma_f32_16x16x32_bf16 v[52:55], v[164:167], v[192:195], v[52:55]
	v_mfma_f32_16x16x32_bf16 v[48:51], v[172:175], v[192:195], v[48:51]
	v_mfma_f32_16x16x32_bf16 v[44:47], v[164:167], v[200:203], v[44:47]
	v_mfma_f32_16x16x32_bf16 v[40:43], v[172:175], v[200:203], v[40:43]
	v_mfma_f32_16x16x32_bf16 v[36:39], v[164:167], v[208:211], v[36:39]
	v_mfma_f32_16x16x32_bf16 v[32:35], v[172:175], v[208:211], v[32:35]
	s_setprio 0
	s_barrier
	v_lshl_add_u64 v[156:157], v[236:237], 0, s[66:67]
	s_add_u32 m0, s3, 0x14000
	s_nop 0
	global_load_lds_dwordx4 v[156:157], off
	v_lshl_add_u64 v[156:157], v[238:239], 0, s[66:67]
	s_add_u32 m0, s3, 0x16000
	s_nop 0
	global_load_lds_dwordx4 v[156:157], off
	s_waitcnt vmcnt(6)
	s_barrier
	s_setprio 1
	v_mfma_f32_16x16x32_bf16 v[28:31], v[212:215], v[180:183], v[28:31]
	v_mfma_f32_16x16x32_bf16 v[24:27], v[222:225], v[180:183], v[24:27]
	v_mfma_f32_16x16x32_bf16 v[20:23], v[212:215], v[188:191], v[20:23]
	v_mfma_f32_16x16x32_bf16 v[16:19], v[222:225], v[188:191], v[16:19]
	v_mfma_f32_16x16x32_bf16 v[12:15], v[212:215], v[196:199], v[12:15]
	v_mfma_f32_16x16x32_bf16 v[8:11], v[222:225], v[196:199], v[8:11]
	v_mfma_f32_16x16x32_bf16 v[4:7], v[212:215], v[204:207], v[4:7]
	v_mfma_f32_16x16x32_bf16 v[0:3], v[222:225], v[204:207], v[0:3]
	v_mfma_f32_16x16x32_bf16 v[28:31], v[216:219], v[184:187], v[28:31]
	v_mfma_f32_16x16x32_bf16 v[24:27], v[226:229], v[184:187], v[24:27]
	v_mfma_f32_16x16x32_bf16 v[20:23], v[216:219], v[192:195], v[20:23]
	v_mfma_f32_16x16x32_bf16 v[16:19], v[226:229], v[192:195], v[16:19]
	v_mfma_f32_16x16x32_bf16 v[12:15], v[216:219], v[200:203], v[12:15]
	v_mfma_f32_16x16x32_bf16 v[8:11], v[226:229], v[200:203], v[8:11]
	v_mfma_f32_16x16x32_bf16 v[4:7], v[216:219], v[208:211], v[4:7]
	v_mfma_f32_16x16x32_bf16 v[0:3], v[226:229], v[208:211], v[0:3]
	s_setprio 0
	s_barrier
	ds_read_b128 v[156:159], v144
	ds_read_b128 v[164:167], v144 offset:1024
	ds_read_b128 v[168:171], v144 offset:2048
	ds_read_b128 v[172:175], v144 offset:3072
	v_lshl_add_u64 v[212:213], v[160:161], 0, s[66:67]
	s_add_u32 m0, s3, 0x4000
	ds_read_b128 v[180:183], v141 offset:32768
	ds_read_b128 v[184:187], v141 offset:33792
	ds_read_b128 v[188:191], v140 offset:32768
	ds_read_b128 v[192:195], v140 offset:33792
	ds_read_b128 v[196:199], v139 offset:32768
	ds_read_b128 v[200:203], v139 offset:33792
	ds_read_b128 v[204:207], v138 offset:32768
	ds_read_b128 v[208:211], v138 offset:33792
	global_load_lds_dwordx4 v[212:213], off
	v_lshl_add_u64 v[212:213], v[234:235], 0, s[66:67]
	s_add_u32 m0, s3, 0x6000
	s_nop 0
	global_load_lds_dwordx4 v[212:213], off
	s_waitcnt lgkmcnt(8)
	s_barrier
	s_waitcnt lgkmcnt(0)
	s_setprio 1
	s_waitcnt lgkmcnt(0)
	v_mfma_f32_16x16x32_bf16 v[124:127], v[156:159], v[180:183], v[124:127]
	v_mfma_f32_16x16x32_bf16 v[120:123], v[168:171], v[180:183], v[120:123]
	v_mfma_f32_16x16x32_bf16 v[116:119], v[156:159], v[188:191], v[116:119]
	v_mfma_f32_16x16x32_bf16 v[112:115], v[168:171], v[188:191], v[112:115]
	v_mfma_f32_16x16x32_bf16 v[108:111], v[156:159], v[196:199], v[108:111]
	v_mfma_f32_16x16x32_bf16 v[104:107], v[168:171], v[196:199], v[104:107]
	v_mfma_f32_16x16x32_bf16 v[100:103], v[156:159], v[204:207], v[100:103]
	v_mfma_f32_16x16x32_bf16 v[96:99], v[168:171], v[204:207], v[96:99]
	v_mfma_f32_16x16x32_bf16 v[124:127], v[164:167], v[184:187], v[124:127]
	v_mfma_f32_16x16x32_bf16 v[120:123], v[172:175], v[184:187], v[120:123]
	v_mfma_f32_16x16x32_bf16 v[116:119], v[164:167], v[192:195], v[116:119]
	v_mfma_f32_16x16x32_bf16 v[112:115], v[172:175], v[192:195], v[112:115]
	v_mfma_f32_16x16x32_bf16 v[108:111], v[164:167], v[200:203], v[108:111]
	v_mfma_f32_16x16x32_bf16 v[104:107], v[172:175], v[200:203], v[104:107]
	v_mfma_f32_16x16x32_bf16 v[100:103], v[164:167], v[208:211], v[100:103]
	v_mfma_f32_16x16x32_bf16 v[96:99], v[172:175], v[208:211], v[96:99]
	s_setprio 0
	s_barrier
	v_lshl_add_u64 v[240:241], v[236:237], 0, s[68:69]
	s_add_u32 m0, s3, 0x18000
	ds_read_b128 v[212:215], v142
	ds_read_b128 v[216:219], v142 offset:1024
	ds_read_b128 v[222:225], v142 offset:2048
	ds_read_b128 v[226:229], v142 offset:3072
	global_load_lds_dwordx4 v[240:241], off
	v_lshl_add_u64 v[240:241], v[238:239], 0, s[68:69]
	s_add_u32 m0, s3, 0x1a000
	s_nop 0
	global_load_lds_dwordx4 v[240:241], off
	s_barrier
; #define STAGE_A(P, half, kt) do { const char* _u = Ab + ((size_t)(half) * 128 * lda + (size_t)(kt) * BK) * 2; \
;     _Pragma("unroll") for (int _i = 0; _i < 2; ++_i) \
;       __builtin_amdgcn_global_load_lds((const unsigned*)(_u + offA[_i]), \
;         (__attribute__((address_space(3))) unsigned*)((__attribute__((address_space(3))) char*)(P) + tidg * 16 + _i * 8192), 16, 0, 0); } while (0)
; #define STAGE_B(P, half, kt) do { const char* _u = Bb + ((size_t)(half) * 128 * ldb + (size_t)(kt) * BK) * 2; \
;     _Pragma("unroll") for (int _i = 0; _i < 2; ++_i) \
;       __builtin_amdgcn_global_load_lds((const unsigned*)(_u + offB[_i]), \
;         (__attribute__((address_space(3))) unsigned*)((__attribute__((address_space(3))) char*)(P) + tidg * 16 + _i * 8192), 16, 0, 0); } while (0)
; #define LDA(dst, b, h) _Pragma("unroll") for (int m = 0; m < 4; ++m) _Pragma("unroll") for (int k = 0; k < 2; ++k) \
;     dst[m][k] = *reinterpret_cast<const bf16x8*>((const char*)SA(b, h) + lds_byte(wr * 64 + m * 16 + fr, k * 32 + fq * 8))
; #define LDB(dst, b, h) _Pragma("unroll") for (int n = 0; n < 2; ++n) _Pragma("unroll") for (int k = 0; k < 2; ++k) \
;     dst[n][k] = *reinterpret_cast<const bf16x8*>((const char*)SB(b, h) + lds_byte(wc * 32 + n * 16 + fr, k * 32 + fq * 8))
; #define MMA(ai, bj, At_, Bt_) do { __builtin_amdgcn_s_setprio(1); \
;     _Pragma("unroll") for (int m = 0; m < 4; ++m) _Pragma("unroll") for (int n = 0; n < 2; ++n) _Pragma("unroll") for (int k = 0; k < 2; ++k) \
;       acc[ai][bj][m][n] = __builtin_amdgcn_mfma_f32_16x16x32_bf16(Bt_[n][k], At_[m][k], acc[ai][bj][m][n], 0, 0, 0); \
;     __builtin_amdgcn_s_setprio(0); } while (0)
; #define BAR __builtin_amdgcn_s_barrier()
; template <bool PF = true, class Epi, class KRF = KRFull>
; __device__ __forceinline__ void gemm_phase(const u16* __restrict__ A, int lda, const u16* __restrict__ Bt, int ldb, int K, int nM, int nN,
;                                            lds_u16* shm, Epi epi, KRF krf = KRFull(), bool flip = false) {
;     ...
;       LDB(B1, 1, 1); STAGE_B(SB(1, 0), 0, t + 3);
;       BAR; WAIT_L(0); MMA(0, 1, At, B1); BAR;
;       LDA(At, 1, 1); STAGE_A(SA(1, 0), 0, t + 3);
;       BAR; WAIT_L(0); MMA(1, 0, At, B0); BAR; SCHED;
;       STAGE_B(SB(1, 1), 1, t + 3);
;       WAIT_V(6); BAR; MMA(1, 1, At, B1); BAR;
;     }
;     { LDB(B0, 0, 0); LDA(At, 0, 0); STAGE_A(SA(1, 1), 1, nt - 1);
	s_waitcnt lgkmcnt(0)
	s_setprio 1
	s_waitcnt lgkmcnt(0)
	v_mfma_f32_16x16x32_bf16 v[92:95], v[212:215], v[180:183], v[92:95]
	v_mfma_f32_16x16x32_bf16 v[88:91], v[222:225], v[180:183], v[88:91]
	v_mfma_f32_16x16x32_bf16 v[84:87], v[212:215], v[188:191], v[84:87]
	v_mfma_f32_16x16x32_bf16 v[80:83], v[222:225], v[188:191], v[80:83]
	v_mfma_f32_16x16x32_bf16 v[76:79], v[212:215], v[196:199], v[76:79]
	v_mfma_f32_16x16x32_bf16 v[72:75], v[222:225], v[196:199], v[72:75]
	v_mfma_f32_16x16x32_bf16 v[68:71], v[212:215], v[204:207], v[68:71]
	v_mfma_f32_16x16x32_bf16 v[64:67], v[222:225], v[204:207], v[64:67]
	v_mfma_f32_16x16x32_bf16 v[92:95], v[216:219], v[184:187], v[92:95]
	v_mfma_f32_16x16x32_bf16 v[88:91], v[226:229], v[184:187], v[88:91]
	v_mfma_f32_16x16x32_bf16 v[84:87], v[216:219], v[192:195], v[84:87]
	v_mfma_f32_16x16x32_bf16 v[80:83], v[226:229], v[192:195], v[80:83]
	v_mfma_f32_16x16x32_bf16 v[76:79], v[216:219], v[200:203], v[76:79]
	v_mfma_f32_16x16x32_bf16 v[72:75], v[226:229], v[200:203], v[72:75]
	v_mfma_f32_16x16x32_bf16 v[68:71], v[216:219], v[208:211], v[68:71]
	v_mfma_f32_16x16x32_bf16 v[64:67], v[226:229], v[208:211], v[64:67]
	s_setprio 0
	v_lshl_add_u64 v[160:161], v[160:161], 0, s[68:69]
	s_add_u32 m0, s3, 0x8000
	s_barrier
	ds_read_b128 v[180:183], v141 offset:49152
	ds_read_b128 v[184:187], v141 offset:50176
	ds_read_b128 v[188:191], v140 offset:49152
	ds_read_b128 v[192:195], v140 offset:50176
	ds_read_b128 v[196:199], v139 offset:49152
	ds_read_b128 v[200:203], v139 offset:50176
	ds_read_b128 v[204:207], v138 offset:49152
	ds_read_b128 v[208:211], v138 offset:50176
	global_load_lds_dwordx4 v[160:161], off
	v_lshl_add_u64 v[160:161], v[234:235], 0, s[68:69]
	s_add_u32 m0, s3, 0xa000
	s_nop 0
	global_load_lds_dwordx4 v[160:161], off
	s_barrier
	s_waitcnt lgkmcnt(0)
	s_setprio 1
	s_waitcnt lgkmcnt(0)
	v_mfma_f32_16x16x32_bf16 v[60:63], v[156:159], v[180:183], v[60:63]
	v_mfma_f32_16x16x32_bf16 v[56:59], v[168:171], v[180:183], v[56:59]
	v_mfma_f32_16x16x32_bf16 v[52:55], v[156:159], v[188:191], v[52:55]
	v_mfma_f32_16x16x32_bf16 v[48:51], v[168:171], v[188:191], v[48:51]
	v_mfma_f32_16x16x32_bf16 v[44:47], v[156:159], v[196:199], v[44:47]
	v_mfma_f32_16x16x32_bf16 v[40:43], v[168:171], v[196:199], v[40:43]
	v_mfma_f32_16x16x32_bf16 v[36:39], v[156:159], v[204:207], v[36:39]
	v_mfma_f32_16x16x32_bf16 v[32:35], v[168:171], v[204:207], v[32:35]
	v_mfma_f32_16x16x32_bf16 v[60:63], v[164:167], v[184:187], v[60:63]
	v_mfma_f32_16x16x32_bf16 v[56:59], v[172:175], v[184:187], v[56:59]
	v_mfma_f32_16x16x32_bf16 v[52:55], v[164:167], v[192:195], v[52:55]
	v_mfma_f32_16x16x32_bf16 v[48:51], v[172:175], v[192:195], v[48:51]
	v_mfma_f32_16x16x32_bf16 v[44:47], v[164:167], v[200:203], v[44:47]
	v_mfma_f32_16x16x32_bf16 v[40:43], v[172:175], v[200:203], v[40:43]
	v_mfma_f32_16x16x32_bf16 v[36:39], v[164:167], v[208:211], v[36:39]
	v_mfma_f32_16x16x32_bf16 v[32:35], v[172:175], v[208:211], v[32:35]
	s_setprio 0
	s_barrier
	v_lshl_add_u64 v[156:157], v[236:237], 0, s[70:71]
	s_add_u32 m0, s3, 0x1c000
	s_nop 0
	global_load_lds_dwordx4 v[156:157], off
	v_lshl_add_u64 v[156:157], v[238:239], 0, s[70:71]
	s_add_u32 m0, s3, 0x1e000
	s_nop 0
	global_load_lds_dwordx4 v[156:157], off
	s_waitcnt vmcnt(6)
	s_barrier
	s_setprio 1
	v_mfma_f32_16x16x32_bf16 v[28:31], v[212:215], v[180:183], v[28:31]
	v_mfma_f32_16x16x32_bf16 v[24:27], v[222:225], v[180:183], v[24:27]
	v_mfma_f32_16x16x32_bf16 v[20:23], v[212:215], v[188:191], v[20:23]
	v_mfma_f32_16x16x32_bf16 v[16:19], v[222:225], v[188:191], v[16:19]
	v_mfma_f32_16x16x32_bf16 v[12:15], v[212:215], v[196:199], v[12:15]
	v_mfma_f32_16x16x32_bf16 v[8:11], v[222:225], v[196:199], v[8:11]
	v_mfma_f32_16x16x32_bf16 v[4:7], v[212:215], v[204:207], v[4:7]
	v_mfma_f32_16x16x32_bf16 v[0:3], v[222:225], v[204:207], v[0:3]
	v_mfma_f32_16x16x32_bf16 v[28:31], v[216:219], v[184:187], v[28:31]
	v_mfma_f32_16x16x32_bf16 v[24:27], v[226:229], v[184:187], v[24:27]
	v_mfma_f32_16x16x32_bf16 v[20:23], v[216:219], v[192:195], v[20:23]
	v_mfma_f32_16x16x32_bf16 v[16:19], v[226:229], v[192:195], v[16:19]
	v_mfma_f32_16x16x32_bf16 v[12:15], v[216:219], v[200:203], v[12:15]
	v_mfma_f32_16x16x32_bf16 v[8:11], v[226:229], v[200:203], v[8:11]
	v_mfma_f32_16x16x32_bf16 v[4:7], v[216:219], v[208:211], v[4:7]
	v_mfma_f32_16x16x32_bf16 v[0:3], v[226:229], v[208:211], v[0:3]
	s_setprio 0
	s_add_i32 s2, s2, 2
	s_add_u32 s20, s20, 0x100
	s_addc_u32 s21, s21, 0
	s_cmp_gt_u32 s2, 27
	s_barrier
	s_cbranch_scc0 .LBB0_2517
	v_add_u32_e32 v154, 0xc000, v143
	v_add_u32_e32 v155, 0xe000, v143
	v_add_u32_e32 v163, 0x6000, v143
	s_add_u32 s2, s12, 0x80f80
	s_addc_u32 s3, s13, 0
	v_readfirstlane_b32 s15, v154
	v_lshl_add_u64 v[150:151], s[2:3], 0, v[178:179]
	s_mov_b32 m0, s15
	v_lshl_add_u64 v[128:129], s[2:3], 0, v[128:129]
	v_readfirstlane_b32 s2, v155
	ds_read_b128 v[130:133], v153
	ds_read_b128 v[134:137], v153 offset:1024
	ds_read_b128 v[146:149], v153 offset:2048
	ds_read_b128 v[156:159], v153 offset:3072
	ds_read_b128 v[164:167], v141
	ds_read_b128 v[168:171], v141 offset:1024
	ds_read_b128 v[172:175], v140
	ds_read_b128 v[180:183], v140 offset:1024
	ds_read_b128 v[184:187], v139
	ds_read_b128 v[188:191], v139 offset:1024
	ds_read_b128 v[192:195], v138
	ds_read_b128 v[196:199], v138 offset:1024
	global_load_lds_dwordx4 v[150:151], off
	s_mov_b32 m0, s2
	s_nop 0
	global_load_lds_dwordx4 v[128:129], off
	s_barrier
; #define STAGE_A(P, half, kt) do { const char* _u = Ab + ((size_t)(half) * 128 * lda + (size_t)(kt) * BK) * 2; \
;     _Pragma("unroll") for (int _i = 0; _i < 2; ++_i) \
;       __builtin_amdgcn_global_load_lds((const unsigned*)(_u + offA[_i]), \
;         (__attribute__((address_space(3))) unsigned*)((__attribute__((address_space(3))) char*)(P) + tidg * 16 + _i * 8192), 16, 0, 0); } while (0)
; #define LDA(dst, b, h) _Pragma("unroll") for (int m = 0; m < 4; ++m) _Pragma("unroll") for (int k = 0; k < 2; ++k) \
;     dst[m][k] = *reinterpret_cast<const bf16x8*>((const char*)SA(b, h) + lds_byte(wr * 64 + m * 16 + fr, k * 32 + fq * 8))
; #define LDB(dst, b, h) _Pragma("unroll") for (int n = 0; n < 2; ++n) _Pragma("unroll") for (int k = 0; k < 2; ++k) \
;     dst[n][k] = *reinterpret_cast<const bf16x8*>((const char*)SB(b, h) + lds_byte(wc * 32 + n * 16 + fr, k * 32 + fq * 8))
; #define MMA(ai, bj, At_, Bt_) do { __builtin_amdgcn_s_setprio(1); \
;     _Pragma("unroll") for (int m = 0; m < 4; ++m) _Pragma("unroll") for (int n = 0; n < 2; ++n) _Pragma("unroll") for (int k = 0; k < 2; ++k) \
;       acc[ai][bj][m][n] = __builtin_amdgcn_mfma_f32_16x16x32_bf16(Bt_[n][k], At_[m][k], acc[ai][bj][m][n], 0, 0, 0); \
;     __builtin_amdgcn_s_setprio(0); } while (0)
; #define WAIT_V(n) asm volatile("s_waitcnt vmcnt(" #n ")" ::: "memory")
; #define WAIT_L(n) asm volatile("s_waitcnt lgkmcnt(" #n ")" ::: "memory")
; #define BAR __builtin_amdgcn_s_barrier()
; template <bool PF = true, class Epi, class KRF = KRFull>
; __device__ __forceinline__ void gemm_phase(const u16* __restrict__ A, int lda, const u16* __restrict__ Bt, int ldb, int K, int nM, int nN,
;                                            lds_u16* shm, Epi epi, KRF krf = KRFull(), bool flip = false) {
;     ...
;     { LDB(B0, 0, 0); LDA(At, 0, 0); STAGE_A(SA(1, 1), 1, nt - 1);
;       BAR; WAIT_L(0); MMA(0, 0, At, B0); BAR;
;       LDB(B1, 0, 1); BAR; WAIT_L(0); MMA(0, 1, At, B1); BAR;
;       LDA(At, 0, 1); WAIT_V(4); BAR; WAIT_L(0); MMA(1, 0, At, B0); MMA(1, 1, At, B1); BAR; }
;     { LDB(B0, 1, 0); LDA(At, 1, 0); WAIT_V(2); BAR; WAIT_L(0); MMA(0, 0, At, B0); BAR;
	s_waitcnt lgkmcnt(0)
	s_setprio 1
	s_waitcnt lgkmcnt(0)
	v_mfma_f32_16x16x32_bf16 v[124:127], v[130:133], v[164:167], v[124:127]
	v_mfma_f32_16x16x32_bf16 v[120:123], v[146:149], v[164:167], v[120:123]
	v_mfma_f32_16x16x32_bf16 v[116:119], v[130:133], v[172:175], v[116:119]
	v_mfma_f32_16x16x32_bf16 v[112:115], v[146:149], v[172:175], v[112:115]
	v_mfma_f32_16x16x32_bf16 v[100:103], v[130:133], v[192:195], v[100:103]
	v_mfma_f32_16x16x32_bf16 v[96:99], v[146:149], v[192:195], v[96:99]
	v_mfma_f32_16x16x32_bf16 v[124:127], v[134:137], v[168:171], v[124:127]
	v_mfma_f32_16x16x32_bf16 v[120:123], v[156:159], v[168:171], v[120:123]
	v_mfma_f32_16x16x32_bf16 v[116:119], v[134:137], v[180:183], v[116:119]
	v_mfma_f32_16x16x32_bf16 v[112:115], v[156:159], v[180:183], v[112:115]
	v_mfma_f32_16x16x32_bf16 v[108:111], v[130:133], v[184:187], v[108:111]
	v_mfma_f32_16x16x32_bf16 v[104:107], v[146:149], v[184:187], v[104:107]
	v_mfma_f32_16x16x32_bf16 v[100:103], v[134:137], v[196:199], v[100:103]
	v_mfma_f32_16x16x32_bf16 v[96:99], v[156:159], v[196:199], v[96:99]
	v_mfma_f32_16x16x32_bf16 v[200:203], v[134:137], v[188:191], v[108:111]
	v_mfma_f32_16x16x32_bf16 v[204:207], v[156:159], v[188:191], v[104:107]
	s_setprio 0
	s_barrier
	s_nop 1
	ds_read_b128 v[104:107], v152
	ds_read_b128 v[108:111], v152 offset:1024
	ds_read_b128 v[208:211], v152 offset:2048
	ds_read_b128 v[150:153], v152 offset:3072
	s_barrier
	s_waitcnt lgkmcnt(0)
	s_setprio 1
	s_waitcnt lgkmcnt(0)
	v_mfma_f32_16x16x32_bf16 v[84:87], v[104:107], v[172:175], v[84:87]
	v_mfma_f32_16x16x32_bf16 v[80:83], v[208:211], v[172:175], v[80:83]
	v_mfma_f32_16x16x32_bf16 v[68:71], v[104:107], v[192:195], v[68:71]
	v_mfma_f32_16x16x32_bf16 v[64:67], v[208:211], v[192:195], v[64:67]
	v_mfma_f32_16x16x32_bf16 v[92:95], v[104:107], v[164:167], v[92:95]
	v_mfma_f32_16x16x32_bf16 v[88:91], v[208:211], v[164:167], v[88:91]
	v_mfma_f32_16x16x32_bf16 v[84:87], v[108:111], v[180:183], v[84:87]
	v_mfma_f32_16x16x32_bf16 v[80:83], v[150:153], v[180:183], v[80:83]
	v_mfma_f32_16x16x32_bf16 v[76:79], v[104:107], v[184:187], v[76:79]
	v_mfma_f32_16x16x32_bf16 v[72:75], v[208:211], v[184:187], v[72:75]
	v_mfma_f32_16x16x32_bf16 v[68:71], v[108:111], v[196:199], v[68:71]
	v_mfma_f32_16x16x32_bf16 v[64:67], v[150:153], v[196:199], v[64:67]
	v_mfma_f32_16x16x32_bf16 v[212:215], v[108:111], v[168:171], v[92:95]
	v_mfma_f32_16x16x32_bf16 v[164:167], v[150:153], v[168:171], v[88:91]
	v_mfma_f32_16x16x32_bf16 v[168:171], v[108:111], v[188:191], v[76:79]
	v_mfma_f32_16x16x32_bf16 v[172:175], v[150:153], v[188:191], v[72:75]
	s_setprio 0
	s_barrier
	s_nop 0
	ds_read_b128 v[72:75], v141 offset:16384
	ds_read_b128 v[76:79], v141 offset:17408
	ds_read_b128 v[88:91], v140 offset:16384
	ds_read_b128 v[92:95], v140 offset:17408
	ds_read_b128 v[180:183], v139 offset:16384
	ds_read_b128 v[184:187], v139 offset:17408
	ds_read_b128 v[188:191], v138 offset:16384
	ds_read_b128 v[192:195], v138 offset:17408
	s_waitcnt vmcnt(4)
	s_barrier
	s_waitcnt lgkmcnt(0)
	s_setprio 1
	s_waitcnt lgkmcnt(0)
	v_mfma_f32_16x16x32_bf16 v[60:63], v[130:133], v[72:75], v[60:63]
	v_mfma_f32_16x16x32_bf16 v[56:59], v[146:149], v[72:75], v[56:59]
	v_mfma_f32_16x16x32_bf16 v[52:55], v[130:133], v[88:91], v[52:55]
	v_mfma_f32_16x16x32_bf16 v[48:51], v[146:149], v[88:91], v[48:51]
	v_mfma_f32_16x16x32_bf16 v[36:39], v[130:133], v[188:191], v[36:39]
	v_mfma_f32_16x16x32_bf16 v[32:35], v[146:149], v[188:191], v[32:35]
	v_mfma_f32_16x16x32_bf16 v[60:63], v[134:137], v[76:79], v[60:63]
	v_mfma_f32_16x16x32_bf16 v[56:59], v[156:159], v[76:79], v[56:59]
	v_mfma_f32_16x16x32_bf16 v[52:55], v[134:137], v[92:95], v[52:55]
	v_mfma_f32_16x16x32_bf16 v[48:51], v[156:159], v[92:95], v[48:51]
	v_mfma_f32_16x16x32_bf16 v[44:47], v[130:133], v[180:183], v[44:47]
	v_mfma_f32_16x16x32_bf16 v[40:43], v[146:149], v[180:183], v[40:43]
	v_mfma_f32_16x16x32_bf16 v[36:39], v[134:137], v[192:195], v[36:39]
	v_mfma_f32_16x16x32_bf16 v[32:35], v[156:159], v[192:195], v[32:35]
	v_mfma_f32_16x16x32_bf16 v[196:199], v[134:137], v[184:187], v[44:47]
	v_mfma_f32_16x16x32_bf16 v[216:219], v[156:159], v[184:187], v[40:43]
	s_setprio 0
	s_setprio 1
	v_mfma_f32_16x16x32_bf16 v[20:23], v[104:107], v[88:91], v[20:23]
	v_mfma_f32_16x16x32_bf16 v[16:19], v[208:211], v[88:91], v[16:19]
	v_mfma_f32_16x16x32_bf16 v[4:7], v[104:107], v[188:191], v[4:7]
	v_mfma_f32_16x16x32_bf16 v[0:3], v[208:211], v[188:191], v[0:3]
	v_mfma_f32_16x16x32_bf16 v[28:31], v[104:107], v[72:75], v[28:31]
	v_mfma_f32_16x16x32_bf16 v[24:27], v[208:211], v[72:75], v[24:27]
	v_mfma_f32_16x16x32_bf16 v[20:23], v[108:111], v[92:95], v[20:23]
	v_mfma_f32_16x16x32_bf16 v[16:19], v[150:153], v[92:95], v[16:19]
	v_mfma_f32_16x16x32_bf16 v[12:15], v[104:107], v[180:183], v[12:15]
	v_mfma_f32_16x16x32_bf16 v[8:11], v[208:211], v[180:183], v[8:11]
	v_mfma_f32_16x16x32_bf16 v[4:7], v[108:111], v[192:195], v[4:7]
	v_mfma_f32_16x16x32_bf16 v[0:3], v[150:153], v[192:195], v[0:3]
	v_mfma_f32_16x16x32_bf16 v[128:131], v[108:111], v[76:79], v[28:31]
	v_mfma_f32_16x16x32_bf16 v[132:135], v[150:153], v[76:79], v[24:27]
	v_mfma_f32_16x16x32_bf16 v[146:149], v[108:111], v[184:187], v[12:15]
	v_mfma_f32_16x16x32_bf16 v[154:157], v[150:153], v[184:187], v[8:11]
	s_setprio 0
	s_barrier
	s_nop 0
	ds_read_b128 v[8:11], v144
	ds_read_b128 v[12:15], v144 offset:1024
	ds_read_b128 v[150:153], v144 offset:2048
	ds_read_b128 v[158:161], v144 offset:3072
	ds_read_b128 v[24:27], v141 offset:32768
	ds_read_b128 v[28:31], v141 offset:33792
	ds_read_b128 v[40:43], v140 offset:32768
	ds_read_b128 v[44:47], v140 offset:33792
	ds_read_b128 v[180:183], v139 offset:32768
	ds_read_b128 v[184:187], v139 offset:33792
	ds_read_b128 v[188:191], v138 offset:32768
	ds_read_b128 v[192:195], v138 offset:33792
	s_waitcnt vmcnt(2)
	s_barrier
; #define LDA(dst, b, h) _Pragma("unroll") for (int m = 0; m < 4; ++m) _Pragma("unroll") for (int k = 0; k < 2; ++k) \
;     dst[m][k] = *reinterpret_cast<const bf16x8*>((const char*)SA(b, h) + lds_byte(wr * 64 + m * 16 + fr, k * 32 + fq * 8))
; #define LDB(dst, b, h) _Pragma("unroll") for (int n = 0; n < 2; ++n) _Pragma("unroll") for (int k = 0; k < 2; ++k) \
;     dst[n][k] = *reinterpret_cast<const bf16x8*>((const char*)SB(b, h) + lds_byte(wc * 32 + n * 16 + fr, k * 32 + fq * 8))
; #define MMA(ai, bj, At_, Bt_) do { __builtin_amdgcn_s_setprio(1); \
;     _Pragma("unroll") for (int m = 0; m < 4; ++m) _Pragma("unroll") for (int n = 0; n < 2; ++n) _Pragma("unroll") for (int k = 0; k < 2; ++k) \
;       acc[ai][bj][m][n] = __builtin_amdgcn_mfma_f32_16x16x32_bf16(Bt_[n][k], At_[m][k], acc[ai][bj][m][n], 0, 0, 0); \
;     __builtin_amdgcn_s_setprio(0); } while (0)
; #define WAIT_V(n) asm volatile("s_waitcnt vmcnt(" #n ")" ::: "memory")
; #define WAIT_L(n) asm volatile("s_waitcnt lgkmcnt(" #n ")" ::: "memory")
; #define BAR __builtin_amdgcn_s_barrier()
; template <bool PF = true, class Epi, class KRF = KRFull>
; __device__ __forceinline__ void gemm_phase(const u16* __restrict__ A, int lda, const u16* __restrict__ Bt, int ldb, int K, int nM, int nN,
;                                            lds_u16* shm, Epi epi, KRF krf = KRFull(), bool flip = false) {
;     ...
;     { LDB(B0, 1, 0); LDA(At, 1, 0); WAIT_V(2); BAR; WAIT_L(0); MMA(0, 0, At, B0); BAR;
;       LDB(B1, 1, 1); WAIT_V(0); BAR; WAIT_L(0); MMA(0, 1, At, B1); BAR;
;       LDA(At, 1, 1); BAR; WAIT_L(0); MMA(1, 0, At, B0); MMA(1, 1, At, B1); BAR; }
;     if (wr == 0) BAR;
	s_waitcnt lgkmcnt(0)
	s_setprio 1
	s_waitcnt lgkmcnt(0)
	v_mfma_f32_16x16x32_bf16 v[72:75], v[8:11], v[24:27], v[124:127]
	v_mfma_f32_16x16x32_bf16 v[124:127], v[12:15], v[28:31], v[72:75]
	v_mfma_f32_16x16x32_bf16 v[72:75], v[150:153], v[24:27], v[120:123]
	v_mfma_f32_16x16x32_bf16 v[120:123], v[158:161], v[28:31], v[72:75]
	v_mfma_f32_16x16x32_bf16 v[72:75], v[8:11], v[40:43], v[116:119]
	v_mfma_f32_16x16x32_bf16 v[108:111], v[12:15], v[44:47], v[72:75]
	v_mfma_f32_16x16x32_bf16 v[72:75], v[150:153], v[40:43], v[112:115]
	v_mfma_f32_16x16x32_bf16 v[104:107], v[158:161], v[44:47], v[72:75]
	v_mfma_f32_16x16x32_bf16 v[72:75], v[8:11], v[180:183], v[200:203]
	v_mfma_f32_16x16x32_bf16 v[92:95], v[12:15], v[184:187], v[72:75]
	v_mfma_f32_16x16x32_bf16 v[72:75], v[150:153], v[180:183], v[204:207]
	v_mfma_f32_16x16x32_bf16 v[88:91], v[158:161], v[184:187], v[72:75]
	v_mfma_f32_16x16x32_bf16 v[72:75], v[8:11], v[188:191], v[100:103]
	v_mfma_f32_16x16x32_bf16 v[76:79], v[12:15], v[192:195], v[72:75]
	v_mfma_f32_16x16x32_bf16 v[72:75], v[150:153], v[188:191], v[96:99]
	v_mfma_f32_16x16x32_bf16 v[72:75], v[158:161], v[192:195], v[72:75]
	s_setprio 0
	s_barrier
	ds_read_b128 v[200:203], v142
	ds_read_b128 v[204:207], v142 offset:1024
	ds_read_b128 v[208:211], v142 offset:2048
	ds_read_b128 v[142:145], v142 offset:3072
	s_waitcnt vmcnt(0)
	s_barrier
	s_waitcnt lgkmcnt(0)
	s_setprio 1
	s_waitcnt lgkmcnt(0)
	v_mfma_f32_16x16x32_bf16 v[96:99], v[200:203], v[24:27], v[212:215]
	v_mfma_f32_16x16x32_bf16 v[24:27], v[208:211], v[24:27], v[164:167]
	v_mfma_f32_16x16x32_bf16 v[112:115], v[142:145], v[28:31], v[24:27]
	v_mfma_f32_16x16x32_bf16 v[24:27], v[200:203], v[40:43], v[84:87]
	v_mfma_f32_16x16x32_bf16 v[100:103], v[204:207], v[44:47], v[24:27]
	v_mfma_f32_16x16x32_bf16 v[24:27], v[208:211], v[40:43], v[80:83]
	v_mfma_f32_16x16x32_bf16 v[116:119], v[204:207], v[28:31], v[96:99]
	v_mfma_f32_16x16x32_bf16 v[96:99], v[142:145], v[44:47], v[24:27]
	v_mfma_f32_16x16x32_bf16 v[24:27], v[200:203], v[180:183], v[168:171]
	v_mfma_f32_16x16x32_bf16 v[84:87], v[204:207], v[184:187], v[24:27]
	v_mfma_f32_16x16x32_bf16 v[24:27], v[208:211], v[180:183], v[172:175]
	v_mfma_f32_16x16x32_bf16 v[80:83], v[142:145], v[184:187], v[24:27]
	v_mfma_f32_16x16x32_bf16 v[24:27], v[200:203], v[188:191], v[68:71]
	v_mfma_f32_16x16x32_bf16 v[68:71], v[204:207], v[192:195], v[24:27]
	v_mfma_f32_16x16x32_bf16 v[24:27], v[208:211], v[188:191], v[64:67]
	v_mfma_f32_16x16x32_bf16 v[64:67], v[142:145], v[192:195], v[24:27]
	s_setprio 0
	s_barrier
	ds_read_b128 v[164:167], v141 offset:49152
	ds_read_b128 v[168:171], v141 offset:50176
	ds_read_b128 v[172:175], v140 offset:49152
	ds_read_b128 v[180:183], v140 offset:50176
	ds_read_b128 v[184:187], v139 offset:49152
	ds_read_b128 v[188:191], v139 offset:50176
	ds_read_b128 v[192:195], v138 offset:49152
	ds_read_b128 v[136:139], v138 offset:50176
	s_barrier
	s_waitcnt lgkmcnt(0)
	s_setprio 1
	s_waitcnt lgkmcnt(0)
	v_mfma_f32_16x16x32_bf16 v[24:27], v[8:11], v[164:167], v[60:63]
	v_mfma_f32_16x16x32_bf16 v[60:63], v[12:15], v[168:171], v[24:27]
	v_mfma_f32_16x16x32_bf16 v[24:27], v[150:153], v[164:167], v[56:59]
	v_mfma_f32_16x16x32_bf16 v[56:59], v[158:161], v[168:171], v[24:27]
	v_mfma_f32_16x16x32_bf16 v[24:27], v[8:11], v[172:175], v[52:55]
	v_mfma_f32_16x16x32_bf16 v[44:47], v[12:15], v[180:183], v[24:27]
	v_mfma_f32_16x16x32_bf16 v[24:27], v[150:153], v[172:175], v[48:51]
	v_mfma_f32_16x16x32_bf16 v[40:43], v[158:161], v[180:183], v[24:27]
	v_mfma_f32_16x16x32_bf16 v[24:27], v[8:11], v[184:187], v[196:199]
	v_mfma_f32_16x16x32_bf16 v[8:11], v[8:11], v[192:195], v[36:39]
	v_mfma_f32_16x16x32_bf16 v[28:31], v[12:15], v[188:191], v[24:27]
	v_mfma_f32_16x16x32_bf16 v[24:27], v[150:153], v[184:187], v[216:219]
	v_mfma_f32_16x16x32_bf16 v[12:15], v[12:15], v[136:139], v[8:11]
	v_mfma_f32_16x16x32_bf16 v[8:11], v[150:153], v[192:195], v[32:35]
	v_mfma_f32_16x16x32_bf16 v[24:27], v[158:161], v[188:191], v[24:27]
	v_mfma_f32_16x16x32_bf16 v[8:11], v[158:161], v[136:139], v[8:11]
	s_setprio 0
	s_setprio 1
	v_mfma_f32_16x16x32_bf16 v[32:35], v[200:203], v[164:167], v[128:131]
	v_mfma_f32_16x16x32_bf16 v[52:55], v[204:207], v[168:171], v[32:35]
	v_mfma_f32_16x16x32_bf16 v[32:35], v[208:211], v[164:167], v[132:135]
	v_mfma_f32_16x16x32_bf16 v[16:19], v[208:211], v[172:175], v[16:19]
	v_mfma_f32_16x16x32_bf16 v[48:51], v[142:145], v[168:171], v[32:35]
	v_mfma_f32_16x16x32_bf16 v[20:23], v[200:203], v[172:175], v[20:23]
	v_mfma_f32_16x16x32_bf16 v[32:35], v[142:145], v[180:183], v[16:19]
	v_mfma_f32_16x16x32_bf16 v[16:19], v[200:203], v[184:187], v[146:149]
	v_mfma_f32_16x16x32_bf16 v[36:39], v[204:207], v[180:183], v[20:23]
	v_mfma_f32_16x16x32_bf16 v[20:23], v[204:207], v[188:191], v[16:19]
	v_mfma_f32_16x16x32_bf16 v[16:19], v[208:211], v[184:187], v[154:157]
	v_mfma_f32_16x16x32_bf16 v[4:7], v[200:203], v[192:195], v[4:7]
	v_mfma_f32_16x16x32_bf16 v[0:3], v[208:211], v[192:195], v[0:3]
	v_mfma_f32_16x16x32_bf16 v[16:19], v[142:145], v[188:191], v[16:19]
	v_mfma_f32_16x16x32_bf16 v[4:7], v[204:207], v[136:139], v[4:7]
	v_mfma_f32_16x16x32_bf16 v[0:3], v[142:145], v[136:139], v[0:3]
	s_setprio 0
	v_cmp_gt_u32_e32 vcc, s95, v162
	s_barrier
	s_and_saveexec_b64 s[16:17], vcc
	s_cbranch_execz .LBB0_2520
	s_barrier

; __device__ __forceinline__ int tid_l() { int t = threadIdx.x; asm volatile("" : "+v"(t)); return t; }
; __device__ __forceinline__ int bid_l() { int t = blockIdx.x; asm volatile("" : "+s"(t)); return t; }
; __device__ __forceinline__ int gdim_l() { int t = gridDim.x; asm volatile("" : "+s"(t)); return t; }
; #define STAGE_A(P, half, kt) do { const char* _u = Ab + ((size_t)(half) * 128 * lda + (size_t)(kt) * BK) * 2; \
;     _Pragma("unroll") for (int _i = 0; _i < 2; ++_i) \
;       __builtin_amdgcn_global_load_lds((const unsigned*)(_u + offA[_i]), \
;         (__attribute__((address_space(3))) unsigned*)((__attribute__((address_space(3))) char*)(P) + tidg * 16 + _i * 8192), 16, 0, 0); } while (0)
; #define WAIT_V(n) asm volatile("s_waitcnt vmcnt(" #n ")" ::: "memory")
; #define BAR __builtin_amdgcn_s_barrier()
; template <bool PF = true, class Epi, class KRF = KRFull>
; __device__ __forceinline__ void gemm_phase(const u16* __restrict__ A, int lda, const u16* __restrict__ Bt, int ldb, int K, int nM, int nN,
;                                            lds_u16* shm, Epi epi, KRF krf = KRFull(), bool flip = false) {
;   int tidg = tid_l();
;   int wid, lane, wr, wc, fr, fq;
;   int nt;
;   unsigned offA[2], offB[2];
;     ...
;   G_THREAD();
;   int ntile = nM * nN;
;   const int gdg = gdim_l();
;   const int bidg = flip ? (gdg - 1 - bid_l()) : bid_l();
;   int tix = bidg;
;   if (tix >= ntile) return;
;   int pm, pn; tile_map(tix, nM, nN, pm, pn);
;   int brow = pm * 256, bcol = pn * 256;
;   int2 kr = krf(bcol, K);
;   int nt_next = kr.y;
;   const char* Ab = (const char*)A + (size_t)brow * lda * 2 + kr.x * (BK * 2);
;   const char* Bb = (const char*)Bt + (size_t)bcol * ldb * 2 + kr.x * (BK * 2);
;   __syncthreads();
;   STAGE_B(SB(0, 0), 0, 0); STAGE_A(SA(0, 0), 0, 0);
;   STAGE_B(SB(0, 1), 1, 0); STAGE_A(SA(0, 1), 1, 0);
;   for (;;) {
;     G_THREAD();
;     nt = nt_next;
;     f32x4 acc[2][2][4][2] = {};
;     bf16x8 At[4][2], B0[2][2], B1[2][2];
;     if (wr == 1) BAR;
;     WAIT_V(4); BAR;
;     STAGE_B(SB(1, 0), 0, 1); STAGE_A(SA(1, 0), 0, 1); STAGE_B(SB(1, 1), 1, 1);
;     WAIT_V(6); BAR;
.LBB0_2534:
	s_or_b64 exec, exec, s[16:17]
	v_bfe_i32 v2, v138, 27, 1
	v_lshlrev_b32_e32 v144, 4, v138
	v_lshrrev_b32_e32 v2, 22, v2
	v_add_u32_e32 v2, v144, v2
	v_and_b32_e32 v2, 0xfffffc00, v2
	v_sub_u32_e32 v2, v144, v2
	v_lshrrev_b32_e32 v3, 4, v2
	v_bitop3_b32 v2, v3, v2, 32 bitop3:0x6c
	v_ashrrev_i32_e32 v5, 31, v2
	v_ashrrev_i32_e32 v1, 31, v138
	v_lshrrev_b32_e32 v5, 26, v5
	v_lshrrev_b32_e32 v1, 26, v1
	v_add_u32_e32 v5, v2, v5
	v_add_u32_e32 v1, v138, v1
	v_ashrrev_i32_e32 v6, 6, v5
	v_and_b32_e32 v5, 0xc0, v5
	v_ashrrev_i32_e32 v4, 6, v1
	v_sub_u32_e32 v2, v2, v5
	v_lshlrev_b32_e32 v3, 3, v4
	v_lshlrev_b32_e32 v7, 5, v4
	v_ashrrev_i16_sdwa v2, v232, sext(v2) dst_sel:DWORD dst_unused:UNUSED_PAD src0_sel:DWORD src1_sel:BYTE_0
	v_and_b32_e32 v3, 0xffff0, v3
	v_and_b32_e32 v7, 32, v7
	v_bfe_i32 v5, v2, 0, 16
	v_add_u32_e32 v2, v7, v5
	v_add_lshl_u32 v3, v6, v3, 12
	v_add_u32_e32 v146, 0x2000, v144
	v_lshl_add_u32 v178, v2, 1, v3
	v_ashrrev_i32_e32 v2, 31, v146
	v_lshrrev_b32_e32 v2, 22, v2
	v_add_u32_e32 v2, v146, v2
	v_ashrrev_i32_e32 v7, 10, v2
	v_mul_i32_i24_e32 v2, 0x400, v7
	v_sub_u32_e32 v2, v146, v2
	v_lshrrev_b32_e32 v3, 4, v2
	v_bitop3_b32 v2, v3, v2, 32 bitop3:0x6c
	v_ashrrev_i32_e32 v8, 31, v2
	v_lshrrev_b32_e32 v8, 26, v8
	v_add_u32_e32 v8, v2, v8
	v_ashrrev_i32_e32 v9, 6, v8
	v_and_b32_e32 v8, 0xc0, v8
	v_sub_u32_e32 v2, v2, v8
	v_lshlrev_b32_e32 v3, 3, v7
	v_lshlrev_b32_e32 v10, 5, v7
	v_ashrrev_i16_sdwa v2, v232, sext(v2) dst_sel:DWORD dst_unused:UNUSED_PAD src0_sel:DWORD src1_sel:BYTE_0
	v_and_b32_e32 v3, 0xffff0, v3
	v_and_b32_e32 v10, 32, v10
	v_bfe_i32 v8, v2, 0, 16
	v_add_u32_e32 v2, v10, v8
	v_add_lshl_u32 v3, v9, v3, 12
	v_add_u32_e32 v147, 0x18000, v144
	v_lshl_add_u32 v128, v2, 1, v3
	v_lshl_add_u64 v[2:3], s[4:5], 0, v[178:179]
	v_readfirstlane_b32 s13, v147
	v_lshl_add_u64 v[2:3], v[2:3], 0, s[60:61]
	s_mov_b32 m0, s13
	v_mov_b32_e32 v129, v179
	v_add_u32_e32 v148, 0x1a000, v144
	s_waitcnt vmcnt(4)
	s_barrier
	global_load_lds_dwordx4 v[2:3], off
	v_lshl_add_u64 v[2:3], s[4:5], 0, v[128:129]
	v_readfirstlane_b32 s13, v148
	v_lshl_add_u64 v[2:3], v[2:3], 0, s[60:61]
	s_mov_b32 m0, s13
	v_add_u32_e32 v149, 0x8000, v144
	global_load_lds_dwordx4 v[2:3], off
	v_lshl_add_u64 v[2:3], s[6:7], 0, v[178:179]
	v_readfirstlane_b32 s13, v149
	v_lshl_add_u64 v[2:3], v[2:3], 0, s[60:61]
	s_mov_b32 m0, s13
	v_add_u32_e32 v150, 0xa000, v144
	global_load_lds_dwordx4 v[2:3], off
	v_lshl_add_u64 v[2:3], s[6:7], 0, v[128:129]
	v_readfirstlane_b32 s13, v150
	v_add_u32_e32 v151, 0x1c000, v144
	v_lshl_add_u64 v[2:3], v[2:3], 0, s[60:61]
	s_mov_b32 m0, s13
	s_add_u32 s16, s4, 0x80080
	v_readfirstlane_b32 s13, v151
	v_add_u32_e32 v152, 0x1e000, v144
	global_load_lds_dwordx4 v[2:3], off
	s_addc_u32 s17, s5, 0
	s_mov_b32 m0, s13
	v_readfirstlane_b32 s13, v152
	global_load_lds_dwordx4 v178, s[16:17]
	s_mov_b32 m0, s13
	v_and_b32_e32 v10, 15, v138
	global_load_lds_dwordx4 v128, s[16:17]
	v_lshlrev_b32_e32 v2, 6, v10
	v_lshlrev_b32_e32 v10, 2, v138
	v_and_b32_e32 v11, 48, v138
	v_and_b32_e32 v10, 32, v10
	v_or_b32_e32 v3, v2, v11
	v_bitop3_b32 v12, v2, v10, v11 bitop3:0x36
	s_mov_b32 s13, 0x14000
	v_lshlrev_b32_e32 v2, 6, v138
	v_bitop3_b32 v14, v3, s13, v10 bitop3:0xde
	s_mov_b32 s13, 0x18000
	v_lshlrev_b32_e32 v18, 13, v0
	v_and_b32_e32 v0, 0x3c0, v2
	v_bitop3_b32 v13, v3, s94, v10 bitop3:0xde
	v_bitop3_b32 v15, v3, s13, v10 bitop3:0xde
	v_bitop3_b32 v16, v3, s97, v10 bitop3:0xde
	v_bitop3_b32 v10, v0, v10, v11 bitop3:0x36
	v_lshlrev_b32_e32 v0, 15, v4
	v_and_b32_e32 v17, 0x3000, v2
	v_and_b32_e32 v0, 0xffff0000, v0
	v_lshlrev_b32_e32 v2, 15, v7
	v_lshl_add_u32 v0, v6, 12, v0
	v_and_b32_e32 v2, 0xffff0000, v2
	v_and_or_b32 v0, v1, 64, v0
	v_lshl_add_u32 v2, v9, 12, v2
	v_lshlrev_b32_e32 v3, 6, v7
	s_waitcnt vmcnt(6)
	v_lshl_add_u32 v0, v5, 1, v0
	v_mov_b32_e32 v1, v179
	v_and_or_b32 v2, v3, 64, v2
	v_or_b32_e32 v11, 0x800, v18
	v_or_b32_e32 v19, 0x1000, v18
	v_or_b32_e32 v20, 0x1800, v18
	v_lshl_add_u64 v[130:131], s[4:5], 0, v[0:1]
	v_lshl_add_u32 v2, v8, 1, v2
	v_mov_b32_e32 v3, v179
	v_lshl_add_u64 v[134:135], s[6:7], 0, v[0:1]
	v_mov_b32_e32 v0, 0
	v_lshl_add_u64 v[132:133], s[4:5], 0, v[2:3]
	v_lshl_add_u64 v[136:137], s[6:7], 0, v[2:3]
	s_mov_b32 s13, -2
	s_mov_b64 s[18:19], 0
	v_add_u32_e32 v154, v13, v17
	v_add_u32_e32 v142, v12, v18
	v_add_u32_e32 v141, v10, v11
	v_add_u32_e32 v140, v10, v19
	v_add_u32_e32 v139, v10, v20
	v_add_u32_e32 v153, v14, v17
	v_add_u32_e32 v145, v15, v17
	v_add_u32_e32 v143, v16, v17
	v_mov_b32_e32 v1, v0
	v_mov_b32_e32 v2, v0
	v_mov_b32_e32 v3, v0
	v_mov_b32_e32 v4, v0
	v_mov_b32_e32 v5, v0
	v_mov_b32_e32 v6, v0
	v_mov_b32_e32 v7, v0
	v_mov_b32_e32 v8, v0
	v_mov_b32_e32 v9, v0
	v_mov_b32_e32 v10, v0
	v_mov_b32_e32 v11, v0
	v_mov_b32_e32 v12, v0
	v_mov_b32_e32 v13, v0
	v_mov_b32_e32 v14, v0
	v_mov_b32_e32 v15, v0
	v_mov_b32_e32 v16, v0
	v_mov_b32_e32 v17, v0
	v_mov_b32_e32 v18, v0
	v_mov_b32_e32 v19, v0
	v_mov_b32_e32 v20, v0
	v_mov_b32_e32 v21, v0
	v_mov_b32_e32 v22, v0
	v_mov_b32_e32 v23, v0
	v_mov_b32_e32 v24, v0
	v_mov_b32_e32 v25, v0
	v_mov_b32_e32 v26, v0
	v_mov_b32_e32 v27, v0
	v_mov_b32_e32 v28, v0
	v_mov_b32_e32 v29, v0
	v_mov_b32_e32 v30, v0
	v_mov_b32_e32 v31, v0
	v_mov_b32_e32 v32, v0
	v_mov_b32_e32 v33, v0
	v_mov_b32_e32 v34, v0
	v_mov_b32_e32 v35, v0
	v_mov_b32_e32 v36, v0
	v_mov_b32_e32 v37, v0
	v_mov_b32_e32 v38, v0
	v_mov_b32_e32 v39, v0
	v_mov_b32_e32 v40, v0
	v_mov_b32_e32 v41, v0
	v_mov_b32_e32 v42, v0
	v_mov_b32_e32 v43, v0
	v_mov_b32_e32 v44, v0
	v_mov_b32_e32 v45, v0
	v_mov_b32_e32 v46, v0
	v_mov_b32_e32 v47, v0
	v_mov_b32_e32 v48, v0
	v_mov_b32_e32 v49, v0
	v_mov_b32_e32 v50, v0
; #define STAGE_A(P, half, kt) do { const char* _u = Ab + ((size_t)(half) * 128 * lda + (size_t)(kt) * BK) * 2; \
;     _Pragma("unroll") for (int _i = 0; _i < 2; ++_i) \
;       __builtin_amdgcn_global_load_lds((const unsigned*)(_u + offA[_i]), \
;         (__attribute__((address_space(3))) unsigned*)((__attribute__((address_space(3))) char*)(P) + tidg * 16 + _i * 8192), 16, 0, 0); } while (0)
; #define STAGE_B(P, half, kt) do { const char* _u = Bb + ((size_t)(half) * 128 * ldb + (size_t)(kt) * BK) * 2; \
;     _Pragma("unroll") for (int _i = 0; _i < 2; ++_i) \
;       __builtin_amdgcn_global_load_lds((const unsigned*)(_u + offB[_i]), \
;         (__attribute__((address_space(3))) unsigned*)((__attribute__((address_space(3))) char*)(P) + tidg * 16 + _i * 8192), 16, 0, 0); } while (0)
; #define LDA(dst, b, h) _Pragma("unroll") for (int m = 0; m < 4; ++m) _Pragma("unroll") for (int k = 0; k < 2; ++k) \
;     dst[m][k] = *reinterpret_cast<const bf16x8*>((const char*)SA(b, h) + lds_byte(wr * 64 + m * 16 + fr, k * 32 + fq * 8))
; #define LDB(dst, b, h) _Pragma("unroll") for (int n = 0; n < 2; ++n) _Pragma("unroll") for (int k = 0; k < 2; ++k) \
;     dst[n][k] = *reinterpret_cast<const bf16x8*>((const char*)SB(b, h) + lds_byte(wc * 32 + n * 16 + fr, k * 32 + fq * 8))
; #define WAIT_V(n) asm volatile("s_waitcnt vmcnt(" #n ")" ::: "memory")
; #define WAIT_L(n) asm volatile("s_waitcnt lgkmcnt(" #n ")" ::: "memory")
; template <bool PF = true, class Epi, class KRF = KRFull>
; __device__ __forceinline__ void gemm_phase(const u16* __restrict__ A, int lda, const u16* __restrict__ Bt, int ldb, int K, int nM, int nN,
;                                            lds_u16* shm, Epi epi, KRF krf = KRFull(), bool flip = false) {
;     ...
;     f32x4 acc[2][2][4][2] = {};
;     bf16x8 At[4][2], B0[2][2], B1[2][2];
;     if (wr == 1) BAR;
;     WAIT_V(4); BAR;
;     STAGE_B(SB(1, 0), 0, 1); STAGE_A(SA(1, 0), 0, 1); STAGE_B(SB(1, 1), 1, 1);
;     WAIT_V(6); BAR;
;     for (int t = 0; t < nt - 2; t += 2) {
;       LDB(B0, 0, 0); SCHED; LDA(At, 0, 0); STAGE_A(SA(1, 1), 1, t + 1);
;       WAIT_L(8); BAR; WAIT_L(0); MMA(0, 0, At, B0); BAR; SCHED;
;       LDB(B1, 0, 1); STAGE_B(SB(0, 0), 0, t + 2);
;       BAR; WAIT_L(0); MMA(0, 1, At, B1); BAR;
;       LDA(At, 0, 1); STAGE_A(SA(0, 0), 0, t + 2);
;       BAR; WAIT_L(0); MMA(1, 0, At, B0); BAR; SCHED;
;       STAGE_B(SB(0, 1), 1, t + 2);
	v_mov_b32_e32 v51, v0
	v_mov_b32_e32 v52, v0
	v_mov_b32_e32 v53, v0
	v_mov_b32_e32 v54, v0
	v_mov_b32_e32 v55, v0
	v_mov_b32_e32 v56, v0
	v_mov_b32_e32 v57, v0
	v_mov_b32_e32 v58, v0
	v_mov_b32_e32 v59, v0
	v_mov_b32_e32 v60, v0
	v_mov_b32_e32 v61, v0
	v_mov_b32_e32 v62, v0
	v_mov_b32_e32 v63, v0
	v_mov_b32_e32 v64, v0
	v_mov_b32_e32 v65, v0
	v_mov_b32_e32 v66, v0
	v_mov_b32_e32 v67, v0
	v_mov_b32_e32 v68, v0
	v_mov_b32_e32 v69, v0
	v_mov_b32_e32 v70, v0
	v_mov_b32_e32 v71, v0
	v_mov_b32_e32 v72, v0
	v_mov_b32_e32 v73, v0
	v_mov_b32_e32 v74, v0
	v_mov_b32_e32 v75, v0
	v_mov_b32_e32 v76, v0
	v_mov_b32_e32 v77, v0
	v_mov_b32_e32 v78, v0
	v_mov_b32_e32 v79, v0
	v_mov_b32_e32 v80, v0
	v_mov_b32_e32 v81, v0
	v_mov_b32_e32 v82, v0
	v_mov_b32_e32 v83, v0
	v_mov_b32_e32 v84, v0
	v_mov_b32_e32 v85, v0
	v_mov_b32_e32 v86, v0
	v_mov_b32_e32 v87, v0
	v_mov_b32_e32 v88, v0
	v_mov_b32_e32 v89, v0
	v_mov_b32_e32 v90, v0
	v_mov_b32_e32 v91, v0
	v_mov_b32_e32 v92, v0
	v_mov_b32_e32 v93, v0
	v_mov_b32_e32 v94, v0
	v_mov_b32_e32 v95, v0
	v_mov_b32_e32 v96, v0
	v_mov_b32_e32 v97, v0
	v_mov_b32_e32 v98, v0
	v_mov_b32_e32 v99, v0
	v_mov_b32_e32 v100, v0
	v_mov_b32_e32 v101, v0
	v_mov_b32_e32 v102, v0
	v_mov_b32_e32 v103, v0
	v_mov_b32_e32 v104, v0
	v_mov_b32_e32 v105, v0
	v_mov_b32_e32 v106, v0
	v_mov_b32_e32 v107, v0
	v_mov_b32_e32 v108, v0
	v_mov_b32_e32 v109, v0
	v_mov_b32_e32 v110, v0
	v_mov_b32_e32 v111, v0
	v_mov_b32_e32 v112, v0
	v_mov_b32_e32 v113, v0
	v_mov_b32_e32 v114, v0
	v_mov_b32_e32 v115, v0
	v_mov_b32_e32 v116, v0
	v_mov_b32_e32 v117, v0
	v_mov_b32_e32 v118, v0
	v_mov_b32_e32 v119, v0
	v_mov_b32_e32 v120, v0
	v_mov_b32_e32 v121, v0
	v_mov_b32_e32 v122, v0
	v_mov_b32_e32 v123, v0
	v_mov_b32_e32 v124, v0
	v_mov_b32_e32 v125, v0
	v_mov_b32_e32 v126, v0
	v_mov_b32_e32 v127, v0
	s_barrier
	v_readfirstlane_b32 s15, v144
.LBB0_2535:
	ds_read_b128 v[158:161], v154
	ds_read_b128 v[162:165], v154 offset:1024
	ds_read_b128 v[166:169], v154 offset:2048
	ds_read_b128 v[170:173], v154 offset:3072
	v_lshl_add_u64 v[174:175], v[134:135], 0, s[18:19]
	v_lshl_add_u64 v[156:157], v[174:175], 0, s[62:63]
	s_add_u32 m0, s15, 0xc000
	ds_read_b128 v[180:183], v142
	ds_read_b128 v[184:187], v142 offset:1024
	ds_read_b128 v[188:191], v141
	ds_read_b128 v[192:195], v141 offset:1024
	ds_read_b128 v[196:199], v140
	ds_read_b128 v[200:203], v140 offset:1024
	ds_read_b128 v[204:207], v139
	ds_read_b128 v[208:211], v139 offset:1024
	global_load_lds_dwordx4 v[156:157], off
	v_lshl_add_u64 v[234:235], v[136:137], 0, s[18:19]
	v_lshl_add_u64 v[212:213], v[234:235], 0, s[62:63]
	s_add_u32 m0, s15, 0xe000
	s_nop 0
	global_load_lds_dwordx4 v[212:213], off
	s_waitcnt lgkmcnt(8)
	s_barrier
	s_waitcnt lgkmcnt(0)
	s_setprio 1
	s_waitcnt lgkmcnt(0)
	v_mfma_f32_16x16x32_bf16 v[124:127], v[158:161], v[180:183], v[124:127]
	v_mfma_f32_16x16x32_bf16 v[120:123], v[166:169], v[180:183], v[120:123]
	v_mfma_f32_16x16x32_bf16 v[116:119], v[158:161], v[188:191], v[116:119]
	v_mfma_f32_16x16x32_bf16 v[112:115], v[166:169], v[188:191], v[112:115]
	v_mfma_f32_16x16x32_bf16 v[108:111], v[158:161], v[196:199], v[108:111]
	v_mfma_f32_16x16x32_bf16 v[104:107], v[166:169], v[196:199], v[104:107]
	v_mfma_f32_16x16x32_bf16 v[100:103], v[158:161], v[204:207], v[100:103]
	v_mfma_f32_16x16x32_bf16 v[96:99], v[166:169], v[204:207], v[96:99]
	v_mfma_f32_16x16x32_bf16 v[124:127], v[162:165], v[184:187], v[124:127]
	v_mfma_f32_16x16x32_bf16 v[120:123], v[170:173], v[184:187], v[120:123]
	v_mfma_f32_16x16x32_bf16 v[116:119], v[162:165], v[192:195], v[116:119]
	v_mfma_f32_16x16x32_bf16 v[112:115], v[170:173], v[192:195], v[112:115]
	v_mfma_f32_16x16x32_bf16 v[108:111], v[162:165], v[200:203], v[108:111]
	v_mfma_f32_16x16x32_bf16 v[104:107], v[170:173], v[200:203], v[104:107]
	v_mfma_f32_16x16x32_bf16 v[100:103], v[162:165], v[208:211], v[100:103]
	v_mfma_f32_16x16x32_bf16 v[96:99], v[170:173], v[208:211], v[96:99]
	s_setprio 0
	s_barrier
	v_lshl_add_u64 v[236:237], v[130:131], 0, s[18:19]
	v_lshl_add_u64 v[238:239], v[236:237], 0, s[64:65]
	s_add_u32 m0, s15, 0x10000
	ds_read_b128 v[212:215], v153
	ds_read_b128 v[216:219], v153 offset:1024
	ds_read_b128 v[222:225], v153 offset:2048
	ds_read_b128 v[226:229], v153 offset:3072
	global_load_lds_dwordx4 v[238:239], off
	v_lshl_add_u64 v[238:239], v[132:133], 0, s[18:19]
	v_lshl_add_u64 v[240:241], v[238:239], 0, s[64:65]
	s_add_u32 m0, s15, 0x12000
	s_nop 0
	global_load_lds_dwordx4 v[240:241], off
	s_barrier
	s_waitcnt lgkmcnt(0)
	s_setprio 1
	s_waitcnt lgkmcnt(0)
	v_mfma_f32_16x16x32_bf16 v[92:95], v[212:215], v[180:183], v[92:95]
	v_mfma_f32_16x16x32_bf16 v[88:91], v[222:225], v[180:183], v[88:91]
	v_mfma_f32_16x16x32_bf16 v[84:87], v[212:215], v[188:191], v[84:87]
	v_mfma_f32_16x16x32_bf16 v[80:83], v[222:225], v[188:191], v[80:83]
	v_mfma_f32_16x16x32_bf16 v[76:79], v[212:215], v[196:199], v[76:79]
	v_mfma_f32_16x16x32_bf16 v[72:75], v[222:225], v[196:199], v[72:75]
	v_mfma_f32_16x16x32_bf16 v[68:71], v[212:215], v[204:207], v[68:71]
	v_mfma_f32_16x16x32_bf16 v[64:67], v[222:225], v[204:207], v[64:67]
	v_mfma_f32_16x16x32_bf16 v[92:95], v[216:219], v[184:187], v[92:95]
	v_mfma_f32_16x16x32_bf16 v[88:91], v[226:229], v[184:187], v[88:91]
	v_mfma_f32_16x16x32_bf16 v[84:87], v[216:219], v[192:195], v[84:87]
	v_mfma_f32_16x16x32_bf16 v[80:83], v[226:229], v[192:195], v[80:83]
	v_mfma_f32_16x16x32_bf16 v[76:79], v[216:219], v[200:203], v[76:79]
	v_mfma_f32_16x16x32_bf16 v[72:75], v[226:229], v[200:203], v[72:75]
	v_mfma_f32_16x16x32_bf16 v[68:71], v[216:219], v[208:211], v[68:71]
	v_mfma_f32_16x16x32_bf16 v[64:67], v[226:229], v[208:211], v[64:67]
	s_setprio 0
	v_lshl_add_u64 v[240:241], v[174:175], 0, s[64:65]
	s_mov_b32 m0, s15
	s_barrier
; #define STAGE_A(P, half, kt) do { const char* _u = Ab + ((size_t)(half) * 128 * lda + (size_t)(kt) * BK) * 2; \
;     _Pragma("unroll") for (int _i = 0; _i < 2; ++_i) \
;       __builtin_amdgcn_global_load_lds((const unsigned*)(_u + offA[_i]), \
;         (__attribute__((address_space(3))) unsigned*)((__attribute__((address_space(3))) char*)(P) + tidg * 16 + _i * 8192), 16, 0, 0); } while (0)
; #define STAGE_B(P, half, kt) do { const char* _u = Bb + ((size_t)(half) * 128 * ldb + (size_t)(kt) * BK) * 2; \
;     _Pragma("unroll") for (int _i = 0; _i < 2; ++_i) \
;       __builtin_amdgcn_global_load_lds((const unsigned*)(_u + offB[_i]), \
;         (__attribute__((address_space(3))) unsigned*)((__attribute__((address_space(3))) char*)(P) + tidg * 16 + _i * 8192), 16, 0, 0); } while (0)
; #define LDA(dst, b, h) _Pragma("unroll") for (int m = 0; m < 4; ++m) _Pragma("unroll") for (int k = 0; k < 2; ++k) \
;     dst[m][k] = *reinterpret_cast<const bf16x8*>((const char*)SA(b, h) + lds_byte(wr * 64 + m * 16 + fr, k * 32 + fq * 8))
; #define LDB(dst, b, h) _Pragma("unroll") for (int n = 0; n < 2; ++n) _Pragma("unroll") for (int k = 0; k < 2; ++k) \
;     dst[n][k] = *reinterpret_cast<const bf16x8*>((const char*)SB(b, h) + lds_byte(wc * 32 + n * 16 + fr, k * 32 + fq * 8))
; #define MMA(ai, bj, At_, Bt_) do { __builtin_amdgcn_s_setprio(1); \
;     _Pragma("unroll") for (int m = 0; m < 4; ++m) _Pragma("unroll") for (int n = 0; n < 2; ++n) _Pragma("unroll") for (int k = 0; k < 2; ++k) \
;       acc[ai][bj][m][n] = __builtin_amdgcn_mfma_f32_16x16x32_bf16(Bt_[n][k], At_[m][k], acc[ai][bj][m][n], 0, 0, 0); \
;     __builtin_amdgcn_s_setprio(0); } while (0)
; template <bool PF = true, class Epi, class KRF = KRFull>
; __device__ __forceinline__ void gemm_phase(const u16* __restrict__ A, int lda, const u16* __restrict__ Bt, int ldb, int K, int nM, int nN,
;                                            lds_u16* shm, Epi epi, KRF krf = KRFull(), bool flip = false) {
;     ...
;       LDA(At, 0, 1); STAGE_A(SA(0, 0), 0, t + 2);
;       BAR; WAIT_L(0); MMA(1, 0, At, B0); BAR; SCHED;
;       STAGE_B(SB(0, 1), 1, t + 2);
;       WAIT_V(6); BAR; MMA(1, 1, At, B1); BAR;
;       LDB(B0, 1, 0); SCHED; LDA(At, 1, 0); STAGE_A(SA(0, 1), 1, t + 2);
;       WAIT_L(8); BAR; WAIT_L(0); MMA(0, 0, At, B0); BAR; SCHED;
;       LDB(B1, 1, 1); STAGE_B(SB(1, 0), 0, t + 3);
	ds_read_b128 v[180:183], v142 offset:16384
	ds_read_b128 v[184:187], v142 offset:17408
	ds_read_b128 v[188:191], v141 offset:16384
	ds_read_b128 v[192:195], v141 offset:17408
	ds_read_b128 v[196:199], v140 offset:16384
	ds_read_b128 v[200:203], v140 offset:17408
	ds_read_b128 v[204:207], v139 offset:16384
	ds_read_b128 v[208:211], v139 offset:17408
	global_load_lds_dwordx4 v[240:241], off
	v_lshl_add_u64 v[240:241], v[234:235], 0, s[64:65]
	s_add_u32 m0, s15, 0x2000
	s_nop 0
	global_load_lds_dwordx4 v[240:241], off
	s_barrier
	s_waitcnt lgkmcnt(0)
	s_setprio 1
	s_waitcnt lgkmcnt(0)
	v_mfma_f32_16x16x32_bf16 v[60:63], v[158:161], v[180:183], v[60:63]
	v_mfma_f32_16x16x32_bf16 v[56:59], v[166:169], v[180:183], v[56:59]
	v_mfma_f32_16x16x32_bf16 v[52:55], v[158:161], v[188:191], v[52:55]
	v_mfma_f32_16x16x32_bf16 v[48:51], v[166:169], v[188:191], v[48:51]
	v_mfma_f32_16x16x32_bf16 v[44:47], v[158:161], v[196:199], v[44:47]
	v_mfma_f32_16x16x32_bf16 v[40:43], v[166:169], v[196:199], v[40:43]
	v_mfma_f32_16x16x32_bf16 v[36:39], v[158:161], v[204:207], v[36:39]
	v_mfma_f32_16x16x32_bf16 v[32:35], v[166:169], v[204:207], v[32:35]
	v_mfma_f32_16x16x32_bf16 v[60:63], v[162:165], v[184:187], v[60:63]
	v_mfma_f32_16x16x32_bf16 v[56:59], v[170:173], v[184:187], v[56:59]
	v_mfma_f32_16x16x32_bf16 v[52:55], v[162:165], v[192:195], v[52:55]
	v_mfma_f32_16x16x32_bf16 v[48:51], v[170:173], v[192:195], v[48:51]
	v_mfma_f32_16x16x32_bf16 v[44:47], v[162:165], v[200:203], v[44:47]
	v_mfma_f32_16x16x32_bf16 v[40:43], v[170:173], v[200:203], v[40:43]
	v_mfma_f32_16x16x32_bf16 v[36:39], v[162:165], v[208:211], v[36:39]
	v_mfma_f32_16x16x32_bf16 v[32:35], v[170:173], v[208:211], v[32:35]
	s_setprio 0
	s_barrier
	v_lshl_add_u64 v[158:159], v[236:237], 0, s[66:67]
	s_add_u32 m0, s15, 0x14000
	s_nop 0
	global_load_lds_dwordx4 v[158:159], off
	v_lshl_add_u64 v[158:159], v[238:239], 0, s[66:67]
	s_add_u32 m0, s15, 0x16000
	s_nop 0
	global_load_lds_dwordx4 v[158:159], off
	s_waitcnt vmcnt(6)
	s_barrier
	s_setprio 1
	v_mfma_f32_16x16x32_bf16 v[28:31], v[212:215], v[180:183], v[28:31]
	v_mfma_f32_16x16x32_bf16 v[24:27], v[222:225], v[180:183], v[24:27]
	v_mfma_f32_16x16x32_bf16 v[20:23], v[212:215], v[188:191], v[20:23]
	v_mfma_f32_16x16x32_bf16 v[16:19], v[222:225], v[188:191], v[16:19]
	v_mfma_f32_16x16x32_bf16 v[12:15], v[212:215], v[196:199], v[12:15]
	v_mfma_f32_16x16x32_bf16 v[8:11], v[222:225], v[196:199], v[8:11]
	v_mfma_f32_16x16x32_bf16 v[4:7], v[212:215], v[204:207], v[4:7]
	v_mfma_f32_16x16x32_bf16 v[0:3], v[222:225], v[204:207], v[0:3]
	v_mfma_f32_16x16x32_bf16 v[28:31], v[216:219], v[184:187], v[28:31]
	v_mfma_f32_16x16x32_bf16 v[24:27], v[226:229], v[184:187], v[24:27]
	v_mfma_f32_16x16x32_bf16 v[20:23], v[216:219], v[192:195], v[20:23]
	v_mfma_f32_16x16x32_bf16 v[16:19], v[226:229], v[192:195], v[16:19]
	v_mfma_f32_16x16x32_bf16 v[12:15], v[216:219], v[200:203], v[12:15]
	v_mfma_f32_16x16x32_bf16 v[8:11], v[226:229], v[200:203], v[8:11]
	v_mfma_f32_16x16x32_bf16 v[4:7], v[216:219], v[208:211], v[4:7]
	v_mfma_f32_16x16x32_bf16 v[0:3], v[226:229], v[208:211], v[0:3]
	s_setprio 0
	s_barrier
	ds_read_b128 v[158:161], v145
	ds_read_b128 v[162:165], v145 offset:1024
	ds_read_b128 v[166:169], v145 offset:2048
	ds_read_b128 v[170:173], v145 offset:3072
	v_lshl_add_u64 v[212:213], v[174:175], 0, s[66:67]
	s_add_u32 m0, s15, 0x4000
	ds_read_b128 v[180:183], v142 offset:32768
	ds_read_b128 v[184:187], v142 offset:33792
	ds_read_b128 v[188:191], v141 offset:32768
	ds_read_b128 v[192:195], v141 offset:33792
	ds_read_b128 v[196:199], v140 offset:32768
	ds_read_b128 v[200:203], v140 offset:33792
	ds_read_b128 v[204:207], v139 offset:32768
	ds_read_b128 v[208:211], v139 offset:33792
	global_load_lds_dwordx4 v[212:213], off
	v_lshl_add_u64 v[212:213], v[234:235], 0, s[66:67]
	s_add_u32 m0, s15, 0x6000
	s_nop 0
	global_load_lds_dwordx4 v[212:213], off
	s_waitcnt lgkmcnt(8)
	s_barrier
	s_waitcnt lgkmcnt(0)
	s_setprio 1
	s_waitcnt lgkmcnt(0)
	v_mfma_f32_16x16x32_bf16 v[124:127], v[158:161], v[180:183], v[124:127]
	v_mfma_f32_16x16x32_bf16 v[120:123], v[166:169], v[180:183], v[120:123]
	v_mfma_f32_16x16x32_bf16 v[116:119], v[158:161], v[188:191], v[116:119]
	v_mfma_f32_16x16x32_bf16 v[112:115], v[166:169], v[188:191], v[112:115]
	v_mfma_f32_16x16x32_bf16 v[108:111], v[158:161], v[196:199], v[108:111]
	v_mfma_f32_16x16x32_bf16 v[104:107], v[166:169], v[196:199], v[104:107]
	v_mfma_f32_16x16x32_bf16 v[100:103], v[158:161], v[204:207], v[100:103]
	v_mfma_f32_16x16x32_bf16 v[96:99], v[166:169], v[204:207], v[96:99]
	v_mfma_f32_16x16x32_bf16 v[124:127], v[162:165], v[184:187], v[124:127]
	v_mfma_f32_16x16x32_bf16 v[120:123], v[170:173], v[184:187], v[120:123]
	v_mfma_f32_16x16x32_bf16 v[116:119], v[162:165], v[192:195], v[116:119]
	v_mfma_f32_16x16x32_bf16 v[112:115], v[170:173], v[192:195], v[112:115]
	v_mfma_f32_16x16x32_bf16 v[108:111], v[162:165], v[200:203], v[108:111]
	v_mfma_f32_16x16x32_bf16 v[104:107], v[170:173], v[200:203], v[104:107]
	v_mfma_f32_16x16x32_bf16 v[100:103], v[162:165], v[208:211], v[100:103]
	v_mfma_f32_16x16x32_bf16 v[96:99], v[170:173], v[208:211], v[96:99]
	s_setprio 0
	s_barrier
	v_lshl_add_u64 v[240:241], v[236:237], 0, s[68:69]
	s_add_u32 m0, s15, 0x18000
	ds_read_b128 v[212:215], v143
	ds_read_b128 v[216:219], v143 offset:1024
	ds_read_b128 v[222:225], v143 offset:2048
	ds_read_b128 v[226:229], v143 offset:3072
	global_load_lds_dwordx4 v[240:241], off
	v_lshl_add_u64 v[240:241], v[238:239], 0, s[68:69]
	s_add_u32 m0, s15, 0x1a000
	s_nop 0
	global_load_lds_dwordx4 v[240:241], off
	s_barrier
; #define STAGE_A(P, half, kt) do { const char* _u = Ab + ((size_t)(half) * 128 * lda + (size_t)(kt) * BK) * 2; \
;     _Pragma("unroll") for (int _i = 0; _i < 2; ++_i) \
;       __builtin_amdgcn_global_load_lds((const unsigned*)(_u + offA[_i]), \
;         (__attribute__((address_space(3))) unsigned*)((__attribute__((address_space(3))) char*)(P) + tidg * 16 + _i * 8192), 16, 0, 0); } while (0)
; #define STAGE_B(P, half, kt) do { const char* _u = Bb + ((size_t)(half) * 128 * ldb + (size_t)(kt) * BK) * 2; \
;     _Pragma("unroll") for (int _i = 0; _i < 2; ++_i) \
;       __builtin_amdgcn_global_load_lds((const unsigned*)(_u + offB[_i]), \
;         (__attribute__((address_space(3))) unsigned*)((__attribute__((address_space(3))) char*)(P) + tidg * 16 + _i * 8192), 16, 0, 0); } while (0)
; #define LDA(dst, b, h) _Pragma("unroll") for (int m = 0; m < 4; ++m) _Pragma("unroll") for (int k = 0; k < 2; ++k) \
;     dst[m][k] = *reinterpret_cast<const bf16x8*>((const char*)SA(b, h) + lds_byte(wr * 64 + m * 16 + fr, k * 32 + fq * 8))
; #define LDB(dst, b, h) _Pragma("unroll") for (int n = 0; n < 2; ++n) _Pragma("unroll") for (int k = 0; k < 2; ++k) \
;     dst[n][k] = *reinterpret_cast<const bf16x8*>((const char*)SB(b, h) + lds_byte(wc * 32 + n * 16 + fr, k * 32 + fq * 8))
; #define MMA(ai, bj, At_, Bt_) do { __builtin_amdgcn_s_setprio(1); \
;     _Pragma("unroll") for (int m = 0; m < 4; ++m) _Pragma("unroll") for (int n = 0; n < 2; ++n) _Pragma("unroll") for (int k = 0; k < 2; ++k) \
;       acc[ai][bj][m][n] = __builtin_amdgcn_mfma_f32_16x16x32_bf16(Bt_[n][k], At_[m][k], acc[ai][bj][m][n], 0, 0, 0); \
;     __builtin_amdgcn_s_setprio(0); } while (0)
; #define BAR __builtin_amdgcn_s_barrier()
; template <bool PF = true, class Epi, class KRF = KRFull>
; __device__ __forceinline__ void gemm_phase(const u16* __restrict__ A, int lda, const u16* __restrict__ Bt, int ldb, int K, int nM, int nN,
;                                            lds_u16* shm, Epi epi, KRF krf = KRFull(), bool flip = false) {
;     ...
;       LDB(B1, 1, 1); STAGE_B(SB(1, 0), 0, t + 3);
;       BAR; WAIT_L(0); MMA(0, 1, At, B1); BAR;
;       LDA(At, 1, 1); STAGE_A(SA(1, 0), 0, t + 3);
;       BAR; WAIT_L(0); MMA(1, 0, At, B0); BAR; SCHED;
;       STAGE_B(SB(1, 1), 1, t + 3);
;       WAIT_V(6); BAR; MMA(1, 1, At, B1); BAR;
;     }
;     { LDB(B0, 0, 0); LDA(At, 0, 0); STAGE_A(SA(1, 1), 1, nt - 1);
	s_waitcnt lgkmcnt(0)
	s_setprio 1
	s_waitcnt lgkmcnt(0)
	v_mfma_f32_16x16x32_bf16 v[92:95], v[212:215], v[180:183], v[92:95]
	v_mfma_f32_16x16x32_bf16 v[88:91], v[222:225], v[180:183], v[88:91]
	v_mfma_f32_16x16x32_bf16 v[84:87], v[212:215], v[188:191], v[84:87]
	v_mfma_f32_16x16x32_bf16 v[80:83], v[222:225], v[188:191], v[80:83]
	v_mfma_f32_16x16x32_bf16 v[76:79], v[212:215], v[196:199], v[76:79]
	v_mfma_f32_16x16x32_bf16 v[72:75], v[222:225], v[196:199], v[72:75]
	v_mfma_f32_16x16x32_bf16 v[68:71], v[212:215], v[204:207], v[68:71]
	v_mfma_f32_16x16x32_bf16 v[64:67], v[222:225], v[204:207], v[64:67]
	v_mfma_f32_16x16x32_bf16 v[92:95], v[216:219], v[184:187], v[92:95]
	v_mfma_f32_16x16x32_bf16 v[88:91], v[226:229], v[184:187], v[88:91]
	v_mfma_f32_16x16x32_bf16 v[84:87], v[216:219], v[192:195], v[84:87]
	v_mfma_f32_16x16x32_bf16 v[80:83], v[226:229], v[192:195], v[80:83]
	v_mfma_f32_16x16x32_bf16 v[76:79], v[216:219], v[200:203], v[76:79]
	v_mfma_f32_16x16x32_bf16 v[72:75], v[226:229], v[200:203], v[72:75]
	v_mfma_f32_16x16x32_bf16 v[68:71], v[216:219], v[208:211], v[68:71]
	v_mfma_f32_16x16x32_bf16 v[64:67], v[226:229], v[208:211], v[64:67]
	s_setprio 0
	v_lshl_add_u64 v[174:175], v[174:175], 0, s[68:69]
	s_add_u32 m0, s15, 0x8000
	s_barrier
	ds_read_b128 v[180:183], v142 offset:49152
	ds_read_b128 v[184:187], v142 offset:50176
	ds_read_b128 v[188:191], v141 offset:49152
	ds_read_b128 v[192:195], v141 offset:50176
	ds_read_b128 v[196:199], v140 offset:49152
	ds_read_b128 v[200:203], v140 offset:50176
	ds_read_b128 v[204:207], v139 offset:49152
	ds_read_b128 v[208:211], v139 offset:50176
	global_load_lds_dwordx4 v[174:175], off
	v_lshl_add_u64 v[174:175], v[234:235], 0, s[68:69]
	s_add_u32 m0, s15, 0xa000
	s_nop 0
	global_load_lds_dwordx4 v[174:175], off
	s_barrier
	s_waitcnt lgkmcnt(0)
	s_setprio 1
	s_waitcnt lgkmcnt(0)
	v_mfma_f32_16x16x32_bf16 v[60:63], v[158:161], v[180:183], v[60:63]
	v_mfma_f32_16x16x32_bf16 v[56:59], v[166:169], v[180:183], v[56:59]
	v_mfma_f32_16x16x32_bf16 v[52:55], v[158:161], v[188:191], v[52:55]
	v_mfma_f32_16x16x32_bf16 v[48:51], v[166:169], v[188:191], v[48:51]
	v_mfma_f32_16x16x32_bf16 v[44:47], v[158:161], v[196:199], v[44:47]
	v_mfma_f32_16x16x32_bf16 v[40:43], v[166:169], v[196:199], v[40:43]
	v_mfma_f32_16x16x32_bf16 v[36:39], v[158:161], v[204:207], v[36:39]
	v_mfma_f32_16x16x32_bf16 v[32:35], v[166:169], v[204:207], v[32:35]
	v_mfma_f32_16x16x32_bf16 v[60:63], v[162:165], v[184:187], v[60:63]
	v_mfma_f32_16x16x32_bf16 v[56:59], v[170:173], v[184:187], v[56:59]
	v_mfma_f32_16x16x32_bf16 v[52:55], v[162:165], v[192:195], v[52:55]
	v_mfma_f32_16x16x32_bf16 v[48:51], v[170:173], v[192:195], v[48:51]
	v_mfma_f32_16x16x32_bf16 v[44:47], v[162:165], v[200:203], v[44:47]
	v_mfma_f32_16x16x32_bf16 v[40:43], v[170:173], v[200:203], v[40:43]
	v_mfma_f32_16x16x32_bf16 v[36:39], v[162:165], v[208:211], v[36:39]
	v_mfma_f32_16x16x32_bf16 v[32:35], v[170:173], v[208:211], v[32:35]
	s_setprio 0
	s_barrier
	v_lshl_add_u64 v[158:159], v[236:237], 0, s[70:71]
	s_add_u32 m0, s15, 0x1c000
	s_nop 0
	global_load_lds_dwordx4 v[158:159], off
	v_lshl_add_u64 v[158:159], v[238:239], 0, s[70:71]
	s_add_u32 m0, s15, 0x1e000
	s_nop 0
	global_load_lds_dwordx4 v[158:159], off
	s_waitcnt vmcnt(6)
	s_barrier
	s_setprio 1
	v_mfma_f32_16x16x32_bf16 v[28:31], v[212:215], v[180:183], v[28:31]
	v_mfma_f32_16x16x32_bf16 v[24:27], v[222:225], v[180:183], v[24:27]
	v_mfma_f32_16x16x32_bf16 v[20:23], v[212:215], v[188:191], v[20:23]
	v_mfma_f32_16x16x32_bf16 v[16:19], v[222:225], v[188:191], v[16:19]
	v_mfma_f32_16x16x32_bf16 v[12:15], v[212:215], v[196:199], v[12:15]
	v_mfma_f32_16x16x32_bf16 v[8:11], v[222:225], v[196:199], v[8:11]
	v_mfma_f32_16x16x32_bf16 v[4:7], v[212:215], v[204:207], v[4:7]
	v_mfma_f32_16x16x32_bf16 v[0:3], v[222:225], v[204:207], v[0:3]
	v_mfma_f32_16x16x32_bf16 v[28:31], v[216:219], v[184:187], v[28:31]
	v_mfma_f32_16x16x32_bf16 v[24:27], v[226:229], v[184:187], v[24:27]
	v_mfma_f32_16x16x32_bf16 v[20:23], v[216:219], v[192:195], v[20:23]
	v_mfma_f32_16x16x32_bf16 v[16:19], v[226:229], v[192:195], v[16:19]
	v_mfma_f32_16x16x32_bf16 v[12:15], v[216:219], v[200:203], v[12:15]
	v_mfma_f32_16x16x32_bf16 v[8:11], v[226:229], v[200:203], v[8:11]
	v_mfma_f32_16x16x32_bf16 v[4:7], v[216:219], v[208:211], v[4:7]
	v_mfma_f32_16x16x32_bf16 v[0:3], v[226:229], v[208:211], v[0:3]
	s_setprio 0
	s_add_i32 s13, s13, 2
	s_add_u32 s18, s18, 0x100
	s_addc_u32 s19, s19, 0
	s_cmp_gt_u32 s13, 27
	s_barrier
	s_cbranch_scc0 .LBB0_2535
	v_add_u32_e32 v155, 0xc000, v144
	v_add_u32_e32 v156, 0xe000, v144
	v_add_u32_e32 v157, 0x6000, v144
	s_add_u32 s16, s6, 0x80f80
	s_addc_u32 s17, s7, 0
	v_readfirstlane_b32 s13, v155
	v_lshl_add_u64 v[150:151], s[16:17], 0, v[178:179]
	s_mov_b32 m0, s13
	v_readfirstlane_b32 s13, v156
	ds_read_b128 v[130:133], v154
	ds_read_b128 v[134:137], v154 offset:1024
	ds_read_b128 v[146:149], v154 offset:2048
	ds_read_b128 v[158:161], v154 offset:3072
	ds_read_b128 v[162:165], v142
	ds_read_b128 v[166:169], v142 offset:1024
	ds_read_b128 v[170:173], v141
	ds_read_b128 v[180:183], v141 offset:1024
	ds_read_b128 v[184:187], v140
	ds_read_b128 v[188:191], v140 offset:1024
	ds_read_b128 v[192:195], v139
	ds_read_b128 v[196:199], v139 offset:1024
	global_load_lds_dwordx4 v[150:151], off
	v_lshl_add_u64 v[128:129], s[16:17], 0, v[128:129]
	s_mov_b32 m0, s13
	s_nop 0
	global_load_lds_dwordx4 v[128:129], off
	s_barrier
; #define STAGE_A(P, half, kt) do { const char* _u = Ab + ((size_t)(half) * 128 * lda + (size_t)(kt) * BK) * 2; \
;     _Pragma("unroll") for (int _i = 0; _i < 2; ++_i) \
;       __builtin_amdgcn_global_load_lds((const unsigned*)(_u + offA[_i]), \
;         (__attribute__((address_space(3))) unsigned*)((__attribute__((address_space(3))) char*)(P) + tidg * 16 + _i * 8192), 16, 0, 0); } while (0)
; #define LDA(dst, b, h) _Pragma("unroll") for (int m = 0; m < 4; ++m) _Pragma("unroll") for (int k = 0; k < 2; ++k) \
;     dst[m][k] = *reinterpret_cast<const bf16x8*>((const char*)SA(b, h) + lds_byte(wr * 64 + m * 16 + fr, k * 32 + fq * 8))
; #define LDB(dst, b, h) _Pragma("unroll") for (int n = 0; n < 2; ++n) _Pragma("unroll") for (int k = 0; k < 2; ++k) \
;     dst[n][k] = *reinterpret_cast<const bf16x8*>((const char*)SB(b, h) + lds_byte(wc * 32 + n * 16 + fr, k * 32 + fq * 8))
; #define MMA(ai, bj, At_, Bt_) do { __builtin_amdgcn_s_setprio(1); \
;     _Pragma("unroll") for (int m = 0; m < 4; ++m) _Pragma("unroll") for (int n = 0; n < 2; ++n) _Pragma("unroll") for (int k = 0; k < 2; ++k) \
;       acc[ai][bj][m][n] = __builtin_amdgcn_mfma_f32_16x16x32_bf16(Bt_[n][k], At_[m][k], acc[ai][bj][m][n], 0, 0, 0); \
;     __builtin_amdgcn_s_setprio(0); } while (0)
; #define WAIT_V(n) asm volatile("s_waitcnt vmcnt(" #n ")" ::: "memory")
; #define WAIT_L(n) asm volatile("s_waitcnt lgkmcnt(" #n ")" ::: "memory")
; #define BAR __builtin_amdgcn_s_barrier()
; template <bool PF = true, class Epi, class KRF = KRFull>
; __device__ __forceinline__ void gemm_phase(const u16* __restrict__ A, int lda, const u16* __restrict__ Bt, int ldb, int K, int nM, int nN,
;                                            lds_u16* shm, Epi epi, KRF krf = KRFull(), bool flip = false) {
;     ...
;     { LDB(B0, 0, 0); LDA(At, 0, 0); STAGE_A(SA(1, 1), 1, nt - 1);
;       BAR; WAIT_L(0); MMA(0, 0, At, B0); BAR;
;       LDB(B1, 0, 1); BAR; WAIT_L(0); MMA(0, 1, At, B1); BAR;
;       LDA(At, 0, 1); WAIT_V(4); BAR; WAIT_L(0); MMA(1, 0, At, B0); MMA(1, 1, At, B1); BAR; }
;     { LDB(B0, 1, 0); LDA(At, 1, 0); WAIT_V(2); BAR; WAIT_L(0); MMA(0, 0, At, B0); BAR;
	s_waitcnt lgkmcnt(0)
	s_setprio 1
	s_waitcnt lgkmcnt(0)
	v_mfma_f32_16x16x32_bf16 v[124:127], v[130:133], v[162:165], v[124:127]
	v_mfma_f32_16x16x32_bf16 v[120:123], v[146:149], v[162:165], v[120:123]
	v_mfma_f32_16x16x32_bf16 v[116:119], v[130:133], v[170:173], v[116:119]
	v_mfma_f32_16x16x32_bf16 v[112:115], v[146:149], v[170:173], v[112:115]
	v_mfma_f32_16x16x32_bf16 v[108:111], v[130:133], v[184:187], v[108:111]
	v_mfma_f32_16x16x32_bf16 v[104:107], v[146:149], v[184:187], v[104:107]
	v_mfma_f32_16x16x32_bf16 v[100:103], v[130:133], v[192:195], v[100:103]
	v_mfma_f32_16x16x32_bf16 v[96:99], v[146:149], v[192:195], v[96:99]
	v_mfma_f32_16x16x32_bf16 v[124:127], v[134:137], v[166:169], v[124:127]
	v_mfma_f32_16x16x32_bf16 v[120:123], v[158:161], v[166:169], v[120:123]
	v_mfma_f32_16x16x32_bf16 v[116:119], v[134:137], v[180:183], v[116:119]
	v_mfma_f32_16x16x32_bf16 v[112:115], v[158:161], v[180:183], v[112:115]
	v_mfma_f32_16x16x32_bf16 v[108:111], v[134:137], v[188:191], v[108:111]
	v_mfma_f32_16x16x32_bf16 v[104:107], v[158:161], v[188:191], v[104:107]
	v_mfma_f32_16x16x32_bf16 v[100:103], v[134:137], v[196:199], v[100:103]
	v_mfma_f32_16x16x32_bf16 v[96:99], v[158:161], v[196:199], v[96:99]
	s_setprio 0
	s_barrier
	ds_read_b128 v[154:157], v153
	ds_read_b128 v[200:203], v153 offset:1024
	ds_read_b128 v[204:207], v153 offset:2048
	ds_read_b128 v[150:153], v153 offset:3072
	s_barrier
	s_waitcnt lgkmcnt(0)
	s_setprio 1
	s_waitcnt lgkmcnt(0)
	v_mfma_f32_16x16x32_bf16 v[92:95], v[154:157], v[162:165], v[92:95]
	v_mfma_f32_16x16x32_bf16 v[88:91], v[204:207], v[162:165], v[88:91]
	v_mfma_f32_16x16x32_bf16 v[84:87], v[154:157], v[170:173], v[84:87]
	v_mfma_f32_16x16x32_bf16 v[80:83], v[204:207], v[170:173], v[80:83]
	v_mfma_f32_16x16x32_bf16 v[76:79], v[154:157], v[184:187], v[76:79]
	v_mfma_f32_16x16x32_bf16 v[72:75], v[204:207], v[184:187], v[72:75]
	v_mfma_f32_16x16x32_bf16 v[68:71], v[154:157], v[192:195], v[68:71]
	v_mfma_f32_16x16x32_bf16 v[64:67], v[204:207], v[192:195], v[64:67]
	v_mfma_f32_16x16x32_bf16 v[92:95], v[200:203], v[166:169], v[92:95]
	v_mfma_f32_16x16x32_bf16 v[88:91], v[150:153], v[166:169], v[88:91]
	v_mfma_f32_16x16x32_bf16 v[84:87], v[200:203], v[180:183], v[84:87]
	v_mfma_f32_16x16x32_bf16 v[80:83], v[150:153], v[180:183], v[80:83]
	v_mfma_f32_16x16x32_bf16 v[76:79], v[200:203], v[188:191], v[76:79]
	v_mfma_f32_16x16x32_bf16 v[72:75], v[150:153], v[188:191], v[72:75]
	v_mfma_f32_16x16x32_bf16 v[68:71], v[200:203], v[196:199], v[68:71]
	v_mfma_f32_16x16x32_bf16 v[64:67], v[150:153], v[196:199], v[64:67]
	s_setprio 0
	s_barrier
	ds_read_b128 v[162:165], v142 offset:16384
	ds_read_b128 v[166:169], v142 offset:17408
	ds_read_b128 v[170:173], v141 offset:16384
	ds_read_b128 v[180:183], v141 offset:17408
	ds_read_b128 v[184:187], v140 offset:16384
	ds_read_b128 v[188:191], v140 offset:17408
	ds_read_b128 v[192:195], v139 offset:16384
	ds_read_b128 v[196:199], v139 offset:17408
	s_waitcnt vmcnt(4)
	s_barrier
	s_waitcnt lgkmcnt(0)
	s_setprio 1
	s_waitcnt lgkmcnt(0)
	v_mfma_f32_16x16x32_bf16 v[60:63], v[130:133], v[162:165], v[60:63]
	v_mfma_f32_16x16x32_bf16 v[56:59], v[146:149], v[162:165], v[56:59]
	v_mfma_f32_16x16x32_bf16 v[52:55], v[130:133], v[170:173], v[52:55]
	v_mfma_f32_16x16x32_bf16 v[48:51], v[146:149], v[170:173], v[48:51]
	v_mfma_f32_16x16x32_bf16 v[44:47], v[130:133], v[184:187], v[44:47]
	v_mfma_f32_16x16x32_bf16 v[40:43], v[146:149], v[184:187], v[40:43]
	v_mfma_f32_16x16x32_bf16 v[36:39], v[130:133], v[192:195], v[36:39]
	v_mfma_f32_16x16x32_bf16 v[32:35], v[146:149], v[192:195], v[32:35]
	v_mfma_f32_16x16x32_bf16 v[60:63], v[134:137], v[166:169], v[60:63]
	v_mfma_f32_16x16x32_bf16 v[56:59], v[158:161], v[166:169], v[56:59]
	v_mfma_f32_16x16x32_bf16 v[52:55], v[134:137], v[180:183], v[52:55]
	v_mfma_f32_16x16x32_bf16 v[48:51], v[158:161], v[180:183], v[48:51]
	v_mfma_f32_16x16x32_bf16 v[44:47], v[134:137], v[188:191], v[44:47]
	v_mfma_f32_16x16x32_bf16 v[40:43], v[158:161], v[188:191], v[40:43]
	v_mfma_f32_16x16x32_bf16 v[36:39], v[134:137], v[196:199], v[36:39]
	v_mfma_f32_16x16x32_bf16 v[32:35], v[158:161], v[196:199], v[32:35]
	s_setprio 0
	s_setprio 1
	v_mfma_f32_16x16x32_bf16 v[28:31], v[154:157], v[162:165], v[28:31]
	v_mfma_f32_16x16x32_bf16 v[24:27], v[204:207], v[162:165], v[24:27]
	v_mfma_f32_16x16x32_bf16 v[20:23], v[154:157], v[170:173], v[20:23]
	v_mfma_f32_16x16x32_bf16 v[16:19], v[204:207], v[170:173], v[16:19]
	v_mfma_f32_16x16x32_bf16 v[12:15], v[154:157], v[184:187], v[12:15]
	v_mfma_f32_16x16x32_bf16 v[8:11], v[204:207], v[184:187], v[8:11]
	v_mfma_f32_16x16x32_bf16 v[4:7], v[154:157], v[192:195], v[4:7]
	v_mfma_f32_16x16x32_bf16 v[0:3], v[204:207], v[192:195], v[0:3]
	v_mfma_f32_16x16x32_bf16 v[28:31], v[200:203], v[166:169], v[28:31]
	v_mfma_f32_16x16x32_bf16 v[24:27], v[150:153], v[166:169], v[24:27]
	v_mfma_f32_16x16x32_bf16 v[20:23], v[200:203], v[180:183], v[20:23]
	v_mfma_f32_16x16x32_bf16 v[16:19], v[150:153], v[180:183], v[16:19]
	v_mfma_f32_16x16x32_bf16 v[12:15], v[200:203], v[188:191], v[12:15]
	v_mfma_f32_16x16x32_bf16 v[8:11], v[150:153], v[188:191], v[8:11]
	v_mfma_f32_16x16x32_bf16 v[4:7], v[200:203], v[196:199], v[4:7]
	v_mfma_f32_16x16x32_bf16 v[0:3], v[150:153], v[196:199], v[0:3]
	s_setprio 0
	s_barrier
	ds_read_b128 v[128:131], v145
	ds_read_b128 v[132:135], v145 offset:1024
	ds_read_b128 v[146:149], v145 offset:2048
	ds_read_b128 v[150:153], v145 offset:3072
	ds_read_b128 v[154:157], v142 offset:32768
	ds_read_b128 v[158:161], v142 offset:33792
	ds_read_b128 v[162:165], v141 offset:32768
	ds_read_b128 v[166:169], v141 offset:33792
	ds_read_b128 v[170:173], v140 offset:32768
	ds_read_b128 v[180:183], v140 offset:33792
	ds_read_b128 v[184:187], v139 offset:32768
	ds_read_b128 v[188:191], v139 offset:33792
	s_waitcnt vmcnt(2)
	s_barrier
; #define LDA(dst, b, h) _Pragma("unroll") for (int m = 0; m < 4; ++m) _Pragma("unroll") for (int k = 0; k < 2; ++k) \
;     dst[m][k] = *reinterpret_cast<const bf16x8*>((const char*)SA(b, h) + lds_byte(wr * 64 + m * 16 + fr, k * 32 + fq * 8))
; #define LDB(dst, b, h) _Pragma("unroll") for (int n = 0; n < 2; ++n) _Pragma("unroll") for (int k = 0; k < 2; ++k) \
;     dst[n][k] = *reinterpret_cast<const bf16x8*>((const char*)SB(b, h) + lds_byte(wc * 32 + n * 16 + fr, k * 32 + fq * 8))
; #define MMA(ai, bj, At_, Bt_) do { __builtin_amdgcn_s_setprio(1); \
;     _Pragma("unroll") for (int m = 0; m < 4; ++m) _Pragma("unroll") for (int n = 0; n < 2; ++n) _Pragma("unroll") for (int k = 0; k < 2; ++k) \
;       acc[ai][bj][m][n] = __builtin_amdgcn_mfma_f32_16x16x32_bf16(Bt_[n][k], At_[m][k], acc[ai][bj][m][n], 0, 0, 0); \
;     __builtin_amdgcn_s_setprio(0); } while (0)
; #define WAIT_V(n) asm volatile("s_waitcnt vmcnt(" #n ")" ::: "memory")
; #define WAIT_L(n) asm volatile("s_waitcnt lgkmcnt(" #n ")" ::: "memory")
; #define BAR __builtin_amdgcn_s_barrier()
; template <bool PF = true, class Epi, class KRF = KRFull>
; __device__ __forceinline__ void gemm_phase(const u16* __restrict__ A, int lda, const u16* __restrict__ Bt, int ldb, int K, int nM, int nN,
;                                            lds_u16* shm, Epi epi, KRF krf = KRFull(), bool flip = false) {
;     ...
;     { LDB(B0, 1, 0); LDA(At, 1, 0); WAIT_V(2); BAR; WAIT_L(0); MMA(0, 0, At, B0); BAR;
;       LDB(B1, 1, 1); WAIT_V(0); BAR; WAIT_L(0); MMA(0, 1, At, B1); BAR;
;       LDA(At, 1, 1); BAR; WAIT_L(0); MMA(1, 0, At, B0); MMA(1, 1, At, B1); BAR; }
;     if (wr == 0) BAR;
	s_waitcnt lgkmcnt(0)
	s_setprio 1
	s_waitcnt lgkmcnt(0)
	v_mfma_f32_16x16x32_bf16 v[124:127], v[128:131], v[154:157], v[124:127]
	v_mfma_f32_16x16x32_bf16 v[120:123], v[146:149], v[154:157], v[120:123]
	v_mfma_f32_16x16x32_bf16 v[116:119], v[128:131], v[162:165], v[116:119]
	v_mfma_f32_16x16x32_bf16 v[112:115], v[146:149], v[162:165], v[112:115]
	v_mfma_f32_16x16x32_bf16 v[108:111], v[128:131], v[170:173], v[108:111]
	v_mfma_f32_16x16x32_bf16 v[104:107], v[146:149], v[170:173], v[104:107]
	v_mfma_f32_16x16x32_bf16 v[100:103], v[128:131], v[184:187], v[100:103]
	v_mfma_f32_16x16x32_bf16 v[96:99], v[146:149], v[184:187], v[96:99]
	v_mfma_f32_16x16x32_bf16 v[124:127], v[132:135], v[158:161], v[124:127]
	v_mfma_f32_16x16x32_bf16 v[120:123], v[150:153], v[158:161], v[120:123]
	v_mfma_f32_16x16x32_bf16 v[116:119], v[132:135], v[166:169], v[116:119]
	v_mfma_f32_16x16x32_bf16 v[112:115], v[150:153], v[166:169], v[112:115]
	v_mfma_f32_16x16x32_bf16 v[108:111], v[132:135], v[180:183], v[108:111]
	v_mfma_f32_16x16x32_bf16 v[104:107], v[150:153], v[180:183], v[104:107]
	v_mfma_f32_16x16x32_bf16 v[100:103], v[132:135], v[188:191], v[100:103]
	v_mfma_f32_16x16x32_bf16 v[96:99], v[150:153], v[188:191], v[96:99]
	s_setprio 0
	s_barrier
	ds_read_b128 v[192:195], v143
	ds_read_b128 v[196:199], v143 offset:1024
	ds_read_b128 v[200:203], v143 offset:2048
	ds_read_b128 v[204:207], v143 offset:3072
	s_waitcnt vmcnt(0)
	s_barrier
	s_waitcnt lgkmcnt(0)
	s_setprio 1
	s_waitcnt lgkmcnt(0)
	v_mfma_f32_16x16x32_bf16 v[92:95], v[192:195], v[154:157], v[92:95]
	v_mfma_f32_16x16x32_bf16 v[88:91], v[200:203], v[154:157], v[88:91]
	v_mfma_f32_16x16x32_bf16 v[84:87], v[192:195], v[162:165], v[84:87]
	v_mfma_f32_16x16x32_bf16 v[80:83], v[200:203], v[162:165], v[80:83]
	v_mfma_f32_16x16x32_bf16 v[76:79], v[192:195], v[170:173], v[76:79]
	v_mfma_f32_16x16x32_bf16 v[72:75], v[200:203], v[170:173], v[72:75]
	v_mfma_f32_16x16x32_bf16 v[68:71], v[192:195], v[184:187], v[68:71]
	v_mfma_f32_16x16x32_bf16 v[64:67], v[200:203], v[184:187], v[64:67]
	v_mfma_f32_16x16x32_bf16 v[92:95], v[196:199], v[158:161], v[92:95]
	v_mfma_f32_16x16x32_bf16 v[88:91], v[204:207], v[158:161], v[88:91]
	v_mfma_f32_16x16x32_bf16 v[84:87], v[196:199], v[166:169], v[84:87]
	v_mfma_f32_16x16x32_bf16 v[80:83], v[204:207], v[166:169], v[80:83]
	v_mfma_f32_16x16x32_bf16 v[76:79], v[196:199], v[180:183], v[76:79]
	v_mfma_f32_16x16x32_bf16 v[72:75], v[204:207], v[180:183], v[72:75]
	v_mfma_f32_16x16x32_bf16 v[68:71], v[196:199], v[188:191], v[68:71]
	v_mfma_f32_16x16x32_bf16 v[64:67], v[204:207], v[188:191], v[64:67]
	s_setprio 0
	s_barrier
	ds_read_b128 v[154:157], v142 offset:49152
	ds_read_b128 v[142:145], v142 offset:50176
	ds_read_b128 v[158:161], v141 offset:49152
	ds_read_b128 v[162:165], v141 offset:50176
	ds_read_b128 v[166:169], v140 offset:49152
	ds_read_b128 v[170:173], v140 offset:50176
	ds_read_b128 v[180:183], v139 offset:49152
	ds_read_b128 v[184:187], v139 offset:50176
	s_barrier
	s_waitcnt lgkmcnt(0)
	s_setprio 1
	s_waitcnt lgkmcnt(0)
	v_mfma_f32_16x16x32_bf16 v[60:63], v[128:131], v[154:157], v[60:63]
	v_mfma_f32_16x16x32_bf16 v[56:59], v[146:149], v[154:157], v[56:59]
	v_mfma_f32_16x16x32_bf16 v[52:55], v[128:131], v[158:161], v[52:55]
	v_mfma_f32_16x16x32_bf16 v[48:51], v[146:149], v[158:161], v[48:51]
	v_mfma_f32_16x16x32_bf16 v[44:47], v[128:131], v[166:169], v[44:47]
	v_mfma_f32_16x16x32_bf16 v[40:43], v[146:149], v[166:169], v[40:43]
	v_mfma_f32_16x16x32_bf16 v[36:39], v[128:131], v[180:183], v[36:39]
	v_mfma_f32_16x16x32_bf16 v[32:35], v[146:149], v[180:183], v[32:35]
	v_mfma_f32_16x16x32_bf16 v[60:63], v[132:135], v[142:145], v[60:63]
	v_mfma_f32_16x16x32_bf16 v[56:59], v[150:153], v[142:145], v[56:59]
	v_mfma_f32_16x16x32_bf16 v[52:55], v[132:135], v[162:165], v[52:55]
	v_mfma_f32_16x16x32_bf16 v[48:51], v[150:153], v[162:165], v[48:51]
	v_mfma_f32_16x16x32_bf16 v[44:47], v[132:135], v[170:173], v[44:47]
	v_mfma_f32_16x16x32_bf16 v[40:43], v[150:153], v[170:173], v[40:43]
	v_mfma_f32_16x16x32_bf16 v[36:39], v[132:135], v[184:187], v[36:39]
	v_mfma_f32_16x16x32_bf16 v[32:35], v[150:153], v[184:187], v[32:35]
	s_setprio 0
	s_setprio 1
	v_mfma_f32_16x16x32_bf16 v[28:31], v[192:195], v[154:157], v[28:31]
	v_mfma_f32_16x16x32_bf16 v[24:27], v[200:203], v[154:157], v[24:27]
	v_mfma_f32_16x16x32_bf16 v[20:23], v[192:195], v[158:161], v[20:23]
	v_mfma_f32_16x16x32_bf16 v[16:19], v[200:203], v[158:161], v[16:19]
	v_mfma_f32_16x16x32_bf16 v[12:15], v[192:195], v[166:169], v[12:15]
	v_mfma_f32_16x16x32_bf16 v[8:11], v[200:203], v[166:169], v[8:11]
	v_mfma_f32_16x16x32_bf16 v[4:7], v[192:195], v[180:183], v[4:7]
	v_mfma_f32_16x16x32_bf16 v[0:3], v[200:203], v[180:183], v[0:3]
	v_mfma_f32_16x16x32_bf16 v[28:31], v[196:199], v[142:145], v[28:31]
	v_mfma_f32_16x16x32_bf16 v[24:27], v[204:207], v[142:145], v[24:27]
	v_mfma_f32_16x16x32_bf16 v[20:23], v[196:199], v[162:165], v[20:23]
	v_mfma_f32_16x16x32_bf16 v[16:19], v[204:207], v[162:165], v[16:19]
	v_mfma_f32_16x16x32_bf16 v[12:15], v[196:199], v[170:173], v[12:15]
	v_mfma_f32_16x16x32_bf16 v[8:11], v[204:207], v[170:173], v[8:11]
	v_mfma_f32_16x16x32_bf16 v[4:7], v[196:199], v[184:187], v[4:7]
	v_mfma_f32_16x16x32_bf16 v[0:3], v[204:207], v[184:187], v[0:3]
	s_setprio 0
	v_cmp_gt_u32_e32 vcc, s95, v138
	s_barrier
	s_and_saveexec_b64 s[16:17], vcc
	s_cbranch_execz .LBB0_2538
	s_barrier

; __device__ __forceinline__ int tid_l() { int t = threadIdx.x; asm volatile("" : "+v"(t)); return t; }
; __device__ __forceinline__ int bid_l() { int t = blockIdx.x; asm volatile("" : "+s"(t)); return t; }
; __device__ __forceinline__ int gdim_l() { int t = gridDim.x; asm volatile("" : "+s"(t)); return t; }
; #define STAGE_A(P, half, kt) do { const char* _u = Ab + ((size_t)(half) * 128 * lda + (size_t)(kt) * BK) * 2; \
;     _Pragma("unroll") for (int _i = 0; _i < 2; ++_i) \
;       __builtin_amdgcn_global_load_lds((const unsigned*)(_u + offA[_i]), \
;         (__attribute__((address_space(3))) unsigned*)((__attribute__((address_space(3))) char*)(P) + tidg * 16 + _i * 8192), 16, 0, 0); } while (0)
; #define WAIT_V(n) asm volatile("s_waitcnt vmcnt(" #n ")" ::: "memory")
; #define BAR __builtin_amdgcn_s_barrier()
; template <bool PF = true, class Epi, class KRF = KRFull>
; __device__ __forceinline__ void gemm_phase(const u16* __restrict__ A, int lda, const u16* __restrict__ Bt, int ldb, int K, int nM, int nN,
;                                            lds_u16* shm, Epi epi, KRF krf = KRFull(), bool flip = false) {
;   int tidg = tid_l();
;   int wid, lane, wr, wc, fr, fq;
;   int nt;
;   unsigned offA[2], offB[2];
;     ...
;   G_THREAD();
;   int ntile = nM * nN;
;   const int gdg = gdim_l();
;   const int bidg = flip ? (gdg - 1 - bid_l()) : bid_l();
;   int tix = bidg;
;   if (tix >= ntile) return;
;   int pm, pn; tile_map(tix, nM, nN, pm, pn);
;   int brow = pm * 256, bcol = pn * 256;
;   int2 kr = krf(bcol, K);
;   int nt_next = kr.y;
;   const char* Ab = (const char*)A + (size_t)brow * lda * 2 + kr.x * (BK * 2);
;   const char* Bb = (const char*)Bt + (size_t)bcol * ldb * 2 + kr.x * (BK * 2);
;   __syncthreads();
;   STAGE_B(SB(0, 0), 0, 0); STAGE_A(SA(0, 0), 0, 0);
;   STAGE_B(SB(0, 1), 1, 0); STAGE_A(SA(0, 1), 1, 0);
;   for (;;) {
;     G_THREAD();
;     nt = nt_next;
;     f32x4 acc[2][2][4][2] = {};
;     bf16x8 At[4][2], B0[2][2], B1[2][2];
;     if (wr == 1) BAR;
;     WAIT_V(4); BAR;
;     STAGE_B(SB(1, 0), 0, 1); STAGE_A(SA(1, 0), 0, 1); STAGE_B(SB(1, 1), 1, 1);
;     WAIT_V(6); BAR;
.LBB0_2561:
	s_or_b64 exec, exec, s[12:13]
	v_bfe_i32 v2, v138, 27, 1
	v_lshlrev_b32_e32 v144, 4, v138
	v_lshrrev_b32_e32 v2, 22, v2
	v_add_u32_e32 v2, v144, v2
	v_and_b32_e32 v2, 0xfffffc00, v2
	v_sub_u32_e32 v2, v144, v2
	v_lshrrev_b32_e32 v3, 4, v2
	v_bitop3_b32 v2, v3, v2, 32 bitop3:0x6c
	v_ashrrev_i32_e32 v5, 31, v2
	v_ashrrev_i32_e32 v1, 31, v138
	v_lshrrev_b32_e32 v5, 26, v5
	v_lshrrev_b32_e32 v1, 26, v1
	v_add_u32_e32 v5, v2, v5
	v_add_u32_e32 v1, v138, v1
	v_ashrrev_i32_e32 v6, 6, v5
	v_and_b32_e32 v5, 0xc0, v5
	v_ashrrev_i32_e32 v4, 6, v1
	v_sub_u32_e32 v2, v2, v5
	v_lshlrev_b32_e32 v3, 3, v4
	v_lshlrev_b32_e32 v7, 5, v4
	v_ashrrev_i16_sdwa v2, v232, sext(v2) dst_sel:DWORD dst_unused:UNUSED_PAD src0_sel:DWORD src1_sel:BYTE_0
	v_and_b32_e32 v3, 0xffff0, v3
	v_and_b32_e32 v7, 32, v7
	v_bfe_i32 v5, v2, 0, 16
	v_add_u32_e32 v2, v7, v5
	v_add_lshl_u32 v3, v6, v3, 12
	v_add_u32_e32 v146, 0x2000, v144
	v_lshl_add_u32 v178, v2, 1, v3
	v_ashrrev_i32_e32 v2, 31, v146
	v_lshrrev_b32_e32 v2, 22, v2
	v_add_u32_e32 v2, v146, v2
	v_ashrrev_i32_e32 v7, 10, v2
	v_mul_i32_i24_e32 v2, 0x400, v7
	v_sub_u32_e32 v2, v146, v2
	v_lshrrev_b32_e32 v3, 4, v2
	v_bitop3_b32 v2, v3, v2, 32 bitop3:0x6c
	v_ashrrev_i32_e32 v8, 31, v2
	v_lshrrev_b32_e32 v8, 26, v8
	v_add_u32_e32 v8, v2, v8
	v_ashrrev_i32_e32 v9, 6, v8
	v_and_b32_e32 v8, 0xc0, v8
	v_sub_u32_e32 v2, v2, v8
	v_lshlrev_b32_e32 v3, 3, v7
	v_lshlrev_b32_e32 v10, 5, v7
	v_ashrrev_i16_sdwa v2, v232, sext(v2) dst_sel:DWORD dst_unused:UNUSED_PAD src0_sel:DWORD src1_sel:BYTE_0
	v_and_b32_e32 v3, 0xffff0, v3
	v_and_b32_e32 v10, 32, v10
	v_bfe_i32 v8, v2, 0, 16
	v_add_u32_e32 v2, v10, v8
	v_add_lshl_u32 v3, v9, v3, 12
	v_add_u32_e32 v147, 0x18000, v144
	v_lshl_add_u32 v128, v2, 1, v3
	v_lshl_add_u64 v[2:3], s[8:9], 0, v[178:179]
	v_readfirstlane_b32 s2, v147
	v_lshl_add_u64 v[2:3], v[2:3], 0, s[60:61]
	s_mov_b32 m0, s2
	v_mov_b32_e32 v129, v179
	v_add_u32_e32 v148, 0x1a000, v144
	s_waitcnt vmcnt(4)
	s_barrier
	global_load_lds_dwordx4 v[2:3], off
	v_lshl_add_u64 v[2:3], s[8:9], 0, v[128:129]
	v_readfirstlane_b32 s2, v148
	v_lshl_add_u64 v[2:3], v[2:3], 0, s[60:61]
	s_mov_b32 m0, s2
	v_add_u32_e32 v149, 0x8000, v144
	global_load_lds_dwordx4 v[2:3], off
	v_lshl_add_u64 v[2:3], s[10:11], 0, v[178:179]
	v_readfirstlane_b32 s2, v149
	v_lshl_add_u64 v[2:3], v[2:3], 0, s[60:61]
	s_mov_b32 m0, s2
	v_add_u32_e32 v150, 0xa000, v144
	global_load_lds_dwordx4 v[2:3], off
	v_lshl_add_u64 v[2:3], s[10:11], 0, v[128:129]
	v_readfirstlane_b32 s2, v150
	v_add_u32_e32 v151, 0x1c000, v144
	v_lshl_add_u64 v[2:3], v[2:3], 0, s[60:61]
	s_mov_b32 m0, s2
	s_add_u32 s2, s8, 0x80080
	v_readfirstlane_b32 s12, v151
	v_add_u32_e32 v152, 0x1e000, v144
	global_load_lds_dwordx4 v[2:3], off
	s_addc_u32 s3, s9, 0
	s_mov_b32 m0, s12
	v_readfirstlane_b32 s12, v152
	global_load_lds_dwordx4 v178, s[2:3]
	s_mov_b32 m0, s12
	v_and_b32_e32 v10, 15, v138
	global_load_lds_dwordx4 v128, s[2:3]
	v_lshlrev_b32_e32 v2, 6, v10
	v_lshlrev_b32_e32 v10, 2, v138
	v_and_b32_e32 v11, 48, v138
	v_and_b32_e32 v10, 32, v10
	v_or_b32_e32 v3, v2, v11
	v_bitop3_b32 v12, v2, v10, v11 bitop3:0x36
	s_mov_b32 s2, 0x14000
	v_lshlrev_b32_e32 v2, 6, v138
	v_bitop3_b32 v14, v3, s2, v10 bitop3:0xde
	s_mov_b32 s2, 0x18000
	v_lshlrev_b32_e32 v18, 13, v0
	v_and_b32_e32 v0, 0x3c0, v2
	v_bitop3_b32 v13, v3, s94, v10 bitop3:0xde
	v_bitop3_b32 v15, v3, s2, v10 bitop3:0xde
	v_bitop3_b32 v16, v3, s97, v10 bitop3:0xde
	v_bitop3_b32 v10, v0, v10, v11 bitop3:0x36
	v_lshlrev_b32_e32 v0, 15, v4
	v_and_b32_e32 v17, 0x3000, v2
	v_and_b32_e32 v0, 0xffff0000, v0
	v_lshlrev_b32_e32 v2, 15, v7
	v_lshl_add_u32 v0, v6, 12, v0
	v_and_b32_e32 v2, 0xffff0000, v2
	v_and_or_b32 v0, v1, 64, v0
	v_lshl_add_u32 v2, v9, 12, v2
	v_lshlrev_b32_e32 v3, 6, v7
	s_waitcnt vmcnt(6)
	v_lshl_add_u32 v0, v5, 1, v0
	v_mov_b32_e32 v1, v179
	v_and_or_b32 v2, v3, 64, v2
	v_or_b32_e32 v11, 0x800, v18
	v_or_b32_e32 v19, 0x1000, v18
	v_or_b32_e32 v20, 0x1800, v18
	v_lshl_add_u64 v[130:131], s[8:9], 0, v[0:1]
	v_lshl_add_u32 v2, v8, 1, v2
	v_mov_b32_e32 v3, v179
	v_lshl_add_u64 v[134:135], s[10:11], 0, v[0:1]
	v_mov_b32_e32 v0, 0
	v_lshl_add_u64 v[132:133], s[8:9], 0, v[2:3]
	v_lshl_add_u64 v[136:137], s[10:11], 0, v[2:3]
	s_mov_b32 s2, -2
	s_mov_b64 s[12:13], 0
	v_add_u32_e32 v154, v13, v17
	v_add_u32_e32 v142, v12, v18
	v_add_u32_e32 v141, v10, v11
	v_add_u32_e32 v140, v10, v19
	v_add_u32_e32 v139, v10, v20
	v_add_u32_e32 v153, v14, v17
	v_add_u32_e32 v145, v15, v17
	v_add_u32_e32 v143, v16, v17
	v_mov_b32_e32 v1, v0
	v_mov_b32_e32 v2, v0
	v_mov_b32_e32 v3, v0
	v_mov_b32_e32 v4, v0
	v_mov_b32_e32 v5, v0
	v_mov_b32_e32 v6, v0
	v_mov_b32_e32 v7, v0
	v_mov_b32_e32 v8, v0
	v_mov_b32_e32 v9, v0
	v_mov_b32_e32 v10, v0
	v_mov_b32_e32 v11, v0
	v_mov_b32_e32 v12, v0
	v_mov_b32_e32 v13, v0
	v_mov_b32_e32 v14, v0
	v_mov_b32_e32 v15, v0
	v_mov_b32_e32 v16, v0
	v_mov_b32_e32 v17, v0
	v_mov_b32_e32 v18, v0
	v_mov_b32_e32 v19, v0
	v_mov_b32_e32 v20, v0
	v_mov_b32_e32 v21, v0
	v_mov_b32_e32 v22, v0
	v_mov_b32_e32 v23, v0
	v_mov_b32_e32 v24, v0
	v_mov_b32_e32 v25, v0
	v_mov_b32_e32 v26, v0
	v_mov_b32_e32 v27, v0
	v_mov_b32_e32 v28, v0
	v_mov_b32_e32 v29, v0
	v_mov_b32_e32 v30, v0
	v_mov_b32_e32 v31, v0
	v_mov_b32_e32 v32, v0
	v_mov_b32_e32 v33, v0
	v_mov_b32_e32 v34, v0
	v_mov_b32_e32 v35, v0
	v_mov_b32_e32 v36, v0
	v_mov_b32_e32 v37, v0
	v_mov_b32_e32 v38, v0
	v_mov_b32_e32 v39, v0
	v_mov_b32_e32 v40, v0
	v_mov_b32_e32 v41, v0
	v_mov_b32_e32 v42, v0
	v_mov_b32_e32 v43, v0
	v_mov_b32_e32 v44, v0
	v_mov_b32_e32 v45, v0
	v_mov_b32_e32 v46, v0
	v_mov_b32_e32 v47, v0
	v_mov_b32_e32 v48, v0
	v_mov_b32_e32 v49, v0
	v_mov_b32_e32 v50, v0
; #define STAGE_A(P, half, kt) do { const char* _u = Ab + ((size_t)(half) * 128 * lda + (size_t)(kt) * BK) * 2; \
;     _Pragma("unroll") for (int _i = 0; _i < 2; ++_i) \
;       __builtin_amdgcn_global_load_lds((const unsigned*)(_u + offA[_i]), \
;         (__attribute__((address_space(3))) unsigned*)((__attribute__((address_space(3))) char*)(P) + tidg * 16 + _i * 8192), 16, 0, 0); } while (0)
; #define STAGE_B(P, half, kt) do { const char* _u = Bb + ((size_t)(half) * 128 * ldb + (size_t)(kt) * BK) * 2; \
;     _Pragma("unroll") for (int _i = 0; _i < 2; ++_i) \
;       __builtin_amdgcn_global_load_lds((const unsigned*)(_u + offB[_i]), \
;         (__attribute__((address_space(3))) unsigned*)((__attribute__((address_space(3))) char*)(P) + tidg * 16 + _i * 8192), 16, 0, 0); } while (0)
; #define LDA(dst, b, h) _Pragma("unroll") for (int m = 0; m < 4; ++m) _Pragma("unroll") for (int k = 0; k < 2; ++k) \
;     dst[m][k] = *reinterpret_cast<const bf16x8*>((const char*)SA(b, h) + lds_byte(wr * 64 + m * 16 + fr, k * 32 + fq * 8))
; #define LDB(dst, b, h) _Pragma("unroll") for (int n = 0; n < 2; ++n) _Pragma("unroll") for (int k = 0; k < 2; ++k) \
;     dst[n][k] = *reinterpret_cast<const bf16x8*>((const char*)SB(b, h) + lds_byte(wc * 32 + n * 16 + fr, k * 32 + fq * 8))
; #define WAIT_V(n) asm volatile("s_waitcnt vmcnt(" #n ")" ::: "memory")
; #define WAIT_L(n) asm volatile("s_waitcnt lgkmcnt(" #n ")" ::: "memory")
; template <bool PF = true, class Epi, class KRF = KRFull>
; __device__ __forceinline__ void gemm_phase(const u16* __restrict__ A, int lda, const u16* __restrict__ Bt, int ldb, int K, int nM, int nN,
;                                            lds_u16* shm, Epi epi, KRF krf = KRFull(), bool flip = false) {
;     ...
;     f32x4 acc[2][2][4][2] = {};
;     bf16x8 At[4][2], B0[2][2], B1[2][2];
;     if (wr == 1) BAR;
;     WAIT_V(4); BAR;
;     STAGE_B(SB(1, 0), 0, 1); STAGE_A(SA(1, 0), 0, 1); STAGE_B(SB(1, 1), 1, 1);
;     WAIT_V(6); BAR;
;     for (int t = 0; t < nt - 2; t += 2) {
;       LDB(B0, 0, 0); SCHED; LDA(At, 0, 0); STAGE_A(SA(1, 1), 1, t + 1);
;       WAIT_L(8); BAR; WAIT_L(0); MMA(0, 0, At, B0); BAR; SCHED;
;       LDB(B1, 0, 1); STAGE_B(SB(0, 0), 0, t + 2);
;       BAR; WAIT_L(0); MMA(0, 1, At, B1); BAR;
;       LDA(At, 0, 1); STAGE_A(SA(0, 0), 0, t + 2);
;       BAR; WAIT_L(0); MMA(1, 0, At, B0); BAR; SCHED;
;       STAGE_B(SB(0, 1), 1, t + 2);
	v_mov_b32_e32 v51, v0
	v_mov_b32_e32 v52, v0
	v_mov_b32_e32 v53, v0
	v_mov_b32_e32 v54, v0
	v_mov_b32_e32 v55, v0
	v_mov_b32_e32 v56, v0
	v_mov_b32_e32 v57, v0
	v_mov_b32_e32 v58, v0
	v_mov_b32_e32 v59, v0
	v_mov_b32_e32 v60, v0
	v_mov_b32_e32 v61, v0
	v_mov_b32_e32 v62, v0
	v_mov_b32_e32 v63, v0
	v_mov_b32_e32 v64, v0
	v_mov_b32_e32 v65, v0
	v_mov_b32_e32 v66, v0
	v_mov_b32_e32 v67, v0
	v_mov_b32_e32 v68, v0
	v_mov_b32_e32 v69, v0
	v_mov_b32_e32 v70, v0
	v_mov_b32_e32 v71, v0
	v_mov_b32_e32 v72, v0
	v_mov_b32_e32 v73, v0
	v_mov_b32_e32 v74, v0
	v_mov_b32_e32 v75, v0
	v_mov_b32_e32 v76, v0
	v_mov_b32_e32 v77, v0
	v_mov_b32_e32 v78, v0
	v_mov_b32_e32 v79, v0
	v_mov_b32_e32 v80, v0
	v_mov_b32_e32 v81, v0
	v_mov_b32_e32 v82, v0
	v_mov_b32_e32 v83, v0
	v_mov_b32_e32 v84, v0
	v_mov_b32_e32 v85, v0
	v_mov_b32_e32 v86, v0
	v_mov_b32_e32 v87, v0
	v_mov_b32_e32 v88, v0
	v_mov_b32_e32 v89, v0
	v_mov_b32_e32 v90, v0
	v_mov_b32_e32 v91, v0
	v_mov_b32_e32 v92, v0
	v_mov_b32_e32 v93, v0
	v_mov_b32_e32 v94, v0
	v_mov_b32_e32 v95, v0
	v_mov_b32_e32 v96, v0
	v_mov_b32_e32 v97, v0
	v_mov_b32_e32 v98, v0
	v_mov_b32_e32 v99, v0
	v_mov_b32_e32 v100, v0
	v_mov_b32_e32 v101, v0
	v_mov_b32_e32 v102, v0
	v_mov_b32_e32 v103, v0
	v_mov_b32_e32 v104, v0
	v_mov_b32_e32 v105, v0
	v_mov_b32_e32 v106, v0
	v_mov_b32_e32 v107, v0
	v_mov_b32_e32 v108, v0
	v_mov_b32_e32 v109, v0
	v_mov_b32_e32 v110, v0
	v_mov_b32_e32 v111, v0
	v_mov_b32_e32 v112, v0
	v_mov_b32_e32 v113, v0
	v_mov_b32_e32 v114, v0
	v_mov_b32_e32 v115, v0
	v_mov_b32_e32 v116, v0
	v_mov_b32_e32 v117, v0
	v_mov_b32_e32 v118, v0
	v_mov_b32_e32 v119, v0
	v_mov_b32_e32 v120, v0
	v_mov_b32_e32 v121, v0
	v_mov_b32_e32 v122, v0
	v_mov_b32_e32 v123, v0
	v_mov_b32_e32 v124, v0
	v_mov_b32_e32 v125, v0
	v_mov_b32_e32 v126, v0
	v_mov_b32_e32 v127, v0
	s_barrier
	v_readfirstlane_b32 s3, v144
.LBB0_2562:
	ds_read_b128 v[158:161], v154
	ds_read_b128 v[162:165], v154 offset:1024
	ds_read_b128 v[166:169], v154 offset:2048
	ds_read_b128 v[170:173], v154 offset:3072
	v_lshl_add_u64 v[174:175], v[134:135], 0, s[12:13]
	v_lshl_add_u64 v[156:157], v[174:175], 0, s[62:63]
	s_add_u32 m0, s3, 0xc000
	ds_read_b128 v[180:183], v142
	ds_read_b128 v[184:187], v142 offset:1024
	ds_read_b128 v[188:191], v141
	ds_read_b128 v[192:195], v141 offset:1024
	ds_read_b128 v[196:199], v140
	ds_read_b128 v[200:203], v140 offset:1024
	ds_read_b128 v[204:207], v139
	ds_read_b128 v[208:211], v139 offset:1024
	global_load_lds_dwordx4 v[156:157], off
	v_lshl_add_u64 v[234:235], v[136:137], 0, s[12:13]
	v_lshl_add_u64 v[212:213], v[234:235], 0, s[62:63]
	s_add_u32 m0, s3, 0xe000
	s_nop 0
	global_load_lds_dwordx4 v[212:213], off
	s_waitcnt lgkmcnt(8)
	s_barrier
	s_waitcnt lgkmcnt(0)
	s_setprio 1
	s_waitcnt lgkmcnt(0)
	v_mfma_f32_16x16x32_bf16 v[124:127], v[158:161], v[180:183], v[124:127]
	v_mfma_f32_16x16x32_bf16 v[120:123], v[166:169], v[180:183], v[120:123]
	v_mfma_f32_16x16x32_bf16 v[116:119], v[158:161], v[188:191], v[116:119]
	v_mfma_f32_16x16x32_bf16 v[112:115], v[166:169], v[188:191], v[112:115]
	v_mfma_f32_16x16x32_bf16 v[108:111], v[158:161], v[196:199], v[108:111]
	v_mfma_f32_16x16x32_bf16 v[104:107], v[166:169], v[196:199], v[104:107]
	v_mfma_f32_16x16x32_bf16 v[100:103], v[158:161], v[204:207], v[100:103]
	v_mfma_f32_16x16x32_bf16 v[96:99], v[166:169], v[204:207], v[96:99]
	v_mfma_f32_16x16x32_bf16 v[124:127], v[162:165], v[184:187], v[124:127]
	v_mfma_f32_16x16x32_bf16 v[120:123], v[170:173], v[184:187], v[120:123]
	v_mfma_f32_16x16x32_bf16 v[116:119], v[162:165], v[192:195], v[116:119]
	v_mfma_f32_16x16x32_bf16 v[112:115], v[170:173], v[192:195], v[112:115]
	v_mfma_f32_16x16x32_bf16 v[108:111], v[162:165], v[200:203], v[108:111]
	v_mfma_f32_16x16x32_bf16 v[104:107], v[170:173], v[200:203], v[104:107]
	v_mfma_f32_16x16x32_bf16 v[100:103], v[162:165], v[208:211], v[100:103]
	v_mfma_f32_16x16x32_bf16 v[96:99], v[170:173], v[208:211], v[96:99]
	s_setprio 0
	s_barrier
	v_lshl_add_u64 v[236:237], v[130:131], 0, s[12:13]
	v_lshl_add_u64 v[238:239], v[236:237], 0, s[64:65]
	s_add_u32 m0, s3, 0x10000
	ds_read_b128 v[212:215], v153
	ds_read_b128 v[216:219], v153 offset:1024
	ds_read_b128 v[222:225], v153 offset:2048
	ds_read_b128 v[226:229], v153 offset:3072
	global_load_lds_dwordx4 v[238:239], off
	v_lshl_add_u64 v[238:239], v[132:133], 0, s[12:13]
	v_lshl_add_u64 v[240:241], v[238:239], 0, s[64:65]
	s_add_u32 m0, s3, 0x12000
	s_nop 0
	global_load_lds_dwordx4 v[240:241], off
	s_barrier
	s_waitcnt lgkmcnt(0)
	s_setprio 1
	s_waitcnt lgkmcnt(0)
	v_mfma_f32_16x16x32_bf16 v[92:95], v[212:215], v[180:183], v[92:95]
	v_mfma_f32_16x16x32_bf16 v[88:91], v[222:225], v[180:183], v[88:91]
	v_mfma_f32_16x16x32_bf16 v[84:87], v[212:215], v[188:191], v[84:87]
	v_mfma_f32_16x16x32_bf16 v[80:83], v[222:225], v[188:191], v[80:83]
	v_mfma_f32_16x16x32_bf16 v[76:79], v[212:215], v[196:199], v[76:79]
	v_mfma_f32_16x16x32_bf16 v[72:75], v[222:225], v[196:199], v[72:75]
	v_mfma_f32_16x16x32_bf16 v[68:71], v[212:215], v[204:207], v[68:71]
	v_mfma_f32_16x16x32_bf16 v[64:67], v[222:225], v[204:207], v[64:67]
	v_mfma_f32_16x16x32_bf16 v[92:95], v[216:219], v[184:187], v[92:95]
	v_mfma_f32_16x16x32_bf16 v[88:91], v[226:229], v[184:187], v[88:91]
	v_mfma_f32_16x16x32_bf16 v[84:87], v[216:219], v[192:195], v[84:87]
	v_mfma_f32_16x16x32_bf16 v[80:83], v[226:229], v[192:195], v[80:83]
	v_mfma_f32_16x16x32_bf16 v[76:79], v[216:219], v[200:203], v[76:79]
	v_mfma_f32_16x16x32_bf16 v[72:75], v[226:229], v[200:203], v[72:75]
	v_mfma_f32_16x16x32_bf16 v[68:71], v[216:219], v[208:211], v[68:71]
	v_mfma_f32_16x16x32_bf16 v[64:67], v[226:229], v[208:211], v[64:67]
	s_setprio 0
	v_lshl_add_u64 v[240:241], v[174:175], 0, s[64:65]
	s_mov_b32 m0, s3
	s_barrier
; #define STAGE_A(P, half, kt) do { const char* _u = Ab + ((size_t)(half) * 128 * lda + (size_t)(kt) * BK) * 2; \
;     _Pragma("unroll") for (int _i = 0; _i < 2; ++_i) \
;       __builtin_amdgcn_global_load_lds((const unsigned*)(_u + offA[_i]), \
;         (__attribute__((address_space(3))) unsigned*)((__attribute__((address_space(3))) char*)(P) + tidg * 16 + _i * 8192), 16, 0, 0); } while (0)
; #define STAGE_B(P, half, kt) do { const char* _u = Bb + ((size_t)(half) * 128 * ldb + (size_t)(kt) * BK) * 2; \
;     _Pragma("unroll") for (int _i = 0; _i < 2; ++_i) \
;       __builtin_amdgcn_global_load_lds((const unsigned*)(_u + offB[_i]), \
;         (__attribute__((address_space(3))) unsigned*)((__attribute__((address_space(3))) char*)(P) + tidg * 16 + _i * 8192), 16, 0, 0); } while (0)
; #define LDA(dst, b, h) _Pragma("unroll") for (int m = 0; m < 4; ++m) _Pragma("unroll") for (int k = 0; k < 2; ++k) \
;     dst[m][k] = *reinterpret_cast<const bf16x8*>((const char*)SA(b, h) + lds_byte(wr * 64 + m * 16 + fr, k * 32 + fq * 8))
; #define LDB(dst, b, h) _Pragma("unroll") for (int n = 0; n < 2; ++n) _Pragma("unroll") for (int k = 0; k < 2; ++k) \
;     dst[n][k] = *reinterpret_cast<const bf16x8*>((const char*)SB(b, h) + lds_byte(wc * 32 + n * 16 + fr, k * 32 + fq * 8))
; #define MMA(ai, bj, At_, Bt_) do { __builtin_amdgcn_s_setprio(1); \
;     _Pragma("unroll") for (int m = 0; m < 4; ++m) _Pragma("unroll") for (int n = 0; n < 2; ++n) _Pragma("unroll") for (int k = 0; k < 2; ++k) \
;       acc[ai][bj][m][n] = __builtin_amdgcn_mfma_f32_16x16x32_bf16(Bt_[n][k], At_[m][k], acc[ai][bj][m][n], 0, 0, 0); \
;     __builtin_amdgcn_s_setprio(0); } while (0)
; template <bool PF = true, class Epi, class KRF = KRFull>
; __device__ __forceinline__ void gemm_phase(const u16* __restrict__ A, int lda, const u16* __restrict__ Bt, int ldb, int K, int nM, int nN,
;                                            lds_u16* shm, Epi epi, KRF krf = KRFull(), bool flip = false) {
;     ...
;       LDA(At, 0, 1); STAGE_A(SA(0, 0), 0, t + 2);
;       BAR; WAIT_L(0); MMA(1, 0, At, B0); BAR; SCHED;
;       STAGE_B(SB(0, 1), 1, t + 2);
;       WAIT_V(6); BAR; MMA(1, 1, At, B1); BAR;
;       LDB(B0, 1, 0); SCHED; LDA(At, 1, 0); STAGE_A(SA(0, 1), 1, t + 2);
;       WAIT_L(8); BAR; WAIT_L(0); MMA(0, 0, At, B0); BAR; SCHED;
;       LDB(B1, 1, 1); STAGE_B(SB(1, 0), 0, t + 3);
	ds_read_b128 v[180:183], v142 offset:16384
	ds_read_b128 v[184:187], v142 offset:17408
	ds_read_b128 v[188:191], v141 offset:16384
	ds_read_b128 v[192:195], v141 offset:17408
	ds_read_b128 v[196:199], v140 offset:16384
	ds_read_b128 v[200:203], v140 offset:17408
	ds_read_b128 v[204:207], v139 offset:16384
	ds_read_b128 v[208:211], v139 offset:17408
	global_load_lds_dwordx4 v[240:241], off
	v_lshl_add_u64 v[240:241], v[234:235], 0, s[64:65]
	s_add_u32 m0, s3, 0x2000
	s_nop 0
	global_load_lds_dwordx4 v[240:241], off
	s_barrier
	s_waitcnt lgkmcnt(0)
	s_setprio 1
	s_waitcnt lgkmcnt(0)
	v_mfma_f32_16x16x32_bf16 v[60:63], v[158:161], v[180:183], v[60:63]
	v_mfma_f32_16x16x32_bf16 v[56:59], v[166:169], v[180:183], v[56:59]
	v_mfma_f32_16x16x32_bf16 v[52:55], v[158:161], v[188:191], v[52:55]
	v_mfma_f32_16x16x32_bf16 v[48:51], v[166:169], v[188:191], v[48:51]
	v_mfma_f32_16x16x32_bf16 v[44:47], v[158:161], v[196:199], v[44:47]
	v_mfma_f32_16x16x32_bf16 v[40:43], v[166:169], v[196:199], v[40:43]
	v_mfma_f32_16x16x32_bf16 v[36:39], v[158:161], v[204:207], v[36:39]
	v_mfma_f32_16x16x32_bf16 v[32:35], v[166:169], v[204:207], v[32:35]
	v_mfma_f32_16x16x32_bf16 v[60:63], v[162:165], v[184:187], v[60:63]
	v_mfma_f32_16x16x32_bf16 v[56:59], v[170:173], v[184:187], v[56:59]
	v_mfma_f32_16x16x32_bf16 v[52:55], v[162:165], v[192:195], v[52:55]
	v_mfma_f32_16x16x32_bf16 v[48:51], v[170:173], v[192:195], v[48:51]
	v_mfma_f32_16x16x32_bf16 v[44:47], v[162:165], v[200:203], v[44:47]
	v_mfma_f32_16x16x32_bf16 v[40:43], v[170:173], v[200:203], v[40:43]
	v_mfma_f32_16x16x32_bf16 v[36:39], v[162:165], v[208:211], v[36:39]
	v_mfma_f32_16x16x32_bf16 v[32:35], v[170:173], v[208:211], v[32:35]
	s_setprio 0
	s_barrier
	v_lshl_add_u64 v[158:159], v[236:237], 0, s[66:67]
	s_add_u32 m0, s3, 0x14000
	s_nop 0
	global_load_lds_dwordx4 v[158:159], off
	v_lshl_add_u64 v[158:159], v[238:239], 0, s[66:67]
	s_add_u32 m0, s3, 0x16000
	s_nop 0
	global_load_lds_dwordx4 v[158:159], off
	s_waitcnt vmcnt(6)
	s_barrier
	s_setprio 1
	v_mfma_f32_16x16x32_bf16 v[28:31], v[212:215], v[180:183], v[28:31]
	v_mfma_f32_16x16x32_bf16 v[24:27], v[222:225], v[180:183], v[24:27]
	v_mfma_f32_16x16x32_bf16 v[20:23], v[212:215], v[188:191], v[20:23]
	v_mfma_f32_16x16x32_bf16 v[16:19], v[222:225], v[188:191], v[16:19]
	v_mfma_f32_16x16x32_bf16 v[12:15], v[212:215], v[196:199], v[12:15]
	v_mfma_f32_16x16x32_bf16 v[8:11], v[222:225], v[196:199], v[8:11]
	v_mfma_f32_16x16x32_bf16 v[4:7], v[212:215], v[204:207], v[4:7]
	v_mfma_f32_16x16x32_bf16 v[0:3], v[222:225], v[204:207], v[0:3]
	v_mfma_f32_16x16x32_bf16 v[28:31], v[216:219], v[184:187], v[28:31]
	v_mfma_f32_16x16x32_bf16 v[24:27], v[226:229], v[184:187], v[24:27]
	v_mfma_f32_16x16x32_bf16 v[20:23], v[216:219], v[192:195], v[20:23]
	v_mfma_f32_16x16x32_bf16 v[16:19], v[226:229], v[192:195], v[16:19]
	v_mfma_f32_16x16x32_bf16 v[12:15], v[216:219], v[200:203], v[12:15]
	v_mfma_f32_16x16x32_bf16 v[8:11], v[226:229], v[200:203], v[8:11]
	v_mfma_f32_16x16x32_bf16 v[4:7], v[216:219], v[208:211], v[4:7]
	v_mfma_f32_16x16x32_bf16 v[0:3], v[226:229], v[208:211], v[0:3]
	s_setprio 0
	s_barrier
	ds_read_b128 v[158:161], v145
	ds_read_b128 v[162:165], v145 offset:1024
	ds_read_b128 v[166:169], v145 offset:2048
	ds_read_b128 v[170:173], v145 offset:3072
	v_lshl_add_u64 v[212:213], v[174:175], 0, s[66:67]
	s_add_u32 m0, s3, 0x4000
	ds_read_b128 v[180:183], v142 offset:32768
	ds_read_b128 v[184:187], v142 offset:33792
	ds_read_b128 v[188:191], v141 offset:32768
	ds_read_b128 v[192:195], v141 offset:33792
	ds_read_b128 v[196:199], v140 offset:32768
	ds_read_b128 v[200:203], v140 offset:33792
	ds_read_b128 v[204:207], v139 offset:32768
	ds_read_b128 v[208:211], v139 offset:33792
	global_load_lds_dwordx4 v[212:213], off
	v_lshl_add_u64 v[212:213], v[234:235], 0, s[66:67]
	s_add_u32 m0, s3, 0x6000
	s_nop 0
	global_load_lds_dwordx4 v[212:213], off
	s_waitcnt lgkmcnt(8)
	s_barrier
	s_waitcnt lgkmcnt(0)
	s_setprio 1
	s_waitcnt lgkmcnt(0)
	v_mfma_f32_16x16x32_bf16 v[124:127], v[158:161], v[180:183], v[124:127]
	v_mfma_f32_16x16x32_bf16 v[120:123], v[166:169], v[180:183], v[120:123]
	v_mfma_f32_16x16x32_bf16 v[116:119], v[158:161], v[188:191], v[116:119]
	v_mfma_f32_16x16x32_bf16 v[112:115], v[166:169], v[188:191], v[112:115]
	v_mfma_f32_16x16x32_bf16 v[108:111], v[158:161], v[196:199], v[108:111]
	v_mfma_f32_16x16x32_bf16 v[104:107], v[166:169], v[196:199], v[104:107]
	v_mfma_f32_16x16x32_bf16 v[100:103], v[158:161], v[204:207], v[100:103]
	v_mfma_f32_16x16x32_bf16 v[96:99], v[166:169], v[204:207], v[96:99]
	v_mfma_f32_16x16x32_bf16 v[124:127], v[162:165], v[184:187], v[124:127]
	v_mfma_f32_16x16x32_bf16 v[120:123], v[170:173], v[184:187], v[120:123]
	v_mfma_f32_16x16x32_bf16 v[116:119], v[162:165], v[192:195], v[116:119]
	v_mfma_f32_16x16x32_bf16 v[112:115], v[170:173], v[192:195], v[112:115]
	v_mfma_f32_16x16x32_bf16 v[108:111], v[162:165], v[200:203], v[108:111]
	v_mfma_f32_16x16x32_bf16 v[104:107], v[170:173], v[200:203], v[104:107]
	v_mfma_f32_16x16x32_bf16 v[100:103], v[162:165], v[208:211], v[100:103]
	v_mfma_f32_16x16x32_bf16 v[96:99], v[170:173], v[208:211], v[96:99]
	s_setprio 0
	s_barrier
	v_lshl_add_u64 v[240:241], v[236:237], 0, s[68:69]
	s_add_u32 m0, s3, 0x18000
	ds_read_b128 v[212:215], v143
	ds_read_b128 v[216:219], v143 offset:1024
	ds_read_b128 v[222:225], v143 offset:2048
	ds_read_b128 v[226:229], v143 offset:3072
	global_load_lds_dwordx4 v[240:241], off
	v_lshl_add_u64 v[240:241], v[238:239], 0, s[68:69]
	s_add_u32 m0, s3, 0x1a000
	s_nop 0
	global_load_lds_dwordx4 v[240:241], off
	s_barrier
; #define STAGE_A(P, half, kt) do { const char* _u = Ab + ((size_t)(half) * 128 * lda + (size_t)(kt) * BK) * 2; \
;     _Pragma("unroll") for (int _i = 0; _i < 2; ++_i) \
;       __builtin_amdgcn_global_load_lds((const unsigned*)(_u + offA[_i]), \
;         (__attribute__((address_space(3))) unsigned*)((__attribute__((address_space(3))) char*)(P) + tidg * 16 + _i * 8192), 16, 0, 0); } while (0)
; #define STAGE_B(P, half, kt) do { const char* _u = Bb + ((size_t)(half) * 128 * ldb + (size_t)(kt) * BK) * 2; \
;     _Pragma("unroll") for (int _i = 0; _i < 2; ++_i) \
;       __builtin_amdgcn_global_load_lds((const unsigned*)(_u + offB[_i]), \
;         (__attribute__((address_space(3))) unsigned*)((__attribute__((address_space(3))) char*)(P) + tidg * 16 + _i * 8192), 16, 0, 0); } while (0)
; #define LDA(dst, b, h) _Pragma("unroll") for (int m = 0; m < 4; ++m) _Pragma("unroll") for (int k = 0; k < 2; ++k) \
;     dst[m][k] = *reinterpret_cast<const bf16x8*>((const char*)SA(b, h) + lds_byte(wr * 64 + m * 16 + fr, k * 32 + fq * 8))
; #define LDB(dst, b, h) _Pragma("unroll") for (int n = 0; n < 2; ++n) _Pragma("unroll") for (int k = 0; k < 2; ++k) \
;     dst[n][k] = *reinterpret_cast<const bf16x8*>((const char*)SB(b, h) + lds_byte(wc * 32 + n * 16 + fr, k * 32 + fq * 8))
; #define MMA(ai, bj, At_, Bt_) do { __builtin_amdgcn_s_setprio(1); \
;     _Pragma("unroll") for (int m = 0; m < 4; ++m) _Pragma("unroll") for (int n = 0; n < 2; ++n) _Pragma("unroll") for (int k = 0; k < 2; ++k) \
;       acc[ai][bj][m][n] = __builtin_amdgcn_mfma_f32_16x16x32_bf16(Bt_[n][k], At_[m][k], acc[ai][bj][m][n], 0, 0, 0); \
;     __builtin_amdgcn_s_setprio(0); } while (0)
; #define BAR __builtin_amdgcn_s_barrier()
; template <bool PF = true, class Epi, class KRF = KRFull>
; __device__ __forceinline__ void gemm_phase(const u16* __restrict__ A, int lda, const u16* __restrict__ Bt, int ldb, int K, int nM, int nN,
;                                            lds_u16* shm, Epi epi, KRF krf = KRFull(), bool flip = false) {
;     ...
;       LDB(B1, 1, 1); STAGE_B(SB(1, 0), 0, t + 3);
;       BAR; WAIT_L(0); MMA(0, 1, At, B1); BAR;
;       LDA(At, 1, 1); STAGE_A(SA(1, 0), 0, t + 3);
;       BAR; WAIT_L(0); MMA(1, 0, At, B0); BAR; SCHED;
;       STAGE_B(SB(1, 1), 1, t + 3);
;       WAIT_V(6); BAR; MMA(1, 1, At, B1); BAR;
;     }
;     { LDB(B0, 0, 0); LDA(At, 0, 0); STAGE_A(SA(1, 1), 1, nt - 1);
	s_waitcnt lgkmcnt(0)
	s_setprio 1
	s_waitcnt lgkmcnt(0)
	v_mfma_f32_16x16x32_bf16 v[92:95], v[212:215], v[180:183], v[92:95]
	v_mfma_f32_16x16x32_bf16 v[88:91], v[222:225], v[180:183], v[88:91]
	v_mfma_f32_16x16x32_bf16 v[84:87], v[212:215], v[188:191], v[84:87]
	v_mfma_f32_16x16x32_bf16 v[80:83], v[222:225], v[188:191], v[80:83]
	v_mfma_f32_16x16x32_bf16 v[76:79], v[212:215], v[196:199], v[76:79]
	v_mfma_f32_16x16x32_bf16 v[72:75], v[222:225], v[196:199], v[72:75]
	v_mfma_f32_16x16x32_bf16 v[68:71], v[212:215], v[204:207], v[68:71]
	v_mfma_f32_16x16x32_bf16 v[64:67], v[222:225], v[204:207], v[64:67]
	v_mfma_f32_16x16x32_bf16 v[92:95], v[216:219], v[184:187], v[92:95]
	v_mfma_f32_16x16x32_bf16 v[88:91], v[226:229], v[184:187], v[88:91]
	v_mfma_f32_16x16x32_bf16 v[84:87], v[216:219], v[192:195], v[84:87]
	v_mfma_f32_16x16x32_bf16 v[80:83], v[226:229], v[192:195], v[80:83]
	v_mfma_f32_16x16x32_bf16 v[76:79], v[216:219], v[200:203], v[76:79]
	v_mfma_f32_16x16x32_bf16 v[72:75], v[226:229], v[200:203], v[72:75]
	v_mfma_f32_16x16x32_bf16 v[68:71], v[216:219], v[208:211], v[68:71]
	v_mfma_f32_16x16x32_bf16 v[64:67], v[226:229], v[208:211], v[64:67]
	s_setprio 0
	v_lshl_add_u64 v[174:175], v[174:175], 0, s[68:69]
	s_add_u32 m0, s3, 0x8000
	s_barrier
	ds_read_b128 v[180:183], v142 offset:49152
	ds_read_b128 v[184:187], v142 offset:50176
	ds_read_b128 v[188:191], v141 offset:49152
	ds_read_b128 v[192:195], v141 offset:50176
	ds_read_b128 v[196:199], v140 offset:49152
	ds_read_b128 v[200:203], v140 offset:50176
	ds_read_b128 v[204:207], v139 offset:49152
	ds_read_b128 v[208:211], v139 offset:50176
	global_load_lds_dwordx4 v[174:175], off
	v_lshl_add_u64 v[174:175], v[234:235], 0, s[68:69]
	s_add_u32 m0, s3, 0xa000
	s_nop 0
	global_load_lds_dwordx4 v[174:175], off
	s_barrier
	s_waitcnt lgkmcnt(0)
	s_setprio 1
	s_waitcnt lgkmcnt(0)
	v_mfma_f32_16x16x32_bf16 v[60:63], v[158:161], v[180:183], v[60:63]
	v_mfma_f32_16x16x32_bf16 v[56:59], v[166:169], v[180:183], v[56:59]
	v_mfma_f32_16x16x32_bf16 v[52:55], v[158:161], v[188:191], v[52:55]
	v_mfma_f32_16x16x32_bf16 v[48:51], v[166:169], v[188:191], v[48:51]
	v_mfma_f32_16x16x32_bf16 v[44:47], v[158:161], v[196:199], v[44:47]
	v_mfma_f32_16x16x32_bf16 v[40:43], v[166:169], v[196:199], v[40:43]
	v_mfma_f32_16x16x32_bf16 v[36:39], v[158:161], v[204:207], v[36:39]
	v_mfma_f32_16x16x32_bf16 v[32:35], v[166:169], v[204:207], v[32:35]
	v_mfma_f32_16x16x32_bf16 v[60:63], v[162:165], v[184:187], v[60:63]
	v_mfma_f32_16x16x32_bf16 v[56:59], v[170:173], v[184:187], v[56:59]
	v_mfma_f32_16x16x32_bf16 v[52:55], v[162:165], v[192:195], v[52:55]
	v_mfma_f32_16x16x32_bf16 v[48:51], v[170:173], v[192:195], v[48:51]
	v_mfma_f32_16x16x32_bf16 v[44:47], v[162:165], v[200:203], v[44:47]
	v_mfma_f32_16x16x32_bf16 v[40:43], v[170:173], v[200:203], v[40:43]
	v_mfma_f32_16x16x32_bf16 v[36:39], v[162:165], v[208:211], v[36:39]
	v_mfma_f32_16x16x32_bf16 v[32:35], v[170:173], v[208:211], v[32:35]
	s_setprio 0
	s_barrier
	v_lshl_add_u64 v[158:159], v[236:237], 0, s[70:71]
	s_add_u32 m0, s3, 0x1c000
	s_nop 0
	global_load_lds_dwordx4 v[158:159], off
	v_lshl_add_u64 v[158:159], v[238:239], 0, s[70:71]
	s_add_u32 m0, s3, 0x1e000
	s_nop 0
	global_load_lds_dwordx4 v[158:159], off
	s_waitcnt vmcnt(6)
	s_barrier
	s_setprio 1
	v_mfma_f32_16x16x32_bf16 v[28:31], v[212:215], v[180:183], v[28:31]
	v_mfma_f32_16x16x32_bf16 v[24:27], v[222:225], v[180:183], v[24:27]
	v_mfma_f32_16x16x32_bf16 v[20:23], v[212:215], v[188:191], v[20:23]
	v_mfma_f32_16x16x32_bf16 v[16:19], v[222:225], v[188:191], v[16:19]
	v_mfma_f32_16x16x32_bf16 v[12:15], v[212:215], v[196:199], v[12:15]
	v_mfma_f32_16x16x32_bf16 v[8:11], v[222:225], v[196:199], v[8:11]
	v_mfma_f32_16x16x32_bf16 v[4:7], v[212:215], v[204:207], v[4:7]
	v_mfma_f32_16x16x32_bf16 v[0:3], v[222:225], v[204:207], v[0:3]
	v_mfma_f32_16x16x32_bf16 v[28:31], v[216:219], v[184:187], v[28:31]
	v_mfma_f32_16x16x32_bf16 v[24:27], v[226:229], v[184:187], v[24:27]
	v_mfma_f32_16x16x32_bf16 v[20:23], v[216:219], v[192:195], v[20:23]
	v_mfma_f32_16x16x32_bf16 v[16:19], v[226:229], v[192:195], v[16:19]
	v_mfma_f32_16x16x32_bf16 v[12:15], v[216:219], v[200:203], v[12:15]
	v_mfma_f32_16x16x32_bf16 v[8:11], v[226:229], v[200:203], v[8:11]
	v_mfma_f32_16x16x32_bf16 v[4:7], v[216:219], v[208:211], v[4:7]
	v_mfma_f32_16x16x32_bf16 v[0:3], v[226:229], v[208:211], v[0:3]
	s_setprio 0
	s_add_i32 s2, s2, 2
	s_add_u32 s12, s12, 0x100
	s_addc_u32 s13, s13, 0
	s_cmp_gt_u32 s2, 27
	s_barrier
	s_cbranch_scc0 .LBB0_2562
	v_add_u32_e32 v155, 0xc000, v144
	v_add_u32_e32 v156, 0xe000, v144
	v_add_u32_e32 v157, 0x6000, v144
	s_add_u32 s2, s10, 0x80f80
	s_addc_u32 s3, s11, 0
	v_readfirstlane_b32 s12, v155
	v_lshl_add_u64 v[150:151], s[2:3], 0, v[178:179]
	s_mov_b32 m0, s12
	v_lshl_add_u64 v[128:129], s[2:3], 0, v[128:129]
	v_readfirstlane_b32 s2, v156
	ds_read_b128 v[130:133], v154
	ds_read_b128 v[134:137], v154 offset:1024
	ds_read_b128 v[146:149], v154 offset:2048
	ds_read_b128 v[158:161], v154 offset:3072
	ds_read_b128 v[162:165], v142
	ds_read_b128 v[166:169], v142 offset:1024
	ds_read_b128 v[170:173], v141
	ds_read_b128 v[180:183], v141 offset:1024
	ds_read_b128 v[184:187], v140
	ds_read_b128 v[188:191], v140 offset:1024
	ds_read_b128 v[192:195], v139
	ds_read_b128 v[196:199], v139 offset:1024
	global_load_lds_dwordx4 v[150:151], off
	s_mov_b32 m0, s2
	s_nop 0
	global_load_lds_dwordx4 v[128:129], off
	s_barrier
; #define STAGE_A(P, half, kt) do { const char* _u = Ab + ((size_t)(half) * 128 * lda + (size_t)(kt) * BK) * 2; \
;     _Pragma("unroll") for (int _i = 0; _i < 2; ++_i) \
;       __builtin_amdgcn_global_load_lds((const unsigned*)(_u + offA[_i]), \
;         (__attribute__((address_space(3))) unsigned*)((__attribute__((address_space(3))) char*)(P) + tidg * 16 + _i * 8192), 16, 0, 0); } while (0)
; #define LDA(dst, b, h) _Pragma("unroll") for (int m = 0; m < 4; ++m) _Pragma("unroll") for (int k = 0; k < 2; ++k) \
;     dst[m][k] = *reinterpret_cast<const bf16x8*>((const char*)SA(b, h) + lds_byte(wr * 64 + m * 16 + fr, k * 32 + fq * 8))
; #define LDB(dst, b, h) _Pragma("unroll") for (int n = 0; n < 2; ++n) _Pragma("unroll") for (int k = 0; k < 2; ++k) \
;     dst[n][k] = *reinterpret_cast<const bf16x8*>((const char*)SB(b, h) + lds_byte(wc * 32 + n * 16 + fr, k * 32 + fq * 8))
; #define MMA(ai, bj, At_, Bt_) do { __builtin_amdgcn_s_setprio(1); \
;     _Pragma("unroll") for (int m = 0; m < 4; ++m) _Pragma("unroll") for (int n = 0; n < 2; ++n) _Pragma("unroll") for (int k = 0; k < 2; ++k) \
;       acc[ai][bj][m][n] = __builtin_amdgcn_mfma_f32_16x16x32_bf16(Bt_[n][k], At_[m][k], acc[ai][bj][m][n], 0, 0, 0); \
;     __builtin_amdgcn_s_setprio(0); } while (0)
; #define WAIT_V(n) asm volatile("s_waitcnt vmcnt(" #n ")" ::: "memory")
; #define WAIT_L(n) asm volatile("s_waitcnt lgkmcnt(" #n ")" ::: "memory")
; #define BAR __builtin_amdgcn_s_barrier()
; template <bool PF = true, class Epi, class KRF = KRFull>
; __device__ __forceinline__ void gemm_phase(const u16* __restrict__ A, int lda, const u16* __restrict__ Bt, int ldb, int K, int nM, int nN,
;                                            lds_u16* shm, Epi epi, KRF krf = KRFull(), bool flip = false) {
;     ...
;     { LDB(B0, 0, 0); LDA(At, 0, 0); STAGE_A(SA(1, 1), 1, nt - 1);
;       BAR; WAIT_L(0); MMA(0, 0, At, B0); BAR;
;       LDB(B1, 0, 1); BAR; WAIT_L(0); MMA(0, 1, At, B1); BAR;
;       LDA(At, 0, 1); WAIT_V(4); BAR; WAIT_L(0); MMA(1, 0, At, B0); MMA(1, 1, At, B1); BAR; }
;     { LDB(B0, 1, 0); LDA(At, 1, 0); WAIT_V(2); BAR; WAIT_L(0); MMA(0, 0, At, B0); BAR;
	s_waitcnt lgkmcnt(0)
	s_setprio 1
	s_waitcnt lgkmcnt(0)
	v_mfma_f32_16x16x32_bf16 v[124:127], v[130:133], v[162:165], v[124:127]
	v_mfma_f32_16x16x32_bf16 v[120:123], v[146:149], v[162:165], v[120:123]
	v_mfma_f32_16x16x32_bf16 v[116:119], v[130:133], v[170:173], v[116:119]
	v_mfma_f32_16x16x32_bf16 v[112:115], v[146:149], v[170:173], v[112:115]
	v_mfma_f32_16x16x32_bf16 v[108:111], v[130:133], v[184:187], v[108:111]
	v_mfma_f32_16x16x32_bf16 v[104:107], v[146:149], v[184:187], v[104:107]
	v_mfma_f32_16x16x32_bf16 v[100:103], v[130:133], v[192:195], v[100:103]
	v_mfma_f32_16x16x32_bf16 v[96:99], v[146:149], v[192:195], v[96:99]
	v_mfma_f32_16x16x32_bf16 v[124:127], v[134:137], v[166:169], v[124:127]
	v_mfma_f32_16x16x32_bf16 v[120:123], v[158:161], v[166:169], v[120:123]
	v_mfma_f32_16x16x32_bf16 v[116:119], v[134:137], v[180:183], v[116:119]
	v_mfma_f32_16x16x32_bf16 v[112:115], v[158:161], v[180:183], v[112:115]
	v_mfma_f32_16x16x32_bf16 v[108:111], v[134:137], v[188:191], v[108:111]
	v_mfma_f32_16x16x32_bf16 v[104:107], v[158:161], v[188:191], v[104:107]
	v_mfma_f32_16x16x32_bf16 v[100:103], v[134:137], v[196:199], v[100:103]
	v_mfma_f32_16x16x32_bf16 v[96:99], v[158:161], v[196:199], v[96:99]
	s_setprio 0
	s_barrier
	ds_read_b128 v[154:157], v153
	ds_read_b128 v[200:203], v153 offset:1024
	ds_read_b128 v[204:207], v153 offset:2048
	ds_read_b128 v[150:153], v153 offset:3072
	s_barrier
	s_waitcnt lgkmcnt(0)
	s_setprio 1
	s_waitcnt lgkmcnt(0)
	v_mfma_f32_16x16x32_bf16 v[92:95], v[154:157], v[162:165], v[92:95]
	v_mfma_f32_16x16x32_bf16 v[88:91], v[204:207], v[162:165], v[88:91]
	v_mfma_f32_16x16x32_bf16 v[84:87], v[154:157], v[170:173], v[84:87]
	v_mfma_f32_16x16x32_bf16 v[80:83], v[204:207], v[170:173], v[80:83]
	v_mfma_f32_16x16x32_bf16 v[76:79], v[154:157], v[184:187], v[76:79]
	v_mfma_f32_16x16x32_bf16 v[72:75], v[204:207], v[184:187], v[72:75]
	v_mfma_f32_16x16x32_bf16 v[68:71], v[154:157], v[192:195], v[68:71]
	v_mfma_f32_16x16x32_bf16 v[64:67], v[204:207], v[192:195], v[64:67]
	v_mfma_f32_16x16x32_bf16 v[92:95], v[200:203], v[166:169], v[92:95]
	v_mfma_f32_16x16x32_bf16 v[88:91], v[150:153], v[166:169], v[88:91]
	v_mfma_f32_16x16x32_bf16 v[84:87], v[200:203], v[180:183], v[84:87]
	v_mfma_f32_16x16x32_bf16 v[80:83], v[150:153], v[180:183], v[80:83]
	v_mfma_f32_16x16x32_bf16 v[76:79], v[200:203], v[188:191], v[76:79]
	v_mfma_f32_16x16x32_bf16 v[72:75], v[150:153], v[188:191], v[72:75]
	v_mfma_f32_16x16x32_bf16 v[68:71], v[200:203], v[196:199], v[68:71]
	v_mfma_f32_16x16x32_bf16 v[64:67], v[150:153], v[196:199], v[64:67]
	s_setprio 0
	s_barrier
	ds_read_b128 v[162:165], v142 offset:16384
	ds_read_b128 v[166:169], v142 offset:17408
	ds_read_b128 v[170:173], v141 offset:16384
	ds_read_b128 v[180:183], v141 offset:17408
	ds_read_b128 v[184:187], v140 offset:16384
	ds_read_b128 v[188:191], v140 offset:17408
	ds_read_b128 v[192:195], v139 offset:16384
	ds_read_b128 v[196:199], v139 offset:17408
	s_waitcnt vmcnt(4)
	s_barrier
	s_waitcnt lgkmcnt(0)
	s_setprio 1
	s_waitcnt lgkmcnt(0)
	v_mfma_f32_16x16x32_bf16 v[60:63], v[130:133], v[162:165], v[60:63]
	v_mfma_f32_16x16x32_bf16 v[56:59], v[146:149], v[162:165], v[56:59]
	v_mfma_f32_16x16x32_bf16 v[52:55], v[130:133], v[170:173], v[52:55]
	v_mfma_f32_16x16x32_bf16 v[48:51], v[146:149], v[170:173], v[48:51]
	v_mfma_f32_16x16x32_bf16 v[44:47], v[130:133], v[184:187], v[44:47]
	v_mfma_f32_16x16x32_bf16 v[40:43], v[146:149], v[184:187], v[40:43]
	v_mfma_f32_16x16x32_bf16 v[36:39], v[130:133], v[192:195], v[36:39]
	v_mfma_f32_16x16x32_bf16 v[32:35], v[146:149], v[192:195], v[32:35]
	v_mfma_f32_16x16x32_bf16 v[60:63], v[134:137], v[166:169], v[60:63]
	v_mfma_f32_16x16x32_bf16 v[56:59], v[158:161], v[166:169], v[56:59]
	v_mfma_f32_16x16x32_bf16 v[52:55], v[134:137], v[180:183], v[52:55]
	v_mfma_f32_16x16x32_bf16 v[48:51], v[158:161], v[180:183], v[48:51]
	v_mfma_f32_16x16x32_bf16 v[44:47], v[134:137], v[188:191], v[44:47]
	v_mfma_f32_16x16x32_bf16 v[40:43], v[158:161], v[188:191], v[40:43]
	v_mfma_f32_16x16x32_bf16 v[36:39], v[134:137], v[196:199], v[36:39]
	v_mfma_f32_16x16x32_bf16 v[32:35], v[158:161], v[196:199], v[32:35]
	s_setprio 0
	s_setprio 1
	v_mfma_f32_16x16x32_bf16 v[28:31], v[154:157], v[162:165], v[28:31]
	v_mfma_f32_16x16x32_bf16 v[24:27], v[204:207], v[162:165], v[24:27]
	v_mfma_f32_16x16x32_bf16 v[20:23], v[154:157], v[170:173], v[20:23]
	v_mfma_f32_16x16x32_bf16 v[16:19], v[204:207], v[170:173], v[16:19]
	v_mfma_f32_16x16x32_bf16 v[12:15], v[154:157], v[184:187], v[12:15]
	v_mfma_f32_16x16x32_bf16 v[8:11], v[204:207], v[184:187], v[8:11]
	v_mfma_f32_16x16x32_bf16 v[4:7], v[154:157], v[192:195], v[4:7]
	v_mfma_f32_16x16x32_bf16 v[0:3], v[204:207], v[192:195], v[0:3]
	v_mfma_f32_16x16x32_bf16 v[28:31], v[200:203], v[166:169], v[28:31]
	v_mfma_f32_16x16x32_bf16 v[24:27], v[150:153], v[166:169], v[24:27]
	v_mfma_f32_16x16x32_bf16 v[20:23], v[200:203], v[180:183], v[20:23]
	v_mfma_f32_16x16x32_bf16 v[16:19], v[150:153], v[180:183], v[16:19]
	v_mfma_f32_16x16x32_bf16 v[12:15], v[200:203], v[188:191], v[12:15]
	v_mfma_f32_16x16x32_bf16 v[8:11], v[150:153], v[188:191], v[8:11]
	v_mfma_f32_16x16x32_bf16 v[4:7], v[200:203], v[196:199], v[4:7]
	v_mfma_f32_16x16x32_bf16 v[0:3], v[150:153], v[196:199], v[0:3]
	s_setprio 0
	s_barrier
	ds_read_b128 v[128:131], v145
	ds_read_b128 v[132:135], v145 offset:1024
	ds_read_b128 v[146:149], v145 offset:2048
	ds_read_b128 v[150:153], v145 offset:3072
	ds_read_b128 v[154:157], v142 offset:32768
	ds_read_b128 v[158:161], v142 offset:33792
	ds_read_b128 v[162:165], v141 offset:32768
	ds_read_b128 v[166:169], v141 offset:33792
	ds_read_b128 v[170:173], v140 offset:32768
	ds_read_b128 v[180:183], v140 offset:33792
	ds_read_b128 v[184:187], v139 offset:32768
	ds_read_b128 v[188:191], v139 offset:33792
	s_waitcnt vmcnt(2)
	s_barrier
; #define LDA(dst, b, h) _Pragma("unroll") for (int m = 0; m < 4; ++m) _Pragma("unroll") for (int k = 0; k < 2; ++k) \
;     dst[m][k] = *reinterpret_cast<const bf16x8*>((const char*)SA(b, h) + lds_byte(wr * 64 + m * 16 + fr, k * 32 + fq * 8))
; #define LDB(dst, b, h) _Pragma("unroll") for (int n = 0; n < 2; ++n) _Pragma("unroll") for (int k = 0; k < 2; ++k) \
;     dst[n][k] = *reinterpret_cast<const bf16x8*>((const char*)SB(b, h) + lds_byte(wc * 32 + n * 16 + fr, k * 32 + fq * 8))
; #define MMA(ai, bj, At_, Bt_) do { __builtin_amdgcn_s_setprio(1); \
;     _Pragma("unroll") for (int m = 0; m < 4; ++m) _Pragma("unroll") for (int n = 0; n < 2; ++n) _Pragma("unroll") for (int k = 0; k < 2; ++k) \
;       acc[ai][bj][m][n] = __builtin_amdgcn_mfma_f32_16x16x32_bf16(Bt_[n][k], At_[m][k], acc[ai][bj][m][n], 0, 0, 0); \
;     __builtin_amdgcn_s_setprio(0); } while (0)
; #define WAIT_V(n) asm volatile("s_waitcnt vmcnt(" #n ")" ::: "memory")
; #define WAIT_L(n) asm volatile("s_waitcnt lgkmcnt(" #n ")" ::: "memory")
; #define BAR __builtin_amdgcn_s_barrier()
; template <bool PF = true, class Epi, class KRF = KRFull>
; __device__ __forceinline__ void gemm_phase(const u16* __restrict__ A, int lda, const u16* __restrict__ Bt, int ldb, int K, int nM, int nN,
;                                            lds_u16* shm, Epi epi, KRF krf = KRFull(), bool flip = false) {
;     ...
;     { LDB(B0, 1, 0); LDA(At, 1, 0); WAIT_V(2); BAR; WAIT_L(0); MMA(0, 0, At, B0); BAR;
;       LDB(B1, 1, 1); WAIT_V(0); BAR; WAIT_L(0); MMA(0, 1, At, B1); BAR;
;       LDA(At, 1, 1); BAR; WAIT_L(0); MMA(1, 0, At, B0); MMA(1, 1, At, B1); BAR; }
;     if (wr == 0) BAR;
	s_waitcnt lgkmcnt(0)
	s_setprio 1
	s_waitcnt lgkmcnt(0)
	v_mfma_f32_16x16x32_bf16 v[124:127], v[128:131], v[154:157], v[124:127]
	v_mfma_f32_16x16x32_bf16 v[120:123], v[146:149], v[154:157], v[120:123]
	v_mfma_f32_16x16x32_bf16 v[116:119], v[128:131], v[162:165], v[116:119]
	v_mfma_f32_16x16x32_bf16 v[112:115], v[146:149], v[162:165], v[112:115]
	v_mfma_f32_16x16x32_bf16 v[108:111], v[128:131], v[170:173], v[108:111]
	v_mfma_f32_16x16x32_bf16 v[104:107], v[146:149], v[170:173], v[104:107]
	v_mfma_f32_16x16x32_bf16 v[100:103], v[128:131], v[184:187], v[100:103]
	v_mfma_f32_16x16x32_bf16 v[96:99], v[146:149], v[184:187], v[96:99]
	v_mfma_f32_16x16x32_bf16 v[124:127], v[132:135], v[158:161], v[124:127]
	v_mfma_f32_16x16x32_bf16 v[120:123], v[150:153], v[158:161], v[120:123]
	v_mfma_f32_16x16x32_bf16 v[116:119], v[132:135], v[166:169], v[116:119]
	v_mfma_f32_16x16x32_bf16 v[112:115], v[150:153], v[166:169], v[112:115]
	v_mfma_f32_16x16x32_bf16 v[108:111], v[132:135], v[180:183], v[108:111]
	v_mfma_f32_16x16x32_bf16 v[104:107], v[150:153], v[180:183], v[104:107]
	v_mfma_f32_16x16x32_bf16 v[100:103], v[132:135], v[188:191], v[100:103]
	v_mfma_f32_16x16x32_bf16 v[96:99], v[150:153], v[188:191], v[96:99]
	s_setprio 0
	s_barrier
	ds_read_b128 v[192:195], v143
	ds_read_b128 v[196:199], v143 offset:1024
	ds_read_b128 v[200:203], v143 offset:2048
	ds_read_b128 v[204:207], v143 offset:3072
	s_waitcnt vmcnt(0)
	s_barrier
	s_waitcnt lgkmcnt(0)
	s_setprio 1
	s_waitcnt lgkmcnt(0)
	v_mfma_f32_16x16x32_bf16 v[92:95], v[192:195], v[154:157], v[92:95]
	v_mfma_f32_16x16x32_bf16 v[88:91], v[200:203], v[154:157], v[88:91]
	v_mfma_f32_16x16x32_bf16 v[84:87], v[192:195], v[162:165], v[84:87]
	v_mfma_f32_16x16x32_bf16 v[80:83], v[200:203], v[162:165], v[80:83]
	v_mfma_f32_16x16x32_bf16 v[76:79], v[192:195], v[170:173], v[76:79]
	v_mfma_f32_16x16x32_bf16 v[72:75], v[200:203], v[170:173], v[72:75]
	v_mfma_f32_16x16x32_bf16 v[68:71], v[192:195], v[184:187], v[68:71]
	v_mfma_f32_16x16x32_bf16 v[64:67], v[200:203], v[184:187], v[64:67]
	v_mfma_f32_16x16x32_bf16 v[92:95], v[196:199], v[158:161], v[92:95]
	v_mfma_f32_16x16x32_bf16 v[88:91], v[204:207], v[158:161], v[88:91]
	v_mfma_f32_16x16x32_bf16 v[84:87], v[196:199], v[166:169], v[84:87]
	v_mfma_f32_16x16x32_bf16 v[80:83], v[204:207], v[166:169], v[80:83]
	v_mfma_f32_16x16x32_bf16 v[76:79], v[196:199], v[180:183], v[76:79]
	v_mfma_f32_16x16x32_bf16 v[72:75], v[204:207], v[180:183], v[72:75]
	v_mfma_f32_16x16x32_bf16 v[68:71], v[196:199], v[188:191], v[68:71]
	v_mfma_f32_16x16x32_bf16 v[64:67], v[204:207], v[188:191], v[64:67]
	s_setprio 0
	s_barrier
	ds_read_b128 v[154:157], v142 offset:49152
	ds_read_b128 v[142:145], v142 offset:50176
	ds_read_b128 v[158:161], v141 offset:49152
	ds_read_b128 v[162:165], v141 offset:50176
	ds_read_b128 v[166:169], v140 offset:49152
	ds_read_b128 v[170:173], v140 offset:50176
	ds_read_b128 v[180:183], v139 offset:49152
	ds_read_b128 v[184:187], v139 offset:50176
	s_barrier
	s_waitcnt lgkmcnt(0)
	s_setprio 1
	s_waitcnt lgkmcnt(0)
	v_mfma_f32_16x16x32_bf16 v[60:63], v[128:131], v[154:157], v[60:63]
	v_mfma_f32_16x16x32_bf16 v[56:59], v[146:149], v[154:157], v[56:59]
	v_mfma_f32_16x16x32_bf16 v[52:55], v[128:131], v[158:161], v[52:55]
	v_mfma_f32_16x16x32_bf16 v[48:51], v[146:149], v[158:161], v[48:51]
	v_mfma_f32_16x16x32_bf16 v[44:47], v[128:131], v[166:169], v[44:47]
	v_mfma_f32_16x16x32_bf16 v[40:43], v[146:149], v[166:169], v[40:43]
	v_mfma_f32_16x16x32_bf16 v[36:39], v[128:131], v[180:183], v[36:39]
	v_mfma_f32_16x16x32_bf16 v[32:35], v[146:149], v[180:183], v[32:35]
	v_mfma_f32_16x16x32_bf16 v[60:63], v[132:135], v[142:145], v[60:63]
	v_mfma_f32_16x16x32_bf16 v[56:59], v[150:153], v[142:145], v[56:59]
	v_mfma_f32_16x16x32_bf16 v[52:55], v[132:135], v[162:165], v[52:55]
	v_mfma_f32_16x16x32_bf16 v[48:51], v[150:153], v[162:165], v[48:51]
	v_mfma_f32_16x16x32_bf16 v[44:47], v[132:135], v[170:173], v[44:47]
	v_mfma_f32_16x16x32_bf16 v[40:43], v[150:153], v[170:173], v[40:43]
	v_mfma_f32_16x16x32_bf16 v[36:39], v[132:135], v[184:187], v[36:39]
	v_mfma_f32_16x16x32_bf16 v[32:35], v[150:153], v[184:187], v[32:35]
	s_setprio 0
	s_setprio 1
	v_mfma_f32_16x16x32_bf16 v[28:31], v[192:195], v[154:157], v[28:31]
	v_mfma_f32_16x16x32_bf16 v[24:27], v[200:203], v[154:157], v[24:27]
	v_mfma_f32_16x16x32_bf16 v[20:23], v[192:195], v[158:161], v[20:23]
	v_mfma_f32_16x16x32_bf16 v[16:19], v[200:203], v[158:161], v[16:19]
	v_mfma_f32_16x16x32_bf16 v[12:15], v[192:195], v[166:169], v[12:15]
	v_mfma_f32_16x16x32_bf16 v[8:11], v[200:203], v[166:169], v[8:11]
	v_mfma_f32_16x16x32_bf16 v[4:7], v[192:195], v[180:183], v[4:7]
	v_mfma_f32_16x16x32_bf16 v[0:3], v[200:203], v[180:183], v[0:3]
	v_mfma_f32_16x16x32_bf16 v[28:31], v[196:199], v[142:145], v[28:31]
	v_mfma_f32_16x16x32_bf16 v[24:27], v[204:207], v[142:145], v[24:27]
	v_mfma_f32_16x16x32_bf16 v[20:23], v[196:199], v[162:165], v[20:23]
	v_mfma_f32_16x16x32_bf16 v[16:19], v[204:207], v[162:165], v[16:19]
	v_mfma_f32_16x16x32_bf16 v[12:15], v[196:199], v[170:173], v[12:15]
	v_mfma_f32_16x16x32_bf16 v[8:11], v[204:207], v[170:173], v[8:11]
	v_mfma_f32_16x16x32_bf16 v[4:7], v[196:199], v[184:187], v[4:7]
	v_mfma_f32_16x16x32_bf16 v[0:3], v[204:207], v[184:187], v[0:3]
	s_setprio 0
	v_cmp_gt_u32_e32 vcc, s95, v138
	s_barrier
	s_and_saveexec_b64 s[12:13], vcc
	s_cbranch_execz .LBB0_2565
	s_barrier

; __device__ __forceinline__ int tid_l() { int t = threadIdx.x; asm volatile("" : "+v"(t)); return t; }
; __device__ __forceinline__ int bid_l() { int t = blockIdx.x; asm volatile("" : "+s"(t)); return t; }
; __device__ __forceinline__ int gdim_l() { int t = gridDim.x; asm volatile("" : "+s"(t)); return t; }
; #define STAGE_A(P, half, kt) do { const char* _u = Ab + ((size_t)(half) * 128 * lda + (size_t)(kt) * BK) * 2; \
;     _Pragma("unroll") for (int _i = 0; _i < 2; ++_i) \
;       __builtin_amdgcn_global_load_lds((const unsigned*)(_u + offA[_i]), \
;         (__attribute__((address_space(3))) unsigned*)((__attribute__((address_space(3))) char*)(P) + tidg * 16 + _i * 8192), 16, 0, 0); } while (0)
; #define WAIT_V(n) asm volatile("s_waitcnt vmcnt(" #n ")" ::: "memory")
; #define BAR __builtin_amdgcn_s_barrier()
; template <bool PF = true, class Epi, class KRF = KRFull>
; __device__ __forceinline__ void gemm_phase(const u16* __restrict__ A, int lda, const u16* __restrict__ Bt, int ldb, int K, int nM, int nN,
;                                            lds_u16* shm, Epi epi, KRF krf = KRFull(), bool flip = false) {
;   int tidg = tid_l();
;   int wid, lane, wr, wc, fr, fq;
;   int nt;
;   unsigned offA[2], offB[2];
;     ...
;   G_THREAD();
;   int ntile = nM * nN;
;   const int gdg = gdim_l();
;   const int bidg = flip ? (gdg - 1 - bid_l()) : bid_l();
;   int tix = bidg;
;   if (tix >= ntile) return;
;   int pm, pn; tile_map(tix, nM, nN, pm, pn);
;   int brow = pm * 256, bcol = pn * 256;
;   int2 kr = krf(bcol, K);
;   int nt_next = kr.y;
;   const char* Ab = (const char*)A + (size_t)brow * lda * 2 + kr.x * (BK * 2);
;   const char* Bb = (const char*)Bt + (size_t)bcol * ldb * 2 + kr.x * (BK * 2);
;   __syncthreads();
;   STAGE_B(SB(0, 0), 0, 0); STAGE_A(SA(0, 0), 0, 0);
;   STAGE_B(SB(0, 1), 1, 0); STAGE_A(SA(0, 1), 1, 0);
;   for (;;) {
;     G_THREAD();
;     nt = nt_next;
;     f32x4 acc[2][2][4][2] = {};
;     bf16x8 At[4][2], B0[2][2], B1[2][2];
;     if (wr == 1) BAR;
;     WAIT_V(4); BAR;
;     STAGE_B(SB(1, 0), 0, 1); STAGE_A(SA(1, 0), 0, 1); STAGE_B(SB(1, 1), 1, 1);
;     WAIT_V(6); BAR;
.LBB0_2579:
	s_or_b64 exec, exec, s[12:13]
	v_bfe_i32 v2, v138, 27, 1
	v_lshlrev_b32_e32 v144, 4, v138
	v_lshrrev_b32_e32 v2, 22, v2
	v_add_u32_e32 v2, v144, v2
	v_and_b32_e32 v2, 0xfffffc00, v2
	v_sub_u32_e32 v2, v144, v2
	v_lshrrev_b32_e32 v3, 4, v2
	v_ashrrev_i32_e32 v1, 31, v138
	v_bitop3_b32 v2, v3, v2, 32 bitop3:0x6c
	v_lshrrev_b32_e32 v1, 26, v1
	v_ashrrev_i32_e32 v4, 31, v2
	v_add_u32_e32 v1, v138, v1
	v_lshrrev_b32_e32 v4, 26, v4
	v_ashrrev_i32_e32 v1, 6, v1
	v_add_u32_e32 v4, v2, v4
	v_lshlrev_b32_e32 v3, 3, v1
	v_ashrrev_i32_e32 v5, 6, v4
	v_and_b32_e32 v4, 0xc0, v4
	v_and_b32_e32 v3, 0x7ffff0, v3
	v_sub_u32_e32 v2, v2, v4
	v_add_u32_e32 v3, v5, v3
	v_lshlrev_b32_e32 v6, 5, v1
	v_ashrrev_i16_sdwa v2, v232, sext(v2) dst_sel:DWORD dst_unused:UNUSED_PAD src0_sel:DWORD src1_sel:BYTE_0
	s_movk_i32 s22, 0x1600
	v_and_b32_e32 v6, 32, v6
	v_bfe_i32 v4, v2, 0, 16
	v_mul_lo_u32 v2, v3, s22
	v_or_b32_e32 v2, v2, v6
	v_add_u32_e32 v146, 0x2000, v144
	v_add_lshl_u32 v178, v2, v4, 1
	v_ashrrev_i32_e32 v2, 31, v146
	v_lshrrev_b32_e32 v2, 22, v2
	v_add_u32_e32 v2, v146, v2
	v_ashrrev_i32_e32 v7, 10, v2
	v_mul_i32_i24_e32 v2, 0x400, v7
	v_sub_u32_e32 v2, v146, v2
	v_lshrrev_b32_e32 v3, 4, v2
	v_bitop3_b32 v2, v3, v2, 32 bitop3:0x6c
	v_ashrrev_i32_e32 v8, 31, v2
	v_lshrrev_b32_e32 v8, 26, v8
	v_add_u32_e32 v8, v2, v8
	v_lshlrev_b32_e32 v3, 3, v7
	v_ashrrev_i32_e32 v9, 6, v8
	v_and_b32_e32 v8, 0xc0, v8
	v_and_b32_e32 v3, 0x7ffff0, v3
	v_sub_u32_e32 v2, v2, v8
	v_add_u32_e32 v3, v9, v3
	v_lshlrev_b32_e32 v10, 5, v7
	v_ashrrev_i16_sdwa v2, v232, sext(v2) dst_sel:DWORD dst_unused:UNUSED_PAD src0_sel:DWORD src1_sel:BYTE_0
	v_and_b32_e32 v10, 32, v10
	v_bfe_i32 v8, v2, 0, 16
	v_mul_lo_u32 v2, v3, s22
	v_or_b32_e32 v2, v2, v10
	v_add_u32_e32 v147, 0x18000, v144
	v_add_lshl_u32 v128, v2, v8, 1
	v_lshl_add_u64 v[2:3], s[4:5], 0, v[178:179]
	v_readfirstlane_b32 s12, v147
	v_lshl_add_u64 v[2:3], v[2:3], 0, s[60:61]
	s_mov_b32 m0, s12
	v_mov_b32_e32 v129, v179
	v_add_u32_e32 v148, 0x1a000, v144
	s_waitcnt vmcnt(4)
	s_barrier
	global_load_lds_dwordx4 v[2:3], off
	v_lshl_add_u64 v[2:3], s[4:5], 0, v[128:129]
	v_readfirstlane_b32 s12, v148
	v_lshl_add_u64 v[2:3], v[2:3], 0, s[60:61]
	s_mov_b32 m0, s12
	v_add_u32_e32 v149, 0x8000, v144
	global_load_lds_dwordx4 v[2:3], off
	v_lshl_add_u64 v[2:3], s[6:7], 0, v[178:179]
	v_readfirstlane_b32 s12, v149
	v_lshl_add_u64 v[2:3], v[2:3], 0, s[60:61]
	s_mov_b32 m0, s12
	v_add_u32_e32 v150, 0xa000, v144
	global_load_lds_dwordx4 v[2:3], off
	v_lshl_add_u64 v[2:3], s[6:7], 0, v[128:129]
	v_readfirstlane_b32 s12, v150
	v_add_u32_e32 v151, 0x1c000, v144
	v_lshl_add_u64 v[2:3], v[2:3], 0, s[60:61]
	s_mov_b32 m0, s12
	s_add_u32 s12, s4, 0x160080
	v_readfirstlane_b32 s21, v151
	v_add_u32_e32 v152, 0x1e000, v144
	global_load_lds_dwordx4 v[2:3], off
	s_addc_u32 s13, s5, 0
	s_mov_b32 m0, s21
	v_readfirstlane_b32 s21, v152
	global_load_lds_dwordx4 v178, s[12:13]
	s_mov_b32 m0, s21
	v_and_b32_e32 v11, 15, v138
	global_load_lds_dwordx4 v128, s[12:13]
	v_lshlrev_b32_e32 v2, 6, v11
	v_lshlrev_b32_e32 v11, 2, v138
	v_and_b32_e32 v12, 48, v138
	v_and_b32_e32 v11, 32, v11
	v_or_b32_e32 v3, v2, v12
	v_bitop3_b32 v13, v2, v11, v12 bitop3:0x36
	s_mov_b32 s12, 0x14000
	v_lshlrev_b32_e32 v2, 6, v138
	v_bitop3_b32 v15, v3, s12, v11 bitop3:0xde
	s_mov_b32 s12, 0x18000
	v_lshlrev_b32_e32 v19, 13, v0
	v_and_b32_e32 v0, 0x3c0, v2
	v_bitop3_b32 v14, v3, s94, v11 bitop3:0xde
	v_bitop3_b32 v16, v3, s12, v11 bitop3:0xde
	v_bitop3_b32 v17, v3, s97, v11 bitop3:0xde
	v_bitop3_b32 v11, v0, v11, v12 bitop3:0x36
	v_lshrrev_b32_e32 v1, 1, v1
	v_mul_lo_u32 v0, v5, s22
	v_and_b32_e32 v18, 0x3000, v2
	v_mad_u64_u32 v[0:1], s[12:13], v1, s34, v[0:1]
	v_lshrrev_b32_e32 v3, 1, v7
	v_mul_lo_u32 v2, v9, s22
	v_or_b32_e32 v0, v0, v6
	v_mad_u64_u32 v[2:3], s[12:13], v3, s34, v[2:3]
	s_waitcnt vmcnt(6)
	v_add_lshl_u32 v0, v0, v4, 1
	v_mov_b32_e32 v1, v179
	v_or_b32_e32 v2, v2, v10
	v_or_b32_e32 v12, 0x800, v19
	v_or_b32_e32 v20, 0x1000, v19
	v_or_b32_e32 v21, 0x1800, v19
	v_lshl_add_u64 v[130:131], s[4:5], 0, v[0:1]
	v_add_lshl_u32 v2, v2, v8, 1
	v_mov_b32_e32 v3, v179
	v_lshl_add_u64 v[134:135], s[6:7], 0, v[0:1]
	v_mov_b32_e32 v0, 0
	v_lshl_add_u64 v[132:133], s[4:5], 0, v[2:3]
	v_lshl_add_u64 v[136:137], s[6:7], 0, v[2:3]
	s_mov_b32 s21, -2
	s_mov_b64 s[12:13], 0
	v_add_u32_e32 v154, v14, v18
	v_add_u32_e32 v142, v13, v19
	v_add_u32_e32 v141, v11, v12
	v_add_u32_e32 v140, v11, v20
	v_add_u32_e32 v139, v11, v21
	v_add_u32_e32 v153, v15, v18
	v_add_u32_e32 v145, v16, v18
	v_add_u32_e32 v143, v17, v18
	v_mov_b32_e32 v1, v0
	v_mov_b32_e32 v2, v0
	v_mov_b32_e32 v3, v0
	v_mov_b32_e32 v4, v0
	v_mov_b32_e32 v5, v0
	v_mov_b32_e32 v6, v0
	v_mov_b32_e32 v7, v0
	v_mov_b32_e32 v8, v0
	v_mov_b32_e32 v9, v0
	v_mov_b32_e32 v10, v0
	v_mov_b32_e32 v11, v0
	v_mov_b32_e32 v12, v0
	v_mov_b32_e32 v13, v0
	v_mov_b32_e32 v14, v0
	v_mov_b32_e32 v15, v0
	v_mov_b32_e32 v16, v0
	v_mov_b32_e32 v17, v0
	v_mov_b32_e32 v18, v0
	v_mov_b32_e32 v19, v0
	v_mov_b32_e32 v20, v0
	v_mov_b32_e32 v21, v0
	v_mov_b32_e32 v22, v0
	v_mov_b32_e32 v23, v0
	v_mov_b32_e32 v24, v0
	v_mov_b32_e32 v25, v0
	v_mov_b32_e32 v26, v0
	v_mov_b32_e32 v27, v0
	v_mov_b32_e32 v28, v0
	v_mov_b32_e32 v29, v0
	v_mov_b32_e32 v30, v0
	v_mov_b32_e32 v31, v0
	v_mov_b32_e32 v32, v0
	v_mov_b32_e32 v33, v0
	v_mov_b32_e32 v34, v0
	v_mov_b32_e32 v35, v0
	v_mov_b32_e32 v36, v0
	v_mov_b32_e32 v37, v0
	v_mov_b32_e32 v38, v0
	v_mov_b32_e32 v39, v0
	v_mov_b32_e32 v40, v0
	v_mov_b32_e32 v41, v0
	v_mov_b32_e32 v42, v0
	v_mov_b32_e32 v43, v0
	v_mov_b32_e32 v44, v0
	v_mov_b32_e32 v45, v0
	v_mov_b32_e32 v46, v0
	v_mov_b32_e32 v47, v0
	v_mov_b32_e32 v48, v0
; #define STAGE_A(P, half, kt) do { const char* _u = Ab + ((size_t)(half) * 128 * lda + (size_t)(kt) * BK) * 2; \
;     _Pragma("unroll") for (int _i = 0; _i < 2; ++_i) \
;       __builtin_amdgcn_global_load_lds((const unsigned*)(_u + offA[_i]), \
;         (__attribute__((address_space(3))) unsigned*)((__attribute__((address_space(3))) char*)(P) + tidg * 16 + _i * 8192), 16, 0, 0); } while (0)
; #define STAGE_B(P, half, kt) do { const char* _u = Bb + ((size_t)(half) * 128 * ldb + (size_t)(kt) * BK) * 2; \
;     _Pragma("unroll") for (int _i = 0; _i < 2; ++_i) \
;       __builtin_amdgcn_global_load_lds((const unsigned*)(_u + offB[_i]), \
;         (__attribute__((address_space(3))) unsigned*)((__attribute__((address_space(3))) char*)(P) + tidg * 16 + _i * 8192), 16, 0, 0); } while (0)
; #define LDA(dst, b, h) _Pragma("unroll") for (int m = 0; m < 4; ++m) _Pragma("unroll") for (int k = 0; k < 2; ++k) \
;     dst[m][k] = *reinterpret_cast<const bf16x8*>((const char*)SA(b, h) + lds_byte(wr * 64 + m * 16 + fr, k * 32 + fq * 8))
; #define LDB(dst, b, h) _Pragma("unroll") for (int n = 0; n < 2; ++n) _Pragma("unroll") for (int k = 0; k < 2; ++k) \
;     dst[n][k] = *reinterpret_cast<const bf16x8*>((const char*)SB(b, h) + lds_byte(wc * 32 + n * 16 + fr, k * 32 + fq * 8))
; #define WAIT_V(n) asm volatile("s_waitcnt vmcnt(" #n ")" ::: "memory")
; template <bool PF = true, class Epi, class KRF = KRFull>
; __device__ __forceinline__ void gemm_phase(const u16* __restrict__ A, int lda, const u16* __restrict__ Bt, int ldb, int K, int nM, int nN,
;                                            lds_u16* shm, Epi epi, KRF krf = KRFull(), bool flip = false) {
;     ...
;     f32x4 acc[2][2][4][2] = {};
;     bf16x8 At[4][2], B0[2][2], B1[2][2];
;     if (wr == 1) BAR;
;     WAIT_V(4); BAR;
;     STAGE_B(SB(1, 0), 0, 1); STAGE_A(SA(1, 0), 0, 1); STAGE_B(SB(1, 1), 1, 1);
;     WAIT_V(6); BAR;
;     for (int t = 0; t < nt - 2; t += 2) {
;       LDB(B0, 0, 0); SCHED; LDA(At, 0, 0); STAGE_A(SA(1, 1), 1, t + 1);
;       WAIT_L(8); BAR; WAIT_L(0); MMA(0, 0, At, B0); BAR; SCHED;
;       LDB(B1, 0, 1); STAGE_B(SB(0, 0), 0, t + 2);
;       BAR; WAIT_L(0); MMA(0, 1, At, B1); BAR;
;       LDA(At, 0, 1); STAGE_A(SA(0, 0), 0, t + 2);
;       BAR; WAIT_L(0); MMA(1, 0, At, B0); BAR; SCHED;
;       STAGE_B(SB(0, 1), 1, t + 2);
;       WAIT_V(6); BAR; MMA(1, 1, At, B1); BAR;
	v_mov_b32_e32 v49, v0
	v_mov_b32_e32 v50, v0
	v_mov_b32_e32 v51, v0
	v_mov_b32_e32 v52, v0
	v_mov_b32_e32 v53, v0
	v_mov_b32_e32 v54, v0
	v_mov_b32_e32 v55, v0
	v_mov_b32_e32 v56, v0
	v_mov_b32_e32 v57, v0
	v_mov_b32_e32 v58, v0
	v_mov_b32_e32 v59, v0
	v_mov_b32_e32 v60, v0
	v_mov_b32_e32 v61, v0
	v_mov_b32_e32 v62, v0
	v_mov_b32_e32 v63, v0
	v_mov_b32_e32 v64, v0
	v_mov_b32_e32 v65, v0
	v_mov_b32_e32 v66, v0
	v_mov_b32_e32 v67, v0
	v_mov_b32_e32 v68, v0
	v_mov_b32_e32 v69, v0
	v_mov_b32_e32 v70, v0
	v_mov_b32_e32 v71, v0
	v_mov_b32_e32 v72, v0
	v_mov_b32_e32 v73, v0
	v_mov_b32_e32 v74, v0
	v_mov_b32_e32 v75, v0
	v_mov_b32_e32 v76, v0
	v_mov_b32_e32 v77, v0
	v_mov_b32_e32 v78, v0
	v_mov_b32_e32 v79, v0
	v_mov_b32_e32 v80, v0
	v_mov_b32_e32 v81, v0
	v_mov_b32_e32 v82, v0
	v_mov_b32_e32 v83, v0
	v_mov_b32_e32 v84, v0
	v_mov_b32_e32 v85, v0
	v_mov_b32_e32 v86, v0
	v_mov_b32_e32 v87, v0
	v_mov_b32_e32 v88, v0
	v_mov_b32_e32 v89, v0
	v_mov_b32_e32 v90, v0
	v_mov_b32_e32 v91, v0
	v_mov_b32_e32 v92, v0
	v_mov_b32_e32 v93, v0
	v_mov_b32_e32 v94, v0
	v_mov_b32_e32 v95, v0
	v_mov_b32_e32 v96, v0
	v_mov_b32_e32 v97, v0
	v_mov_b32_e32 v98, v0
	v_mov_b32_e32 v99, v0
	v_mov_b32_e32 v100, v0
	v_mov_b32_e32 v101, v0
	v_mov_b32_e32 v102, v0
	v_mov_b32_e32 v103, v0
	v_mov_b32_e32 v104, v0
	v_mov_b32_e32 v105, v0
	v_mov_b32_e32 v106, v0
	v_mov_b32_e32 v107, v0
	v_mov_b32_e32 v108, v0
	v_mov_b32_e32 v109, v0
	v_mov_b32_e32 v110, v0
	v_mov_b32_e32 v111, v0
	v_mov_b32_e32 v112, v0
	v_mov_b32_e32 v113, v0
	v_mov_b32_e32 v114, v0
	v_mov_b32_e32 v115, v0
	v_mov_b32_e32 v116, v0
	v_mov_b32_e32 v117, v0
	v_mov_b32_e32 v118, v0
	v_mov_b32_e32 v119, v0
	v_mov_b32_e32 v120, v0
	v_mov_b32_e32 v121, v0
	v_mov_b32_e32 v122, v0
	v_mov_b32_e32 v123, v0
	v_mov_b32_e32 v124, v0
	v_mov_b32_e32 v125, v0
	v_mov_b32_e32 v126, v0
	v_mov_b32_e32 v127, v0
	s_barrier
	v_readfirstlane_b32 s22, v144
.LBB0_2580:
	ds_read_b128 v[158:161], v154
	ds_read_b128 v[162:165], v154 offset:1024
	ds_read_b128 v[166:169], v154 offset:2048
	ds_read_b128 v[170:173], v154 offset:3072
	v_lshl_add_u64 v[174:175], v[134:135], 0, s[12:13]
	v_lshl_add_u64 v[156:157], v[174:175], 0, s[72:73]
	s_add_u32 m0, s22, 0xc000
	ds_read_b128 v[180:183], v142
	ds_read_b128 v[184:187], v142 offset:1024
	ds_read_b128 v[188:191], v141
	ds_read_b128 v[192:195], v141 offset:1024
	ds_read_b128 v[196:199], v140
	ds_read_b128 v[200:203], v140 offset:1024
	ds_read_b128 v[204:207], v139
	ds_read_b128 v[208:211], v139 offset:1024
	global_load_lds_dwordx4 v[156:157], off
	v_lshl_add_u64 v[234:235], v[136:137], 0, s[12:13]
	v_lshl_add_u64 v[212:213], v[234:235], 0, s[72:73]
	s_add_u32 m0, s22, 0xe000
	s_nop 0
	global_load_lds_dwordx4 v[212:213], off
	s_waitcnt lgkmcnt(8)
	s_barrier
	s_waitcnt lgkmcnt(0)
	s_setprio 1
	s_waitcnt lgkmcnt(0)
	v_mfma_f32_16x16x32_bf16 v[124:127], v[158:161], v[180:183], v[124:127]
	v_mfma_f32_16x16x32_bf16 v[120:123], v[166:169], v[180:183], v[120:123]
	v_mfma_f32_16x16x32_bf16 v[116:119], v[158:161], v[188:191], v[116:119]
	v_mfma_f32_16x16x32_bf16 v[112:115], v[166:169], v[188:191], v[112:115]
	v_mfma_f32_16x16x32_bf16 v[108:111], v[158:161], v[196:199], v[108:111]
	v_mfma_f32_16x16x32_bf16 v[104:107], v[166:169], v[196:199], v[104:107]
	v_mfma_f32_16x16x32_bf16 v[100:103], v[158:161], v[204:207], v[100:103]
	v_mfma_f32_16x16x32_bf16 v[96:99], v[166:169], v[204:207], v[96:99]
	v_mfma_f32_16x16x32_bf16 v[124:127], v[162:165], v[184:187], v[124:127]
	v_mfma_f32_16x16x32_bf16 v[120:123], v[170:173], v[184:187], v[120:123]
	v_mfma_f32_16x16x32_bf16 v[116:119], v[162:165], v[192:195], v[116:119]
	v_mfma_f32_16x16x32_bf16 v[112:115], v[170:173], v[192:195], v[112:115]
	v_mfma_f32_16x16x32_bf16 v[108:111], v[162:165], v[200:203], v[108:111]
	v_mfma_f32_16x16x32_bf16 v[104:107], v[170:173], v[200:203], v[104:107]
	v_mfma_f32_16x16x32_bf16 v[100:103], v[162:165], v[208:211], v[100:103]
	v_mfma_f32_16x16x32_bf16 v[96:99], v[170:173], v[208:211], v[96:99]
	s_setprio 0
	s_barrier
	v_lshl_add_u64 v[236:237], v[130:131], 0, s[12:13]
	v_lshl_add_u64 v[238:239], v[236:237], 0, s[64:65]
	s_add_u32 m0, s22, 0x10000
	ds_read_b128 v[212:215], v153
	ds_read_b128 v[216:219], v153 offset:1024
	ds_read_b128 v[222:225], v153 offset:2048
	ds_read_b128 v[226:229], v153 offset:3072
	global_load_lds_dwordx4 v[238:239], off
	v_lshl_add_u64 v[238:239], v[132:133], 0, s[12:13]
	v_lshl_add_u64 v[240:241], v[238:239], 0, s[64:65]
	s_add_u32 m0, s22, 0x12000
	s_nop 0
	global_load_lds_dwordx4 v[240:241], off
	s_barrier
	s_waitcnt lgkmcnt(0)
	s_setprio 1
	s_waitcnt lgkmcnt(0)
	v_mfma_f32_16x16x32_bf16 v[92:95], v[212:215], v[180:183], v[92:95]
	v_mfma_f32_16x16x32_bf16 v[88:91], v[222:225], v[180:183], v[88:91]
	v_mfma_f32_16x16x32_bf16 v[84:87], v[212:215], v[188:191], v[84:87]
	v_mfma_f32_16x16x32_bf16 v[80:83], v[222:225], v[188:191], v[80:83]
	v_mfma_f32_16x16x32_bf16 v[76:79], v[212:215], v[196:199], v[76:79]
	v_mfma_f32_16x16x32_bf16 v[72:75], v[222:225], v[196:199], v[72:75]
	v_mfma_f32_16x16x32_bf16 v[68:71], v[212:215], v[204:207], v[68:71]
	v_mfma_f32_16x16x32_bf16 v[64:67], v[222:225], v[204:207], v[64:67]
	v_mfma_f32_16x16x32_bf16 v[92:95], v[216:219], v[184:187], v[92:95]
	v_mfma_f32_16x16x32_bf16 v[88:91], v[226:229], v[184:187], v[88:91]
	v_mfma_f32_16x16x32_bf16 v[84:87], v[216:219], v[192:195], v[84:87]
	v_mfma_f32_16x16x32_bf16 v[80:83], v[226:229], v[192:195], v[80:83]
	v_mfma_f32_16x16x32_bf16 v[76:79], v[216:219], v[200:203], v[76:79]
	v_mfma_f32_16x16x32_bf16 v[72:75], v[226:229], v[200:203], v[72:75]
	v_mfma_f32_16x16x32_bf16 v[68:71], v[216:219], v[208:211], v[68:71]
	v_mfma_f32_16x16x32_bf16 v[64:67], v[226:229], v[208:211], v[64:67]
	s_setprio 0
	v_lshl_add_u64 v[240:241], v[174:175], 0, s[64:65]
	s_mov_b32 m0, s22
	s_barrier
; #define STAGE_A(P, half, kt) do { const char* _u = Ab + ((size_t)(half) * 128 * lda + (size_t)(kt) * BK) * 2; \
;     _Pragma("unroll") for (int _i = 0; _i < 2; ++_i) \
;       __builtin_amdgcn_global_load_lds((const unsigned*)(_u + offA[_i]), \
;         (__attribute__((address_space(3))) unsigned*)((__attribute__((address_space(3))) char*)(P) + tidg * 16 + _i * 8192), 16, 0, 0); } while (0)
; #define STAGE_B(P, half, kt) do { const char* _u = Bb + ((size_t)(half) * 128 * ldb + (size_t)(kt) * BK) * 2; \
;     _Pragma("unroll") for (int _i = 0; _i < 2; ++_i) \
;       __builtin_amdgcn_global_load_lds((const unsigned*)(_u + offB[_i]), \
;         (__attribute__((address_space(3))) unsigned*)((__attribute__((address_space(3))) char*)(P) + tidg * 16 + _i * 8192), 16, 0, 0); } while (0)
; #define LDA(dst, b, h) _Pragma("unroll") for (int m = 0; m < 4; ++m) _Pragma("unroll") for (int k = 0; k < 2; ++k) \
;     dst[m][k] = *reinterpret_cast<const bf16x8*>((const char*)SA(b, h) + lds_byte(wr * 64 + m * 16 + fr, k * 32 + fq * 8))
; #define LDB(dst, b, h) _Pragma("unroll") for (int n = 0; n < 2; ++n) _Pragma("unroll") for (int k = 0; k < 2; ++k) \
;     dst[n][k] = *reinterpret_cast<const bf16x8*>((const char*)SB(b, h) + lds_byte(wc * 32 + n * 16 + fr, k * 32 + fq * 8))
; #define WAIT_V(n) asm volatile("s_waitcnt vmcnt(" #n ")" ::: "memory")
; #define WAIT_L(n) asm volatile("s_waitcnt lgkmcnt(" #n ")" ::: "memory")
; #define BAR __builtin_amdgcn_s_barrier()
; #define SCHED __builtin_amdgcn_sched_barrier(0)
; template <bool PF = true, class Epi, class KRF = KRFull>
; __device__ __forceinline__ void gemm_phase(const u16* __restrict__ A, int lda, const u16* __restrict__ Bt, int ldb, int K, int nM, int nN,
;                                            lds_u16* shm, Epi epi, KRF krf = KRFull(), bool flip = false) {
;     ...
;       LDA(At, 0, 1); STAGE_A(SA(0, 0), 0, t + 2);
;       BAR; WAIT_L(0); MMA(1, 0, At, B0); BAR; SCHED;
;       STAGE_B(SB(0, 1), 1, t + 2);
;       WAIT_V(6); BAR; MMA(1, 1, At, B1); BAR;
;       LDB(B0, 1, 0); SCHED; LDA(At, 1, 0); STAGE_A(SA(0, 1), 1, t + 2);
;       WAIT_L(8); BAR; WAIT_L(0); MMA(0, 0, At, B0); BAR; SCHED;
;       LDB(B1, 1, 1); STAGE_B(SB(1, 0), 0, t + 3);
;       BAR; WAIT_L(0); MMA(0, 1, At, B1); BAR;
;       LDA(At, 1, 1); STAGE_A(SA(1, 0), 0, t + 3);
	ds_read_b128 v[180:183], v142 offset:16384
	ds_read_b128 v[184:187], v142 offset:17408
	ds_read_b128 v[188:191], v141 offset:16384
	ds_read_b128 v[192:195], v141 offset:17408
	ds_read_b128 v[196:199], v140 offset:16384
	ds_read_b128 v[200:203], v140 offset:17408
	ds_read_b128 v[204:207], v139 offset:16384
	ds_read_b128 v[208:211], v139 offset:17408
	global_load_lds_dwordx4 v[240:241], off
	v_lshl_add_u64 v[240:241], v[234:235], 0, s[64:65]
	s_add_u32 m0, s22, 0x2000
	s_nop 0
	global_load_lds_dwordx4 v[240:241], off
	s_barrier
	s_waitcnt lgkmcnt(0)
	s_setprio 1
	s_waitcnt lgkmcnt(0)
	v_mfma_f32_16x16x32_bf16 v[60:63], v[158:161], v[180:183], v[60:63]
	v_mfma_f32_16x16x32_bf16 v[56:59], v[166:169], v[180:183], v[56:59]
	v_mfma_f32_16x16x32_bf16 v[52:55], v[158:161], v[188:191], v[52:55]
	v_mfma_f32_16x16x32_bf16 v[48:51], v[166:169], v[188:191], v[48:51]
	v_mfma_f32_16x16x32_bf16 v[44:47], v[158:161], v[196:199], v[44:47]
	v_mfma_f32_16x16x32_bf16 v[40:43], v[166:169], v[196:199], v[40:43]
	v_mfma_f32_16x16x32_bf16 v[36:39], v[158:161], v[204:207], v[36:39]
	v_mfma_f32_16x16x32_bf16 v[32:35], v[166:169], v[204:207], v[32:35]
	v_mfma_f32_16x16x32_bf16 v[60:63], v[162:165], v[184:187], v[60:63]
	v_mfma_f32_16x16x32_bf16 v[56:59], v[170:173], v[184:187], v[56:59]
	v_mfma_f32_16x16x32_bf16 v[52:55], v[162:165], v[192:195], v[52:55]
	v_mfma_f32_16x16x32_bf16 v[48:51], v[170:173], v[192:195], v[48:51]
	v_mfma_f32_16x16x32_bf16 v[44:47], v[162:165], v[200:203], v[44:47]
	v_mfma_f32_16x16x32_bf16 v[40:43], v[170:173], v[200:203], v[40:43]
	v_mfma_f32_16x16x32_bf16 v[36:39], v[162:165], v[208:211], v[36:39]
	v_mfma_f32_16x16x32_bf16 v[32:35], v[170:173], v[208:211], v[32:35]
	s_setprio 0
	s_barrier
	v_lshl_add_u64 v[158:159], v[236:237], 0, s[74:75]
	s_add_u32 m0, s22, 0x14000
	s_nop 0
	global_load_lds_dwordx4 v[158:159], off
	v_lshl_add_u64 v[158:159], v[238:239], 0, s[74:75]
	s_add_u32 m0, s22, 0x16000
	s_nop 0
	global_load_lds_dwordx4 v[158:159], off
	s_waitcnt vmcnt(6)
	s_barrier
	s_setprio 1
	v_mfma_f32_16x16x32_bf16 v[28:31], v[212:215], v[180:183], v[28:31]
	v_mfma_f32_16x16x32_bf16 v[24:27], v[222:225], v[180:183], v[24:27]
	v_mfma_f32_16x16x32_bf16 v[20:23], v[212:215], v[188:191], v[20:23]
	v_mfma_f32_16x16x32_bf16 v[16:19], v[222:225], v[188:191], v[16:19]
	v_mfma_f32_16x16x32_bf16 v[12:15], v[212:215], v[196:199], v[12:15]
	v_mfma_f32_16x16x32_bf16 v[8:11], v[222:225], v[196:199], v[8:11]
	v_mfma_f32_16x16x32_bf16 v[4:7], v[212:215], v[204:207], v[4:7]
	v_mfma_f32_16x16x32_bf16 v[0:3], v[222:225], v[204:207], v[0:3]
	v_mfma_f32_16x16x32_bf16 v[28:31], v[216:219], v[184:187], v[28:31]
	v_mfma_f32_16x16x32_bf16 v[24:27], v[226:229], v[184:187], v[24:27]
	v_mfma_f32_16x16x32_bf16 v[20:23], v[216:219], v[192:195], v[20:23]
	v_mfma_f32_16x16x32_bf16 v[16:19], v[226:229], v[192:195], v[16:19]
	v_mfma_f32_16x16x32_bf16 v[12:15], v[216:219], v[200:203], v[12:15]
	v_mfma_f32_16x16x32_bf16 v[8:11], v[226:229], v[200:203], v[8:11]
	v_mfma_f32_16x16x32_bf16 v[4:7], v[216:219], v[208:211], v[4:7]
	v_mfma_f32_16x16x32_bf16 v[0:3], v[226:229], v[208:211], v[0:3]
	s_setprio 0
	s_barrier
	ds_read_b128 v[158:161], v145
	ds_read_b128 v[162:165], v145 offset:1024
	ds_read_b128 v[166:169], v145 offset:2048
	ds_read_b128 v[170:173], v145 offset:3072
	v_lshl_add_u64 v[212:213], v[174:175], 0, s[74:75]
	s_add_u32 m0, s22, 0x4000
	ds_read_b128 v[180:183], v142 offset:32768
	ds_read_b128 v[184:187], v142 offset:33792
	ds_read_b128 v[188:191], v141 offset:32768
	ds_read_b128 v[192:195], v141 offset:33792
	ds_read_b128 v[196:199], v140 offset:32768
	ds_read_b128 v[200:203], v140 offset:33792
	ds_read_b128 v[204:207], v139 offset:32768
	ds_read_b128 v[208:211], v139 offset:33792
	global_load_lds_dwordx4 v[212:213], off
	v_lshl_add_u64 v[212:213], v[234:235], 0, s[74:75]
	s_add_u32 m0, s22, 0x6000
	s_nop 0
	global_load_lds_dwordx4 v[212:213], off
	s_waitcnt lgkmcnt(8)
	s_barrier
	s_waitcnt lgkmcnt(0)
	s_setprio 1
	s_waitcnt lgkmcnt(0)
	v_mfma_f32_16x16x32_bf16 v[124:127], v[158:161], v[180:183], v[124:127]
	v_mfma_f32_16x16x32_bf16 v[120:123], v[166:169], v[180:183], v[120:123]
	v_mfma_f32_16x16x32_bf16 v[116:119], v[158:161], v[188:191], v[116:119]
	v_mfma_f32_16x16x32_bf16 v[112:115], v[166:169], v[188:191], v[112:115]
	v_mfma_f32_16x16x32_bf16 v[108:111], v[158:161], v[196:199], v[108:111]
	v_mfma_f32_16x16x32_bf16 v[104:107], v[166:169], v[196:199], v[104:107]
	v_mfma_f32_16x16x32_bf16 v[100:103], v[158:161], v[204:207], v[100:103]
	v_mfma_f32_16x16x32_bf16 v[96:99], v[166:169], v[204:207], v[96:99]
	v_mfma_f32_16x16x32_bf16 v[124:127], v[162:165], v[184:187], v[124:127]
	v_mfma_f32_16x16x32_bf16 v[120:123], v[170:173], v[184:187], v[120:123]
	v_mfma_f32_16x16x32_bf16 v[116:119], v[162:165], v[192:195], v[116:119]
	v_mfma_f32_16x16x32_bf16 v[112:115], v[170:173], v[192:195], v[112:115]
	v_mfma_f32_16x16x32_bf16 v[108:111], v[162:165], v[200:203], v[108:111]
	v_mfma_f32_16x16x32_bf16 v[104:107], v[170:173], v[200:203], v[104:107]
	v_mfma_f32_16x16x32_bf16 v[100:103], v[162:165], v[208:211], v[100:103]
	v_mfma_f32_16x16x32_bf16 v[96:99], v[170:173], v[208:211], v[96:99]
	s_setprio 0
	s_barrier
	v_lshl_add_u64 v[240:241], v[236:237], 0, s[68:69]
	s_add_u32 m0, s22, 0x18000
	ds_read_b128 v[212:215], v143
	ds_read_b128 v[216:219], v143 offset:1024
	ds_read_b128 v[222:225], v143 offset:2048
	ds_read_b128 v[226:229], v143 offset:3072
	global_load_lds_dwordx4 v[240:241], off
	v_lshl_add_u64 v[240:241], v[238:239], 0, s[68:69]
	s_add_u32 m0, s22, 0x1a000
	s_nop 0
	global_load_lds_dwordx4 v[240:241], off
	s_barrier
; #define STAGE_A(P, half, kt) do { const char* _u = Ab + ((size_t)(half) * 128 * lda + (size_t)(kt) * BK) * 2; \
;     _Pragma("unroll") for (int _i = 0; _i < 2; ++_i) \
;       __builtin_amdgcn_global_load_lds((const unsigned*)(_u + offA[_i]), \
;         (__attribute__((address_space(3))) unsigned*)((__attribute__((address_space(3))) char*)(P) + tidg * 16 + _i * 8192), 16, 0, 0); } while (0)
; #define STAGE_B(P, half, kt) do { const char* _u = Bb + ((size_t)(half) * 128 * ldb + (size_t)(kt) * BK) * 2; \
;     _Pragma("unroll") for (int _i = 0; _i < 2; ++_i) \
;       __builtin_amdgcn_global_load_lds((const unsigned*)(_u + offB[_i]), \
;         (__attribute__((address_space(3))) unsigned*)((__attribute__((address_space(3))) char*)(P) + tidg * 16 + _i * 8192), 16, 0, 0); } while (0)
; #define LDA(dst, b, h) _Pragma("unroll") for (int m = 0; m < 4; ++m) _Pragma("unroll") for (int k = 0; k < 2; ++k) \
;     dst[m][k] = *reinterpret_cast<const bf16x8*>((const char*)SA(b, h) + lds_byte(wr * 64 + m * 16 + fr, k * 32 + fq * 8))
; #define LDB(dst, b, h) _Pragma("unroll") for (int n = 0; n < 2; ++n) _Pragma("unroll") for (int k = 0; k < 2; ++k) \
;     dst[n][k] = *reinterpret_cast<const bf16x8*>((const char*)SB(b, h) + lds_byte(wc * 32 + n * 16 + fr, k * 32 + fq * 8))
; #define MMA(ai, bj, At_, Bt_) do { __builtin_amdgcn_s_setprio(1); \
;     _Pragma("unroll") for (int m = 0; m < 4; ++m) _Pragma("unroll") for (int n = 0; n < 2; ++n) _Pragma("unroll") for (int k = 0; k < 2; ++k) \
;       acc[ai][bj][m][n] = __builtin_amdgcn_mfma_f32_16x16x32_bf16(Bt_[n][k], At_[m][k], acc[ai][bj][m][n], 0, 0, 0); \
;     __builtin_amdgcn_s_setprio(0); } while (0)
; #define WAIT_V(n) asm volatile("s_waitcnt vmcnt(" #n ")" ::: "memory")
; template <bool PF = true, class Epi, class KRF = KRFull>
; __device__ __forceinline__ void gemm_phase(const u16* __restrict__ A, int lda, const u16* __restrict__ Bt, int ldb, int K, int nM, int nN,
;                                            lds_u16* shm, Epi epi, KRF krf = KRFull(), bool flip = false) {
;     ...
;       BAR; WAIT_L(0); MMA(0, 1, At, B1); BAR;
;       LDA(At, 1, 1); STAGE_A(SA(1, 0), 0, t + 3);
;       BAR; WAIT_L(0); MMA(1, 0, At, B0); BAR; SCHED;
;       STAGE_B(SB(1, 1), 1, t + 3);
;       WAIT_V(6); BAR; MMA(1, 1, At, B1); BAR;
;     }
;     { LDB(B0, 0, 0); LDA(At, 0, 0); STAGE_A(SA(1, 1), 1, nt - 1);
	s_waitcnt lgkmcnt(0)
	s_setprio 1
	s_waitcnt lgkmcnt(0)
	v_mfma_f32_16x16x32_bf16 v[92:95], v[212:215], v[180:183], v[92:95]
	v_mfma_f32_16x16x32_bf16 v[88:91], v[222:225], v[180:183], v[88:91]
	v_mfma_f32_16x16x32_bf16 v[84:87], v[212:215], v[188:191], v[84:87]
	v_mfma_f32_16x16x32_bf16 v[80:83], v[222:225], v[188:191], v[80:83]
	v_mfma_f32_16x16x32_bf16 v[76:79], v[212:215], v[196:199], v[76:79]
	v_mfma_f32_16x16x32_bf16 v[72:75], v[222:225], v[196:199], v[72:75]
	v_mfma_f32_16x16x32_bf16 v[68:71], v[212:215], v[204:207], v[68:71]
	v_mfma_f32_16x16x32_bf16 v[64:67], v[222:225], v[204:207], v[64:67]
	v_mfma_f32_16x16x32_bf16 v[92:95], v[216:219], v[184:187], v[92:95]
	v_mfma_f32_16x16x32_bf16 v[88:91], v[226:229], v[184:187], v[88:91]
	v_mfma_f32_16x16x32_bf16 v[84:87], v[216:219], v[192:195], v[84:87]
	v_mfma_f32_16x16x32_bf16 v[80:83], v[226:229], v[192:195], v[80:83]
	v_mfma_f32_16x16x32_bf16 v[76:79], v[216:219], v[200:203], v[76:79]
	v_mfma_f32_16x16x32_bf16 v[72:75], v[226:229], v[200:203], v[72:75]
	v_mfma_f32_16x16x32_bf16 v[68:71], v[216:219], v[208:211], v[68:71]
	v_mfma_f32_16x16x32_bf16 v[64:67], v[226:229], v[208:211], v[64:67]
	s_setprio 0
	v_lshl_add_u64 v[174:175], v[174:175], 0, s[68:69]
	s_add_u32 m0, s22, 0x8000
	s_barrier
	ds_read_b128 v[180:183], v142 offset:49152
	ds_read_b128 v[184:187], v142 offset:50176
	ds_read_b128 v[188:191], v141 offset:49152
	ds_read_b128 v[192:195], v141 offset:50176
	ds_read_b128 v[196:199], v140 offset:49152
	ds_read_b128 v[200:203], v140 offset:50176
	ds_read_b128 v[204:207], v139 offset:49152
	ds_read_b128 v[208:211], v139 offset:50176
	global_load_lds_dwordx4 v[174:175], off
	v_lshl_add_u64 v[174:175], v[234:235], 0, s[68:69]
	s_add_u32 m0, s22, 0xa000
	s_nop 0
	global_load_lds_dwordx4 v[174:175], off
	s_barrier
	s_waitcnt lgkmcnt(0)
	s_setprio 1
	s_waitcnt lgkmcnt(0)
	v_mfma_f32_16x16x32_bf16 v[60:63], v[158:161], v[180:183], v[60:63]
	v_mfma_f32_16x16x32_bf16 v[56:59], v[166:169], v[180:183], v[56:59]
	v_mfma_f32_16x16x32_bf16 v[52:55], v[158:161], v[188:191], v[52:55]
	v_mfma_f32_16x16x32_bf16 v[48:51], v[166:169], v[188:191], v[48:51]
	v_mfma_f32_16x16x32_bf16 v[44:47], v[158:161], v[196:199], v[44:47]
	v_mfma_f32_16x16x32_bf16 v[40:43], v[166:169], v[196:199], v[40:43]
	v_mfma_f32_16x16x32_bf16 v[36:39], v[158:161], v[204:207], v[36:39]
	v_mfma_f32_16x16x32_bf16 v[32:35], v[166:169], v[204:207], v[32:35]
	v_mfma_f32_16x16x32_bf16 v[60:63], v[162:165], v[184:187], v[60:63]
	v_mfma_f32_16x16x32_bf16 v[56:59], v[170:173], v[184:187], v[56:59]
	v_mfma_f32_16x16x32_bf16 v[52:55], v[162:165], v[192:195], v[52:55]
	v_mfma_f32_16x16x32_bf16 v[48:51], v[170:173], v[192:195], v[48:51]
	v_mfma_f32_16x16x32_bf16 v[44:47], v[162:165], v[200:203], v[44:47]
	v_mfma_f32_16x16x32_bf16 v[40:43], v[170:173], v[200:203], v[40:43]
	v_mfma_f32_16x16x32_bf16 v[36:39], v[162:165], v[208:211], v[36:39]
	v_mfma_f32_16x16x32_bf16 v[32:35], v[170:173], v[208:211], v[32:35]
	s_setprio 0
	s_barrier
	v_lshl_add_u64 v[158:159], v[236:237], 0, s[76:77]
	s_add_u32 m0, s22, 0x1c000
	s_nop 0
	global_load_lds_dwordx4 v[158:159], off
	v_lshl_add_u64 v[158:159], v[238:239], 0, s[76:77]
	s_add_u32 m0, s22, 0x1e000
	s_nop 0
	global_load_lds_dwordx4 v[158:159], off
	s_waitcnt vmcnt(6)
	s_barrier
	s_setprio 1
	v_mfma_f32_16x16x32_bf16 v[28:31], v[212:215], v[180:183], v[28:31]
	v_mfma_f32_16x16x32_bf16 v[24:27], v[222:225], v[180:183], v[24:27]
	v_mfma_f32_16x16x32_bf16 v[20:23], v[212:215], v[188:191], v[20:23]
	v_mfma_f32_16x16x32_bf16 v[16:19], v[222:225], v[188:191], v[16:19]
	v_mfma_f32_16x16x32_bf16 v[12:15], v[212:215], v[196:199], v[12:15]
	v_mfma_f32_16x16x32_bf16 v[8:11], v[222:225], v[196:199], v[8:11]
	v_mfma_f32_16x16x32_bf16 v[4:7], v[212:215], v[204:207], v[4:7]
	v_mfma_f32_16x16x32_bf16 v[0:3], v[222:225], v[204:207], v[0:3]
	v_mfma_f32_16x16x32_bf16 v[28:31], v[216:219], v[184:187], v[28:31]
	v_mfma_f32_16x16x32_bf16 v[24:27], v[226:229], v[184:187], v[24:27]
	v_mfma_f32_16x16x32_bf16 v[20:23], v[216:219], v[192:195], v[20:23]
	v_mfma_f32_16x16x32_bf16 v[16:19], v[226:229], v[192:195], v[16:19]
	v_mfma_f32_16x16x32_bf16 v[12:15], v[216:219], v[200:203], v[12:15]
	v_mfma_f32_16x16x32_bf16 v[8:11], v[226:229], v[200:203], v[8:11]
	v_mfma_f32_16x16x32_bf16 v[4:7], v[216:219], v[208:211], v[4:7]
	v_mfma_f32_16x16x32_bf16 v[0:3], v[226:229], v[208:211], v[0:3]
	s_setprio 0
	s_add_i32 s21, s21, 2
	s_add_u32 s12, s12, 0x100
	s_addc_u32 s13, s13, 0
	s_cmpk_gt_u32 s21, 0x53
	s_barrier
	s_cbranch_scc0 .LBB0_2580
	v_add_u32_e32 v155, 0xc000, v144
	v_add_u32_e32 v156, 0xe000, v144
	v_add_u32_e32 v157, 0x6000, v144
	s_add_u32 s12, s6, 0x162b80
	s_addc_u32 s13, s7, 0
	v_readfirstlane_b32 s21, v155
	v_lshl_add_u64 v[150:151], s[12:13], 0, v[178:179]
	s_mov_b32 m0, s21
	v_lshl_add_u64 v[128:129], s[12:13], 0, v[128:129]
	v_readfirstlane_b32 s12, v156
	ds_read_b128 v[130:133], v154
	ds_read_b128 v[134:137], v154 offset:1024
	ds_read_b128 v[146:149], v154 offset:2048
	ds_read_b128 v[158:161], v154 offset:3072
	ds_read_b128 v[162:165], v142
	ds_read_b128 v[166:169], v142 offset:1024
	ds_read_b128 v[170:173], v141
	ds_read_b128 v[180:183], v141 offset:1024
	ds_read_b128 v[184:187], v140
	ds_read_b128 v[188:191], v140 offset:1024
	ds_read_b128 v[192:195], v139
	ds_read_b128 v[196:199], v139 offset:1024
	global_load_lds_dwordx4 v[150:151], off
	s_mov_b32 m0, s12
	s_nop 0
	global_load_lds_dwordx4 v[128:129], off
	s_barrier
; #define LDA(dst, b, h) _Pragma("unroll") for (int m = 0; m < 4; ++m) _Pragma("unroll") for (int k = 0; k < 2; ++k) \
;     dst[m][k] = *reinterpret_cast<const bf16x8*>((const char*)SA(b, h) + lds_byte(wr * 64 + m * 16 + fr, k * 32 + fq * 8))
; #define LDB(dst, b, h) _Pragma("unroll") for (int n = 0; n < 2; ++n) _Pragma("unroll") for (int k = 0; k < 2; ++k) \
;     dst[n][k] = *reinterpret_cast<const bf16x8*>((const char*)SB(b, h) + lds_byte(wc * 32 + n * 16 + fr, k * 32 + fq * 8))
; #define MMA(ai, bj, At_, Bt_) do { __builtin_amdgcn_s_setprio(1); \
;     _Pragma("unroll") for (int m = 0; m < 4; ++m) _Pragma("unroll") for (int n = 0; n < 2; ++n) _Pragma("unroll") for (int k = 0; k < 2; ++k) \
;       acc[ai][bj][m][n] = __builtin_amdgcn_mfma_f32_16x16x32_bf16(Bt_[n][k], At_[m][k], acc[ai][bj][m][n], 0, 0, 0); \
;     __builtin_amdgcn_s_setprio(0); } while (0)
; #define WAIT_V(n) asm volatile("s_waitcnt vmcnt(" #n ")" ::: "memory")
; #define WAIT_L(n) asm volatile("s_waitcnt lgkmcnt(" #n ")" ::: "memory")
; #define BAR __builtin_amdgcn_s_barrier()
; template <bool PF = true, class Epi, class KRF = KRFull>
; __device__ __forceinline__ void gemm_phase(const u16* __restrict__ A, int lda, const u16* __restrict__ Bt, int ldb, int K, int nM, int nN,
;                                            lds_u16* shm, Epi epi, KRF krf = KRFull(), bool flip = false) {
;     ...
;       BAR; WAIT_L(0); MMA(0, 0, At, B0); BAR;
;       LDB(B1, 0, 1); BAR; WAIT_L(0); MMA(0, 1, At, B1); BAR;
;       LDA(At, 0, 1); WAIT_V(4); BAR; WAIT_L(0); MMA(1, 0, At, B0); MMA(1, 1, At, B1); BAR; }
;     { LDB(B0, 1, 0); LDA(At, 1, 0); WAIT_V(2); BAR; WAIT_L(0); MMA(0, 0, At, B0); BAR;
	s_waitcnt lgkmcnt(0)
	s_setprio 1
	s_waitcnt lgkmcnt(0)
	v_mfma_f32_16x16x32_bf16 v[124:127], v[130:133], v[162:165], v[124:127]
	v_mfma_f32_16x16x32_bf16 v[120:123], v[146:149], v[162:165], v[120:123]
	v_mfma_f32_16x16x32_bf16 v[116:119], v[130:133], v[170:173], v[116:119]
	v_mfma_f32_16x16x32_bf16 v[112:115], v[146:149], v[170:173], v[112:115]
	v_mfma_f32_16x16x32_bf16 v[108:111], v[130:133], v[184:187], v[108:111]
	v_mfma_f32_16x16x32_bf16 v[104:107], v[146:149], v[184:187], v[104:107]
	v_mfma_f32_16x16x32_bf16 v[100:103], v[130:133], v[192:195], v[100:103]
	v_mfma_f32_16x16x32_bf16 v[96:99], v[146:149], v[192:195], v[96:99]
	v_mfma_f32_16x16x32_bf16 v[124:127], v[134:137], v[166:169], v[124:127]
	v_mfma_f32_16x16x32_bf16 v[120:123], v[158:161], v[166:169], v[120:123]
	v_mfma_f32_16x16x32_bf16 v[116:119], v[134:137], v[180:183], v[116:119]
	v_mfma_f32_16x16x32_bf16 v[112:115], v[158:161], v[180:183], v[112:115]
	v_mfma_f32_16x16x32_bf16 v[108:111], v[134:137], v[188:191], v[108:111]
	v_mfma_f32_16x16x32_bf16 v[104:107], v[158:161], v[188:191], v[104:107]
	v_mfma_f32_16x16x32_bf16 v[100:103], v[134:137], v[196:199], v[100:103]
	v_mfma_f32_16x16x32_bf16 v[96:99], v[158:161], v[196:199], v[96:99]
	s_setprio 0
	s_barrier
	ds_read_b128 v[154:157], v153
	ds_read_b128 v[200:203], v153 offset:1024
	ds_read_b128 v[204:207], v153 offset:2048
	ds_read_b128 v[150:153], v153 offset:3072
	s_barrier
	s_waitcnt lgkmcnt(0)
	s_setprio 1
	s_waitcnt lgkmcnt(0)
	v_mfma_f32_16x16x32_bf16 v[92:95], v[154:157], v[162:165], v[92:95]
	v_mfma_f32_16x16x32_bf16 v[88:91], v[204:207], v[162:165], v[88:91]
	v_mfma_f32_16x16x32_bf16 v[84:87], v[154:157], v[170:173], v[84:87]
	v_mfma_f32_16x16x32_bf16 v[80:83], v[204:207], v[170:173], v[80:83]
	v_mfma_f32_16x16x32_bf16 v[76:79], v[154:157], v[184:187], v[76:79]
	v_mfma_f32_16x16x32_bf16 v[72:75], v[204:207], v[184:187], v[72:75]
	v_mfma_f32_16x16x32_bf16 v[68:71], v[154:157], v[192:195], v[68:71]
	v_mfma_f32_16x16x32_bf16 v[64:67], v[204:207], v[192:195], v[64:67]
	v_mfma_f32_16x16x32_bf16 v[92:95], v[200:203], v[166:169], v[92:95]
	v_mfma_f32_16x16x32_bf16 v[88:91], v[150:153], v[166:169], v[88:91]
	v_mfma_f32_16x16x32_bf16 v[84:87], v[200:203], v[180:183], v[84:87]
	v_mfma_f32_16x16x32_bf16 v[80:83], v[150:153], v[180:183], v[80:83]
	v_mfma_f32_16x16x32_bf16 v[76:79], v[200:203], v[188:191], v[76:79]
	v_mfma_f32_16x16x32_bf16 v[72:75], v[150:153], v[188:191], v[72:75]
	v_mfma_f32_16x16x32_bf16 v[68:71], v[200:203], v[196:199], v[68:71]
	v_mfma_f32_16x16x32_bf16 v[64:67], v[150:153], v[196:199], v[64:67]
	s_setprio 0
	s_barrier
	ds_read_b128 v[162:165], v142 offset:16384
	ds_read_b128 v[166:169], v142 offset:17408
	ds_read_b128 v[170:173], v141 offset:16384
	ds_read_b128 v[180:183], v141 offset:17408
	ds_read_b128 v[184:187], v140 offset:16384
	ds_read_b128 v[188:191], v140 offset:17408
	ds_read_b128 v[192:195], v139 offset:16384
	ds_read_b128 v[196:199], v139 offset:17408
	s_waitcnt vmcnt(4)
	s_barrier
	s_waitcnt lgkmcnt(0)
	s_setprio 1
	s_waitcnt lgkmcnt(0)
	v_mfma_f32_16x16x32_bf16 v[60:63], v[130:133], v[162:165], v[60:63]
	v_mfma_f32_16x16x32_bf16 v[56:59], v[146:149], v[162:165], v[56:59]
	v_mfma_f32_16x16x32_bf16 v[52:55], v[130:133], v[170:173], v[52:55]
	v_mfma_f32_16x16x32_bf16 v[48:51], v[146:149], v[170:173], v[48:51]
	v_mfma_f32_16x16x32_bf16 v[44:47], v[130:133], v[184:187], v[44:47]
	v_mfma_f32_16x16x32_bf16 v[40:43], v[146:149], v[184:187], v[40:43]
	v_mfma_f32_16x16x32_bf16 v[36:39], v[130:133], v[192:195], v[36:39]
	v_mfma_f32_16x16x32_bf16 v[32:35], v[146:149], v[192:195], v[32:35]
	v_mfma_f32_16x16x32_bf16 v[60:63], v[134:137], v[166:169], v[60:63]
	v_mfma_f32_16x16x32_bf16 v[56:59], v[158:161], v[166:169], v[56:59]
	v_mfma_f32_16x16x32_bf16 v[52:55], v[134:137], v[180:183], v[52:55]
	v_mfma_f32_16x16x32_bf16 v[48:51], v[158:161], v[180:183], v[48:51]
	v_mfma_f32_16x16x32_bf16 v[44:47], v[134:137], v[188:191], v[44:47]
	v_mfma_f32_16x16x32_bf16 v[40:43], v[158:161], v[188:191], v[40:43]
	v_mfma_f32_16x16x32_bf16 v[36:39], v[134:137], v[196:199], v[36:39]
	v_mfma_f32_16x16x32_bf16 v[32:35], v[158:161], v[196:199], v[32:35]
	s_setprio 0
	s_setprio 1
	v_mfma_f32_16x16x32_bf16 v[28:31], v[154:157], v[162:165], v[28:31]
	v_mfma_f32_16x16x32_bf16 v[24:27], v[204:207], v[162:165], v[24:27]
	v_mfma_f32_16x16x32_bf16 v[20:23], v[154:157], v[170:173], v[20:23]
	v_mfma_f32_16x16x32_bf16 v[16:19], v[204:207], v[170:173], v[16:19]
	v_mfma_f32_16x16x32_bf16 v[12:15], v[154:157], v[184:187], v[12:15]
	v_mfma_f32_16x16x32_bf16 v[8:11], v[204:207], v[184:187], v[8:11]
	v_mfma_f32_16x16x32_bf16 v[4:7], v[154:157], v[192:195], v[4:7]
	v_mfma_f32_16x16x32_bf16 v[0:3], v[204:207], v[192:195], v[0:3]
	v_mfma_f32_16x16x32_bf16 v[28:31], v[200:203], v[166:169], v[28:31]
	v_mfma_f32_16x16x32_bf16 v[24:27], v[150:153], v[166:169], v[24:27]
	v_mfma_f32_16x16x32_bf16 v[20:23], v[200:203], v[180:183], v[20:23]
	v_mfma_f32_16x16x32_bf16 v[16:19], v[150:153], v[180:183], v[16:19]
	v_mfma_f32_16x16x32_bf16 v[12:15], v[200:203], v[188:191], v[12:15]
	v_mfma_f32_16x16x32_bf16 v[8:11], v[150:153], v[188:191], v[8:11]
	v_mfma_f32_16x16x32_bf16 v[4:7], v[200:203], v[196:199], v[4:7]
	v_mfma_f32_16x16x32_bf16 v[0:3], v[150:153], v[196:199], v[0:3]
	s_setprio 0
	s_barrier
	ds_read_b128 v[128:131], v145
	ds_read_b128 v[132:135], v145 offset:1024
	ds_read_b128 v[146:149], v145 offset:2048
	ds_read_b128 v[150:153], v145 offset:3072
	ds_read_b128 v[154:157], v142 offset:32768
	ds_read_b128 v[158:161], v142 offset:33792
	ds_read_b128 v[162:165], v141 offset:32768
	ds_read_b128 v[166:169], v141 offset:33792
	ds_read_b128 v[170:173], v140 offset:32768
	ds_read_b128 v[180:183], v140 offset:33792
	ds_read_b128 v[184:187], v139 offset:32768
	ds_read_b128 v[188:191], v139 offset:33792
	s_waitcnt vmcnt(2)
	s_barrier
; #define LDA(dst, b, h) _Pragma("unroll") for (int m = 0; m < 4; ++m) _Pragma("unroll") for (int k = 0; k < 2; ++k) \
;     dst[m][k] = *reinterpret_cast<const bf16x8*>((const char*)SA(b, h) + lds_byte(wr * 64 + m * 16 + fr, k * 32 + fq * 8))
; #define LDB(dst, b, h) _Pragma("unroll") for (int n = 0; n < 2; ++n) _Pragma("unroll") for (int k = 0; k < 2; ++k) \
;     dst[n][k] = *reinterpret_cast<const bf16x8*>((const char*)SB(b, h) + lds_byte(wc * 32 + n * 16 + fr, k * 32 + fq * 8))
; #define MMA(ai, bj, At_, Bt_) do { __builtin_amdgcn_s_setprio(1); \
;     _Pragma("unroll") for (int m = 0; m < 4; ++m) _Pragma("unroll") for (int n = 0; n < 2; ++n) _Pragma("unroll") for (int k = 0; k < 2; ++k) \
;       acc[ai][bj][m][n] = __builtin_amdgcn_mfma_f32_16x16x32_bf16(Bt_[n][k], At_[m][k], acc[ai][bj][m][n], 0, 0, 0); \
;     __builtin_amdgcn_s_setprio(0); } while (0)
; #define WAIT_V(n) asm volatile("s_waitcnt vmcnt(" #n ")" ::: "memory")
; #define WAIT_L(n) asm volatile("s_waitcnt lgkmcnt(" #n ")" ::: "memory")
; #define BAR __builtin_amdgcn_s_barrier()
; template <bool PF = true, class Epi, class KRF = KRFull>
; __device__ __forceinline__ void gemm_phase(const u16* __restrict__ A, int lda, const u16* __restrict__ Bt, int ldb, int K, int nM, int nN,
;                                            lds_u16* shm, Epi epi, KRF krf = KRFull(), bool flip = false) {
;     ...
;     { LDB(B0, 1, 0); LDA(At, 1, 0); WAIT_V(2); BAR; WAIT_L(0); MMA(0, 0, At, B0); BAR;
;       LDB(B1, 1, 1); WAIT_V(0); BAR; WAIT_L(0); MMA(0, 1, At, B1); BAR;
;       LDA(At, 1, 1); BAR; WAIT_L(0); MMA(1, 0, At, B0); MMA(1, 1, At, B1); BAR; }
;     if (wr == 0) BAR;
	s_waitcnt lgkmcnt(0)
	s_setprio 1
	s_waitcnt lgkmcnt(0)
	v_mfma_f32_16x16x32_bf16 v[124:127], v[128:131], v[154:157], v[124:127]
	v_mfma_f32_16x16x32_bf16 v[120:123], v[146:149], v[154:157], v[120:123]
	v_mfma_f32_16x16x32_bf16 v[116:119], v[128:131], v[162:165], v[116:119]
	v_mfma_f32_16x16x32_bf16 v[112:115], v[146:149], v[162:165], v[112:115]
	v_mfma_f32_16x16x32_bf16 v[108:111], v[128:131], v[170:173], v[108:111]
	v_mfma_f32_16x16x32_bf16 v[104:107], v[146:149], v[170:173], v[104:107]
	v_mfma_f32_16x16x32_bf16 v[100:103], v[128:131], v[184:187], v[100:103]
	v_mfma_f32_16x16x32_bf16 v[96:99], v[146:149], v[184:187], v[96:99]
	v_mfma_f32_16x16x32_bf16 v[124:127], v[132:135], v[158:161], v[124:127]
	v_mfma_f32_16x16x32_bf16 v[120:123], v[150:153], v[158:161], v[120:123]
	v_mfma_f32_16x16x32_bf16 v[116:119], v[132:135], v[166:169], v[116:119]
	v_mfma_f32_16x16x32_bf16 v[112:115], v[150:153], v[166:169], v[112:115]
	v_mfma_f32_16x16x32_bf16 v[108:111], v[132:135], v[180:183], v[108:111]
	v_mfma_f32_16x16x32_bf16 v[104:107], v[150:153], v[180:183], v[104:107]
	v_mfma_f32_16x16x32_bf16 v[100:103], v[132:135], v[188:191], v[100:103]
	v_mfma_f32_16x16x32_bf16 v[96:99], v[150:153], v[188:191], v[96:99]
	s_setprio 0
	s_barrier
	ds_read_b128 v[192:195], v143
	ds_read_b128 v[196:199], v143 offset:1024
	ds_read_b128 v[200:203], v143 offset:2048
	ds_read_b128 v[204:207], v143 offset:3072
	s_waitcnt vmcnt(0)
	s_barrier
	s_waitcnt lgkmcnt(0)
	s_setprio 1
	s_waitcnt lgkmcnt(0)
	v_mfma_f32_16x16x32_bf16 v[92:95], v[192:195], v[154:157], v[92:95]
	v_mfma_f32_16x16x32_bf16 v[88:91], v[200:203], v[154:157], v[88:91]
	v_mfma_f32_16x16x32_bf16 v[84:87], v[192:195], v[162:165], v[84:87]
	v_mfma_f32_16x16x32_bf16 v[80:83], v[200:203], v[162:165], v[80:83]
	v_mfma_f32_16x16x32_bf16 v[76:79], v[192:195], v[170:173], v[76:79]
	v_mfma_f32_16x16x32_bf16 v[72:75], v[200:203], v[170:173], v[72:75]
	v_mfma_f32_16x16x32_bf16 v[68:71], v[192:195], v[184:187], v[68:71]
	v_mfma_f32_16x16x32_bf16 v[64:67], v[200:203], v[184:187], v[64:67]
	v_mfma_f32_16x16x32_bf16 v[92:95], v[196:199], v[158:161], v[92:95]
	v_mfma_f32_16x16x32_bf16 v[88:91], v[204:207], v[158:161], v[88:91]
	v_mfma_f32_16x16x32_bf16 v[84:87], v[196:199], v[166:169], v[84:87]
	v_mfma_f32_16x16x32_bf16 v[80:83], v[204:207], v[166:169], v[80:83]
	v_mfma_f32_16x16x32_bf16 v[76:79], v[196:199], v[180:183], v[76:79]
	v_mfma_f32_16x16x32_bf16 v[72:75], v[204:207], v[180:183], v[72:75]
	v_mfma_f32_16x16x32_bf16 v[68:71], v[196:199], v[188:191], v[68:71]
	v_mfma_f32_16x16x32_bf16 v[64:67], v[204:207], v[188:191], v[64:67]
	s_setprio 0
	s_barrier
	ds_read_b128 v[154:157], v142 offset:49152
	ds_read_b128 v[142:145], v142 offset:50176
	ds_read_b128 v[158:161], v141 offset:49152
	ds_read_b128 v[162:165], v141 offset:50176
	ds_read_b128 v[166:169], v140 offset:49152
	ds_read_b128 v[170:173], v140 offset:50176
	ds_read_b128 v[180:183], v139 offset:49152
	ds_read_b128 v[184:187], v139 offset:50176
	s_barrier
	s_waitcnt lgkmcnt(0)
	s_setprio 1
	s_waitcnt lgkmcnt(0)
	v_mfma_f32_16x16x32_bf16 v[60:63], v[128:131], v[154:157], v[60:63]
	v_mfma_f32_16x16x32_bf16 v[56:59], v[146:149], v[154:157], v[56:59]
	v_mfma_f32_16x16x32_bf16 v[52:55], v[128:131], v[158:161], v[52:55]
	v_mfma_f32_16x16x32_bf16 v[48:51], v[146:149], v[158:161], v[48:51]
	v_mfma_f32_16x16x32_bf16 v[44:47], v[128:131], v[166:169], v[44:47]
	v_mfma_f32_16x16x32_bf16 v[40:43], v[146:149], v[166:169], v[40:43]
	v_mfma_f32_16x16x32_bf16 v[36:39], v[128:131], v[180:183], v[36:39]
	v_mfma_f32_16x16x32_bf16 v[32:35], v[146:149], v[180:183], v[32:35]
	v_mfma_f32_16x16x32_bf16 v[60:63], v[132:135], v[142:145], v[60:63]
	v_mfma_f32_16x16x32_bf16 v[56:59], v[150:153], v[142:145], v[56:59]
	v_mfma_f32_16x16x32_bf16 v[52:55], v[132:135], v[162:165], v[52:55]
	v_mfma_f32_16x16x32_bf16 v[48:51], v[150:153], v[162:165], v[48:51]
	v_mfma_f32_16x16x32_bf16 v[44:47], v[132:135], v[170:173], v[44:47]
	v_mfma_f32_16x16x32_bf16 v[40:43], v[150:153], v[170:173], v[40:43]
	v_mfma_f32_16x16x32_bf16 v[36:39], v[132:135], v[184:187], v[36:39]
	v_mfma_f32_16x16x32_bf16 v[32:35], v[150:153], v[184:187], v[32:35]
	s_setprio 0
	s_setprio 1
	v_mfma_f32_16x16x32_bf16 v[28:31], v[192:195], v[154:157], v[28:31]
	v_mfma_f32_16x16x32_bf16 v[24:27], v[200:203], v[154:157], v[24:27]
	v_mfma_f32_16x16x32_bf16 v[20:23], v[192:195], v[158:161], v[20:23]
	v_mfma_f32_16x16x32_bf16 v[16:19], v[200:203], v[158:161], v[16:19]
	v_mfma_f32_16x16x32_bf16 v[12:15], v[192:195], v[166:169], v[12:15]
	v_mfma_f32_16x16x32_bf16 v[8:11], v[200:203], v[166:169], v[8:11]
	v_mfma_f32_16x16x32_bf16 v[4:7], v[192:195], v[180:183], v[4:7]
	v_mfma_f32_16x16x32_bf16 v[0:3], v[200:203], v[180:183], v[0:3]
	v_mfma_f32_16x16x32_bf16 v[28:31], v[196:199], v[142:145], v[28:31]
	v_mfma_f32_16x16x32_bf16 v[24:27], v[204:207], v[142:145], v[24:27]
	v_mfma_f32_16x16x32_bf16 v[20:23], v[196:199], v[162:165], v[20:23]
	v_mfma_f32_16x16x32_bf16 v[16:19], v[204:207], v[162:165], v[16:19]
	v_mfma_f32_16x16x32_bf16 v[12:15], v[196:199], v[170:173], v[12:15]
	v_mfma_f32_16x16x32_bf16 v[8:11], v[204:207], v[170:173], v[8:11]
	v_mfma_f32_16x16x32_bf16 v[4:7], v[196:199], v[184:187], v[4:7]
	v_mfma_f32_16x16x32_bf16 v[0:3], v[204:207], v[184:187], v[0:3]
	s_setprio 0
	v_cmp_gt_u32_e32 vcc, s95, v138
	s_barrier
	s_and_saveexec_b64 s[12:13], vcc
	s_cbranch_execz .LBB0_2583
	s_barrier
